# K-loop load segments: the LDS-DMA loads are issued before the segment's ds_reads (dependence-preserving reorder inside each barrier-bounded segment)
# speedup vs baseline: 1.0005x; 1.0005x over previous
.Llbb_0:
	s_add_i32 s47, s44, 2
	s_add_u32 s4, s42, 0x80
	s_addc_u32 s5, s43, 0
	s_add_i32 s54, 0, 0x10000
	s_cmp_eq_u32 s69, s44
	s_cselect_b32 s45, s13, s5
	s_cselect_b32 s44, s12, s4
	s_cselect_b32 vcc_hi, s1, s11
	s_cselect_b32 vcc_lo, s0, s10
	s_add_i32 s4, 0, 0x14000
	v_add_u32_e32 v140, s54, v223
	v_add_u32_e32 v156, s4, v223
	s_waitcnt lgkmcnt(0)
	ds_read_b128 v[128:131], v140
	ds_read_b128 v[132:135], v140 offset:1024
	ds_read_b128 v[136:139], v140 offset:2048
	ds_read_b128 v[140:143], v140 offset:3072
	ds_read_b128 v[144:147], v156
	ds_read_b128 v[148:151], v156 offset:1024
	ds_read_b128 v[152:155], v156 offset:2048
	ds_read_b128 v[156:159], v156 offset:3072
	v_lshl_add_u64 v[214:215], s[42:43], 0, v[194:195]
	s_add_i32 m0, s59, 0xc000
	ds_read_b128 v[160:163], v228
	ds_read_b128 v[164:167], v228 offset:1024
	ds_read_b128 v[168:171], v228 offset:2048
	ds_read_b128 v[172:175], v228 offset:3072
	ds_read_b128 v[198:201], v228 offset:4096
	ds_read_b128 v[202:205], v228 offset:5120
	ds_read_b128 v[206:209], v228 offset:6144
	ds_read_b128 v[210:213], v228 offset:7168
	global_load_lds_dwordx4 v[214:215], off
	v_lshl_add_u64 v[214:215], s[42:43], 0, v[196:197]
	s_add_i32 m0, s59, 0xe000
	s_nop 0
	global_load_lds_dwordx4 v[214:215], off
	s_waitcnt vmcnt(8)
	s_waitcnt lgkmcnt(0)
	s_barrier
	s_waitcnt lgkmcnt(0)
	v_mfma_f32_16x16x32_bf16 v[120:123], v[128:131], v[160:163], 0
	v_mfma_f32_16x16x32_bf16 v[116:119], v[136:139], v[160:163], 0
	v_mfma_f32_16x16x32_bf16 v[108:111], v[128:131], v[168:171], 0
	v_mfma_f32_16x16x32_bf16 v[100:103], v[136:139], v[168:171], 0
	v_mfma_f32_16x16x32_bf16 v[92:95], v[128:131], v[198:201], 0
	v_mfma_f32_16x16x32_bf16 v[84:87], v[136:139], v[198:201], 0
	v_mfma_f32_16x16x32_bf16 v[76:79], v[128:131], v[206:209], 0
	v_mfma_f32_16x16x32_bf16 v[68:71], v[136:139], v[206:209], 0
	v_mfma_f32_16x16x32_bf16 v[120:123], v[132:135], v[164:167], v[120:123]
	v_mfma_f32_16x16x32_bf16 v[116:119], v[140:143], v[164:167], v[116:119]
	v_mfma_f32_16x16x32_bf16 v[108:111], v[132:135], v[172:175], v[108:111]
	v_mfma_f32_16x16x32_bf16 v[100:103], v[140:143], v[172:175], v[100:103]
	v_mfma_f32_16x16x32_bf16 v[92:95], v[132:135], v[202:205], v[92:95]
	v_mfma_f32_16x16x32_bf16 v[84:87], v[140:143], v[202:205], v[84:87]
	v_mfma_f32_16x16x32_bf16 v[76:79], v[132:135], v[210:213], v[76:79]
	v_mfma_f32_16x16x32_bf16 v[68:71], v[140:143], v[210:213], v[68:71]
	v_mfma_f32_16x16x32_bf16 v[124:127], v[144:147], v[160:163], 0
	v_mfma_f32_16x16x32_bf16 v[112:115], v[152:155], v[160:163], 0
	v_mfma_f32_16x16x32_bf16 v[104:107], v[144:147], v[168:171], 0
	v_mfma_f32_16x16x32_bf16 v[96:99], v[152:155], v[168:171], 0
	v_mfma_f32_16x16x32_bf16 v[88:91], v[144:147], v[198:201], 0
	v_mfma_f32_16x16x32_bf16 v[80:83], v[152:155], v[198:201], 0
	v_mfma_f32_16x16x32_bf16 v[72:75], v[144:147], v[206:209], 0
	v_mfma_f32_16x16x32_bf16 v[64:67], v[152:155], v[206:209], 0
	v_mfma_f32_16x16x32_bf16 v[124:127], v[148:151], v[164:167], v[124:127]
	v_mfma_f32_16x16x32_bf16 v[112:115], v[156:159], v[164:167], v[112:115]
	v_mfma_f32_16x16x32_bf16 v[104:107], v[148:151], v[172:175], v[104:107]
	v_mfma_f32_16x16x32_bf16 v[96:99], v[156:159], v[172:175], v[96:99]
	v_mfma_f32_16x16x32_bf16 v[88:91], v[148:151], v[202:205], v[88:91]
	v_mfma_f32_16x16x32_bf16 v[80:83], v[156:159], v[202:205], v[80:83]
	v_mfma_f32_16x16x32_bf16 v[72:75], v[148:151], v[210:213], v[72:75]
	v_mfma_f32_16x16x32_bf16 v[64:67], v[156:159], v[210:213], v[64:67]
	s_barrier
	s_add_i32 s5, s54, s58
	v_lshl_add_u64 v[214:215], vcc, 0, v[190:191]
	s_mov_b32 m0, s5
	global_load_lds_dwordx4 v[214:215], off
	s_add_i32 m0, s5, 0x2000
	v_lshl_add_u64 v[216:217], vcc, 0, v[186:187]
	s_add_u32 vcc_lo, vcc_lo, s24
	s_addc_u32 vcc_hi, vcc_hi, s25
	s_add_i32 s4, s4, s58
	global_load_lds_dwordx4 v[216:217], off
	v_lshl_add_u64 v[230:231], vcc, 0, v[190:191]
	s_mov_b32 m0, s4
	v_lshl_add_u64 v[232:233], vcc, 0, v[186:187]
	global_load_lds_dwordx4 v[230:231], off
	s_add_i32 m0, s4, 0x2000
	v_lshl_add_u64 v[234:235], s[44:45], 0, v[192:193]
	global_load_lds_dwordx4 v[232:233], off
	s_mov_b32 m0, s59
	v_lshl_add_u64 v[236:237], s[44:45], 0, v[188:189]
	global_load_lds_dwordx4 v[234:235], off
	s_mov_b32 m0, s60
	s_nop 0
	global_load_lds_dwordx4 v[236:237], off
	ds_read_b128 v[160:163], v228 offset:16384
	ds_read_b128 v[164:167], v228 offset:17408
	ds_read_b128 v[168:171], v228 offset:18432
	ds_read_b128 v[172:175], v228 offset:19456
	ds_read_b128 v[198:201], v228 offset:20480
	ds_read_b128 v[202:205], v228 offset:21504
	ds_read_b128 v[206:209], v228 offset:22528
	ds_read_b128 v[210:213], v228 offset:23552
	s_waitcnt vmcnt(8)
	s_waitcnt lgkmcnt(0)
	s_barrier
	s_waitcnt lgkmcnt(0)
	v_mfma_f32_16x16x32_bf16 v[60:63], v[128:131], v[160:163], 0
	v_mfma_f32_16x16x32_bf16 v[52:55], v[136:139], v[160:163], 0
	v_mfma_f32_16x16x32_bf16 v[44:47], v[128:131], v[168:171], 0
	v_mfma_f32_16x16x32_bf16 v[36:39], v[136:139], v[168:171], 0
	v_mfma_f32_16x16x32_bf16 v[28:31], v[128:131], v[198:201], 0
	v_mfma_f32_16x16x32_bf16 v[20:23], v[136:139], v[198:201], 0
	v_mfma_f32_16x16x32_bf16 v[12:15], v[128:131], v[206:209], 0
	v_mfma_f32_16x16x32_bf16 v[4:7], v[136:139], v[206:209], 0
	v_mfma_f32_16x16x32_bf16 v[60:63], v[132:135], v[164:167], v[60:63]
	v_mfma_f32_16x16x32_bf16 v[52:55], v[140:143], v[164:167], v[52:55]
	v_mfma_f32_16x16x32_bf16 v[44:47], v[132:135], v[172:175], v[44:47]
	v_mfma_f32_16x16x32_bf16 v[36:39], v[140:143], v[172:175], v[36:39]
	v_mfma_f32_16x16x32_bf16 v[28:31], v[132:135], v[202:205], v[28:31]
	v_mfma_f32_16x16x32_bf16 v[20:23], v[140:143], v[202:205], v[20:23]
	v_mfma_f32_16x16x32_bf16 v[12:15], v[132:135], v[210:213], v[12:15]
	v_mfma_f32_16x16x32_bf16 v[4:7], v[140:143], v[210:213], v[4:7]
	v_mfma_f32_16x16x32_bf16 v[56:59], v[144:147], v[160:163], 0
	v_mfma_f32_16x16x32_bf16 v[48:51], v[152:155], v[160:163], 0
	v_mfma_f32_16x16x32_bf16 v[40:43], v[144:147], v[168:171], 0
	v_mfma_f32_16x16x32_bf16 v[32:35], v[152:155], v[168:171], 0
	v_mfma_f32_16x16x32_bf16 v[24:27], v[144:147], v[198:201], 0
	v_mfma_f32_16x16x32_bf16 v[16:19], v[152:155], v[198:201], 0
	v_mfma_f32_16x16x32_bf16 v[8:11], v[144:147], v[206:209], 0
	v_mfma_f32_16x16x32_bf16 v[0:3], v[152:155], v[206:209], 0
	v_mfma_f32_16x16x32_bf16 v[56:59], v[148:151], v[164:167], v[56:59]
	v_mfma_f32_16x16x32_bf16 v[48:51], v[156:159], v[164:167], v[48:51]
	v_mfma_f32_16x16x32_bf16 v[40:43], v[148:151], v[172:175], v[40:43]
	v_mfma_f32_16x16x32_bf16 v[32:35], v[156:159], v[172:175], v[32:35]
	v_mfma_f32_16x16x32_bf16 v[24:27], v[148:151], v[202:205], v[24:27]
	v_mfma_f32_16x16x32_bf16 v[16:19], v[156:159], v[202:205], v[16:19]
	v_mfma_f32_16x16x32_bf16 v[8:11], v[148:151], v[210:213], v[8:11]
	v_mfma_f32_16x16x32_bf16 v[0:3], v[156:159], v[210:213], v[0:3]
	s_barrier
	s_add_i32 s4, 0, 0x18000
	s_add_i32 s5, 0, 0x1c000
	s_add_u32 s44, s44, s24
	s_addc_u32 s45, s45, s25
	s_mov_b32 m0, s61
	v_lshl_add_u64 v[238:239], s[44:45], 0, v[192:193]
	global_load_lds_dwordx4 v[238:239], off
	v_lshl_add_u64 v[238:239], s[44:45], 0, v[188:189]
	s_mov_b32 m0, s62
	s_nop 0
	global_load_lds_dwordx4 v[238:239], off
	v_add_u32_e32 v140, s4, v223
	v_add_u32_e32 v156, s5, v223
	ds_read_b128 v[128:131], v140
	ds_read_b128 v[132:135], v140 offset:1024
	ds_read_b128 v[136:139], v140 offset:2048
	ds_read_b128 v[140:143], v140 offset:3072
	ds_read_b128 v[144:147], v156
	ds_read_b128 v[148:151], v156 offset:1024
	ds_read_b128 v[152:155], v156 offset:2048
	ds_read_b128 v[156:159], v156 offset:3072
	ds_read_b128 v[160:163], v228 offset:32768
	ds_read_b128 v[164:167], v228 offset:33792
	ds_read_b128 v[168:171], v228 offset:34816
	ds_read_b128 v[172:175], v228 offset:35840
	ds_read_b128 v[198:201], v228 offset:36864
	ds_read_b128 v[202:205], v228 offset:37888
	ds_read_b128 v[206:209], v228 offset:38912
	ds_read_b128 v[210:213], v228 offset:39936
	s_waitcnt vmcnt(8)
	s_waitcnt lgkmcnt(0)
	s_barrier
	s_waitcnt lgkmcnt(0)
	v_mfma_f32_16x16x32_bf16 v[120:123], v[128:131], v[160:163], v[120:123]
	v_mfma_f32_16x16x32_bf16 v[116:119], v[136:139], v[160:163], v[116:119]
	v_mfma_f32_16x16x32_bf16 v[108:111], v[128:131], v[168:171], v[108:111]
	v_mfma_f32_16x16x32_bf16 v[100:103], v[136:139], v[168:171], v[100:103]
	v_mfma_f32_16x16x32_bf16 v[92:95], v[128:131], v[198:201], v[92:95]
	v_mfma_f32_16x16x32_bf16 v[84:87], v[136:139], v[198:201], v[84:87]
	v_mfma_f32_16x16x32_bf16 v[76:79], v[128:131], v[206:209], v[76:79]
	v_mfma_f32_16x16x32_bf16 v[68:71], v[136:139], v[206:209], v[68:71]
	v_mfma_f32_16x16x32_bf16 v[120:123], v[132:135], v[164:167], v[120:123]
	v_mfma_f32_16x16x32_bf16 v[116:119], v[140:143], v[164:167], v[116:119]
	v_mfma_f32_16x16x32_bf16 v[108:111], v[132:135], v[172:175], v[108:111]
	v_mfma_f32_16x16x32_bf16 v[100:103], v[140:143], v[172:175], v[100:103]
	v_mfma_f32_16x16x32_bf16 v[92:95], v[132:135], v[202:205], v[92:95]
	v_mfma_f32_16x16x32_bf16 v[84:87], v[140:143], v[202:205], v[84:87]
	v_mfma_f32_16x16x32_bf16 v[76:79], v[132:135], v[210:213], v[76:79]
	v_mfma_f32_16x16x32_bf16 v[68:71], v[140:143], v[210:213], v[68:71]
	v_mfma_f32_16x16x32_bf16 v[124:127], v[144:147], v[160:163], v[124:127]
	v_mfma_f32_16x16x32_bf16 v[112:115], v[152:155], v[160:163], v[112:115]
	v_mfma_f32_16x16x32_bf16 v[104:107], v[144:147], v[168:171], v[104:107]
	v_mfma_f32_16x16x32_bf16 v[96:99], v[152:155], v[168:171], v[96:99]
	v_mfma_f32_16x16x32_bf16 v[88:91], v[144:147], v[198:201], v[88:91]
	v_mfma_f32_16x16x32_bf16 v[80:83], v[152:155], v[198:201], v[80:83]
	v_mfma_f32_16x16x32_bf16 v[72:75], v[144:147], v[206:209], v[72:75]
	v_mfma_f32_16x16x32_bf16 v[64:67], v[152:155], v[206:209], v[64:67]
	v_mfma_f32_16x16x32_bf16 v[124:127], v[148:151], v[164:167], v[124:127]
	v_mfma_f32_16x16x32_bf16 v[112:115], v[156:159], v[164:167], v[112:115]
	v_mfma_f32_16x16x32_bf16 v[104:107], v[148:151], v[172:175], v[104:107]
	v_mfma_f32_16x16x32_bf16 v[96:99], v[156:159], v[172:175], v[96:99]
	v_mfma_f32_16x16x32_bf16 v[88:91], v[148:151], v[202:205], v[88:91]
	v_mfma_f32_16x16x32_bf16 v[80:83], v[156:159], v[202:205], v[80:83]
	v_mfma_f32_16x16x32_bf16 v[72:75], v[148:151], v[210:213], v[72:75]
	v_mfma_f32_16x16x32_bf16 v[64:67], v[156:159], v[210:213], v[64:67]
	s_barrier
	s_add_i32 s4, s4, s58
	v_lshl_add_u64 v[214:215], v[214:215], 0, s[14:15]
	s_mov_b32 m0, s4
	global_load_lds_dwordx4 v[214:215], off
	v_lshl_add_u64 v[214:215], v[216:217], 0, s[14:15]
	s_add_i32 m0, s4, 0x2000
	s_add_i32 s4, s5, s58
	global_load_lds_dwordx4 v[214:215], off
	v_lshl_add_u64 v[214:215], v[230:231], 0, s[14:15]
	s_mov_b32 m0, s4
	s_nop 0
	global_load_lds_dwordx4 v[214:215], off
	v_lshl_add_u64 v[214:215], v[232:233], 0, s[14:15]
	s_add_i32 m0, s4, 0x2000
	s_nop 0
	global_load_lds_dwordx4 v[214:215], off
	v_lshl_add_u64 v[214:215], v[234:235], 0, s[14:15]
	s_mov_b32 m0, s63
	s_nop 0
	global_load_lds_dwordx4 v[214:215], off
	v_lshl_add_u64 v[214:215], v[236:237], 0, s[14:15]
	s_mov_b32 m0, s66
	s_nop 0
	global_load_lds_dwordx4 v[214:215], off
	ds_read_b128 v[160:163], v228 offset:49152
	ds_read_b128 v[164:167], v228 offset:50176
	ds_read_b128 v[168:171], v228 offset:51200
	ds_read_b128 v[172:175], v228 offset:52224
	ds_read_b128 v[198:201], v228 offset:53248
	ds_read_b128 v[202:205], v228 offset:54272
	ds_read_b128 v[206:209], v228 offset:55296
	ds_read_b128 v[210:213], v228 offset:56320
	s_waitcnt vmcnt(8)
	s_waitcnt lgkmcnt(0)
	s_barrier
	s_waitcnt lgkmcnt(0)
	v_mfma_f32_16x16x32_bf16 v[60:63], v[128:131], v[160:163], v[60:63]
	s_add_u32 s42, s42, 0x100
	v_mfma_f32_16x16x32_bf16 v[52:55], v[136:139], v[160:163], v[52:55]
	s_addc_u32 s43, s43, 0
	v_mfma_f32_16x16x32_bf16 v[44:47], v[128:131], v[168:171], v[44:47]
	s_add_u32 s10, s10, 0x100
	v_mfma_f32_16x16x32_bf16 v[36:39], v[136:139], v[168:171], v[36:39]
	s_addc_u32 s11, s11, 0
	v_mfma_f32_16x16x32_bf16 v[28:31], v[128:131], v[198:201], v[28:31]
	s_mov_b32 s44, s47
	v_mfma_f32_16x16x32_bf16 v[20:23], v[136:139], v[198:201], v[20:23]
	s_cmp_ge_i32 s47, s67
	v_mfma_f32_16x16x32_bf16 v[12:15], v[128:131], v[206:209], v[12:15]
	s_cselect_b32 s99, 1, 0
	v_mfma_f32_16x16x32_bf16 v[4:7], v[136:139], v[206:209], v[4:7]
	s_add_i32 s47, s44, 2
	v_mfma_f32_16x16x32_bf16 v[60:63], v[132:135], v[164:167], v[60:63]
	s_add_u32 s4, s42, 0x80
	v_mfma_f32_16x16x32_bf16 v[52:55], v[140:143], v[164:167], v[52:55]
	s_addc_u32 s5, s43, 0
	v_mfma_f32_16x16x32_bf16 v[44:47], v[132:135], v[172:175], v[44:47]
	s_add_i32 s54, 0, 0x10000
	v_mfma_f32_16x16x32_bf16 v[36:39], v[140:143], v[172:175], v[36:39]
	s_cmp_eq_u32 s69, s44
	v_mfma_f32_16x16x32_bf16 v[28:31], v[132:135], v[202:205], v[28:31]
	s_cselect_b32 s45, s13, s5
	v_mfma_f32_16x16x32_bf16 v[20:23], v[140:143], v[202:205], v[20:23]
	s_cselect_b32 s44, s12, s4
	v_mfma_f32_16x16x32_bf16 v[12:15], v[132:135], v[210:213], v[12:15]
	s_cselect_b32 vcc_hi, s1, s11
	v_mfma_f32_16x16x32_bf16 v[4:7], v[140:143], v[210:213], v[4:7]
	s_cselect_b32 vcc_lo, s0, s10
	v_mfma_f32_16x16x32_bf16 v[56:59], v[144:147], v[160:163], v[56:59]
	s_add_i32 s4, 0, 0x14000
	v_mfma_f32_16x16x32_bf16 v[48:51], v[152:155], v[160:163], v[48:51]
	v_mfma_f32_16x16x32_bf16 v[40:43], v[144:147], v[168:171], v[40:43]
	v_mfma_f32_16x16x32_bf16 v[32:35], v[152:155], v[168:171], v[32:35]
	v_mfma_f32_16x16x32_bf16 v[24:27], v[144:147], v[198:201], v[24:27]
	v_mfma_f32_16x16x32_bf16 v[16:19], v[152:155], v[198:201], v[16:19]
	v_mfma_f32_16x16x32_bf16 v[8:11], v[144:147], v[206:209], v[8:11]
	v_mfma_f32_16x16x32_bf16 v[0:3], v[152:155], v[206:209], v[0:3]
	v_mfma_f32_16x16x32_bf16 v[56:59], v[148:151], v[164:167], v[56:59]
	v_mfma_f32_16x16x32_bf16 v[48:51], v[156:159], v[164:167], v[48:51]
	v_mfma_f32_16x16x32_bf16 v[40:43], v[148:151], v[172:175], v[40:43]
	v_mfma_f32_16x16x32_bf16 v[32:35], v[156:159], v[172:175], v[32:35]
	v_mfma_f32_16x16x32_bf16 v[24:27], v[148:151], v[202:205], v[24:27]
	v_mfma_f32_16x16x32_bf16 v[16:19], v[156:159], v[202:205], v[16:19]
	v_mfma_f32_16x16x32_bf16 v[8:11], v[148:151], v[210:213], v[8:11]
	v_mfma_f32_16x16x32_bf16 v[0:3], v[156:159], v[210:213], v[0:3]
	s_barrier
	s_cmp_lg_u32 s99, 0
	s_cbranch_scc1 .Lpeelx_4
.LBB0_155:
	v_add_u32_e32 v140, s54, v223
	v_add_u32_e32 v156, s4, v223
	s_waitcnt lgkmcnt(0)
	ds_read_b128 v[128:131], v140
	ds_read_b128 v[132:135], v140 offset:1024
	ds_read_b128 v[136:139], v140 offset:2048
	ds_read_b128 v[140:143], v140 offset:3072
	ds_read_b128 v[144:147], v156
	ds_read_b128 v[148:151], v156 offset:1024
	ds_read_b128 v[152:155], v156 offset:2048
	ds_read_b128 v[156:159], v156 offset:3072
	v_lshl_add_u64 v[214:215], s[42:43], 0, v[194:195]
	s_add_i32 m0, s59, 0xc000
	ds_read_b128 v[160:163], v228
	ds_read_b128 v[164:167], v228 offset:1024
	ds_read_b128 v[168:171], v228 offset:2048
	ds_read_b128 v[172:175], v228 offset:3072
	ds_read_b128 v[198:201], v228 offset:4096
	ds_read_b128 v[202:205], v228 offset:5120
	ds_read_b128 v[206:209], v228 offset:6144
	ds_read_b128 v[210:213], v228 offset:7168
	global_load_lds_dwordx4 v[214:215], off
	v_lshl_add_u64 v[214:215], s[42:43], 0, v[196:197]
	s_add_i32 m0, s59, 0xe000
	s_nop 0
	global_load_lds_dwordx4 v[214:215], off
	s_waitcnt vmcnt(8)
	s_waitcnt lgkmcnt(0)
	s_barrier
	s_waitcnt lgkmcnt(0)
	v_mfma_f32_16x16x32_bf16 v[120:123], v[128:131], v[160:163], v[120:123]
	v_mfma_f32_16x16x32_bf16 v[116:119], v[136:139], v[160:163], v[116:119]
	v_mfma_f32_16x16x32_bf16 v[108:111], v[128:131], v[168:171], v[108:111]
	v_mfma_f32_16x16x32_bf16 v[100:103], v[136:139], v[168:171], v[100:103]
	v_mfma_f32_16x16x32_bf16 v[92:95], v[128:131], v[198:201], v[92:95]
	v_mfma_f32_16x16x32_bf16 v[84:87], v[136:139], v[198:201], v[84:87]
	v_mfma_f32_16x16x32_bf16 v[76:79], v[128:131], v[206:209], v[76:79]
	v_mfma_f32_16x16x32_bf16 v[68:71], v[136:139], v[206:209], v[68:71]
	v_mfma_f32_16x16x32_bf16 v[120:123], v[132:135], v[164:167], v[120:123]
	v_mfma_f32_16x16x32_bf16 v[116:119], v[140:143], v[164:167], v[116:119]
	v_mfma_f32_16x16x32_bf16 v[108:111], v[132:135], v[172:175], v[108:111]
	v_mfma_f32_16x16x32_bf16 v[100:103], v[140:143], v[172:175], v[100:103]
	v_mfma_f32_16x16x32_bf16 v[92:95], v[132:135], v[202:205], v[92:95]
	v_mfma_f32_16x16x32_bf16 v[84:87], v[140:143], v[202:205], v[84:87]
	v_mfma_f32_16x16x32_bf16 v[76:79], v[132:135], v[210:213], v[76:79]
	v_mfma_f32_16x16x32_bf16 v[68:71], v[140:143], v[210:213], v[68:71]
	v_mfma_f32_16x16x32_bf16 v[124:127], v[144:147], v[160:163], v[124:127]
	v_mfma_f32_16x16x32_bf16 v[112:115], v[152:155], v[160:163], v[112:115]
	v_mfma_f32_16x16x32_bf16 v[104:107], v[144:147], v[168:171], v[104:107]
	v_mfma_f32_16x16x32_bf16 v[96:99], v[152:155], v[168:171], v[96:99]
	v_mfma_f32_16x16x32_bf16 v[88:91], v[144:147], v[198:201], v[88:91]
	v_mfma_f32_16x16x32_bf16 v[80:83], v[152:155], v[198:201], v[80:83]
	v_mfma_f32_16x16x32_bf16 v[72:75], v[144:147], v[206:209], v[72:75]
	v_mfma_f32_16x16x32_bf16 v[64:67], v[152:155], v[206:209], v[64:67]
	v_mfma_f32_16x16x32_bf16 v[124:127], v[148:151], v[164:167], v[124:127]
	v_mfma_f32_16x16x32_bf16 v[112:115], v[156:159], v[164:167], v[112:115]
	v_mfma_f32_16x16x32_bf16 v[104:107], v[148:151], v[172:175], v[104:107]
	v_mfma_f32_16x16x32_bf16 v[96:99], v[156:159], v[172:175], v[96:99]
	v_mfma_f32_16x16x32_bf16 v[88:91], v[148:151], v[202:205], v[88:91]
	v_mfma_f32_16x16x32_bf16 v[80:83], v[156:159], v[202:205], v[80:83]
	v_mfma_f32_16x16x32_bf16 v[72:75], v[148:151], v[210:213], v[72:75]
	v_mfma_f32_16x16x32_bf16 v[64:67], v[156:159], v[210:213], v[64:67]
	s_barrier
	s_add_i32 s5, s54, s58
	v_lshl_add_u64 v[214:215], vcc, 0, v[190:191]
	s_mov_b32 m0, s5
	global_load_lds_dwordx4 v[214:215], off
	s_add_i32 m0, s5, 0x2000
	v_lshl_add_u64 v[216:217], vcc, 0, v[186:187]
	s_add_u32 vcc_lo, vcc_lo, s24
	s_addc_u32 vcc_hi, vcc_hi, s25
	s_add_i32 s4, s4, s58
	global_load_lds_dwordx4 v[216:217], off
	v_lshl_add_u64 v[230:231], vcc, 0, v[190:191]
	s_mov_b32 m0, s4
	v_lshl_add_u64 v[232:233], vcc, 0, v[186:187]
	global_load_lds_dwordx4 v[230:231], off
	s_add_i32 m0, s4, 0x2000
	v_lshl_add_u64 v[234:235], s[44:45], 0, v[192:193]
	global_load_lds_dwordx4 v[232:233], off
	s_mov_b32 m0, s59
	v_lshl_add_u64 v[236:237], s[44:45], 0, v[188:189]
	global_load_lds_dwordx4 v[234:235], off
	s_mov_b32 m0, s60
	s_nop 0
	global_load_lds_dwordx4 v[236:237], off
	ds_read_b128 v[160:163], v228 offset:16384
	ds_read_b128 v[164:167], v228 offset:17408
	ds_read_b128 v[168:171], v228 offset:18432
	ds_read_b128 v[172:175], v228 offset:19456
	ds_read_b128 v[198:201], v228 offset:20480
	ds_read_b128 v[202:205], v228 offset:21504
	ds_read_b128 v[206:209], v228 offset:22528
	ds_read_b128 v[210:213], v228 offset:23552
	s_waitcnt vmcnt(8)
	s_waitcnt lgkmcnt(0)
	s_barrier
	s_waitcnt lgkmcnt(0)
	v_mfma_f32_16x16x32_bf16 v[60:63], v[128:131], v[160:163], v[60:63]
	v_mfma_f32_16x16x32_bf16 v[52:55], v[136:139], v[160:163], v[52:55]
	v_mfma_f32_16x16x32_bf16 v[44:47], v[128:131], v[168:171], v[44:47]
	v_mfma_f32_16x16x32_bf16 v[36:39], v[136:139], v[168:171], v[36:39]
	v_mfma_f32_16x16x32_bf16 v[28:31], v[128:131], v[198:201], v[28:31]
	v_mfma_f32_16x16x32_bf16 v[20:23], v[136:139], v[198:201], v[20:23]
	v_mfma_f32_16x16x32_bf16 v[12:15], v[128:131], v[206:209], v[12:15]
	v_mfma_f32_16x16x32_bf16 v[4:7], v[136:139], v[206:209], v[4:7]
	v_mfma_f32_16x16x32_bf16 v[60:63], v[132:135], v[164:167], v[60:63]
	v_mfma_f32_16x16x32_bf16 v[52:55], v[140:143], v[164:167], v[52:55]
	v_mfma_f32_16x16x32_bf16 v[44:47], v[132:135], v[172:175], v[44:47]
	v_mfma_f32_16x16x32_bf16 v[36:39], v[140:143], v[172:175], v[36:39]
	v_mfma_f32_16x16x32_bf16 v[28:31], v[132:135], v[202:205], v[28:31]
	v_mfma_f32_16x16x32_bf16 v[20:23], v[140:143], v[202:205], v[20:23]
	v_mfma_f32_16x16x32_bf16 v[12:15], v[132:135], v[210:213], v[12:15]
	v_mfma_f32_16x16x32_bf16 v[4:7], v[140:143], v[210:213], v[4:7]
	v_mfma_f32_16x16x32_bf16 v[56:59], v[144:147], v[160:163], v[56:59]
	v_mfma_f32_16x16x32_bf16 v[48:51], v[152:155], v[160:163], v[48:51]
	v_mfma_f32_16x16x32_bf16 v[40:43], v[144:147], v[168:171], v[40:43]
	v_mfma_f32_16x16x32_bf16 v[32:35], v[152:155], v[168:171], v[32:35]
	v_mfma_f32_16x16x32_bf16 v[24:27], v[144:147], v[198:201], v[24:27]
	v_mfma_f32_16x16x32_bf16 v[16:19], v[152:155], v[198:201], v[16:19]
	v_mfma_f32_16x16x32_bf16 v[8:11], v[144:147], v[206:209], v[8:11]
	v_mfma_f32_16x16x32_bf16 v[0:3], v[152:155], v[206:209], v[0:3]
	v_mfma_f32_16x16x32_bf16 v[56:59], v[148:151], v[164:167], v[56:59]
	v_mfma_f32_16x16x32_bf16 v[48:51], v[156:159], v[164:167], v[48:51]
	v_mfma_f32_16x16x32_bf16 v[40:43], v[148:151], v[172:175], v[40:43]
	v_mfma_f32_16x16x32_bf16 v[32:35], v[156:159], v[172:175], v[32:35]
	v_mfma_f32_16x16x32_bf16 v[24:27], v[148:151], v[202:205], v[24:27]
	v_mfma_f32_16x16x32_bf16 v[16:19], v[156:159], v[202:205], v[16:19]
	v_mfma_f32_16x16x32_bf16 v[8:11], v[148:151], v[210:213], v[8:11]
	v_mfma_f32_16x16x32_bf16 v[0:3], v[156:159], v[210:213], v[0:3]
	s_barrier
	s_add_i32 s4, 0, 0x18000
	s_add_i32 s5, 0, 0x1c000
	s_add_u32 s44, s44, s24
	s_addc_u32 s45, s45, s25
	s_mov_b32 m0, s61
	v_lshl_add_u64 v[238:239], s[44:45], 0, v[192:193]
	global_load_lds_dwordx4 v[238:239], off
	v_lshl_add_u64 v[238:239], s[44:45], 0, v[188:189]
	s_mov_b32 m0, s62
	s_nop 0
	global_load_lds_dwordx4 v[238:239], off
	v_add_u32_e32 v140, s4, v223
	v_add_u32_e32 v156, s5, v223
	ds_read_b128 v[128:131], v140
	ds_read_b128 v[132:135], v140 offset:1024
	ds_read_b128 v[136:139], v140 offset:2048
	ds_read_b128 v[140:143], v140 offset:3072
	ds_read_b128 v[144:147], v156
	ds_read_b128 v[148:151], v156 offset:1024
	ds_read_b128 v[152:155], v156 offset:2048
	ds_read_b128 v[156:159], v156 offset:3072
	ds_read_b128 v[160:163], v228 offset:32768
	ds_read_b128 v[164:167], v228 offset:33792
	ds_read_b128 v[168:171], v228 offset:34816
	ds_read_b128 v[172:175], v228 offset:35840
	ds_read_b128 v[198:201], v228 offset:36864
	ds_read_b128 v[202:205], v228 offset:37888
	ds_read_b128 v[206:209], v228 offset:38912
	ds_read_b128 v[210:213], v228 offset:39936
	s_waitcnt vmcnt(8)
	s_waitcnt lgkmcnt(0)
	s_barrier
	s_waitcnt lgkmcnt(0)
	v_mfma_f32_16x16x32_bf16 v[120:123], v[128:131], v[160:163], v[120:123]
	v_mfma_f32_16x16x32_bf16 v[116:119], v[136:139], v[160:163], v[116:119]
	v_mfma_f32_16x16x32_bf16 v[108:111], v[128:131], v[168:171], v[108:111]
	v_mfma_f32_16x16x32_bf16 v[100:103], v[136:139], v[168:171], v[100:103]
	v_mfma_f32_16x16x32_bf16 v[92:95], v[128:131], v[198:201], v[92:95]
	v_mfma_f32_16x16x32_bf16 v[84:87], v[136:139], v[198:201], v[84:87]
	v_mfma_f32_16x16x32_bf16 v[76:79], v[128:131], v[206:209], v[76:79]
	v_mfma_f32_16x16x32_bf16 v[68:71], v[136:139], v[206:209], v[68:71]
	v_mfma_f32_16x16x32_bf16 v[120:123], v[132:135], v[164:167], v[120:123]
	v_mfma_f32_16x16x32_bf16 v[116:119], v[140:143], v[164:167], v[116:119]
	v_mfma_f32_16x16x32_bf16 v[108:111], v[132:135], v[172:175], v[108:111]
	v_mfma_f32_16x16x32_bf16 v[100:103], v[140:143], v[172:175], v[100:103]
	v_mfma_f32_16x16x32_bf16 v[92:95], v[132:135], v[202:205], v[92:95]
	v_mfma_f32_16x16x32_bf16 v[84:87], v[140:143], v[202:205], v[84:87]
	v_mfma_f32_16x16x32_bf16 v[76:79], v[132:135], v[210:213], v[76:79]
	v_mfma_f32_16x16x32_bf16 v[68:71], v[140:143], v[210:213], v[68:71]
	v_mfma_f32_16x16x32_bf16 v[124:127], v[144:147], v[160:163], v[124:127]
	v_mfma_f32_16x16x32_bf16 v[112:115], v[152:155], v[160:163], v[112:115]
	v_mfma_f32_16x16x32_bf16 v[104:107], v[144:147], v[168:171], v[104:107]
	v_mfma_f32_16x16x32_bf16 v[96:99], v[152:155], v[168:171], v[96:99]
	v_mfma_f32_16x16x32_bf16 v[88:91], v[144:147], v[198:201], v[88:91]
	v_mfma_f32_16x16x32_bf16 v[80:83], v[152:155], v[198:201], v[80:83]
	v_mfma_f32_16x16x32_bf16 v[72:75], v[144:147], v[206:209], v[72:75]
	v_mfma_f32_16x16x32_bf16 v[64:67], v[152:155], v[206:209], v[64:67]
	v_mfma_f32_16x16x32_bf16 v[124:127], v[148:151], v[164:167], v[124:127]
	v_mfma_f32_16x16x32_bf16 v[112:115], v[156:159], v[164:167], v[112:115]
	v_mfma_f32_16x16x32_bf16 v[104:107], v[148:151], v[172:175], v[104:107]
	v_mfma_f32_16x16x32_bf16 v[96:99], v[156:159], v[172:175], v[96:99]
	v_mfma_f32_16x16x32_bf16 v[88:91], v[148:151], v[202:205], v[88:91]
	v_mfma_f32_16x16x32_bf16 v[80:83], v[156:159], v[202:205], v[80:83]
	v_mfma_f32_16x16x32_bf16 v[72:75], v[148:151], v[210:213], v[72:75]
	v_mfma_f32_16x16x32_bf16 v[64:67], v[156:159], v[210:213], v[64:67]
	s_barrier
	s_add_i32 s4, s4, s58
	v_lshl_add_u64 v[214:215], v[214:215], 0, s[14:15]
	s_mov_b32 m0, s4
	global_load_lds_dwordx4 v[214:215], off
	v_lshl_add_u64 v[214:215], v[216:217], 0, s[14:15]
	s_add_i32 m0, s4, 0x2000
	s_add_i32 s4, s5, s58
	global_load_lds_dwordx4 v[214:215], off
	v_lshl_add_u64 v[214:215], v[230:231], 0, s[14:15]
	s_mov_b32 m0, s4
	s_nop 0
	global_load_lds_dwordx4 v[214:215], off
	v_lshl_add_u64 v[214:215], v[232:233], 0, s[14:15]
	s_add_i32 m0, s4, 0x2000
	s_nop 0
	global_load_lds_dwordx4 v[214:215], off
	v_lshl_add_u64 v[214:215], v[234:235], 0, s[14:15]
	s_mov_b32 m0, s63
	s_nop 0
	global_load_lds_dwordx4 v[214:215], off
	v_lshl_add_u64 v[214:215], v[236:237], 0, s[14:15]
	s_mov_b32 m0, s66
	s_nop 0
	global_load_lds_dwordx4 v[214:215], off
	ds_read_b128 v[160:163], v228 offset:49152
	ds_read_b128 v[164:167], v228 offset:50176
	ds_read_b128 v[168:171], v228 offset:51200
	ds_read_b128 v[172:175], v228 offset:52224
	ds_read_b128 v[198:201], v228 offset:53248
	ds_read_b128 v[202:205], v228 offset:54272
	ds_read_b128 v[206:209], v228 offset:55296
	ds_read_b128 v[210:213], v228 offset:56320
	s_waitcnt vmcnt(8)
	s_waitcnt lgkmcnt(0)
	s_barrier
	s_waitcnt lgkmcnt(0)
	v_mfma_f32_16x16x32_bf16 v[60:63], v[128:131], v[160:163], v[60:63]
	s_add_u32 s42, s42, 0x100
	v_mfma_f32_16x16x32_bf16 v[52:55], v[136:139], v[160:163], v[52:55]
	s_addc_u32 s43, s43, 0
	v_mfma_f32_16x16x32_bf16 v[44:47], v[128:131], v[168:171], v[44:47]
	s_add_u32 s10, s10, 0x100
	v_mfma_f32_16x16x32_bf16 v[36:39], v[136:139], v[168:171], v[36:39]
	s_addc_u32 s11, s11, 0
	v_mfma_f32_16x16x32_bf16 v[28:31], v[128:131], v[198:201], v[28:31]
	s_mov_b32 s44, s47
	v_mfma_f32_16x16x32_bf16 v[20:23], v[136:139], v[198:201], v[20:23]
	s_cmp_ge_i32 s47, s67
	v_mfma_f32_16x16x32_bf16 v[12:15], v[128:131], v[206:209], v[12:15]
	s_cselect_b32 s99, 1, 0
	v_mfma_f32_16x16x32_bf16 v[4:7], v[136:139], v[206:209], v[4:7]
	s_add_i32 s47, s44, 2
	v_mfma_f32_16x16x32_bf16 v[60:63], v[132:135], v[164:167], v[60:63]
	s_add_u32 s4, s42, 0x80
	v_mfma_f32_16x16x32_bf16 v[52:55], v[140:143], v[164:167], v[52:55]
	s_addc_u32 s5, s43, 0
	v_mfma_f32_16x16x32_bf16 v[44:47], v[132:135], v[172:175], v[44:47]
	s_add_i32 s54, 0, 0x10000
	v_mfma_f32_16x16x32_bf16 v[36:39], v[140:143], v[172:175], v[36:39]
	s_cmp_eq_u32 s69, s44
	v_mfma_f32_16x16x32_bf16 v[28:31], v[132:135], v[202:205], v[28:31]
	s_cselect_b32 s45, s13, s5
	v_mfma_f32_16x16x32_bf16 v[20:23], v[140:143], v[202:205], v[20:23]
	s_cselect_b32 s44, s12, s4
	v_mfma_f32_16x16x32_bf16 v[12:15], v[132:135], v[210:213], v[12:15]
	s_cselect_b32 vcc_hi, s1, s11
	v_mfma_f32_16x16x32_bf16 v[4:7], v[140:143], v[210:213], v[4:7]
	s_cselect_b32 vcc_lo, s0, s10
	v_mfma_f32_16x16x32_bf16 v[56:59], v[144:147], v[160:163], v[56:59]
	s_add_i32 s4, 0, 0x14000
	v_mfma_f32_16x16x32_bf16 v[48:51], v[152:155], v[160:163], v[48:51]
	v_mfma_f32_16x16x32_bf16 v[40:43], v[144:147], v[168:171], v[40:43]
	v_mfma_f32_16x16x32_bf16 v[32:35], v[152:155], v[168:171], v[32:35]
	v_mfma_f32_16x16x32_bf16 v[24:27], v[144:147], v[198:201], v[24:27]
	v_mfma_f32_16x16x32_bf16 v[16:19], v[152:155], v[198:201], v[16:19]
	v_mfma_f32_16x16x32_bf16 v[8:11], v[144:147], v[206:209], v[8:11]
	v_mfma_f32_16x16x32_bf16 v[0:3], v[152:155], v[206:209], v[0:3]
	v_mfma_f32_16x16x32_bf16 v[56:59], v[148:151], v[164:167], v[56:59]
	v_mfma_f32_16x16x32_bf16 v[48:51], v[156:159], v[164:167], v[48:51]
	v_mfma_f32_16x16x32_bf16 v[40:43], v[148:151], v[172:175], v[40:43]
	v_mfma_f32_16x16x32_bf16 v[32:35], v[156:159], v[172:175], v[32:35]
	v_mfma_f32_16x16x32_bf16 v[24:27], v[148:151], v[202:205], v[24:27]
	v_mfma_f32_16x16x32_bf16 v[16:19], v[156:159], v[202:205], v[16:19]
	v_mfma_f32_16x16x32_bf16 v[8:11], v[148:151], v[210:213], v[8:11]
	v_mfma_f32_16x16x32_bf16 v[0:3], v[156:159], v[210:213], v[0:3]
	s_barrier
	s_cmp_lg_u32 s99, 0
	s_cbranch_scc0 .LBB0_155

.Llbb_1:
	s_add_i32 s44, s34, 2
	s_add_u32 s4, s30, 0x80
	s_addc_u32 s5, s31, 0
	s_add_i32 s45, 0, 0x10000
	s_cmp_eq_u32 s62, s34
	s_cselect_b32 s35, s27, s5
	s_cselect_b32 s34, s26, s4
	s_cselect_b32 s5, s29, s11
	s_cselect_b32 s4, s28, s10
	s_add_i32 s54, 0, 0x14000
	v_lshl_add_u64 v[174:175], s[30:31], 0, v[162:163]
	s_add_i32 m0, s38, 0xc000
	global_load_lds_dwordx4 v[174:175], off
	v_lshl_add_u64 v[174:175], s[30:31], 0, v[164:165]
	s_add_i32 m0, s38, 0xe000
	s_nop 0
	global_load_lds_dwordx4 v[174:175], off
	v_add_u32_e32 v140, s45, v195
	v_add_u32_e32 v166, s54, v195
	ds_read_b128 v[128:131], v140
	ds_read_b128 v[132:135], v140 offset:1024
	ds_read_b128 v[136:139], v140 offset:2048
	ds_read_b128 v[140:143], v140 offset:3072
	ds_read_b128 v[144:147], v166
	ds_read_b128 v[148:151], v166 offset:1024
	ds_read_b128 v[152:155], v166 offset:2048
	ds_read_b128 v[166:169], v166 offset:3072
	ds_read_b128 v[170:173], v197
	ds_read_b128 v[186:189], v197 offset:1024
	ds_read_b128 v[190:193], v197 offset:2048
	ds_read_b128 v[198:201], v197 offset:3072
	ds_read_b128 v[202:205], v197 offset:4096
	ds_read_b128 v[206:209], v197 offset:5120
	ds_read_b128 v[210:213], v197 offset:6144
	ds_read_b128 v[214:217], v197 offset:7168
	s_waitcnt vmcnt(8)
	s_waitcnt lgkmcnt(0)
	s_barrier
	s_waitcnt lgkmcnt(0)
	v_mfma_f32_16x16x32_bf16 v[120:123], v[128:131], v[170:173], 0
	v_mfma_f32_16x16x32_bf16 v[124:127], v[136:139], v[170:173], 0
	v_mfma_f32_16x16x32_bf16 v[108:111], v[128:131], v[190:193], 0
	v_mfma_f32_16x16x32_bf16 v[104:107], v[136:139], v[190:193], 0
	v_mfma_f32_16x16x32_bf16 v[92:95], v[128:131], v[202:205], 0
	v_mfma_f32_16x16x32_bf16 v[88:91], v[136:139], v[202:205], 0
	v_mfma_f32_16x16x32_bf16 v[76:79], v[128:131], v[210:213], 0
	v_mfma_f32_16x16x32_bf16 v[72:75], v[136:139], v[210:213], 0
	v_mfma_f32_16x16x32_bf16 v[120:123], v[132:135], v[186:189], v[120:123]
	v_mfma_f32_16x16x32_bf16 v[124:127], v[140:143], v[186:189], v[124:127]
	v_mfma_f32_16x16x32_bf16 v[108:111], v[132:135], v[198:201], v[108:111]
	v_mfma_f32_16x16x32_bf16 v[104:107], v[140:143], v[198:201], v[104:107]
	v_mfma_f32_16x16x32_bf16 v[92:95], v[132:135], v[206:209], v[92:95]
	v_mfma_f32_16x16x32_bf16 v[88:91], v[140:143], v[206:209], v[88:91]
	v_mfma_f32_16x16x32_bf16 v[76:79], v[132:135], v[214:217], v[76:79]
	v_mfma_f32_16x16x32_bf16 v[72:75], v[140:143], v[214:217], v[72:75]
	v_mfma_f32_16x16x32_bf16 v[116:119], v[144:147], v[170:173], 0
	v_mfma_f32_16x16x32_bf16 v[112:115], v[152:155], v[170:173], 0
	v_mfma_f32_16x16x32_bf16 v[100:103], v[144:147], v[190:193], 0
	v_mfma_f32_16x16x32_bf16 v[96:99], v[152:155], v[190:193], 0
	v_mfma_f32_16x16x32_bf16 v[84:87], v[144:147], v[202:205], 0
	v_mfma_f32_16x16x32_bf16 v[80:83], v[152:155], v[202:205], 0
	v_mfma_f32_16x16x32_bf16 v[68:71], v[144:147], v[210:213], 0
	v_mfma_f32_16x16x32_bf16 v[64:67], v[152:155], v[210:213], 0
	v_mfma_f32_16x16x32_bf16 v[116:119], v[148:151], v[186:189], v[116:119]
	v_mfma_f32_16x16x32_bf16 v[112:115], v[166:169], v[186:189], v[112:115]
	v_mfma_f32_16x16x32_bf16 v[100:103], v[148:151], v[198:201], v[100:103]
	v_mfma_f32_16x16x32_bf16 v[96:99], v[166:169], v[198:201], v[96:99]
	v_mfma_f32_16x16x32_bf16 v[84:87], v[148:151], v[206:209], v[84:87]
	v_mfma_f32_16x16x32_bf16 v[80:83], v[166:169], v[206:209], v[80:83]
	v_mfma_f32_16x16x32_bf16 v[68:71], v[148:151], v[214:217], v[68:71]
	v_mfma_f32_16x16x32_bf16 v[64:67], v[166:169], v[214:217], v[64:67]
	s_barrier
	s_add_i32 s45, s45, s37
	v_lshl_add_u64 v[174:175], s[4:5], 0, v[176:177]
	s_mov_b32 m0, s45
	global_load_lds_dwordx4 v[174:175], off
	s_add_i32 m0, s45, 0x2000
	v_lshl_add_u64 v[222:223], s[4:5], 0, v[156:157]
	s_add_u32 s4, s4, s0
	s_addc_u32 s5, s5, s1
	s_add_i32 s45, s54, s37
	global_load_lds_dwordx4 v[222:223], off
	v_lshl_add_u64 v[224:225], s[4:5], 0, v[176:177]
	s_mov_b32 m0, s45
	v_lshl_add_u64 v[226:227], s[4:5], 0, v[156:157]
	global_load_lds_dwordx4 v[224:225], off
	s_add_i32 m0, s45, 0x2000
	v_lshl_add_u64 v[228:229], s[34:35], 0, v[160:161]
	global_load_lds_dwordx4 v[226:227], off
	s_mov_b32 m0, s38
	v_lshl_add_u64 v[230:231], s[34:35], 0, v[158:159]
	global_load_lds_dwordx4 v[228:229], off
	s_mov_b32 m0, s39
	s_nop 0
	global_load_lds_dwordx4 v[230:231], off
	ds_read_b128 v[170:173], v197 offset:16384
	ds_read_b128 v[186:189], v197 offset:17408
	ds_read_b128 v[190:193], v197 offset:18432
	ds_read_b128 v[198:201], v197 offset:19456
	ds_read_b128 v[202:205], v197 offset:20480
	ds_read_b128 v[206:209], v197 offset:21504
	ds_read_b128 v[210:213], v197 offset:22528
	ds_read_b128 v[214:217], v197 offset:23552
	s_waitcnt vmcnt(8)
	s_waitcnt lgkmcnt(0)
	s_barrier
	s_waitcnt lgkmcnt(0)
	v_mfma_f32_16x16x32_bf16 v[60:63], v[128:131], v[170:173], 0
	v_mfma_f32_16x16x32_bf16 v[56:59], v[136:139], v[170:173], 0
	v_mfma_f32_16x16x32_bf16 v[44:47], v[128:131], v[190:193], 0
	v_mfma_f32_16x16x32_bf16 v[40:43], v[136:139], v[190:193], 0
	v_mfma_f32_16x16x32_bf16 v[28:31], v[128:131], v[202:205], 0
	v_mfma_f32_16x16x32_bf16 v[24:27], v[136:139], v[202:205], 0
	v_mfma_f32_16x16x32_bf16 v[12:15], v[128:131], v[210:213], 0
	v_mfma_f32_16x16x32_bf16 v[8:11], v[136:139], v[210:213], 0
	v_mfma_f32_16x16x32_bf16 v[60:63], v[132:135], v[186:189], v[60:63]
	v_mfma_f32_16x16x32_bf16 v[56:59], v[140:143], v[186:189], v[56:59]
	v_mfma_f32_16x16x32_bf16 v[44:47], v[132:135], v[198:201], v[44:47]
	v_mfma_f32_16x16x32_bf16 v[40:43], v[140:143], v[198:201], v[40:43]
	v_mfma_f32_16x16x32_bf16 v[28:31], v[132:135], v[206:209], v[28:31]
	v_mfma_f32_16x16x32_bf16 v[24:27], v[140:143], v[206:209], v[24:27]
	v_mfma_f32_16x16x32_bf16 v[12:15], v[132:135], v[214:217], v[12:15]
	v_mfma_f32_16x16x32_bf16 v[8:11], v[140:143], v[214:217], v[8:11]
	v_mfma_f32_16x16x32_bf16 v[52:55], v[144:147], v[170:173], 0
	v_mfma_f32_16x16x32_bf16 v[48:51], v[152:155], v[170:173], 0
	v_mfma_f32_16x16x32_bf16 v[36:39], v[144:147], v[190:193], 0
	v_mfma_f32_16x16x32_bf16 v[32:35], v[152:155], v[190:193], 0
	v_mfma_f32_16x16x32_bf16 v[20:23], v[144:147], v[202:205], 0
	v_mfma_f32_16x16x32_bf16 v[16:19], v[152:155], v[202:205], 0
	v_mfma_f32_16x16x32_bf16 v[4:7], v[144:147], v[210:213], 0
	v_mfma_f32_16x16x32_bf16 v[0:3], v[152:155], v[210:213], 0
	v_mfma_f32_16x16x32_bf16 v[52:55], v[148:151], v[186:189], v[52:55]
	v_mfma_f32_16x16x32_bf16 v[48:51], v[166:169], v[186:189], v[48:51]
	v_mfma_f32_16x16x32_bf16 v[36:39], v[148:151], v[198:201], v[36:39]
	v_mfma_f32_16x16x32_bf16 v[32:35], v[166:169], v[198:201], v[32:35]
	v_mfma_f32_16x16x32_bf16 v[20:23], v[148:151], v[206:209], v[20:23]
	v_mfma_f32_16x16x32_bf16 v[16:19], v[166:169], v[206:209], v[16:19]
	v_mfma_f32_16x16x32_bf16 v[4:7], v[148:151], v[214:217], v[4:7]
	v_mfma_f32_16x16x32_bf16 v[0:3], v[166:169], v[214:217], v[0:3]
	s_barrier
	s_add_i32 s45, 0, 0x18000
	s_add_i32 s54, 0, 0x1c000
	s_add_u32 s4, s34, s0
	s_addc_u32 s5, s35, s1
	s_mov_b32 m0, s48
	v_lshl_add_u64 v[232:233], s[4:5], 0, v[160:161]
	global_load_lds_dwordx4 v[232:233], off
	v_lshl_add_u64 v[232:233], s[4:5], 0, v[158:159]
	s_mov_b32 m0, s49
	s_nop 0
	global_load_lds_dwordx4 v[232:233], off
	v_add_u32_e32 v140, s45, v195
	v_add_u32_e32 v166, s54, v195
	ds_read_b128 v[128:131], v140
	ds_read_b128 v[132:135], v140 offset:1024
	ds_read_b128 v[136:139], v140 offset:2048
	ds_read_b128 v[140:143], v140 offset:3072
	ds_read_b128 v[144:147], v166
	ds_read_b128 v[148:151], v166 offset:1024
	ds_read_b128 v[152:155], v166 offset:2048
	ds_read_b128 v[166:169], v166 offset:3072
	ds_read_b128 v[170:173], v197 offset:32768
	ds_read_b128 v[186:189], v197 offset:33792
	ds_read_b128 v[190:193], v197 offset:34816
	ds_read_b128 v[198:201], v197 offset:35840
	ds_read_b128 v[202:205], v197 offset:36864
	ds_read_b128 v[206:209], v197 offset:37888
	ds_read_b128 v[210:213], v197 offset:38912
	ds_read_b128 v[214:217], v197 offset:39936
	s_waitcnt vmcnt(8)
	s_waitcnt lgkmcnt(0)
	s_barrier
	s_waitcnt lgkmcnt(0)
	v_mfma_f32_16x16x32_bf16 v[120:123], v[128:131], v[170:173], v[120:123]
	v_mfma_f32_16x16x32_bf16 v[124:127], v[136:139], v[170:173], v[124:127]
	v_mfma_f32_16x16x32_bf16 v[108:111], v[128:131], v[190:193], v[108:111]
	v_mfma_f32_16x16x32_bf16 v[104:107], v[136:139], v[190:193], v[104:107]
	v_mfma_f32_16x16x32_bf16 v[92:95], v[128:131], v[202:205], v[92:95]
	v_mfma_f32_16x16x32_bf16 v[88:91], v[136:139], v[202:205], v[88:91]
	v_mfma_f32_16x16x32_bf16 v[76:79], v[128:131], v[210:213], v[76:79]
	v_mfma_f32_16x16x32_bf16 v[72:75], v[136:139], v[210:213], v[72:75]
	v_mfma_f32_16x16x32_bf16 v[120:123], v[132:135], v[186:189], v[120:123]
	v_mfma_f32_16x16x32_bf16 v[124:127], v[140:143], v[186:189], v[124:127]
	v_mfma_f32_16x16x32_bf16 v[108:111], v[132:135], v[198:201], v[108:111]
	v_mfma_f32_16x16x32_bf16 v[104:107], v[140:143], v[198:201], v[104:107]
	v_mfma_f32_16x16x32_bf16 v[92:95], v[132:135], v[206:209], v[92:95]
	v_mfma_f32_16x16x32_bf16 v[88:91], v[140:143], v[206:209], v[88:91]
	v_mfma_f32_16x16x32_bf16 v[76:79], v[132:135], v[214:217], v[76:79]
	v_mfma_f32_16x16x32_bf16 v[72:75], v[140:143], v[214:217], v[72:75]
	v_mfma_f32_16x16x32_bf16 v[116:119], v[144:147], v[170:173], v[116:119]
	v_mfma_f32_16x16x32_bf16 v[112:115], v[152:155], v[170:173], v[112:115]
	v_mfma_f32_16x16x32_bf16 v[100:103], v[144:147], v[190:193], v[100:103]
	v_mfma_f32_16x16x32_bf16 v[96:99], v[152:155], v[190:193], v[96:99]
	v_mfma_f32_16x16x32_bf16 v[84:87], v[144:147], v[202:205], v[84:87]
	v_mfma_f32_16x16x32_bf16 v[80:83], v[152:155], v[202:205], v[80:83]
	v_mfma_f32_16x16x32_bf16 v[68:71], v[144:147], v[210:213], v[68:71]
	v_mfma_f32_16x16x32_bf16 v[64:67], v[152:155], v[210:213], v[64:67]
	v_mfma_f32_16x16x32_bf16 v[116:119], v[148:151], v[186:189], v[116:119]
	v_mfma_f32_16x16x32_bf16 v[112:115], v[166:169], v[186:189], v[112:115]
	v_mfma_f32_16x16x32_bf16 v[100:103], v[148:151], v[198:201], v[100:103]
	v_mfma_f32_16x16x32_bf16 v[96:99], v[166:169], v[198:201], v[96:99]
	v_mfma_f32_16x16x32_bf16 v[84:87], v[148:151], v[206:209], v[84:87]
	v_mfma_f32_16x16x32_bf16 v[80:83], v[166:169], v[206:209], v[80:83]
	v_mfma_f32_16x16x32_bf16 v[68:71], v[148:151], v[214:217], v[68:71]
	v_mfma_f32_16x16x32_bf16 v[64:67], v[166:169], v[214:217], v[64:67]
	s_barrier
	s_add_i32 s4, s45, s37
	v_lshl_add_u64 v[174:175], v[174:175], 0, s[14:15]
	s_mov_b32 m0, s4
	global_load_lds_dwordx4 v[174:175], off
	v_lshl_add_u64 v[174:175], v[222:223], 0, s[14:15]
	s_add_i32 m0, s4, 0x2000
	s_add_i32 s4, s54, s37
	global_load_lds_dwordx4 v[174:175], off
	v_lshl_add_u64 v[174:175], v[224:225], 0, s[14:15]
	s_mov_b32 m0, s4
	s_nop 0
	global_load_lds_dwordx4 v[174:175], off
	v_lshl_add_u64 v[174:175], v[226:227], 0, s[14:15]
	s_add_i32 m0, s4, 0x2000
	s_nop 0
	global_load_lds_dwordx4 v[174:175], off
	v_lshl_add_u64 v[174:175], v[228:229], 0, s[14:15]
	s_mov_b32 m0, s60
	s_nop 0
	global_load_lds_dwordx4 v[174:175], off
	v_lshl_add_u64 v[174:175], v[230:231], 0, s[14:15]
	s_mov_b32 m0, s61
	s_nop 0
	global_load_lds_dwordx4 v[174:175], off
	ds_read_b128 v[170:173], v197 offset:49152
	ds_read_b128 v[186:189], v197 offset:50176
	ds_read_b128 v[190:193], v197 offset:51200
	ds_read_b128 v[198:201], v197 offset:52224
	ds_read_b128 v[202:205], v197 offset:53248
	ds_read_b128 v[206:209], v197 offset:54272
	ds_read_b128 v[210:213], v197 offset:55296
	ds_read_b128 v[214:217], v197 offset:56320
	s_waitcnt vmcnt(8)
	s_waitcnt lgkmcnt(0)
	s_barrier
	s_waitcnt lgkmcnt(0)
	v_mfma_f32_16x16x32_bf16 v[60:63], v[128:131], v[170:173], v[60:63]
	s_add_u32 s30, s30, 0x100
	v_mfma_f32_16x16x32_bf16 v[56:59], v[136:139], v[170:173], v[56:59]
	s_addc_u32 s31, s31, 0
	v_mfma_f32_16x16x32_bf16 v[44:47], v[128:131], v[190:193], v[44:47]
	s_add_u32 s10, s10, 0x100
	v_mfma_f32_16x16x32_bf16 v[40:43], v[136:139], v[190:193], v[40:43]
	s_addc_u32 s11, s11, 0
	v_mfma_f32_16x16x32_bf16 v[28:31], v[128:131], v[202:205], v[28:31]
	s_mov_b32 s34, s44
	v_mfma_f32_16x16x32_bf16 v[24:27], v[136:139], v[202:205], v[24:27]
	s_cmp_ge_i32 s44, s59
	v_mfma_f32_16x16x32_bf16 v[12:15], v[128:131], v[210:213], v[12:15]
	s_cselect_b32 s99, 1, 0
	v_mfma_f32_16x16x32_bf16 v[8:11], v[136:139], v[210:213], v[8:11]
	s_add_i32 s44, s34, 2
	v_mfma_f32_16x16x32_bf16 v[60:63], v[132:135], v[186:189], v[60:63]
	s_add_u32 s4, s30, 0x80
	v_mfma_f32_16x16x32_bf16 v[56:59], v[140:143], v[186:189], v[56:59]
	s_addc_u32 s5, s31, 0
	v_mfma_f32_16x16x32_bf16 v[44:47], v[132:135], v[198:201], v[44:47]
	s_add_i32 s45, 0, 0x10000
	v_mfma_f32_16x16x32_bf16 v[40:43], v[140:143], v[198:201], v[40:43]
	s_cmp_eq_u32 s62, s34
	v_mfma_f32_16x16x32_bf16 v[28:31], v[132:135], v[206:209], v[28:31]
	s_cselect_b32 s35, s27, s5
	v_mfma_f32_16x16x32_bf16 v[24:27], v[140:143], v[206:209], v[24:27]
	s_cselect_b32 s34, s26, s4
	v_mfma_f32_16x16x32_bf16 v[12:15], v[132:135], v[214:217], v[12:15]
	s_cselect_b32 s5, s29, s11
	v_mfma_f32_16x16x32_bf16 v[8:11], v[140:143], v[214:217], v[8:11]
	s_cselect_b32 s4, s28, s10
	v_mfma_f32_16x16x32_bf16 v[52:55], v[144:147], v[170:173], v[52:55]
	s_add_i32 s54, 0, 0x14000
	v_mfma_f32_16x16x32_bf16 v[48:51], v[152:155], v[170:173], v[48:51]
	v_mfma_f32_16x16x32_bf16 v[36:39], v[144:147], v[190:193], v[36:39]
	v_mfma_f32_16x16x32_bf16 v[32:35], v[152:155], v[190:193], v[32:35]
	v_mfma_f32_16x16x32_bf16 v[20:23], v[144:147], v[202:205], v[20:23]
	v_mfma_f32_16x16x32_bf16 v[16:19], v[152:155], v[202:205], v[16:19]
	v_mfma_f32_16x16x32_bf16 v[4:7], v[144:147], v[210:213], v[4:7]
	v_mfma_f32_16x16x32_bf16 v[0:3], v[152:155], v[210:213], v[0:3]
	v_mfma_f32_16x16x32_bf16 v[52:55], v[148:151], v[186:189], v[52:55]
	v_mfma_f32_16x16x32_bf16 v[48:51], v[166:169], v[186:189], v[48:51]
	v_mfma_f32_16x16x32_bf16 v[36:39], v[148:151], v[198:201], v[36:39]
	v_mfma_f32_16x16x32_bf16 v[32:35], v[166:169], v[198:201], v[32:35]
	v_mfma_f32_16x16x32_bf16 v[20:23], v[148:151], v[206:209], v[20:23]
	v_mfma_f32_16x16x32_bf16 v[16:19], v[166:169], v[206:209], v[16:19]
	v_mfma_f32_16x16x32_bf16 v[4:7], v[148:151], v[214:217], v[4:7]
	v_mfma_f32_16x16x32_bf16 v[0:3], v[166:169], v[214:217], v[0:3]
	s_barrier
	s_cmp_lg_u32 s99, 0
	s_cbranch_scc1 .Lpeelx_5
.LBB0_262:
	v_lshl_add_u64 v[174:175], s[30:31], 0, v[162:163]
	s_add_i32 m0, s38, 0xc000
	global_load_lds_dwordx4 v[174:175], off
	v_lshl_add_u64 v[174:175], s[30:31], 0, v[164:165]
	s_add_i32 m0, s38, 0xe000
	s_nop 0
	global_load_lds_dwordx4 v[174:175], off
	v_add_u32_e32 v140, s45, v195
	v_add_u32_e32 v166, s54, v195
	ds_read_b128 v[128:131], v140
	ds_read_b128 v[132:135], v140 offset:1024
	ds_read_b128 v[136:139], v140 offset:2048
	ds_read_b128 v[140:143], v140 offset:3072
	ds_read_b128 v[144:147], v166
	ds_read_b128 v[148:151], v166 offset:1024
	ds_read_b128 v[152:155], v166 offset:2048
	ds_read_b128 v[166:169], v166 offset:3072
	ds_read_b128 v[170:173], v197
	ds_read_b128 v[186:189], v197 offset:1024
	ds_read_b128 v[190:193], v197 offset:2048
	ds_read_b128 v[198:201], v197 offset:3072
	ds_read_b128 v[202:205], v197 offset:4096
	ds_read_b128 v[206:209], v197 offset:5120
	ds_read_b128 v[210:213], v197 offset:6144
	ds_read_b128 v[214:217], v197 offset:7168
	s_waitcnt vmcnt(8)
	s_waitcnt lgkmcnt(0)
	s_barrier
	s_waitcnt lgkmcnt(0)
	v_mfma_f32_16x16x32_bf16 v[120:123], v[128:131], v[170:173], v[120:123]
	v_mfma_f32_16x16x32_bf16 v[124:127], v[136:139], v[170:173], v[124:127]
	v_mfma_f32_16x16x32_bf16 v[108:111], v[128:131], v[190:193], v[108:111]
	v_mfma_f32_16x16x32_bf16 v[104:107], v[136:139], v[190:193], v[104:107]
	v_mfma_f32_16x16x32_bf16 v[92:95], v[128:131], v[202:205], v[92:95]
	v_mfma_f32_16x16x32_bf16 v[88:91], v[136:139], v[202:205], v[88:91]
	v_mfma_f32_16x16x32_bf16 v[76:79], v[128:131], v[210:213], v[76:79]
	v_mfma_f32_16x16x32_bf16 v[72:75], v[136:139], v[210:213], v[72:75]
	v_mfma_f32_16x16x32_bf16 v[120:123], v[132:135], v[186:189], v[120:123]
	v_mfma_f32_16x16x32_bf16 v[124:127], v[140:143], v[186:189], v[124:127]
	v_mfma_f32_16x16x32_bf16 v[108:111], v[132:135], v[198:201], v[108:111]
	v_mfma_f32_16x16x32_bf16 v[104:107], v[140:143], v[198:201], v[104:107]
	v_mfma_f32_16x16x32_bf16 v[92:95], v[132:135], v[206:209], v[92:95]
	v_mfma_f32_16x16x32_bf16 v[88:91], v[140:143], v[206:209], v[88:91]
	v_mfma_f32_16x16x32_bf16 v[76:79], v[132:135], v[214:217], v[76:79]
	v_mfma_f32_16x16x32_bf16 v[72:75], v[140:143], v[214:217], v[72:75]
	v_mfma_f32_16x16x32_bf16 v[116:119], v[144:147], v[170:173], v[116:119]
	v_mfma_f32_16x16x32_bf16 v[112:115], v[152:155], v[170:173], v[112:115]
	v_mfma_f32_16x16x32_bf16 v[100:103], v[144:147], v[190:193], v[100:103]
	v_mfma_f32_16x16x32_bf16 v[96:99], v[152:155], v[190:193], v[96:99]
	v_mfma_f32_16x16x32_bf16 v[84:87], v[144:147], v[202:205], v[84:87]
	v_mfma_f32_16x16x32_bf16 v[80:83], v[152:155], v[202:205], v[80:83]
	v_mfma_f32_16x16x32_bf16 v[68:71], v[144:147], v[210:213], v[68:71]
	v_mfma_f32_16x16x32_bf16 v[64:67], v[152:155], v[210:213], v[64:67]
	v_mfma_f32_16x16x32_bf16 v[116:119], v[148:151], v[186:189], v[116:119]
	v_mfma_f32_16x16x32_bf16 v[112:115], v[166:169], v[186:189], v[112:115]
	v_mfma_f32_16x16x32_bf16 v[100:103], v[148:151], v[198:201], v[100:103]
	v_mfma_f32_16x16x32_bf16 v[96:99], v[166:169], v[198:201], v[96:99]
	v_mfma_f32_16x16x32_bf16 v[84:87], v[148:151], v[206:209], v[84:87]
	v_mfma_f32_16x16x32_bf16 v[80:83], v[166:169], v[206:209], v[80:83]
	v_mfma_f32_16x16x32_bf16 v[68:71], v[148:151], v[214:217], v[68:71]
	v_mfma_f32_16x16x32_bf16 v[64:67], v[166:169], v[214:217], v[64:67]
	s_barrier
	s_add_i32 s45, s45, s37
	v_lshl_add_u64 v[174:175], s[4:5], 0, v[176:177]
	s_mov_b32 m0, s45
	global_load_lds_dwordx4 v[174:175], off
	s_add_i32 m0, s45, 0x2000
	v_lshl_add_u64 v[222:223], s[4:5], 0, v[156:157]
	s_add_u32 s4, s4, s0
	s_addc_u32 s5, s5, s1
	s_add_i32 s45, s54, s37
	global_load_lds_dwordx4 v[222:223], off
	v_lshl_add_u64 v[224:225], s[4:5], 0, v[176:177]
	s_mov_b32 m0, s45
	v_lshl_add_u64 v[226:227], s[4:5], 0, v[156:157]
	global_load_lds_dwordx4 v[224:225], off
	s_add_i32 m0, s45, 0x2000
	v_lshl_add_u64 v[228:229], s[34:35], 0, v[160:161]
	global_load_lds_dwordx4 v[226:227], off
	s_mov_b32 m0, s38
	v_lshl_add_u64 v[230:231], s[34:35], 0, v[158:159]
	global_load_lds_dwordx4 v[228:229], off
	s_mov_b32 m0, s39
	s_nop 0
	global_load_lds_dwordx4 v[230:231], off
	ds_read_b128 v[170:173], v197 offset:16384
	ds_read_b128 v[186:189], v197 offset:17408
	ds_read_b128 v[190:193], v197 offset:18432
	ds_read_b128 v[198:201], v197 offset:19456
	ds_read_b128 v[202:205], v197 offset:20480
	ds_read_b128 v[206:209], v197 offset:21504
	ds_read_b128 v[210:213], v197 offset:22528
	ds_read_b128 v[214:217], v197 offset:23552
	s_waitcnt vmcnt(8)
	s_waitcnt lgkmcnt(0)
	s_barrier
	s_waitcnt lgkmcnt(0)
	v_mfma_f32_16x16x32_bf16 v[60:63], v[128:131], v[170:173], v[60:63]
	v_mfma_f32_16x16x32_bf16 v[56:59], v[136:139], v[170:173], v[56:59]
	v_mfma_f32_16x16x32_bf16 v[44:47], v[128:131], v[190:193], v[44:47]
	v_mfma_f32_16x16x32_bf16 v[40:43], v[136:139], v[190:193], v[40:43]
	v_mfma_f32_16x16x32_bf16 v[28:31], v[128:131], v[202:205], v[28:31]
	v_mfma_f32_16x16x32_bf16 v[24:27], v[136:139], v[202:205], v[24:27]
	v_mfma_f32_16x16x32_bf16 v[12:15], v[128:131], v[210:213], v[12:15]
	v_mfma_f32_16x16x32_bf16 v[8:11], v[136:139], v[210:213], v[8:11]
	v_mfma_f32_16x16x32_bf16 v[60:63], v[132:135], v[186:189], v[60:63]
	v_mfma_f32_16x16x32_bf16 v[56:59], v[140:143], v[186:189], v[56:59]
	v_mfma_f32_16x16x32_bf16 v[44:47], v[132:135], v[198:201], v[44:47]
	v_mfma_f32_16x16x32_bf16 v[40:43], v[140:143], v[198:201], v[40:43]
	v_mfma_f32_16x16x32_bf16 v[28:31], v[132:135], v[206:209], v[28:31]
	v_mfma_f32_16x16x32_bf16 v[24:27], v[140:143], v[206:209], v[24:27]
	v_mfma_f32_16x16x32_bf16 v[12:15], v[132:135], v[214:217], v[12:15]
	v_mfma_f32_16x16x32_bf16 v[8:11], v[140:143], v[214:217], v[8:11]
	v_mfma_f32_16x16x32_bf16 v[52:55], v[144:147], v[170:173], v[52:55]
	v_mfma_f32_16x16x32_bf16 v[48:51], v[152:155], v[170:173], v[48:51]
	v_mfma_f32_16x16x32_bf16 v[36:39], v[144:147], v[190:193], v[36:39]
	v_mfma_f32_16x16x32_bf16 v[32:35], v[152:155], v[190:193], v[32:35]
	v_mfma_f32_16x16x32_bf16 v[20:23], v[144:147], v[202:205], v[20:23]
	v_mfma_f32_16x16x32_bf16 v[16:19], v[152:155], v[202:205], v[16:19]
	v_mfma_f32_16x16x32_bf16 v[4:7], v[144:147], v[210:213], v[4:7]
	v_mfma_f32_16x16x32_bf16 v[0:3], v[152:155], v[210:213], v[0:3]
	v_mfma_f32_16x16x32_bf16 v[52:55], v[148:151], v[186:189], v[52:55]
	v_mfma_f32_16x16x32_bf16 v[48:51], v[166:169], v[186:189], v[48:51]
	v_mfma_f32_16x16x32_bf16 v[36:39], v[148:151], v[198:201], v[36:39]
	v_mfma_f32_16x16x32_bf16 v[32:35], v[166:169], v[198:201], v[32:35]
	v_mfma_f32_16x16x32_bf16 v[20:23], v[148:151], v[206:209], v[20:23]
	v_mfma_f32_16x16x32_bf16 v[16:19], v[166:169], v[206:209], v[16:19]
	v_mfma_f32_16x16x32_bf16 v[4:7], v[148:151], v[214:217], v[4:7]
	v_mfma_f32_16x16x32_bf16 v[0:3], v[166:169], v[214:217], v[0:3]
	s_barrier
	s_add_i32 s45, 0, 0x18000
	s_add_i32 s54, 0, 0x1c000
	s_add_u32 s4, s34, s0
	s_addc_u32 s5, s35, s1
	s_mov_b32 m0, s48
	v_lshl_add_u64 v[232:233], s[4:5], 0, v[160:161]
	global_load_lds_dwordx4 v[232:233], off
	v_lshl_add_u64 v[232:233], s[4:5], 0, v[158:159]
	s_mov_b32 m0, s49
	s_nop 0
	global_load_lds_dwordx4 v[232:233], off
	v_add_u32_e32 v140, s45, v195
	v_add_u32_e32 v166, s54, v195
	ds_read_b128 v[128:131], v140
	ds_read_b128 v[132:135], v140 offset:1024
	ds_read_b128 v[136:139], v140 offset:2048
	ds_read_b128 v[140:143], v140 offset:3072
	ds_read_b128 v[144:147], v166
	ds_read_b128 v[148:151], v166 offset:1024
	ds_read_b128 v[152:155], v166 offset:2048
	ds_read_b128 v[166:169], v166 offset:3072
	ds_read_b128 v[170:173], v197 offset:32768
	ds_read_b128 v[186:189], v197 offset:33792
	ds_read_b128 v[190:193], v197 offset:34816
	ds_read_b128 v[198:201], v197 offset:35840
	ds_read_b128 v[202:205], v197 offset:36864
	ds_read_b128 v[206:209], v197 offset:37888
	ds_read_b128 v[210:213], v197 offset:38912
	ds_read_b128 v[214:217], v197 offset:39936
	s_waitcnt vmcnt(8)
	s_waitcnt lgkmcnt(0)
	s_barrier
	s_waitcnt lgkmcnt(0)
	v_mfma_f32_16x16x32_bf16 v[120:123], v[128:131], v[170:173], v[120:123]
	v_mfma_f32_16x16x32_bf16 v[124:127], v[136:139], v[170:173], v[124:127]
	v_mfma_f32_16x16x32_bf16 v[108:111], v[128:131], v[190:193], v[108:111]
	v_mfma_f32_16x16x32_bf16 v[104:107], v[136:139], v[190:193], v[104:107]
	v_mfma_f32_16x16x32_bf16 v[92:95], v[128:131], v[202:205], v[92:95]
	v_mfma_f32_16x16x32_bf16 v[88:91], v[136:139], v[202:205], v[88:91]
	v_mfma_f32_16x16x32_bf16 v[76:79], v[128:131], v[210:213], v[76:79]
	v_mfma_f32_16x16x32_bf16 v[72:75], v[136:139], v[210:213], v[72:75]
	v_mfma_f32_16x16x32_bf16 v[120:123], v[132:135], v[186:189], v[120:123]
	v_mfma_f32_16x16x32_bf16 v[124:127], v[140:143], v[186:189], v[124:127]
	v_mfma_f32_16x16x32_bf16 v[108:111], v[132:135], v[198:201], v[108:111]
	v_mfma_f32_16x16x32_bf16 v[104:107], v[140:143], v[198:201], v[104:107]
	v_mfma_f32_16x16x32_bf16 v[92:95], v[132:135], v[206:209], v[92:95]
	v_mfma_f32_16x16x32_bf16 v[88:91], v[140:143], v[206:209], v[88:91]
	v_mfma_f32_16x16x32_bf16 v[76:79], v[132:135], v[214:217], v[76:79]
	v_mfma_f32_16x16x32_bf16 v[72:75], v[140:143], v[214:217], v[72:75]
	v_mfma_f32_16x16x32_bf16 v[116:119], v[144:147], v[170:173], v[116:119]
	v_mfma_f32_16x16x32_bf16 v[112:115], v[152:155], v[170:173], v[112:115]
	v_mfma_f32_16x16x32_bf16 v[100:103], v[144:147], v[190:193], v[100:103]
	v_mfma_f32_16x16x32_bf16 v[96:99], v[152:155], v[190:193], v[96:99]
	v_mfma_f32_16x16x32_bf16 v[84:87], v[144:147], v[202:205], v[84:87]
	v_mfma_f32_16x16x32_bf16 v[80:83], v[152:155], v[202:205], v[80:83]
	v_mfma_f32_16x16x32_bf16 v[68:71], v[144:147], v[210:213], v[68:71]
	v_mfma_f32_16x16x32_bf16 v[64:67], v[152:155], v[210:213], v[64:67]
	v_mfma_f32_16x16x32_bf16 v[116:119], v[148:151], v[186:189], v[116:119]
	v_mfma_f32_16x16x32_bf16 v[112:115], v[166:169], v[186:189], v[112:115]
	v_mfma_f32_16x16x32_bf16 v[100:103], v[148:151], v[198:201], v[100:103]
	v_mfma_f32_16x16x32_bf16 v[96:99], v[166:169], v[198:201], v[96:99]
	v_mfma_f32_16x16x32_bf16 v[84:87], v[148:151], v[206:209], v[84:87]
	v_mfma_f32_16x16x32_bf16 v[80:83], v[166:169], v[206:209], v[80:83]
	v_mfma_f32_16x16x32_bf16 v[68:71], v[148:151], v[214:217], v[68:71]
	v_mfma_f32_16x16x32_bf16 v[64:67], v[166:169], v[214:217], v[64:67]
	s_barrier
	s_add_i32 s4, s45, s37
	v_lshl_add_u64 v[174:175], v[174:175], 0, s[14:15]
	s_mov_b32 m0, s4
	global_load_lds_dwordx4 v[174:175], off
	v_lshl_add_u64 v[174:175], v[222:223], 0, s[14:15]
	s_add_i32 m0, s4, 0x2000
	s_add_i32 s4, s54, s37
	global_load_lds_dwordx4 v[174:175], off
	v_lshl_add_u64 v[174:175], v[224:225], 0, s[14:15]
	s_mov_b32 m0, s4
	s_nop 0
	global_load_lds_dwordx4 v[174:175], off
	v_lshl_add_u64 v[174:175], v[226:227], 0, s[14:15]
	s_add_i32 m0, s4, 0x2000
	s_nop 0
	global_load_lds_dwordx4 v[174:175], off
	v_lshl_add_u64 v[174:175], v[228:229], 0, s[14:15]
	s_mov_b32 m0, s60
	s_nop 0
	global_load_lds_dwordx4 v[174:175], off
	v_lshl_add_u64 v[174:175], v[230:231], 0, s[14:15]
	s_mov_b32 m0, s61
	s_nop 0
	global_load_lds_dwordx4 v[174:175], off
	ds_read_b128 v[170:173], v197 offset:49152
	ds_read_b128 v[186:189], v197 offset:50176
	ds_read_b128 v[190:193], v197 offset:51200
	ds_read_b128 v[198:201], v197 offset:52224
	ds_read_b128 v[202:205], v197 offset:53248
	ds_read_b128 v[206:209], v197 offset:54272
	ds_read_b128 v[210:213], v197 offset:55296
	ds_read_b128 v[214:217], v197 offset:56320
	s_waitcnt vmcnt(8)
	s_waitcnt lgkmcnt(0)
	s_barrier
	s_waitcnt lgkmcnt(0)
	v_mfma_f32_16x16x32_bf16 v[60:63], v[128:131], v[170:173], v[60:63]
	s_add_u32 s30, s30, 0x100
	v_mfma_f32_16x16x32_bf16 v[56:59], v[136:139], v[170:173], v[56:59]
	s_addc_u32 s31, s31, 0
	v_mfma_f32_16x16x32_bf16 v[44:47], v[128:131], v[190:193], v[44:47]
	s_add_u32 s10, s10, 0x100
	v_mfma_f32_16x16x32_bf16 v[40:43], v[136:139], v[190:193], v[40:43]
	s_addc_u32 s11, s11, 0
	v_mfma_f32_16x16x32_bf16 v[28:31], v[128:131], v[202:205], v[28:31]
	s_mov_b32 s34, s44
	v_mfma_f32_16x16x32_bf16 v[24:27], v[136:139], v[202:205], v[24:27]
	s_cmp_ge_i32 s44, s59
	v_mfma_f32_16x16x32_bf16 v[12:15], v[128:131], v[210:213], v[12:15]
	s_cselect_b32 s99, 1, 0
	v_mfma_f32_16x16x32_bf16 v[8:11], v[136:139], v[210:213], v[8:11]
	s_add_i32 s44, s34, 2
	v_mfma_f32_16x16x32_bf16 v[60:63], v[132:135], v[186:189], v[60:63]
	s_add_u32 s4, s30, 0x80
	v_mfma_f32_16x16x32_bf16 v[56:59], v[140:143], v[186:189], v[56:59]
	s_addc_u32 s5, s31, 0
	v_mfma_f32_16x16x32_bf16 v[44:47], v[132:135], v[198:201], v[44:47]
	s_add_i32 s45, 0, 0x10000
	v_mfma_f32_16x16x32_bf16 v[40:43], v[140:143], v[198:201], v[40:43]
	s_cmp_eq_u32 s62, s34
	v_mfma_f32_16x16x32_bf16 v[28:31], v[132:135], v[206:209], v[28:31]
	s_cselect_b32 s35, s27, s5
	v_mfma_f32_16x16x32_bf16 v[24:27], v[140:143], v[206:209], v[24:27]
	s_cselect_b32 s34, s26, s4
	v_mfma_f32_16x16x32_bf16 v[12:15], v[132:135], v[214:217], v[12:15]
	s_cselect_b32 s5, s29, s11
	v_mfma_f32_16x16x32_bf16 v[8:11], v[140:143], v[214:217], v[8:11]
	s_cselect_b32 s4, s28, s10
	v_mfma_f32_16x16x32_bf16 v[52:55], v[144:147], v[170:173], v[52:55]
	s_add_i32 s54, 0, 0x14000
	v_mfma_f32_16x16x32_bf16 v[48:51], v[152:155], v[170:173], v[48:51]
	v_mfma_f32_16x16x32_bf16 v[36:39], v[144:147], v[190:193], v[36:39]
	v_mfma_f32_16x16x32_bf16 v[32:35], v[152:155], v[190:193], v[32:35]
	v_mfma_f32_16x16x32_bf16 v[20:23], v[144:147], v[202:205], v[20:23]
	v_mfma_f32_16x16x32_bf16 v[16:19], v[152:155], v[202:205], v[16:19]
	v_mfma_f32_16x16x32_bf16 v[4:7], v[144:147], v[210:213], v[4:7]
	v_mfma_f32_16x16x32_bf16 v[0:3], v[152:155], v[210:213], v[0:3]
	v_mfma_f32_16x16x32_bf16 v[52:55], v[148:151], v[186:189], v[52:55]
	v_mfma_f32_16x16x32_bf16 v[48:51], v[166:169], v[186:189], v[48:51]
	v_mfma_f32_16x16x32_bf16 v[36:39], v[148:151], v[198:201], v[36:39]
	v_mfma_f32_16x16x32_bf16 v[32:35], v[166:169], v[198:201], v[32:35]
	v_mfma_f32_16x16x32_bf16 v[20:23], v[148:151], v[206:209], v[20:23]
	v_mfma_f32_16x16x32_bf16 v[16:19], v[166:169], v[206:209], v[16:19]
	v_mfma_f32_16x16x32_bf16 v[4:7], v[148:151], v[214:217], v[4:7]
	v_mfma_f32_16x16x32_bf16 v[0:3], v[166:169], v[214:217], v[0:3]
	s_barrier
	s_cmp_lg_u32 s99, 0
	s_cbranch_scc0 .LBB0_262

.Llbb_2:
	s_add_i32 s44, s34, 2
	s_add_u32 s4, s30, 0x80
	s_addc_u32 s5, s31, 0
	s_add_i32 s45, 0, 0x10000
	s_cmp_eq_u32 s62, s34
	s_cselect_b32 s35, s27, s5
	s_cselect_b32 s34, s26, s4
	s_cselect_b32 s5, s29, s11
	s_cselect_b32 s4, s28, s10
	s_add_i32 s54, 0, 0x14000
	v_lshl_add_u64 v[174:175], s[30:31], 0, v[150:151]
	s_add_i32 m0, s38, 0xc000
	global_load_lds_dwordx4 v[174:175], off
	v_lshl_add_u64 v[174:175], s[30:31], 0, v[152:153]
	s_add_i32 m0, s38, 0xe000
	s_nop 0
	global_load_lds_dwordx4 v[174:175], off
	v_add_u32_e32 v140, s45, v163
	v_add_u32_e32 v170, s54, v163
	ds_read_b128 v[128:131], v140
	ds_read_b128 v[132:135], v140 offset:1024
	ds_read_b128 v[136:139], v140 offset:2048
	ds_read_b128 v[140:143], v140 offset:3072
	ds_read_b128 v[154:157], v170
	ds_read_b128 v[158:161], v170 offset:1024
	ds_read_b128 v[166:169], v170 offset:2048
	ds_read_b128 v[170:173], v170 offset:3072
	ds_read_b128 v[186:189], v165
	ds_read_b128 v[190:193], v165 offset:1024
	ds_read_b128 v[194:197], v165 offset:2048
	ds_read_b128 v[198:201], v165 offset:3072
	ds_read_b128 v[202:205], v165 offset:4096
	ds_read_b128 v[206:209], v165 offset:5120
	ds_read_b128 v[210:213], v165 offset:6144
	ds_read_b128 v[214:217], v165 offset:7168
	s_waitcnt vmcnt(8)
	s_waitcnt lgkmcnt(0)
	s_barrier
	s_waitcnt lgkmcnt(0)
	v_mfma_f32_16x16x32_bf16 v[124:127], v[128:131], v[186:189], 0
	v_mfma_f32_16x16x32_bf16 v[120:123], v[136:139], v[186:189], 0
	v_mfma_f32_16x16x32_bf16 v[108:111], v[128:131], v[194:197], 0
	v_mfma_f32_16x16x32_bf16 v[104:107], v[136:139], v[194:197], 0
	v_mfma_f32_16x16x32_bf16 v[92:95], v[128:131], v[202:205], 0
	v_mfma_f32_16x16x32_bf16 v[88:91], v[136:139], v[202:205], 0
	v_mfma_f32_16x16x32_bf16 v[76:79], v[128:131], v[210:213], 0
	v_mfma_f32_16x16x32_bf16 v[72:75], v[136:139], v[210:213], 0
	v_mfma_f32_16x16x32_bf16 v[124:127], v[132:135], v[190:193], v[124:127]
	v_mfma_f32_16x16x32_bf16 v[120:123], v[140:143], v[190:193], v[120:123]
	v_mfma_f32_16x16x32_bf16 v[108:111], v[132:135], v[198:201], v[108:111]
	v_mfma_f32_16x16x32_bf16 v[104:107], v[140:143], v[198:201], v[104:107]
	v_mfma_f32_16x16x32_bf16 v[92:95], v[132:135], v[206:209], v[92:95]
	v_mfma_f32_16x16x32_bf16 v[88:91], v[140:143], v[206:209], v[88:91]
	v_mfma_f32_16x16x32_bf16 v[76:79], v[132:135], v[214:217], v[76:79]
	v_mfma_f32_16x16x32_bf16 v[72:75], v[140:143], v[214:217], v[72:75]
	v_mfma_f32_16x16x32_bf16 v[116:119], v[154:157], v[186:189], 0
	v_mfma_f32_16x16x32_bf16 v[112:115], v[166:169], v[186:189], 0
	v_mfma_f32_16x16x32_bf16 v[100:103], v[154:157], v[194:197], 0
	v_mfma_f32_16x16x32_bf16 v[96:99], v[166:169], v[194:197], 0
	v_mfma_f32_16x16x32_bf16 v[84:87], v[154:157], v[202:205], 0
	v_mfma_f32_16x16x32_bf16 v[80:83], v[166:169], v[202:205], 0
	v_mfma_f32_16x16x32_bf16 v[68:71], v[154:157], v[210:213], 0
	v_mfma_f32_16x16x32_bf16 v[64:67], v[166:169], v[210:213], 0
	v_mfma_f32_16x16x32_bf16 v[116:119], v[158:161], v[190:193], v[116:119]
	v_mfma_f32_16x16x32_bf16 v[112:115], v[170:173], v[190:193], v[112:115]
	v_mfma_f32_16x16x32_bf16 v[100:103], v[158:161], v[198:201], v[100:103]
	v_mfma_f32_16x16x32_bf16 v[96:99], v[170:173], v[198:201], v[96:99]
	v_mfma_f32_16x16x32_bf16 v[84:87], v[158:161], v[206:209], v[84:87]
	v_mfma_f32_16x16x32_bf16 v[80:83], v[170:173], v[206:209], v[80:83]
	v_mfma_f32_16x16x32_bf16 v[68:71], v[158:161], v[214:217], v[68:71]
	v_mfma_f32_16x16x32_bf16 v[64:67], v[170:173], v[214:217], v[64:67]
	s_barrier
	s_add_i32 s45, s45, s37
	v_lshl_add_u64 v[174:175], s[4:5], 0, v[176:177]
	s_mov_b32 m0, s45
	global_load_lds_dwordx4 v[174:175], off
	s_add_i32 m0, s45, 0x2000
	v_lshl_add_u64 v[222:223], s[4:5], 0, v[144:145]
	s_add_u32 s4, s4, s0
	s_addc_u32 s5, s5, s1
	s_add_i32 s45, s54, s37
	global_load_lds_dwordx4 v[222:223], off
	v_lshl_add_u64 v[224:225], s[4:5], 0, v[176:177]
	s_mov_b32 m0, s45
	v_lshl_add_u64 v[226:227], s[4:5], 0, v[144:145]
	global_load_lds_dwordx4 v[224:225], off
	s_add_i32 m0, s45, 0x2000
	v_lshl_add_u64 v[228:229], s[34:35], 0, v[148:149]
	global_load_lds_dwordx4 v[226:227], off
	s_mov_b32 m0, s38
	v_lshl_add_u64 v[230:231], s[34:35], 0, v[146:147]
	global_load_lds_dwordx4 v[228:229], off
	s_mov_b32 m0, s39
	s_nop 0
	global_load_lds_dwordx4 v[230:231], off
	ds_read_b128 v[186:189], v165 offset:16384
	ds_read_b128 v[190:193], v165 offset:17408
	ds_read_b128 v[194:197], v165 offset:18432
	ds_read_b128 v[198:201], v165 offset:19456
	ds_read_b128 v[202:205], v165 offset:20480
	ds_read_b128 v[206:209], v165 offset:21504
	ds_read_b128 v[210:213], v165 offset:22528
	ds_read_b128 v[214:217], v165 offset:23552
	s_waitcnt vmcnt(8)
	s_waitcnt lgkmcnt(0)
	s_barrier
	s_waitcnt lgkmcnt(0)
	v_mfma_f32_16x16x32_bf16 v[60:63], v[128:131], v[186:189], 0
	v_mfma_f32_16x16x32_bf16 v[56:59], v[136:139], v[186:189], 0
	v_mfma_f32_16x16x32_bf16 v[44:47], v[128:131], v[194:197], 0
	v_mfma_f32_16x16x32_bf16 v[40:43], v[136:139], v[194:197], 0
	v_mfma_f32_16x16x32_bf16 v[28:31], v[128:131], v[202:205], 0
	v_mfma_f32_16x16x32_bf16 v[24:27], v[136:139], v[202:205], 0
	v_mfma_f32_16x16x32_bf16 v[12:15], v[128:131], v[210:213], 0
	v_mfma_f32_16x16x32_bf16 v[8:11], v[136:139], v[210:213], 0
	v_mfma_f32_16x16x32_bf16 v[60:63], v[132:135], v[190:193], v[60:63]
	v_mfma_f32_16x16x32_bf16 v[56:59], v[140:143], v[190:193], v[56:59]
	v_mfma_f32_16x16x32_bf16 v[44:47], v[132:135], v[198:201], v[44:47]
	v_mfma_f32_16x16x32_bf16 v[40:43], v[140:143], v[198:201], v[40:43]
	v_mfma_f32_16x16x32_bf16 v[28:31], v[132:135], v[206:209], v[28:31]
	v_mfma_f32_16x16x32_bf16 v[24:27], v[140:143], v[206:209], v[24:27]
	v_mfma_f32_16x16x32_bf16 v[12:15], v[132:135], v[214:217], v[12:15]
	v_mfma_f32_16x16x32_bf16 v[8:11], v[140:143], v[214:217], v[8:11]
	v_mfma_f32_16x16x32_bf16 v[52:55], v[154:157], v[186:189], 0
	v_mfma_f32_16x16x32_bf16 v[48:51], v[166:169], v[186:189], 0
	v_mfma_f32_16x16x32_bf16 v[36:39], v[154:157], v[194:197], 0
	v_mfma_f32_16x16x32_bf16 v[32:35], v[166:169], v[194:197], 0
	v_mfma_f32_16x16x32_bf16 v[20:23], v[154:157], v[202:205], 0
	v_mfma_f32_16x16x32_bf16 v[16:19], v[166:169], v[202:205], 0
	v_mfma_f32_16x16x32_bf16 v[4:7], v[154:157], v[210:213], 0
	v_mfma_f32_16x16x32_bf16 v[0:3], v[166:169], v[210:213], 0
	v_mfma_f32_16x16x32_bf16 v[52:55], v[158:161], v[190:193], v[52:55]
	v_mfma_f32_16x16x32_bf16 v[48:51], v[170:173], v[190:193], v[48:51]
	v_mfma_f32_16x16x32_bf16 v[36:39], v[158:161], v[198:201], v[36:39]
	v_mfma_f32_16x16x32_bf16 v[32:35], v[170:173], v[198:201], v[32:35]
	v_mfma_f32_16x16x32_bf16 v[20:23], v[158:161], v[206:209], v[20:23]
	v_mfma_f32_16x16x32_bf16 v[16:19], v[170:173], v[206:209], v[16:19]
	v_mfma_f32_16x16x32_bf16 v[4:7], v[158:161], v[214:217], v[4:7]
	v_mfma_f32_16x16x32_bf16 v[0:3], v[170:173], v[214:217], v[0:3]
	s_barrier
	s_add_i32 s45, 0, 0x18000
	s_add_i32 s54, 0, 0x1c000
	s_add_u32 s4, s34, s0
	s_addc_u32 s5, s35, s1
	s_mov_b32 m0, s48
	v_lshl_add_u64 v[232:233], s[4:5], 0, v[148:149]
	global_load_lds_dwordx4 v[232:233], off
	v_lshl_add_u64 v[232:233], s[4:5], 0, v[146:147]
	s_mov_b32 m0, s49
	s_nop 0
	global_load_lds_dwordx4 v[232:233], off
	v_add_u32_e32 v140, s45, v163
	v_add_u32_e32 v170, s54, v163
	ds_read_b128 v[128:131], v140
	ds_read_b128 v[132:135], v140 offset:1024
	ds_read_b128 v[136:139], v140 offset:2048
	ds_read_b128 v[140:143], v140 offset:3072
	ds_read_b128 v[154:157], v170
	ds_read_b128 v[158:161], v170 offset:1024
	ds_read_b128 v[166:169], v170 offset:2048
	ds_read_b128 v[170:173], v170 offset:3072
	ds_read_b128 v[186:189], v165 offset:32768
	ds_read_b128 v[190:193], v165 offset:33792
	ds_read_b128 v[194:197], v165 offset:34816
	ds_read_b128 v[198:201], v165 offset:35840
	ds_read_b128 v[202:205], v165 offset:36864
	ds_read_b128 v[206:209], v165 offset:37888
	ds_read_b128 v[210:213], v165 offset:38912
	ds_read_b128 v[214:217], v165 offset:39936
	s_waitcnt vmcnt(8)
	s_waitcnt lgkmcnt(0)
	s_barrier
	s_waitcnt lgkmcnt(0)
	v_mfma_f32_16x16x32_bf16 v[124:127], v[128:131], v[186:189], v[124:127]
	v_mfma_f32_16x16x32_bf16 v[120:123], v[136:139], v[186:189], v[120:123]
	v_mfma_f32_16x16x32_bf16 v[108:111], v[128:131], v[194:197], v[108:111]
	v_mfma_f32_16x16x32_bf16 v[104:107], v[136:139], v[194:197], v[104:107]
	v_mfma_f32_16x16x32_bf16 v[92:95], v[128:131], v[202:205], v[92:95]
	v_mfma_f32_16x16x32_bf16 v[88:91], v[136:139], v[202:205], v[88:91]
	v_mfma_f32_16x16x32_bf16 v[76:79], v[128:131], v[210:213], v[76:79]
	v_mfma_f32_16x16x32_bf16 v[72:75], v[136:139], v[210:213], v[72:75]
	v_mfma_f32_16x16x32_bf16 v[124:127], v[132:135], v[190:193], v[124:127]
	v_mfma_f32_16x16x32_bf16 v[120:123], v[140:143], v[190:193], v[120:123]
	v_mfma_f32_16x16x32_bf16 v[108:111], v[132:135], v[198:201], v[108:111]
	v_mfma_f32_16x16x32_bf16 v[104:107], v[140:143], v[198:201], v[104:107]
	v_mfma_f32_16x16x32_bf16 v[92:95], v[132:135], v[206:209], v[92:95]
	v_mfma_f32_16x16x32_bf16 v[88:91], v[140:143], v[206:209], v[88:91]
	v_mfma_f32_16x16x32_bf16 v[76:79], v[132:135], v[214:217], v[76:79]
	v_mfma_f32_16x16x32_bf16 v[72:75], v[140:143], v[214:217], v[72:75]
	v_mfma_f32_16x16x32_bf16 v[116:119], v[154:157], v[186:189], v[116:119]
	v_mfma_f32_16x16x32_bf16 v[112:115], v[166:169], v[186:189], v[112:115]
	v_mfma_f32_16x16x32_bf16 v[100:103], v[154:157], v[194:197], v[100:103]
	v_mfma_f32_16x16x32_bf16 v[96:99], v[166:169], v[194:197], v[96:99]
	v_mfma_f32_16x16x32_bf16 v[84:87], v[154:157], v[202:205], v[84:87]
	v_mfma_f32_16x16x32_bf16 v[80:83], v[166:169], v[202:205], v[80:83]
	v_mfma_f32_16x16x32_bf16 v[68:71], v[154:157], v[210:213], v[68:71]
	v_mfma_f32_16x16x32_bf16 v[64:67], v[166:169], v[210:213], v[64:67]
	v_mfma_f32_16x16x32_bf16 v[116:119], v[158:161], v[190:193], v[116:119]
	v_mfma_f32_16x16x32_bf16 v[112:115], v[170:173], v[190:193], v[112:115]
	v_mfma_f32_16x16x32_bf16 v[100:103], v[158:161], v[198:201], v[100:103]
	v_mfma_f32_16x16x32_bf16 v[96:99], v[170:173], v[198:201], v[96:99]
	v_mfma_f32_16x16x32_bf16 v[84:87], v[158:161], v[206:209], v[84:87]
	v_mfma_f32_16x16x32_bf16 v[80:83], v[170:173], v[206:209], v[80:83]
	v_mfma_f32_16x16x32_bf16 v[68:71], v[158:161], v[214:217], v[68:71]
	v_mfma_f32_16x16x32_bf16 v[64:67], v[170:173], v[214:217], v[64:67]
	s_barrier
	s_add_i32 s4, s45, s37
	v_lshl_add_u64 v[174:175], v[174:175], 0, s[14:15]
	s_mov_b32 m0, s4
	global_load_lds_dwordx4 v[174:175], off
	v_lshl_add_u64 v[174:175], v[222:223], 0, s[14:15]
	s_add_i32 m0, s4, 0x2000
	s_add_i32 s4, s54, s37
	global_load_lds_dwordx4 v[174:175], off
	v_lshl_add_u64 v[174:175], v[224:225], 0, s[14:15]
	s_mov_b32 m0, s4
	s_nop 0
	global_load_lds_dwordx4 v[174:175], off
	v_lshl_add_u64 v[174:175], v[226:227], 0, s[14:15]
	s_add_i32 m0, s4, 0x2000
	s_nop 0
	global_load_lds_dwordx4 v[174:175], off
	v_lshl_add_u64 v[174:175], v[228:229], 0, s[14:15]
	s_mov_b32 m0, s60
	s_nop 0
	global_load_lds_dwordx4 v[174:175], off
	v_lshl_add_u64 v[174:175], v[230:231], 0, s[14:15]
	s_mov_b32 m0, s61
	s_nop 0
	global_load_lds_dwordx4 v[174:175], off
	ds_read_b128 v[186:189], v165 offset:49152
	ds_read_b128 v[190:193], v165 offset:50176
	ds_read_b128 v[194:197], v165 offset:51200
	ds_read_b128 v[198:201], v165 offset:52224
	ds_read_b128 v[202:205], v165 offset:53248
	ds_read_b128 v[206:209], v165 offset:54272
	ds_read_b128 v[210:213], v165 offset:55296
	ds_read_b128 v[214:217], v165 offset:56320
	s_waitcnt vmcnt(8)
	s_waitcnt lgkmcnt(0)
	s_barrier
	s_waitcnt lgkmcnt(0)
	v_mfma_f32_16x16x32_bf16 v[60:63], v[128:131], v[186:189], v[60:63]
	s_add_u32 s30, s30, 0x100
	v_mfma_f32_16x16x32_bf16 v[56:59], v[136:139], v[186:189], v[56:59]
	s_addc_u32 s31, s31, 0
	v_mfma_f32_16x16x32_bf16 v[44:47], v[128:131], v[194:197], v[44:47]
	s_add_u32 s10, s10, 0x100
	v_mfma_f32_16x16x32_bf16 v[40:43], v[136:139], v[194:197], v[40:43]
	s_addc_u32 s11, s11, 0
	v_mfma_f32_16x16x32_bf16 v[28:31], v[128:131], v[202:205], v[28:31]
	s_mov_b32 s34, s44
	v_mfma_f32_16x16x32_bf16 v[24:27], v[136:139], v[202:205], v[24:27]
	s_cmp_ge_i32 s44, s59
	v_mfma_f32_16x16x32_bf16 v[12:15], v[128:131], v[210:213], v[12:15]
	s_cselect_b32 s99, 1, 0
	v_mfma_f32_16x16x32_bf16 v[8:11], v[136:139], v[210:213], v[8:11]
	s_add_i32 s44, s34, 2
	v_mfma_f32_16x16x32_bf16 v[60:63], v[132:135], v[190:193], v[60:63]
	s_add_u32 s4, s30, 0x80
	v_mfma_f32_16x16x32_bf16 v[56:59], v[140:143], v[190:193], v[56:59]
	s_addc_u32 s5, s31, 0
	v_mfma_f32_16x16x32_bf16 v[44:47], v[132:135], v[198:201], v[44:47]
	s_add_i32 s45, 0, 0x10000
	v_mfma_f32_16x16x32_bf16 v[40:43], v[140:143], v[198:201], v[40:43]
	s_cmp_eq_u32 s62, s34
	v_mfma_f32_16x16x32_bf16 v[28:31], v[132:135], v[206:209], v[28:31]
	s_cselect_b32 s35, s27, s5
	v_mfma_f32_16x16x32_bf16 v[24:27], v[140:143], v[206:209], v[24:27]
	s_cselect_b32 s34, s26, s4
	v_mfma_f32_16x16x32_bf16 v[12:15], v[132:135], v[214:217], v[12:15]
	s_cselect_b32 s5, s29, s11
	v_mfma_f32_16x16x32_bf16 v[8:11], v[140:143], v[214:217], v[8:11]
	s_cselect_b32 s4, s28, s10
	v_mfma_f32_16x16x32_bf16 v[52:55], v[154:157], v[186:189], v[52:55]
	s_add_i32 s54, 0, 0x14000
	v_mfma_f32_16x16x32_bf16 v[48:51], v[166:169], v[186:189], v[48:51]
	v_mfma_f32_16x16x32_bf16 v[36:39], v[154:157], v[194:197], v[36:39]
	v_mfma_f32_16x16x32_bf16 v[32:35], v[166:169], v[194:197], v[32:35]
	v_mfma_f32_16x16x32_bf16 v[20:23], v[154:157], v[202:205], v[20:23]
	v_mfma_f32_16x16x32_bf16 v[16:19], v[166:169], v[202:205], v[16:19]
	v_mfma_f32_16x16x32_bf16 v[4:7], v[154:157], v[210:213], v[4:7]
	v_mfma_f32_16x16x32_bf16 v[0:3], v[166:169], v[210:213], v[0:3]
	v_mfma_f32_16x16x32_bf16 v[52:55], v[158:161], v[190:193], v[52:55]
	v_mfma_f32_16x16x32_bf16 v[48:51], v[170:173], v[190:193], v[48:51]
	v_mfma_f32_16x16x32_bf16 v[36:39], v[158:161], v[198:201], v[36:39]
	v_mfma_f32_16x16x32_bf16 v[32:35], v[170:173], v[198:201], v[32:35]
	v_mfma_f32_16x16x32_bf16 v[20:23], v[158:161], v[206:209], v[20:23]
	v_mfma_f32_16x16x32_bf16 v[16:19], v[170:173], v[206:209], v[16:19]
	v_mfma_f32_16x16x32_bf16 v[4:7], v[158:161], v[214:217], v[4:7]
	v_mfma_f32_16x16x32_bf16 v[0:3], v[170:173], v[214:217], v[0:3]
	s_barrier
	s_cmp_lg_u32 s99, 0
	s_cbranch_scc1 .Lpeelx_6
.LBB0_305:
	v_lshl_add_u64 v[174:175], s[30:31], 0, v[150:151]
	s_add_i32 m0, s38, 0xc000
	global_load_lds_dwordx4 v[174:175], off
	v_lshl_add_u64 v[174:175], s[30:31], 0, v[152:153]
	s_add_i32 m0, s38, 0xe000
	s_nop 0
	global_load_lds_dwordx4 v[174:175], off
	v_add_u32_e32 v140, s45, v163
	v_add_u32_e32 v170, s54, v163
	ds_read_b128 v[128:131], v140
	ds_read_b128 v[132:135], v140 offset:1024
	ds_read_b128 v[136:139], v140 offset:2048
	ds_read_b128 v[140:143], v140 offset:3072
	ds_read_b128 v[154:157], v170
	ds_read_b128 v[158:161], v170 offset:1024
	ds_read_b128 v[166:169], v170 offset:2048
	ds_read_b128 v[170:173], v170 offset:3072
	ds_read_b128 v[186:189], v165
	ds_read_b128 v[190:193], v165 offset:1024
	ds_read_b128 v[194:197], v165 offset:2048
	ds_read_b128 v[198:201], v165 offset:3072
	ds_read_b128 v[202:205], v165 offset:4096
	ds_read_b128 v[206:209], v165 offset:5120
	ds_read_b128 v[210:213], v165 offset:6144
	ds_read_b128 v[214:217], v165 offset:7168
	s_waitcnt vmcnt(8)
	s_waitcnt lgkmcnt(0)
	s_barrier
	s_waitcnt lgkmcnt(0)
	v_mfma_f32_16x16x32_bf16 v[124:127], v[128:131], v[186:189], v[124:127]
	v_mfma_f32_16x16x32_bf16 v[120:123], v[136:139], v[186:189], v[120:123]
	v_mfma_f32_16x16x32_bf16 v[108:111], v[128:131], v[194:197], v[108:111]
	v_mfma_f32_16x16x32_bf16 v[104:107], v[136:139], v[194:197], v[104:107]
	v_mfma_f32_16x16x32_bf16 v[92:95], v[128:131], v[202:205], v[92:95]
	v_mfma_f32_16x16x32_bf16 v[88:91], v[136:139], v[202:205], v[88:91]
	v_mfma_f32_16x16x32_bf16 v[76:79], v[128:131], v[210:213], v[76:79]
	v_mfma_f32_16x16x32_bf16 v[72:75], v[136:139], v[210:213], v[72:75]
	v_mfma_f32_16x16x32_bf16 v[124:127], v[132:135], v[190:193], v[124:127]
	v_mfma_f32_16x16x32_bf16 v[120:123], v[140:143], v[190:193], v[120:123]
	v_mfma_f32_16x16x32_bf16 v[108:111], v[132:135], v[198:201], v[108:111]
	v_mfma_f32_16x16x32_bf16 v[104:107], v[140:143], v[198:201], v[104:107]
	v_mfma_f32_16x16x32_bf16 v[92:95], v[132:135], v[206:209], v[92:95]
	v_mfma_f32_16x16x32_bf16 v[88:91], v[140:143], v[206:209], v[88:91]
	v_mfma_f32_16x16x32_bf16 v[76:79], v[132:135], v[214:217], v[76:79]
	v_mfma_f32_16x16x32_bf16 v[72:75], v[140:143], v[214:217], v[72:75]
	v_mfma_f32_16x16x32_bf16 v[116:119], v[154:157], v[186:189], v[116:119]
	v_mfma_f32_16x16x32_bf16 v[112:115], v[166:169], v[186:189], v[112:115]
	v_mfma_f32_16x16x32_bf16 v[100:103], v[154:157], v[194:197], v[100:103]
	v_mfma_f32_16x16x32_bf16 v[96:99], v[166:169], v[194:197], v[96:99]
	v_mfma_f32_16x16x32_bf16 v[84:87], v[154:157], v[202:205], v[84:87]
	v_mfma_f32_16x16x32_bf16 v[80:83], v[166:169], v[202:205], v[80:83]
	v_mfma_f32_16x16x32_bf16 v[68:71], v[154:157], v[210:213], v[68:71]
	v_mfma_f32_16x16x32_bf16 v[64:67], v[166:169], v[210:213], v[64:67]
	v_mfma_f32_16x16x32_bf16 v[116:119], v[158:161], v[190:193], v[116:119]
	v_mfma_f32_16x16x32_bf16 v[112:115], v[170:173], v[190:193], v[112:115]
	v_mfma_f32_16x16x32_bf16 v[100:103], v[158:161], v[198:201], v[100:103]
	v_mfma_f32_16x16x32_bf16 v[96:99], v[170:173], v[198:201], v[96:99]
	v_mfma_f32_16x16x32_bf16 v[84:87], v[158:161], v[206:209], v[84:87]
	v_mfma_f32_16x16x32_bf16 v[80:83], v[170:173], v[206:209], v[80:83]
	v_mfma_f32_16x16x32_bf16 v[68:71], v[158:161], v[214:217], v[68:71]
	v_mfma_f32_16x16x32_bf16 v[64:67], v[170:173], v[214:217], v[64:67]
	s_barrier
	s_add_i32 s45, s45, s37
	v_lshl_add_u64 v[174:175], s[4:5], 0, v[176:177]
	s_mov_b32 m0, s45
	global_load_lds_dwordx4 v[174:175], off
	s_add_i32 m0, s45, 0x2000
	v_lshl_add_u64 v[222:223], s[4:5], 0, v[144:145]
	s_add_u32 s4, s4, s0
	s_addc_u32 s5, s5, s1
	s_add_i32 s45, s54, s37
	global_load_lds_dwordx4 v[222:223], off
	v_lshl_add_u64 v[224:225], s[4:5], 0, v[176:177]
	s_mov_b32 m0, s45
	v_lshl_add_u64 v[226:227], s[4:5], 0, v[144:145]
	global_load_lds_dwordx4 v[224:225], off
	s_add_i32 m0, s45, 0x2000
	v_lshl_add_u64 v[228:229], s[34:35], 0, v[148:149]
	global_load_lds_dwordx4 v[226:227], off
	s_mov_b32 m0, s38
	v_lshl_add_u64 v[230:231], s[34:35], 0, v[146:147]
	global_load_lds_dwordx4 v[228:229], off
	s_mov_b32 m0, s39
	s_nop 0
	global_load_lds_dwordx4 v[230:231], off
	ds_read_b128 v[186:189], v165 offset:16384
	ds_read_b128 v[190:193], v165 offset:17408
	ds_read_b128 v[194:197], v165 offset:18432
	ds_read_b128 v[198:201], v165 offset:19456
	ds_read_b128 v[202:205], v165 offset:20480
	ds_read_b128 v[206:209], v165 offset:21504
	ds_read_b128 v[210:213], v165 offset:22528
	ds_read_b128 v[214:217], v165 offset:23552
	s_waitcnt vmcnt(8)
	s_waitcnt lgkmcnt(0)
	s_barrier
	s_waitcnt lgkmcnt(0)
	v_mfma_f32_16x16x32_bf16 v[60:63], v[128:131], v[186:189], v[60:63]
	v_mfma_f32_16x16x32_bf16 v[56:59], v[136:139], v[186:189], v[56:59]
	v_mfma_f32_16x16x32_bf16 v[44:47], v[128:131], v[194:197], v[44:47]
	v_mfma_f32_16x16x32_bf16 v[40:43], v[136:139], v[194:197], v[40:43]
	v_mfma_f32_16x16x32_bf16 v[28:31], v[128:131], v[202:205], v[28:31]
	v_mfma_f32_16x16x32_bf16 v[24:27], v[136:139], v[202:205], v[24:27]
	v_mfma_f32_16x16x32_bf16 v[12:15], v[128:131], v[210:213], v[12:15]
	v_mfma_f32_16x16x32_bf16 v[8:11], v[136:139], v[210:213], v[8:11]
	v_mfma_f32_16x16x32_bf16 v[60:63], v[132:135], v[190:193], v[60:63]
	v_mfma_f32_16x16x32_bf16 v[56:59], v[140:143], v[190:193], v[56:59]
	v_mfma_f32_16x16x32_bf16 v[44:47], v[132:135], v[198:201], v[44:47]
	v_mfma_f32_16x16x32_bf16 v[40:43], v[140:143], v[198:201], v[40:43]
	v_mfma_f32_16x16x32_bf16 v[28:31], v[132:135], v[206:209], v[28:31]
	v_mfma_f32_16x16x32_bf16 v[24:27], v[140:143], v[206:209], v[24:27]
	v_mfma_f32_16x16x32_bf16 v[12:15], v[132:135], v[214:217], v[12:15]
	v_mfma_f32_16x16x32_bf16 v[8:11], v[140:143], v[214:217], v[8:11]
	v_mfma_f32_16x16x32_bf16 v[52:55], v[154:157], v[186:189], v[52:55]
	v_mfma_f32_16x16x32_bf16 v[48:51], v[166:169], v[186:189], v[48:51]
	v_mfma_f32_16x16x32_bf16 v[36:39], v[154:157], v[194:197], v[36:39]
	v_mfma_f32_16x16x32_bf16 v[32:35], v[166:169], v[194:197], v[32:35]
	v_mfma_f32_16x16x32_bf16 v[20:23], v[154:157], v[202:205], v[20:23]
	v_mfma_f32_16x16x32_bf16 v[16:19], v[166:169], v[202:205], v[16:19]
	v_mfma_f32_16x16x32_bf16 v[4:7], v[154:157], v[210:213], v[4:7]
	v_mfma_f32_16x16x32_bf16 v[0:3], v[166:169], v[210:213], v[0:3]
	v_mfma_f32_16x16x32_bf16 v[52:55], v[158:161], v[190:193], v[52:55]
	v_mfma_f32_16x16x32_bf16 v[48:51], v[170:173], v[190:193], v[48:51]
	v_mfma_f32_16x16x32_bf16 v[36:39], v[158:161], v[198:201], v[36:39]
	v_mfma_f32_16x16x32_bf16 v[32:35], v[170:173], v[198:201], v[32:35]
	v_mfma_f32_16x16x32_bf16 v[20:23], v[158:161], v[206:209], v[20:23]
	v_mfma_f32_16x16x32_bf16 v[16:19], v[170:173], v[206:209], v[16:19]
	v_mfma_f32_16x16x32_bf16 v[4:7], v[158:161], v[214:217], v[4:7]
	v_mfma_f32_16x16x32_bf16 v[0:3], v[170:173], v[214:217], v[0:3]
	s_barrier
	s_add_i32 s45, 0, 0x18000
	s_add_i32 s54, 0, 0x1c000
	s_add_u32 s4, s34, s0
	s_addc_u32 s5, s35, s1
	s_mov_b32 m0, s48
	v_lshl_add_u64 v[232:233], s[4:5], 0, v[148:149]
	global_load_lds_dwordx4 v[232:233], off
	v_lshl_add_u64 v[232:233], s[4:5], 0, v[146:147]
	s_mov_b32 m0, s49
	s_nop 0
	global_load_lds_dwordx4 v[232:233], off
	v_add_u32_e32 v140, s45, v163
	v_add_u32_e32 v170, s54, v163
	ds_read_b128 v[128:131], v140
	ds_read_b128 v[132:135], v140 offset:1024
	ds_read_b128 v[136:139], v140 offset:2048
	ds_read_b128 v[140:143], v140 offset:3072
	ds_read_b128 v[154:157], v170
	ds_read_b128 v[158:161], v170 offset:1024
	ds_read_b128 v[166:169], v170 offset:2048
	ds_read_b128 v[170:173], v170 offset:3072
	ds_read_b128 v[186:189], v165 offset:32768
	ds_read_b128 v[190:193], v165 offset:33792
	ds_read_b128 v[194:197], v165 offset:34816
	ds_read_b128 v[198:201], v165 offset:35840
	ds_read_b128 v[202:205], v165 offset:36864
	ds_read_b128 v[206:209], v165 offset:37888
	ds_read_b128 v[210:213], v165 offset:38912
	ds_read_b128 v[214:217], v165 offset:39936
	s_waitcnt vmcnt(8)
	s_waitcnt lgkmcnt(0)
	s_barrier
	s_waitcnt lgkmcnt(0)
	v_mfma_f32_16x16x32_bf16 v[124:127], v[128:131], v[186:189], v[124:127]
	v_mfma_f32_16x16x32_bf16 v[120:123], v[136:139], v[186:189], v[120:123]
	v_mfma_f32_16x16x32_bf16 v[108:111], v[128:131], v[194:197], v[108:111]
	v_mfma_f32_16x16x32_bf16 v[104:107], v[136:139], v[194:197], v[104:107]
	v_mfma_f32_16x16x32_bf16 v[92:95], v[128:131], v[202:205], v[92:95]
	v_mfma_f32_16x16x32_bf16 v[88:91], v[136:139], v[202:205], v[88:91]
	v_mfma_f32_16x16x32_bf16 v[76:79], v[128:131], v[210:213], v[76:79]
	v_mfma_f32_16x16x32_bf16 v[72:75], v[136:139], v[210:213], v[72:75]
	v_mfma_f32_16x16x32_bf16 v[124:127], v[132:135], v[190:193], v[124:127]
	v_mfma_f32_16x16x32_bf16 v[120:123], v[140:143], v[190:193], v[120:123]
	v_mfma_f32_16x16x32_bf16 v[108:111], v[132:135], v[198:201], v[108:111]
	v_mfma_f32_16x16x32_bf16 v[104:107], v[140:143], v[198:201], v[104:107]
	v_mfma_f32_16x16x32_bf16 v[92:95], v[132:135], v[206:209], v[92:95]
	v_mfma_f32_16x16x32_bf16 v[88:91], v[140:143], v[206:209], v[88:91]
	v_mfma_f32_16x16x32_bf16 v[76:79], v[132:135], v[214:217], v[76:79]
	v_mfma_f32_16x16x32_bf16 v[72:75], v[140:143], v[214:217], v[72:75]
	v_mfma_f32_16x16x32_bf16 v[116:119], v[154:157], v[186:189], v[116:119]
	v_mfma_f32_16x16x32_bf16 v[112:115], v[166:169], v[186:189], v[112:115]
	v_mfma_f32_16x16x32_bf16 v[100:103], v[154:157], v[194:197], v[100:103]
	v_mfma_f32_16x16x32_bf16 v[96:99], v[166:169], v[194:197], v[96:99]
	v_mfma_f32_16x16x32_bf16 v[84:87], v[154:157], v[202:205], v[84:87]
	v_mfma_f32_16x16x32_bf16 v[80:83], v[166:169], v[202:205], v[80:83]
	v_mfma_f32_16x16x32_bf16 v[68:71], v[154:157], v[210:213], v[68:71]
	v_mfma_f32_16x16x32_bf16 v[64:67], v[166:169], v[210:213], v[64:67]
	v_mfma_f32_16x16x32_bf16 v[116:119], v[158:161], v[190:193], v[116:119]
	v_mfma_f32_16x16x32_bf16 v[112:115], v[170:173], v[190:193], v[112:115]
	v_mfma_f32_16x16x32_bf16 v[100:103], v[158:161], v[198:201], v[100:103]
	v_mfma_f32_16x16x32_bf16 v[96:99], v[170:173], v[198:201], v[96:99]
	v_mfma_f32_16x16x32_bf16 v[84:87], v[158:161], v[206:209], v[84:87]
	v_mfma_f32_16x16x32_bf16 v[80:83], v[170:173], v[206:209], v[80:83]
	v_mfma_f32_16x16x32_bf16 v[68:71], v[158:161], v[214:217], v[68:71]
	v_mfma_f32_16x16x32_bf16 v[64:67], v[170:173], v[214:217], v[64:67]
	s_barrier
	s_add_i32 s4, s45, s37
	v_lshl_add_u64 v[174:175], v[174:175], 0, s[14:15]
	s_mov_b32 m0, s4
	global_load_lds_dwordx4 v[174:175], off
	v_lshl_add_u64 v[174:175], v[222:223], 0, s[14:15]
	s_add_i32 m0, s4, 0x2000
	s_add_i32 s4, s54, s37
	global_load_lds_dwordx4 v[174:175], off
	v_lshl_add_u64 v[174:175], v[224:225], 0, s[14:15]
	s_mov_b32 m0, s4
	s_nop 0
	global_load_lds_dwordx4 v[174:175], off
	v_lshl_add_u64 v[174:175], v[226:227], 0, s[14:15]
	s_add_i32 m0, s4, 0x2000
	s_nop 0
	global_load_lds_dwordx4 v[174:175], off
	v_lshl_add_u64 v[174:175], v[228:229], 0, s[14:15]
	s_mov_b32 m0, s60
	s_nop 0
	global_load_lds_dwordx4 v[174:175], off
	v_lshl_add_u64 v[174:175], v[230:231], 0, s[14:15]
	s_mov_b32 m0, s61
	s_nop 0
	global_load_lds_dwordx4 v[174:175], off
	ds_read_b128 v[186:189], v165 offset:49152
	ds_read_b128 v[190:193], v165 offset:50176
	ds_read_b128 v[194:197], v165 offset:51200
	ds_read_b128 v[198:201], v165 offset:52224
	ds_read_b128 v[202:205], v165 offset:53248
	ds_read_b128 v[206:209], v165 offset:54272
	ds_read_b128 v[210:213], v165 offset:55296
	ds_read_b128 v[214:217], v165 offset:56320
	s_waitcnt vmcnt(8)
	s_waitcnt lgkmcnt(0)
	s_barrier
	s_waitcnt lgkmcnt(0)
	v_mfma_f32_16x16x32_bf16 v[60:63], v[128:131], v[186:189], v[60:63]
	s_add_u32 s30, s30, 0x100
	v_mfma_f32_16x16x32_bf16 v[56:59], v[136:139], v[186:189], v[56:59]
	s_addc_u32 s31, s31, 0
	v_mfma_f32_16x16x32_bf16 v[44:47], v[128:131], v[194:197], v[44:47]
	s_add_u32 s10, s10, 0x100
	v_mfma_f32_16x16x32_bf16 v[40:43], v[136:139], v[194:197], v[40:43]
	s_addc_u32 s11, s11, 0
	v_mfma_f32_16x16x32_bf16 v[28:31], v[128:131], v[202:205], v[28:31]
	s_mov_b32 s34, s44
	v_mfma_f32_16x16x32_bf16 v[24:27], v[136:139], v[202:205], v[24:27]
	s_cmp_ge_i32 s44, s59
	v_mfma_f32_16x16x32_bf16 v[12:15], v[128:131], v[210:213], v[12:15]
	s_cselect_b32 s99, 1, 0
	v_mfma_f32_16x16x32_bf16 v[8:11], v[136:139], v[210:213], v[8:11]
	s_add_i32 s44, s34, 2
	v_mfma_f32_16x16x32_bf16 v[60:63], v[132:135], v[190:193], v[60:63]
	s_add_u32 s4, s30, 0x80
	v_mfma_f32_16x16x32_bf16 v[56:59], v[140:143], v[190:193], v[56:59]
	s_addc_u32 s5, s31, 0
	v_mfma_f32_16x16x32_bf16 v[44:47], v[132:135], v[198:201], v[44:47]
	s_add_i32 s45, 0, 0x10000
	v_mfma_f32_16x16x32_bf16 v[40:43], v[140:143], v[198:201], v[40:43]
	s_cmp_eq_u32 s62, s34
	v_mfma_f32_16x16x32_bf16 v[28:31], v[132:135], v[206:209], v[28:31]
	s_cselect_b32 s35, s27, s5
	v_mfma_f32_16x16x32_bf16 v[24:27], v[140:143], v[206:209], v[24:27]
	s_cselect_b32 s34, s26, s4
	v_mfma_f32_16x16x32_bf16 v[12:15], v[132:135], v[214:217], v[12:15]
	s_cselect_b32 s5, s29, s11
	v_mfma_f32_16x16x32_bf16 v[8:11], v[140:143], v[214:217], v[8:11]
	s_cselect_b32 s4, s28, s10
	v_mfma_f32_16x16x32_bf16 v[52:55], v[154:157], v[186:189], v[52:55]
	s_add_i32 s54, 0, 0x14000
	v_mfma_f32_16x16x32_bf16 v[48:51], v[166:169], v[186:189], v[48:51]
	v_mfma_f32_16x16x32_bf16 v[36:39], v[154:157], v[194:197], v[36:39]
	v_mfma_f32_16x16x32_bf16 v[32:35], v[166:169], v[194:197], v[32:35]
	v_mfma_f32_16x16x32_bf16 v[20:23], v[154:157], v[202:205], v[20:23]
	v_mfma_f32_16x16x32_bf16 v[16:19], v[166:169], v[202:205], v[16:19]
	v_mfma_f32_16x16x32_bf16 v[4:7], v[154:157], v[210:213], v[4:7]
	v_mfma_f32_16x16x32_bf16 v[0:3], v[166:169], v[210:213], v[0:3]
	v_mfma_f32_16x16x32_bf16 v[52:55], v[158:161], v[190:193], v[52:55]
	v_mfma_f32_16x16x32_bf16 v[48:51], v[170:173], v[190:193], v[48:51]
	v_mfma_f32_16x16x32_bf16 v[36:39], v[158:161], v[198:201], v[36:39]
	v_mfma_f32_16x16x32_bf16 v[32:35], v[170:173], v[198:201], v[32:35]
	v_mfma_f32_16x16x32_bf16 v[20:23], v[158:161], v[206:209], v[20:23]
	v_mfma_f32_16x16x32_bf16 v[16:19], v[170:173], v[206:209], v[16:19]
	v_mfma_f32_16x16x32_bf16 v[4:7], v[158:161], v[214:217], v[4:7]
	v_mfma_f32_16x16x32_bf16 v[0:3], v[170:173], v[214:217], v[0:3]
	s_barrier
	s_cmp_lg_u32 s99, 0
	s_cbranch_scc0 .LBB0_305

.Llbb_3:
	s_add_i32 s44, s30, 2
	s_add_u32 s4, s28, 0x80
	s_addc_u32 s5, s29, 0
	s_add_i32 s45, 0, 0x10000
	s_cmp_eq_u32 s61, s30
	s_cselect_b32 s31, s25, s5
	s_cselect_b32 s30, s24, s4
	s_cselect_b32 s5, s27, s11
	s_cselect_b32 s4, s26, s10
	s_add_i32 s54, 0, 0x14000
	v_lshl_add_u64 v[222:223], s[28:29], 0, v[138:139]
	s_add_i32 m0, s37, 0xc000
	global_load_lds_dwordx4 v[222:223], off
	v_lshl_add_u64 v[222:223], s[28:29], 0, v[140:141]
	s_add_i32 m0, s37, 0xe000
	s_nop 0
	global_load_lds_dwordx4 v[222:223], off
	v_add_u32_e32 v156, s45, v151
	v_add_u32_e32 v172, s54, v151
	ds_read_b128 v[128:131], v156
	ds_read_b128 v[142:145], v156 offset:1024
	ds_read_b128 v[146:149], v156 offset:2048
	ds_read_b128 v[156:159], v156 offset:3072
	ds_read_b128 v[160:163], v172
	ds_read_b128 v[164:167], v172 offset:1024
	ds_read_b128 v[168:171], v172 offset:2048
	ds_read_b128 v[172:175], v172 offset:3072
	ds_read_b128 v[186:189], v155
	ds_read_b128 v[190:193], v155 offset:1024
	ds_read_b128 v[194:197], v155 offset:2048
	ds_read_b128 v[198:201], v155 offset:3072
	ds_read_b128 v[202:205], v155 offset:4096
	ds_read_b128 v[206:209], v155 offset:5120
	ds_read_b128 v[210:213], v155 offset:6144
	ds_read_b128 v[214:217], v155 offset:7168
	s_waitcnt vmcnt(8)
	s_waitcnt lgkmcnt(0)
	s_barrier
	s_waitcnt lgkmcnt(0)
	v_mfma_f32_16x16x32_bf16 v[120:123], v[128:131], v[186:189], 0
	v_mfma_f32_16x16x32_bf16 v[116:119], v[146:149], v[186:189], 0
	v_mfma_f32_16x16x32_bf16 v[108:111], v[128:131], v[194:197], 0
	v_mfma_f32_16x16x32_bf16 v[100:103], v[146:149], v[194:197], 0
	v_mfma_f32_16x16x32_bf16 v[92:95], v[128:131], v[202:205], 0
	v_mfma_f32_16x16x32_bf16 v[84:87], v[146:149], v[202:205], 0
	v_mfma_f32_16x16x32_bf16 v[76:79], v[128:131], v[210:213], 0
	v_mfma_f32_16x16x32_bf16 v[68:71], v[146:149], v[210:213], 0
	v_mfma_f32_16x16x32_bf16 v[120:123], v[142:145], v[190:193], v[120:123]
	v_mfma_f32_16x16x32_bf16 v[116:119], v[156:159], v[190:193], v[116:119]
	v_mfma_f32_16x16x32_bf16 v[108:111], v[142:145], v[198:201], v[108:111]
	v_mfma_f32_16x16x32_bf16 v[100:103], v[156:159], v[198:201], v[100:103]
	v_mfma_f32_16x16x32_bf16 v[92:95], v[142:145], v[206:209], v[92:95]
	v_mfma_f32_16x16x32_bf16 v[84:87], v[156:159], v[206:209], v[84:87]
	v_mfma_f32_16x16x32_bf16 v[76:79], v[142:145], v[214:217], v[76:79]
	v_mfma_f32_16x16x32_bf16 v[68:71], v[156:159], v[214:217], v[68:71]
	v_mfma_f32_16x16x32_bf16 v[124:127], v[160:163], v[186:189], 0
	v_mfma_f32_16x16x32_bf16 v[112:115], v[168:171], v[186:189], 0
	v_mfma_f32_16x16x32_bf16 v[104:107], v[160:163], v[194:197], 0
	v_mfma_f32_16x16x32_bf16 v[96:99], v[168:171], v[194:197], 0
	v_mfma_f32_16x16x32_bf16 v[88:91], v[160:163], v[202:205], 0
	v_mfma_f32_16x16x32_bf16 v[80:83], v[168:171], v[202:205], 0
	v_mfma_f32_16x16x32_bf16 v[72:75], v[160:163], v[210:213], 0
	v_mfma_f32_16x16x32_bf16 v[64:67], v[168:171], v[210:213], 0
	v_mfma_f32_16x16x32_bf16 v[124:127], v[164:167], v[190:193], v[124:127]
	v_mfma_f32_16x16x32_bf16 v[112:115], v[172:175], v[190:193], v[112:115]
	v_mfma_f32_16x16x32_bf16 v[104:107], v[164:167], v[198:201], v[104:107]
	v_mfma_f32_16x16x32_bf16 v[96:99], v[172:175], v[198:201], v[96:99]
	v_mfma_f32_16x16x32_bf16 v[88:91], v[164:167], v[206:209], v[88:91]
	v_mfma_f32_16x16x32_bf16 v[80:83], v[172:175], v[206:209], v[80:83]
	v_mfma_f32_16x16x32_bf16 v[72:75], v[164:167], v[214:217], v[72:75]
	v_mfma_f32_16x16x32_bf16 v[64:67], v[172:175], v[214:217], v[64:67]
	s_barrier
	s_add_i32 s45, s45, s36
	v_lshl_add_u64 v[222:223], s[4:5], 0, v[176:177]
	s_mov_b32 m0, s45
	global_load_lds_dwordx4 v[222:223], off
	s_add_i32 m0, s45, 0x2000
	v_lshl_add_u64 v[224:225], s[4:5], 0, v[132:133]
	s_add_u32 s4, s4, s6
	s_addc_u32 s5, s5, s7
	s_add_i32 s45, s54, s36
	global_load_lds_dwordx4 v[224:225], off
	v_lshl_add_u64 v[226:227], s[4:5], 0, v[176:177]
	s_mov_b32 m0, s45
	v_lshl_add_u64 v[228:229], s[4:5], 0, v[132:133]
	global_load_lds_dwordx4 v[226:227], off
	s_add_i32 m0, s45, 0x2000
	v_lshl_add_u64 v[230:231], s[30:31], 0, v[136:137]
	global_load_lds_dwordx4 v[228:229], off
	s_mov_b32 m0, s37
	v_lshl_add_u64 v[232:233], s[30:31], 0, v[134:135]
	global_load_lds_dwordx4 v[230:231], off
	s_mov_b32 m0, s38
	s_nop 0
	global_load_lds_dwordx4 v[232:233], off
	ds_read_b128 v[186:189], v155 offset:16384
	ds_read_b128 v[190:193], v155 offset:17408
	ds_read_b128 v[194:197], v155 offset:18432
	ds_read_b128 v[198:201], v155 offset:19456
	ds_read_b128 v[202:205], v155 offset:20480
	ds_read_b128 v[206:209], v155 offset:21504
	ds_read_b128 v[210:213], v155 offset:22528
	ds_read_b128 v[214:217], v155 offset:23552
	s_waitcnt vmcnt(8)
	s_waitcnt lgkmcnt(0)
	s_barrier
	s_waitcnt lgkmcnt(0)
	v_mfma_f32_16x16x32_bf16 v[60:63], v[128:131], v[186:189], 0
	v_mfma_f32_16x16x32_bf16 v[52:55], v[146:149], v[186:189], 0
	v_mfma_f32_16x16x32_bf16 v[44:47], v[128:131], v[194:197], 0
	v_mfma_f32_16x16x32_bf16 v[36:39], v[146:149], v[194:197], 0
	v_mfma_f32_16x16x32_bf16 v[28:31], v[128:131], v[202:205], 0
	v_mfma_f32_16x16x32_bf16 v[20:23], v[146:149], v[202:205], 0
	v_mfma_f32_16x16x32_bf16 v[12:15], v[128:131], v[210:213], 0
	v_mfma_f32_16x16x32_bf16 v[4:7], v[146:149], v[210:213], 0
	v_mfma_f32_16x16x32_bf16 v[60:63], v[142:145], v[190:193], v[60:63]
	v_mfma_f32_16x16x32_bf16 v[52:55], v[156:159], v[190:193], v[52:55]
	v_mfma_f32_16x16x32_bf16 v[44:47], v[142:145], v[198:201], v[44:47]
	v_mfma_f32_16x16x32_bf16 v[36:39], v[156:159], v[198:201], v[36:39]
	v_mfma_f32_16x16x32_bf16 v[28:31], v[142:145], v[206:209], v[28:31]
	v_mfma_f32_16x16x32_bf16 v[20:23], v[156:159], v[206:209], v[20:23]
	v_mfma_f32_16x16x32_bf16 v[12:15], v[142:145], v[214:217], v[12:15]
	v_mfma_f32_16x16x32_bf16 v[4:7], v[156:159], v[214:217], v[4:7]
	v_mfma_f32_16x16x32_bf16 v[56:59], v[160:163], v[186:189], 0
	v_mfma_f32_16x16x32_bf16 v[48:51], v[168:171], v[186:189], 0
	v_mfma_f32_16x16x32_bf16 v[40:43], v[160:163], v[194:197], 0
	v_mfma_f32_16x16x32_bf16 v[32:35], v[168:171], v[194:197], 0
	v_mfma_f32_16x16x32_bf16 v[24:27], v[160:163], v[202:205], 0
	v_mfma_f32_16x16x32_bf16 v[16:19], v[168:171], v[202:205], 0
	v_mfma_f32_16x16x32_bf16 v[8:11], v[160:163], v[210:213], 0
	v_mfma_f32_16x16x32_bf16 v[0:3], v[168:171], v[210:213], 0
	v_mfma_f32_16x16x32_bf16 v[56:59], v[164:167], v[190:193], v[56:59]
	v_mfma_f32_16x16x32_bf16 v[48:51], v[172:175], v[190:193], v[48:51]
	v_mfma_f32_16x16x32_bf16 v[40:43], v[164:167], v[198:201], v[40:43]
	v_mfma_f32_16x16x32_bf16 v[32:35], v[172:175], v[198:201], v[32:35]
	v_mfma_f32_16x16x32_bf16 v[24:27], v[164:167], v[206:209], v[24:27]
	v_mfma_f32_16x16x32_bf16 v[16:19], v[172:175], v[206:209], v[16:19]
	v_mfma_f32_16x16x32_bf16 v[8:11], v[164:167], v[214:217], v[8:11]
	v_mfma_f32_16x16x32_bf16 v[0:3], v[172:175], v[214:217], v[0:3]
	s_barrier
	s_add_i32 s45, 0, 0x18000
	s_add_i32 s54, 0, 0x1c000
	s_add_u32 s4, s30, s6
	s_addc_u32 s5, s31, s7
	s_mov_b32 m0, s39
	v_lshl_add_u64 v[234:235], s[4:5], 0, v[136:137]
	global_load_lds_dwordx4 v[234:235], off
	v_lshl_add_u64 v[234:235], s[4:5], 0, v[134:135]
	s_mov_b32 m0, s48
	s_nop 0
	global_load_lds_dwordx4 v[234:235], off
	v_add_u32_e32 v156, s45, v151
	v_add_u32_e32 v172, s54, v151
	ds_read_b128 v[128:131], v156
	ds_read_b128 v[142:145], v156 offset:1024
	ds_read_b128 v[146:149], v156 offset:2048
	ds_read_b128 v[156:159], v156 offset:3072
	ds_read_b128 v[160:163], v172
	ds_read_b128 v[164:167], v172 offset:1024
	ds_read_b128 v[168:171], v172 offset:2048
	ds_read_b128 v[172:175], v172 offset:3072
	ds_read_b128 v[186:189], v155 offset:32768
	ds_read_b128 v[190:193], v155 offset:33792
	ds_read_b128 v[194:197], v155 offset:34816
	ds_read_b128 v[198:201], v155 offset:35840
	ds_read_b128 v[202:205], v155 offset:36864
	ds_read_b128 v[206:209], v155 offset:37888
	ds_read_b128 v[210:213], v155 offset:38912
	ds_read_b128 v[214:217], v155 offset:39936
	s_waitcnt vmcnt(8)
	s_waitcnt lgkmcnt(0)
	s_barrier
	s_waitcnt lgkmcnt(0)
	v_mfma_f32_16x16x32_bf16 v[120:123], v[128:131], v[186:189], v[120:123]
	v_mfma_f32_16x16x32_bf16 v[116:119], v[146:149], v[186:189], v[116:119]
	v_mfma_f32_16x16x32_bf16 v[108:111], v[128:131], v[194:197], v[108:111]
	v_mfma_f32_16x16x32_bf16 v[100:103], v[146:149], v[194:197], v[100:103]
	v_mfma_f32_16x16x32_bf16 v[92:95], v[128:131], v[202:205], v[92:95]
	v_mfma_f32_16x16x32_bf16 v[84:87], v[146:149], v[202:205], v[84:87]
	v_mfma_f32_16x16x32_bf16 v[76:79], v[128:131], v[210:213], v[76:79]
	v_mfma_f32_16x16x32_bf16 v[68:71], v[146:149], v[210:213], v[68:71]
	v_mfma_f32_16x16x32_bf16 v[120:123], v[142:145], v[190:193], v[120:123]
	v_mfma_f32_16x16x32_bf16 v[116:119], v[156:159], v[190:193], v[116:119]
	v_mfma_f32_16x16x32_bf16 v[108:111], v[142:145], v[198:201], v[108:111]
	v_mfma_f32_16x16x32_bf16 v[100:103], v[156:159], v[198:201], v[100:103]
	v_mfma_f32_16x16x32_bf16 v[92:95], v[142:145], v[206:209], v[92:95]
	v_mfma_f32_16x16x32_bf16 v[84:87], v[156:159], v[206:209], v[84:87]
	v_mfma_f32_16x16x32_bf16 v[76:79], v[142:145], v[214:217], v[76:79]
	v_mfma_f32_16x16x32_bf16 v[68:71], v[156:159], v[214:217], v[68:71]
	v_mfma_f32_16x16x32_bf16 v[124:127], v[160:163], v[186:189], v[124:127]
	v_mfma_f32_16x16x32_bf16 v[112:115], v[168:171], v[186:189], v[112:115]
	v_mfma_f32_16x16x32_bf16 v[104:107], v[160:163], v[194:197], v[104:107]
	v_mfma_f32_16x16x32_bf16 v[96:99], v[168:171], v[194:197], v[96:99]
	v_mfma_f32_16x16x32_bf16 v[88:91], v[160:163], v[202:205], v[88:91]
	v_mfma_f32_16x16x32_bf16 v[80:83], v[168:171], v[202:205], v[80:83]
	v_mfma_f32_16x16x32_bf16 v[72:75], v[160:163], v[210:213], v[72:75]
	v_mfma_f32_16x16x32_bf16 v[64:67], v[168:171], v[210:213], v[64:67]
	v_mfma_f32_16x16x32_bf16 v[124:127], v[164:167], v[190:193], v[124:127]
	v_mfma_f32_16x16x32_bf16 v[112:115], v[172:175], v[190:193], v[112:115]
	v_mfma_f32_16x16x32_bf16 v[104:107], v[164:167], v[198:201], v[104:107]
	v_mfma_f32_16x16x32_bf16 v[96:99], v[172:175], v[198:201], v[96:99]
	v_mfma_f32_16x16x32_bf16 v[88:91], v[164:167], v[206:209], v[88:91]
	v_mfma_f32_16x16x32_bf16 v[80:83], v[172:175], v[206:209], v[80:83]
	v_mfma_f32_16x16x32_bf16 v[72:75], v[164:167], v[214:217], v[72:75]
	v_mfma_f32_16x16x32_bf16 v[64:67], v[172:175], v[214:217], v[64:67]
	s_barrier
	s_add_i32 s4, s45, s36
	v_lshl_add_u64 v[222:223], v[222:223], 0, s[14:15]
	s_mov_b32 m0, s4
	global_load_lds_dwordx4 v[222:223], off
	v_lshl_add_u64 v[222:223], v[224:225], 0, s[14:15]
	s_add_i32 m0, s4, 0x2000
	s_add_i32 s4, s54, s36
	global_load_lds_dwordx4 v[222:223], off
	v_lshl_add_u64 v[222:223], v[226:227], 0, s[14:15]
	s_mov_b32 m0, s4
	s_nop 0
	global_load_lds_dwordx4 v[222:223], off
	v_lshl_add_u64 v[222:223], v[228:229], 0, s[14:15]
	s_add_i32 m0, s4, 0x2000
	s_nop 0
	global_load_lds_dwordx4 v[222:223], off
	v_lshl_add_u64 v[222:223], v[230:231], 0, s[14:15]
	s_mov_b32 m0, s59
	s_nop 0
	global_load_lds_dwordx4 v[222:223], off
	v_lshl_add_u64 v[222:223], v[232:233], 0, s[14:15]
	s_mov_b32 m0, s60
	s_nop 0
	global_load_lds_dwordx4 v[222:223], off
	ds_read_b128 v[186:189], v155 offset:49152
	ds_read_b128 v[190:193], v155 offset:50176
	ds_read_b128 v[194:197], v155 offset:51200
	ds_read_b128 v[198:201], v155 offset:52224
	ds_read_b128 v[202:205], v155 offset:53248
	ds_read_b128 v[206:209], v155 offset:54272
	ds_read_b128 v[210:213], v155 offset:55296
	ds_read_b128 v[214:217], v155 offset:56320
	s_waitcnt vmcnt(8)
	s_waitcnt lgkmcnt(0)
	s_barrier
	s_waitcnt lgkmcnt(0)
	v_mfma_f32_16x16x32_bf16 v[60:63], v[128:131], v[186:189], v[60:63]
	s_add_u32 s28, s28, 0x100
	v_mfma_f32_16x16x32_bf16 v[52:55], v[146:149], v[186:189], v[52:55]
	s_addc_u32 s29, s29, 0
	v_mfma_f32_16x16x32_bf16 v[44:47], v[128:131], v[194:197], v[44:47]
	s_add_u32 s10, s10, 0x100
	v_mfma_f32_16x16x32_bf16 v[36:39], v[146:149], v[194:197], v[36:39]
	s_addc_u32 s11, s11, 0
	v_mfma_f32_16x16x32_bf16 v[28:31], v[128:131], v[202:205], v[28:31]
	s_mov_b32 s30, s44
	v_mfma_f32_16x16x32_bf16 v[20:23], v[146:149], v[202:205], v[20:23]
	s_cmp_ge_i32 s44, s49
	v_mfma_f32_16x16x32_bf16 v[12:15], v[128:131], v[210:213], v[12:15]
	s_cselect_b32 s99, 1, 0
	v_mfma_f32_16x16x32_bf16 v[4:7], v[146:149], v[210:213], v[4:7]
	s_add_i32 s44, s30, 2
	v_mfma_f32_16x16x32_bf16 v[60:63], v[142:145], v[190:193], v[60:63]
	s_add_u32 s4, s28, 0x80
	v_mfma_f32_16x16x32_bf16 v[52:55], v[156:159], v[190:193], v[52:55]
	s_addc_u32 s5, s29, 0
	v_mfma_f32_16x16x32_bf16 v[44:47], v[142:145], v[198:201], v[44:47]
	s_add_i32 s45, 0, 0x10000
	v_mfma_f32_16x16x32_bf16 v[36:39], v[156:159], v[198:201], v[36:39]
	s_cmp_eq_u32 s61, s30
	v_mfma_f32_16x16x32_bf16 v[28:31], v[142:145], v[206:209], v[28:31]
	s_cselect_b32 s31, s25, s5
	v_mfma_f32_16x16x32_bf16 v[20:23], v[156:159], v[206:209], v[20:23]
	s_cselect_b32 s30, s24, s4
	v_mfma_f32_16x16x32_bf16 v[12:15], v[142:145], v[214:217], v[12:15]
	s_cselect_b32 s5, s27, s11
	v_mfma_f32_16x16x32_bf16 v[4:7], v[156:159], v[214:217], v[4:7]
	s_cselect_b32 s4, s26, s10
	v_mfma_f32_16x16x32_bf16 v[56:59], v[160:163], v[186:189], v[56:59]
	s_add_i32 s54, 0, 0x14000
	v_mfma_f32_16x16x32_bf16 v[48:51], v[168:171], v[186:189], v[48:51]
	v_mfma_f32_16x16x32_bf16 v[40:43], v[160:163], v[194:197], v[40:43]
	v_mfma_f32_16x16x32_bf16 v[32:35], v[168:171], v[194:197], v[32:35]
	v_mfma_f32_16x16x32_bf16 v[24:27], v[160:163], v[202:205], v[24:27]
	v_mfma_f32_16x16x32_bf16 v[16:19], v[168:171], v[202:205], v[16:19]
	v_mfma_f32_16x16x32_bf16 v[8:11], v[160:163], v[210:213], v[8:11]
	v_mfma_f32_16x16x32_bf16 v[0:3], v[168:171], v[210:213], v[0:3]
	v_mfma_f32_16x16x32_bf16 v[56:59], v[164:167], v[190:193], v[56:59]
	v_mfma_f32_16x16x32_bf16 v[48:51], v[172:175], v[190:193], v[48:51]
	v_mfma_f32_16x16x32_bf16 v[40:43], v[164:167], v[198:201], v[40:43]
	v_mfma_f32_16x16x32_bf16 v[32:35], v[172:175], v[198:201], v[32:35]
	v_mfma_f32_16x16x32_bf16 v[24:27], v[164:167], v[206:209], v[24:27]
	v_mfma_f32_16x16x32_bf16 v[16:19], v[172:175], v[206:209], v[16:19]
	v_mfma_f32_16x16x32_bf16 v[8:11], v[164:167], v[214:217], v[8:11]
	v_mfma_f32_16x16x32_bf16 v[0:3], v[172:175], v[214:217], v[0:3]
	s_barrier
	s_cmp_lg_u32 s99, 0
	s_cbranch_scc1 .Lpeelx_7
.LBB0_394:
	v_lshl_add_u64 v[222:223], s[28:29], 0, v[138:139]
	s_add_i32 m0, s37, 0xc000
	global_load_lds_dwordx4 v[222:223], off
	v_lshl_add_u64 v[222:223], s[28:29], 0, v[140:141]
	s_add_i32 m0, s37, 0xe000
	s_nop 0
	global_load_lds_dwordx4 v[222:223], off
	v_add_u32_e32 v156, s45, v151
	v_add_u32_e32 v172, s54, v151
	ds_read_b128 v[128:131], v156
	ds_read_b128 v[142:145], v156 offset:1024
	ds_read_b128 v[146:149], v156 offset:2048
	ds_read_b128 v[156:159], v156 offset:3072
	ds_read_b128 v[160:163], v172
	ds_read_b128 v[164:167], v172 offset:1024
	ds_read_b128 v[168:171], v172 offset:2048
	ds_read_b128 v[172:175], v172 offset:3072
	ds_read_b128 v[186:189], v155
	ds_read_b128 v[190:193], v155 offset:1024
	ds_read_b128 v[194:197], v155 offset:2048
	ds_read_b128 v[198:201], v155 offset:3072
	ds_read_b128 v[202:205], v155 offset:4096
	ds_read_b128 v[206:209], v155 offset:5120
	ds_read_b128 v[210:213], v155 offset:6144
	ds_read_b128 v[214:217], v155 offset:7168
	s_waitcnt vmcnt(8)
	s_waitcnt lgkmcnt(0)
	s_barrier
	s_waitcnt lgkmcnt(0)
	v_mfma_f32_16x16x32_bf16 v[120:123], v[128:131], v[186:189], v[120:123]
	v_mfma_f32_16x16x32_bf16 v[116:119], v[146:149], v[186:189], v[116:119]
	v_mfma_f32_16x16x32_bf16 v[108:111], v[128:131], v[194:197], v[108:111]
	v_mfma_f32_16x16x32_bf16 v[100:103], v[146:149], v[194:197], v[100:103]
	v_mfma_f32_16x16x32_bf16 v[92:95], v[128:131], v[202:205], v[92:95]
	v_mfma_f32_16x16x32_bf16 v[84:87], v[146:149], v[202:205], v[84:87]
	v_mfma_f32_16x16x32_bf16 v[76:79], v[128:131], v[210:213], v[76:79]
	v_mfma_f32_16x16x32_bf16 v[68:71], v[146:149], v[210:213], v[68:71]
	v_mfma_f32_16x16x32_bf16 v[120:123], v[142:145], v[190:193], v[120:123]
	v_mfma_f32_16x16x32_bf16 v[116:119], v[156:159], v[190:193], v[116:119]
	v_mfma_f32_16x16x32_bf16 v[108:111], v[142:145], v[198:201], v[108:111]
	v_mfma_f32_16x16x32_bf16 v[100:103], v[156:159], v[198:201], v[100:103]
	v_mfma_f32_16x16x32_bf16 v[92:95], v[142:145], v[206:209], v[92:95]
	v_mfma_f32_16x16x32_bf16 v[84:87], v[156:159], v[206:209], v[84:87]
	v_mfma_f32_16x16x32_bf16 v[76:79], v[142:145], v[214:217], v[76:79]
	v_mfma_f32_16x16x32_bf16 v[68:71], v[156:159], v[214:217], v[68:71]
	v_mfma_f32_16x16x32_bf16 v[124:127], v[160:163], v[186:189], v[124:127]
	v_mfma_f32_16x16x32_bf16 v[112:115], v[168:171], v[186:189], v[112:115]
	v_mfma_f32_16x16x32_bf16 v[104:107], v[160:163], v[194:197], v[104:107]
	v_mfma_f32_16x16x32_bf16 v[96:99], v[168:171], v[194:197], v[96:99]
	v_mfma_f32_16x16x32_bf16 v[88:91], v[160:163], v[202:205], v[88:91]
	v_mfma_f32_16x16x32_bf16 v[80:83], v[168:171], v[202:205], v[80:83]
	v_mfma_f32_16x16x32_bf16 v[72:75], v[160:163], v[210:213], v[72:75]
	v_mfma_f32_16x16x32_bf16 v[64:67], v[168:171], v[210:213], v[64:67]
	v_mfma_f32_16x16x32_bf16 v[124:127], v[164:167], v[190:193], v[124:127]
	v_mfma_f32_16x16x32_bf16 v[112:115], v[172:175], v[190:193], v[112:115]
	v_mfma_f32_16x16x32_bf16 v[104:107], v[164:167], v[198:201], v[104:107]
	v_mfma_f32_16x16x32_bf16 v[96:99], v[172:175], v[198:201], v[96:99]
	v_mfma_f32_16x16x32_bf16 v[88:91], v[164:167], v[206:209], v[88:91]
	v_mfma_f32_16x16x32_bf16 v[80:83], v[172:175], v[206:209], v[80:83]
	v_mfma_f32_16x16x32_bf16 v[72:75], v[164:167], v[214:217], v[72:75]
	v_mfma_f32_16x16x32_bf16 v[64:67], v[172:175], v[214:217], v[64:67]
	s_barrier
	s_add_i32 s45, s45, s36
	v_lshl_add_u64 v[222:223], s[4:5], 0, v[176:177]
	s_mov_b32 m0, s45
	global_load_lds_dwordx4 v[222:223], off
	s_add_i32 m0, s45, 0x2000
	v_lshl_add_u64 v[224:225], s[4:5], 0, v[132:133]
	s_add_u32 s4, s4, s6
	s_addc_u32 s5, s5, s7
	s_add_i32 s45, s54, s36
	global_load_lds_dwordx4 v[224:225], off
	v_lshl_add_u64 v[226:227], s[4:5], 0, v[176:177]
	s_mov_b32 m0, s45
	v_lshl_add_u64 v[228:229], s[4:5], 0, v[132:133]
	global_load_lds_dwordx4 v[226:227], off
	s_add_i32 m0, s45, 0x2000
	v_lshl_add_u64 v[230:231], s[30:31], 0, v[136:137]
	global_load_lds_dwordx4 v[228:229], off
	s_mov_b32 m0, s37
	v_lshl_add_u64 v[232:233], s[30:31], 0, v[134:135]
	global_load_lds_dwordx4 v[230:231], off
	s_mov_b32 m0, s38
	s_nop 0
	global_load_lds_dwordx4 v[232:233], off
	ds_read_b128 v[186:189], v155 offset:16384
	ds_read_b128 v[190:193], v155 offset:17408
	ds_read_b128 v[194:197], v155 offset:18432
	ds_read_b128 v[198:201], v155 offset:19456
	ds_read_b128 v[202:205], v155 offset:20480
	ds_read_b128 v[206:209], v155 offset:21504
	ds_read_b128 v[210:213], v155 offset:22528
	ds_read_b128 v[214:217], v155 offset:23552
	s_waitcnt vmcnt(8)
	s_waitcnt lgkmcnt(0)
	s_barrier
	s_waitcnt lgkmcnt(0)
	v_mfma_f32_16x16x32_bf16 v[60:63], v[128:131], v[186:189], v[60:63]
	v_mfma_f32_16x16x32_bf16 v[52:55], v[146:149], v[186:189], v[52:55]
	v_mfma_f32_16x16x32_bf16 v[44:47], v[128:131], v[194:197], v[44:47]
	v_mfma_f32_16x16x32_bf16 v[36:39], v[146:149], v[194:197], v[36:39]
	v_mfma_f32_16x16x32_bf16 v[28:31], v[128:131], v[202:205], v[28:31]
	v_mfma_f32_16x16x32_bf16 v[20:23], v[146:149], v[202:205], v[20:23]
	v_mfma_f32_16x16x32_bf16 v[12:15], v[128:131], v[210:213], v[12:15]
	v_mfma_f32_16x16x32_bf16 v[4:7], v[146:149], v[210:213], v[4:7]
	v_mfma_f32_16x16x32_bf16 v[60:63], v[142:145], v[190:193], v[60:63]
	v_mfma_f32_16x16x32_bf16 v[52:55], v[156:159], v[190:193], v[52:55]
	v_mfma_f32_16x16x32_bf16 v[44:47], v[142:145], v[198:201], v[44:47]
	v_mfma_f32_16x16x32_bf16 v[36:39], v[156:159], v[198:201], v[36:39]
	v_mfma_f32_16x16x32_bf16 v[28:31], v[142:145], v[206:209], v[28:31]
	v_mfma_f32_16x16x32_bf16 v[20:23], v[156:159], v[206:209], v[20:23]
	v_mfma_f32_16x16x32_bf16 v[12:15], v[142:145], v[214:217], v[12:15]
	v_mfma_f32_16x16x32_bf16 v[4:7], v[156:159], v[214:217], v[4:7]
	v_mfma_f32_16x16x32_bf16 v[56:59], v[160:163], v[186:189], v[56:59]
	v_mfma_f32_16x16x32_bf16 v[48:51], v[168:171], v[186:189], v[48:51]
	v_mfma_f32_16x16x32_bf16 v[40:43], v[160:163], v[194:197], v[40:43]
	v_mfma_f32_16x16x32_bf16 v[32:35], v[168:171], v[194:197], v[32:35]
	v_mfma_f32_16x16x32_bf16 v[24:27], v[160:163], v[202:205], v[24:27]
	v_mfma_f32_16x16x32_bf16 v[16:19], v[168:171], v[202:205], v[16:19]
	v_mfma_f32_16x16x32_bf16 v[8:11], v[160:163], v[210:213], v[8:11]
	v_mfma_f32_16x16x32_bf16 v[0:3], v[168:171], v[210:213], v[0:3]
	v_mfma_f32_16x16x32_bf16 v[56:59], v[164:167], v[190:193], v[56:59]
	v_mfma_f32_16x16x32_bf16 v[48:51], v[172:175], v[190:193], v[48:51]
	v_mfma_f32_16x16x32_bf16 v[40:43], v[164:167], v[198:201], v[40:43]
	v_mfma_f32_16x16x32_bf16 v[32:35], v[172:175], v[198:201], v[32:35]
	v_mfma_f32_16x16x32_bf16 v[24:27], v[164:167], v[206:209], v[24:27]
	v_mfma_f32_16x16x32_bf16 v[16:19], v[172:175], v[206:209], v[16:19]
	v_mfma_f32_16x16x32_bf16 v[8:11], v[164:167], v[214:217], v[8:11]
	v_mfma_f32_16x16x32_bf16 v[0:3], v[172:175], v[214:217], v[0:3]
	s_barrier
	s_add_i32 s45, 0, 0x18000
	s_add_i32 s54, 0, 0x1c000
	s_add_u32 s4, s30, s6
	s_addc_u32 s5, s31, s7
	s_mov_b32 m0, s39
	v_lshl_add_u64 v[234:235], s[4:5], 0, v[136:137]
	global_load_lds_dwordx4 v[234:235], off
	v_lshl_add_u64 v[234:235], s[4:5], 0, v[134:135]
	s_mov_b32 m0, s48
	s_nop 0
	global_load_lds_dwordx4 v[234:235], off
	v_add_u32_e32 v156, s45, v151
	v_add_u32_e32 v172, s54, v151
	ds_read_b128 v[128:131], v156
	ds_read_b128 v[142:145], v156 offset:1024
	ds_read_b128 v[146:149], v156 offset:2048
	ds_read_b128 v[156:159], v156 offset:3072
	ds_read_b128 v[160:163], v172
	ds_read_b128 v[164:167], v172 offset:1024
	ds_read_b128 v[168:171], v172 offset:2048
	ds_read_b128 v[172:175], v172 offset:3072
	ds_read_b128 v[186:189], v155 offset:32768
	ds_read_b128 v[190:193], v155 offset:33792
	ds_read_b128 v[194:197], v155 offset:34816
	ds_read_b128 v[198:201], v155 offset:35840
	ds_read_b128 v[202:205], v155 offset:36864
	ds_read_b128 v[206:209], v155 offset:37888
	ds_read_b128 v[210:213], v155 offset:38912
	ds_read_b128 v[214:217], v155 offset:39936
	s_waitcnt vmcnt(8)
	s_waitcnt lgkmcnt(0)
	s_barrier
	s_waitcnt lgkmcnt(0)
	v_mfma_f32_16x16x32_bf16 v[120:123], v[128:131], v[186:189], v[120:123]
	v_mfma_f32_16x16x32_bf16 v[116:119], v[146:149], v[186:189], v[116:119]
	v_mfma_f32_16x16x32_bf16 v[108:111], v[128:131], v[194:197], v[108:111]
	v_mfma_f32_16x16x32_bf16 v[100:103], v[146:149], v[194:197], v[100:103]
	v_mfma_f32_16x16x32_bf16 v[92:95], v[128:131], v[202:205], v[92:95]
	v_mfma_f32_16x16x32_bf16 v[84:87], v[146:149], v[202:205], v[84:87]
	v_mfma_f32_16x16x32_bf16 v[76:79], v[128:131], v[210:213], v[76:79]
	v_mfma_f32_16x16x32_bf16 v[68:71], v[146:149], v[210:213], v[68:71]
	v_mfma_f32_16x16x32_bf16 v[120:123], v[142:145], v[190:193], v[120:123]
	v_mfma_f32_16x16x32_bf16 v[116:119], v[156:159], v[190:193], v[116:119]
	v_mfma_f32_16x16x32_bf16 v[108:111], v[142:145], v[198:201], v[108:111]
	v_mfma_f32_16x16x32_bf16 v[100:103], v[156:159], v[198:201], v[100:103]
	v_mfma_f32_16x16x32_bf16 v[92:95], v[142:145], v[206:209], v[92:95]
	v_mfma_f32_16x16x32_bf16 v[84:87], v[156:159], v[206:209], v[84:87]
	v_mfma_f32_16x16x32_bf16 v[76:79], v[142:145], v[214:217], v[76:79]
	v_mfma_f32_16x16x32_bf16 v[68:71], v[156:159], v[214:217], v[68:71]
	v_mfma_f32_16x16x32_bf16 v[124:127], v[160:163], v[186:189], v[124:127]
	v_mfma_f32_16x16x32_bf16 v[112:115], v[168:171], v[186:189], v[112:115]
	v_mfma_f32_16x16x32_bf16 v[104:107], v[160:163], v[194:197], v[104:107]
	v_mfma_f32_16x16x32_bf16 v[96:99], v[168:171], v[194:197], v[96:99]
	v_mfma_f32_16x16x32_bf16 v[88:91], v[160:163], v[202:205], v[88:91]
	v_mfma_f32_16x16x32_bf16 v[80:83], v[168:171], v[202:205], v[80:83]
	v_mfma_f32_16x16x32_bf16 v[72:75], v[160:163], v[210:213], v[72:75]
	v_mfma_f32_16x16x32_bf16 v[64:67], v[168:171], v[210:213], v[64:67]
	v_mfma_f32_16x16x32_bf16 v[124:127], v[164:167], v[190:193], v[124:127]
	v_mfma_f32_16x16x32_bf16 v[112:115], v[172:175], v[190:193], v[112:115]
	v_mfma_f32_16x16x32_bf16 v[104:107], v[164:167], v[198:201], v[104:107]
	v_mfma_f32_16x16x32_bf16 v[96:99], v[172:175], v[198:201], v[96:99]
	v_mfma_f32_16x16x32_bf16 v[88:91], v[164:167], v[206:209], v[88:91]
	v_mfma_f32_16x16x32_bf16 v[80:83], v[172:175], v[206:209], v[80:83]
	v_mfma_f32_16x16x32_bf16 v[72:75], v[164:167], v[214:217], v[72:75]
	v_mfma_f32_16x16x32_bf16 v[64:67], v[172:175], v[214:217], v[64:67]
	s_barrier
	s_add_i32 s4, s45, s36
	v_lshl_add_u64 v[222:223], v[222:223], 0, s[14:15]
	s_mov_b32 m0, s4
	global_load_lds_dwordx4 v[222:223], off
	v_lshl_add_u64 v[222:223], v[224:225], 0, s[14:15]
	s_add_i32 m0, s4, 0x2000
	s_add_i32 s4, s54, s36
	global_load_lds_dwordx4 v[222:223], off
	v_lshl_add_u64 v[222:223], v[226:227], 0, s[14:15]
	s_mov_b32 m0, s4
	s_nop 0
	global_load_lds_dwordx4 v[222:223], off
	v_lshl_add_u64 v[222:223], v[228:229], 0, s[14:15]
	s_add_i32 m0, s4, 0x2000
	s_nop 0
	global_load_lds_dwordx4 v[222:223], off
	v_lshl_add_u64 v[222:223], v[230:231], 0, s[14:15]
	s_mov_b32 m0, s59
	s_nop 0
	global_load_lds_dwordx4 v[222:223], off
	v_lshl_add_u64 v[222:223], v[232:233], 0, s[14:15]
	s_mov_b32 m0, s60
	s_nop 0
	global_load_lds_dwordx4 v[222:223], off
	ds_read_b128 v[186:189], v155 offset:49152
	ds_read_b128 v[190:193], v155 offset:50176
	ds_read_b128 v[194:197], v155 offset:51200
	ds_read_b128 v[198:201], v155 offset:52224
	ds_read_b128 v[202:205], v155 offset:53248
	ds_read_b128 v[206:209], v155 offset:54272
	ds_read_b128 v[210:213], v155 offset:55296
	ds_read_b128 v[214:217], v155 offset:56320
	s_waitcnt vmcnt(8)
	s_waitcnt lgkmcnt(0)
	s_barrier
	s_waitcnt lgkmcnt(0)
	v_mfma_f32_16x16x32_bf16 v[60:63], v[128:131], v[186:189], v[60:63]
	s_add_u32 s28, s28, 0x100
	v_mfma_f32_16x16x32_bf16 v[52:55], v[146:149], v[186:189], v[52:55]
	s_addc_u32 s29, s29, 0
	v_mfma_f32_16x16x32_bf16 v[44:47], v[128:131], v[194:197], v[44:47]
	s_add_u32 s10, s10, 0x100
	v_mfma_f32_16x16x32_bf16 v[36:39], v[146:149], v[194:197], v[36:39]
	s_addc_u32 s11, s11, 0
	v_mfma_f32_16x16x32_bf16 v[28:31], v[128:131], v[202:205], v[28:31]
	s_mov_b32 s30, s44
	v_mfma_f32_16x16x32_bf16 v[20:23], v[146:149], v[202:205], v[20:23]
	s_cmp_ge_i32 s44, s49
	v_mfma_f32_16x16x32_bf16 v[12:15], v[128:131], v[210:213], v[12:15]
	s_cselect_b32 s99, 1, 0
	v_mfma_f32_16x16x32_bf16 v[4:7], v[146:149], v[210:213], v[4:7]
	s_add_i32 s44, s30, 2
	v_mfma_f32_16x16x32_bf16 v[60:63], v[142:145], v[190:193], v[60:63]
	s_add_u32 s4, s28, 0x80
	v_mfma_f32_16x16x32_bf16 v[52:55], v[156:159], v[190:193], v[52:55]
	s_addc_u32 s5, s29, 0
	v_mfma_f32_16x16x32_bf16 v[44:47], v[142:145], v[198:201], v[44:47]
	s_add_i32 s45, 0, 0x10000
	v_mfma_f32_16x16x32_bf16 v[36:39], v[156:159], v[198:201], v[36:39]
	s_cmp_eq_u32 s61, s30
	v_mfma_f32_16x16x32_bf16 v[28:31], v[142:145], v[206:209], v[28:31]
	s_cselect_b32 s31, s25, s5
	v_mfma_f32_16x16x32_bf16 v[20:23], v[156:159], v[206:209], v[20:23]
	s_cselect_b32 s30, s24, s4
	v_mfma_f32_16x16x32_bf16 v[12:15], v[142:145], v[214:217], v[12:15]
	s_cselect_b32 s5, s27, s11
	v_mfma_f32_16x16x32_bf16 v[4:7], v[156:159], v[214:217], v[4:7]
	s_cselect_b32 s4, s26, s10
	v_mfma_f32_16x16x32_bf16 v[56:59], v[160:163], v[186:189], v[56:59]
	s_add_i32 s54, 0, 0x14000
	v_mfma_f32_16x16x32_bf16 v[48:51], v[168:171], v[186:189], v[48:51]
	v_mfma_f32_16x16x32_bf16 v[40:43], v[160:163], v[194:197], v[40:43]
	v_mfma_f32_16x16x32_bf16 v[32:35], v[168:171], v[194:197], v[32:35]
	v_mfma_f32_16x16x32_bf16 v[24:27], v[160:163], v[202:205], v[24:27]
	v_mfma_f32_16x16x32_bf16 v[16:19], v[168:171], v[202:205], v[16:19]
	v_mfma_f32_16x16x32_bf16 v[8:11], v[160:163], v[210:213], v[8:11]
	v_mfma_f32_16x16x32_bf16 v[0:3], v[168:171], v[210:213], v[0:3]
	v_mfma_f32_16x16x32_bf16 v[56:59], v[164:167], v[190:193], v[56:59]
	v_mfma_f32_16x16x32_bf16 v[48:51], v[172:175], v[190:193], v[48:51]
	v_mfma_f32_16x16x32_bf16 v[40:43], v[164:167], v[198:201], v[40:43]
	v_mfma_f32_16x16x32_bf16 v[32:35], v[172:175], v[198:201], v[32:35]
	v_mfma_f32_16x16x32_bf16 v[24:27], v[164:167], v[206:209], v[24:27]
	v_mfma_f32_16x16x32_bf16 v[16:19], v[172:175], v[206:209], v[16:19]
	v_mfma_f32_16x16x32_bf16 v[8:11], v[164:167], v[214:217], v[8:11]
	v_mfma_f32_16x16x32_bf16 v[0:3], v[172:175], v[214:217], v[0:3]
	s_barrier
	s_cmp_lg_u32 s99, 0
	s_cbranch_scc0 .LBB0_394

.Llbb_4:
	s_add_i32 s44, s30, 2
	s_add_u32 s4, s28, 0x80
	s_addc_u32 s5, s29, 0
	s_add_i32 s45, 0, 0x10000
	s_cmp_eq_u32 s61, s30
	s_cselect_b32 s31, s25, s5
	s_cselect_b32 s30, s24, s4
	s_cselect_b32 s5, s27, s11
	s_cselect_b32 s4, s26, s10
	s_add_i32 s54, 0, 0x14000
	v_lshl_add_u64 v[174:175], s[28:29], 0, v[162:163]
	s_add_i32 m0, s38, 0xc000
	global_load_lds_dwordx4 v[174:175], off
	v_lshl_add_u64 v[174:175], s[28:29], 0, v[164:165]
	s_add_i32 m0, s38, 0xe000
	s_nop 0
	global_load_lds_dwordx4 v[174:175], off
	v_add_u32_e32 v140, s45, v195
	v_add_u32_e32 v166, s54, v195
	ds_read_b128 v[128:131], v140
	ds_read_b128 v[132:135], v140 offset:1024
	ds_read_b128 v[136:139], v140 offset:2048
	ds_read_b128 v[140:143], v140 offset:3072
	ds_read_b128 v[144:147], v166
	ds_read_b128 v[148:151], v166 offset:1024
	ds_read_b128 v[152:155], v166 offset:2048
	ds_read_b128 v[166:169], v166 offset:3072
	ds_read_b128 v[170:173], v197
	ds_read_b128 v[186:189], v197 offset:1024
	ds_read_b128 v[190:193], v197 offset:2048
	ds_read_b128 v[198:201], v197 offset:3072
	ds_read_b128 v[202:205], v197 offset:4096
	ds_read_b128 v[206:209], v197 offset:5120
	ds_read_b128 v[210:213], v197 offset:6144
	ds_read_b128 v[214:217], v197 offset:7168
	s_waitcnt vmcnt(8)
	s_waitcnt lgkmcnt(0)
	s_barrier
	s_waitcnt lgkmcnt(0)
	v_mfma_f32_16x16x32_bf16 v[120:123], v[128:131], v[170:173], 0
	v_mfma_f32_16x16x32_bf16 v[124:127], v[136:139], v[170:173], 0
	v_mfma_f32_16x16x32_bf16 v[108:111], v[128:131], v[190:193], 0
	v_mfma_f32_16x16x32_bf16 v[104:107], v[136:139], v[190:193], 0
	v_mfma_f32_16x16x32_bf16 v[92:95], v[128:131], v[202:205], 0
	v_mfma_f32_16x16x32_bf16 v[88:91], v[136:139], v[202:205], 0
	v_mfma_f32_16x16x32_bf16 v[76:79], v[128:131], v[210:213], 0
	v_mfma_f32_16x16x32_bf16 v[72:75], v[136:139], v[210:213], 0
	v_mfma_f32_16x16x32_bf16 v[120:123], v[132:135], v[186:189], v[120:123]
	v_mfma_f32_16x16x32_bf16 v[124:127], v[140:143], v[186:189], v[124:127]
	v_mfma_f32_16x16x32_bf16 v[108:111], v[132:135], v[198:201], v[108:111]
	v_mfma_f32_16x16x32_bf16 v[104:107], v[140:143], v[198:201], v[104:107]
	v_mfma_f32_16x16x32_bf16 v[92:95], v[132:135], v[206:209], v[92:95]
	v_mfma_f32_16x16x32_bf16 v[88:91], v[140:143], v[206:209], v[88:91]
	v_mfma_f32_16x16x32_bf16 v[76:79], v[132:135], v[214:217], v[76:79]
	v_mfma_f32_16x16x32_bf16 v[72:75], v[140:143], v[214:217], v[72:75]
	v_mfma_f32_16x16x32_bf16 v[116:119], v[144:147], v[170:173], 0
	v_mfma_f32_16x16x32_bf16 v[112:115], v[152:155], v[170:173], 0
	v_mfma_f32_16x16x32_bf16 v[100:103], v[144:147], v[190:193], 0
	v_mfma_f32_16x16x32_bf16 v[96:99], v[152:155], v[190:193], 0
	v_mfma_f32_16x16x32_bf16 v[84:87], v[144:147], v[202:205], 0
	v_mfma_f32_16x16x32_bf16 v[80:83], v[152:155], v[202:205], 0
	v_mfma_f32_16x16x32_bf16 v[68:71], v[144:147], v[210:213], 0
	v_mfma_f32_16x16x32_bf16 v[64:67], v[152:155], v[210:213], 0
	v_mfma_f32_16x16x32_bf16 v[116:119], v[148:151], v[186:189], v[116:119]
	v_mfma_f32_16x16x32_bf16 v[112:115], v[166:169], v[186:189], v[112:115]
	v_mfma_f32_16x16x32_bf16 v[100:103], v[148:151], v[198:201], v[100:103]
	v_mfma_f32_16x16x32_bf16 v[96:99], v[166:169], v[198:201], v[96:99]
	v_mfma_f32_16x16x32_bf16 v[84:87], v[148:151], v[206:209], v[84:87]
	v_mfma_f32_16x16x32_bf16 v[80:83], v[166:169], v[206:209], v[80:83]
	v_mfma_f32_16x16x32_bf16 v[68:71], v[148:151], v[214:217], v[68:71]
	v_mfma_f32_16x16x32_bf16 v[64:67], v[166:169], v[214:217], v[64:67]
	s_barrier
	s_add_i32 s45, s45, s37
	v_lshl_add_u64 v[174:175], s[4:5], 0, v[176:177]
	s_mov_b32 m0, s45
	global_load_lds_dwordx4 v[174:175], off
	s_add_i32 m0, s45, 0x2000
	v_lshl_add_u64 v[222:223], s[4:5], 0, v[156:157]
	s_add_u32 s4, s4, s6
	s_addc_u32 s5, s5, s7
	s_add_i32 s45, s54, s37
	global_load_lds_dwordx4 v[222:223], off
	v_lshl_add_u64 v[224:225], s[4:5], 0, v[176:177]
	s_mov_b32 m0, s45
	v_lshl_add_u64 v[226:227], s[4:5], 0, v[156:157]
	global_load_lds_dwordx4 v[224:225], off
	s_add_i32 m0, s45, 0x2000
	v_lshl_add_u64 v[228:229], s[30:31], 0, v[160:161]
	global_load_lds_dwordx4 v[226:227], off
	s_mov_b32 m0, s38
	v_lshl_add_u64 v[230:231], s[30:31], 0, v[158:159]
	global_load_lds_dwordx4 v[228:229], off
	s_mov_b32 m0, s39
	s_nop 0
	global_load_lds_dwordx4 v[230:231], off
	ds_read_b128 v[170:173], v197 offset:16384
	ds_read_b128 v[186:189], v197 offset:17408
	ds_read_b128 v[190:193], v197 offset:18432
	ds_read_b128 v[198:201], v197 offset:19456
	ds_read_b128 v[202:205], v197 offset:20480
	ds_read_b128 v[206:209], v197 offset:21504
	ds_read_b128 v[210:213], v197 offset:22528
	ds_read_b128 v[214:217], v197 offset:23552
	s_waitcnt vmcnt(8)
	s_waitcnt lgkmcnt(0)
	s_barrier
	s_waitcnt lgkmcnt(0)
	v_mfma_f32_16x16x32_bf16 v[60:63], v[128:131], v[170:173], 0
	v_mfma_f32_16x16x32_bf16 v[56:59], v[136:139], v[170:173], 0
	v_mfma_f32_16x16x32_bf16 v[44:47], v[128:131], v[190:193], 0
	v_mfma_f32_16x16x32_bf16 v[40:43], v[136:139], v[190:193], 0
	v_mfma_f32_16x16x32_bf16 v[28:31], v[128:131], v[202:205], 0
	v_mfma_f32_16x16x32_bf16 v[24:27], v[136:139], v[202:205], 0
	v_mfma_f32_16x16x32_bf16 v[12:15], v[128:131], v[210:213], 0
	v_mfma_f32_16x16x32_bf16 v[8:11], v[136:139], v[210:213], 0
	v_mfma_f32_16x16x32_bf16 v[60:63], v[132:135], v[186:189], v[60:63]
	v_mfma_f32_16x16x32_bf16 v[56:59], v[140:143], v[186:189], v[56:59]
	v_mfma_f32_16x16x32_bf16 v[44:47], v[132:135], v[198:201], v[44:47]
	v_mfma_f32_16x16x32_bf16 v[40:43], v[140:143], v[198:201], v[40:43]
	v_mfma_f32_16x16x32_bf16 v[28:31], v[132:135], v[206:209], v[28:31]
	v_mfma_f32_16x16x32_bf16 v[24:27], v[140:143], v[206:209], v[24:27]
	v_mfma_f32_16x16x32_bf16 v[12:15], v[132:135], v[214:217], v[12:15]
	v_mfma_f32_16x16x32_bf16 v[8:11], v[140:143], v[214:217], v[8:11]
	v_mfma_f32_16x16x32_bf16 v[52:55], v[144:147], v[170:173], 0
	v_mfma_f32_16x16x32_bf16 v[48:51], v[152:155], v[170:173], 0
	v_mfma_f32_16x16x32_bf16 v[36:39], v[144:147], v[190:193], 0
	v_mfma_f32_16x16x32_bf16 v[32:35], v[152:155], v[190:193], 0
	v_mfma_f32_16x16x32_bf16 v[20:23], v[144:147], v[202:205], 0
	v_mfma_f32_16x16x32_bf16 v[16:19], v[152:155], v[202:205], 0
	v_mfma_f32_16x16x32_bf16 v[4:7], v[144:147], v[210:213], 0
	v_mfma_f32_16x16x32_bf16 v[0:3], v[152:155], v[210:213], 0
	v_mfma_f32_16x16x32_bf16 v[52:55], v[148:151], v[186:189], v[52:55]
	v_mfma_f32_16x16x32_bf16 v[48:51], v[166:169], v[186:189], v[48:51]
	v_mfma_f32_16x16x32_bf16 v[36:39], v[148:151], v[198:201], v[36:39]
	v_mfma_f32_16x16x32_bf16 v[32:35], v[166:169], v[198:201], v[32:35]
	v_mfma_f32_16x16x32_bf16 v[20:23], v[148:151], v[206:209], v[20:23]
	v_mfma_f32_16x16x32_bf16 v[16:19], v[166:169], v[206:209], v[16:19]
	v_mfma_f32_16x16x32_bf16 v[4:7], v[148:151], v[214:217], v[4:7]
	v_mfma_f32_16x16x32_bf16 v[0:3], v[166:169], v[214:217], v[0:3]
	s_barrier
	s_add_i32 s45, 0, 0x18000
	s_add_i32 s54, 0, 0x1c000
	s_add_u32 s4, s30, s6
	s_addc_u32 s5, s31, s7
	s_mov_b32 m0, s48
	v_lshl_add_u64 v[232:233], s[4:5], 0, v[160:161]
	global_load_lds_dwordx4 v[232:233], off
	v_lshl_add_u64 v[232:233], s[4:5], 0, v[158:159]
	s_mov_b32 m0, s49
	s_nop 0
	global_load_lds_dwordx4 v[232:233], off
	v_add_u32_e32 v140, s45, v195
	v_add_u32_e32 v166, s54, v195
	ds_read_b128 v[128:131], v140
	ds_read_b128 v[132:135], v140 offset:1024
	ds_read_b128 v[136:139], v140 offset:2048
	ds_read_b128 v[140:143], v140 offset:3072
	ds_read_b128 v[144:147], v166
	ds_read_b128 v[148:151], v166 offset:1024
	ds_read_b128 v[152:155], v166 offset:2048
	ds_read_b128 v[166:169], v166 offset:3072
	ds_read_b128 v[170:173], v197 offset:32768
	ds_read_b128 v[186:189], v197 offset:33792
	ds_read_b128 v[190:193], v197 offset:34816
	ds_read_b128 v[198:201], v197 offset:35840
	ds_read_b128 v[202:205], v197 offset:36864
	ds_read_b128 v[206:209], v197 offset:37888
	ds_read_b128 v[210:213], v197 offset:38912
	ds_read_b128 v[214:217], v197 offset:39936
	s_waitcnt vmcnt(8)
	s_waitcnt lgkmcnt(0)
	s_barrier
	s_waitcnt lgkmcnt(0)
	v_mfma_f32_16x16x32_bf16 v[120:123], v[128:131], v[170:173], v[120:123]
	v_mfma_f32_16x16x32_bf16 v[124:127], v[136:139], v[170:173], v[124:127]
	v_mfma_f32_16x16x32_bf16 v[108:111], v[128:131], v[190:193], v[108:111]
	v_mfma_f32_16x16x32_bf16 v[104:107], v[136:139], v[190:193], v[104:107]
	v_mfma_f32_16x16x32_bf16 v[92:95], v[128:131], v[202:205], v[92:95]
	v_mfma_f32_16x16x32_bf16 v[88:91], v[136:139], v[202:205], v[88:91]
	v_mfma_f32_16x16x32_bf16 v[76:79], v[128:131], v[210:213], v[76:79]
	v_mfma_f32_16x16x32_bf16 v[72:75], v[136:139], v[210:213], v[72:75]
	v_mfma_f32_16x16x32_bf16 v[120:123], v[132:135], v[186:189], v[120:123]
	v_mfma_f32_16x16x32_bf16 v[124:127], v[140:143], v[186:189], v[124:127]
	v_mfma_f32_16x16x32_bf16 v[108:111], v[132:135], v[198:201], v[108:111]
	v_mfma_f32_16x16x32_bf16 v[104:107], v[140:143], v[198:201], v[104:107]
	v_mfma_f32_16x16x32_bf16 v[92:95], v[132:135], v[206:209], v[92:95]
	v_mfma_f32_16x16x32_bf16 v[88:91], v[140:143], v[206:209], v[88:91]
	v_mfma_f32_16x16x32_bf16 v[76:79], v[132:135], v[214:217], v[76:79]
	v_mfma_f32_16x16x32_bf16 v[72:75], v[140:143], v[214:217], v[72:75]
	v_mfma_f32_16x16x32_bf16 v[116:119], v[144:147], v[170:173], v[116:119]
	v_mfma_f32_16x16x32_bf16 v[112:115], v[152:155], v[170:173], v[112:115]
	v_mfma_f32_16x16x32_bf16 v[100:103], v[144:147], v[190:193], v[100:103]
	v_mfma_f32_16x16x32_bf16 v[96:99], v[152:155], v[190:193], v[96:99]
	v_mfma_f32_16x16x32_bf16 v[84:87], v[144:147], v[202:205], v[84:87]
	v_mfma_f32_16x16x32_bf16 v[80:83], v[152:155], v[202:205], v[80:83]
	v_mfma_f32_16x16x32_bf16 v[68:71], v[144:147], v[210:213], v[68:71]
	v_mfma_f32_16x16x32_bf16 v[64:67], v[152:155], v[210:213], v[64:67]
	v_mfma_f32_16x16x32_bf16 v[116:119], v[148:151], v[186:189], v[116:119]
	v_mfma_f32_16x16x32_bf16 v[112:115], v[166:169], v[186:189], v[112:115]
	v_mfma_f32_16x16x32_bf16 v[100:103], v[148:151], v[198:201], v[100:103]
	v_mfma_f32_16x16x32_bf16 v[96:99], v[166:169], v[198:201], v[96:99]
	v_mfma_f32_16x16x32_bf16 v[84:87], v[148:151], v[206:209], v[84:87]
	v_mfma_f32_16x16x32_bf16 v[80:83], v[166:169], v[206:209], v[80:83]
	v_mfma_f32_16x16x32_bf16 v[68:71], v[148:151], v[214:217], v[68:71]
	v_mfma_f32_16x16x32_bf16 v[64:67], v[166:169], v[214:217], v[64:67]
	s_barrier
	s_add_i32 s4, s45, s37
	v_lshl_add_u64 v[174:175], v[174:175], 0, s[14:15]
	s_mov_b32 m0, s4
	global_load_lds_dwordx4 v[174:175], off
	v_lshl_add_u64 v[174:175], v[222:223], 0, s[14:15]
	s_add_i32 m0, s4, 0x2000
	s_add_i32 s4, s54, s37
	global_load_lds_dwordx4 v[174:175], off
	v_lshl_add_u64 v[174:175], v[224:225], 0, s[14:15]
	s_mov_b32 m0, s4
	s_nop 0
	global_load_lds_dwordx4 v[174:175], off
	v_lshl_add_u64 v[174:175], v[226:227], 0, s[14:15]
	s_add_i32 m0, s4, 0x2000
	s_nop 0
	global_load_lds_dwordx4 v[174:175], off
	v_lshl_add_u64 v[174:175], v[228:229], 0, s[14:15]
	s_mov_b32 m0, s59
	s_nop 0
	global_load_lds_dwordx4 v[174:175], off
	v_lshl_add_u64 v[174:175], v[230:231], 0, s[14:15]
	s_mov_b32 m0, s60
	s_nop 0
	global_load_lds_dwordx4 v[174:175], off
	ds_read_b128 v[170:173], v197 offset:49152
	ds_read_b128 v[186:189], v197 offset:50176
	ds_read_b128 v[190:193], v197 offset:51200
	ds_read_b128 v[198:201], v197 offset:52224
	ds_read_b128 v[202:205], v197 offset:53248
	ds_read_b128 v[206:209], v197 offset:54272
	ds_read_b128 v[210:213], v197 offset:55296
	ds_read_b128 v[214:217], v197 offset:56320
	s_waitcnt vmcnt(8)
	s_waitcnt lgkmcnt(0)
	s_barrier
	s_waitcnt lgkmcnt(0)
	v_mfma_f32_16x16x32_bf16 v[60:63], v[128:131], v[170:173], v[60:63]
	s_add_u32 s28, s28, 0x100
	v_mfma_f32_16x16x32_bf16 v[56:59], v[136:139], v[170:173], v[56:59]
	s_addc_u32 s29, s29, 0
	v_mfma_f32_16x16x32_bf16 v[44:47], v[128:131], v[190:193], v[44:47]
	s_add_u32 s10, s10, 0x100
	v_mfma_f32_16x16x32_bf16 v[40:43], v[136:139], v[190:193], v[40:43]
	s_addc_u32 s11, s11, 0
	v_mfma_f32_16x16x32_bf16 v[28:31], v[128:131], v[202:205], v[28:31]
	s_mov_b32 s30, s44
	v_mfma_f32_16x16x32_bf16 v[24:27], v[136:139], v[202:205], v[24:27]
	s_cmp_ge_i32 s44, s58
	v_mfma_f32_16x16x32_bf16 v[12:15], v[128:131], v[210:213], v[12:15]
	s_cselect_b32 s99, 1, 0
	v_mfma_f32_16x16x32_bf16 v[8:11], v[136:139], v[210:213], v[8:11]
	s_add_i32 s44, s30, 2
	v_mfma_f32_16x16x32_bf16 v[60:63], v[132:135], v[186:189], v[60:63]
	s_add_u32 s4, s28, 0x80
	v_mfma_f32_16x16x32_bf16 v[56:59], v[140:143], v[186:189], v[56:59]
	s_addc_u32 s5, s29, 0
	v_mfma_f32_16x16x32_bf16 v[44:47], v[132:135], v[198:201], v[44:47]
	s_add_i32 s45, 0, 0x10000
	v_mfma_f32_16x16x32_bf16 v[40:43], v[140:143], v[198:201], v[40:43]
	s_cmp_eq_u32 s61, s30
	v_mfma_f32_16x16x32_bf16 v[28:31], v[132:135], v[206:209], v[28:31]
	s_cselect_b32 s31, s25, s5
	v_mfma_f32_16x16x32_bf16 v[24:27], v[140:143], v[206:209], v[24:27]
	s_cselect_b32 s30, s24, s4
	v_mfma_f32_16x16x32_bf16 v[12:15], v[132:135], v[214:217], v[12:15]
	s_cselect_b32 s5, s27, s11
	v_mfma_f32_16x16x32_bf16 v[8:11], v[140:143], v[214:217], v[8:11]
	s_cselect_b32 s4, s26, s10
	v_mfma_f32_16x16x32_bf16 v[52:55], v[144:147], v[170:173], v[52:55]
	s_add_i32 s54, 0, 0x14000
	v_mfma_f32_16x16x32_bf16 v[48:51], v[152:155], v[170:173], v[48:51]
	v_mfma_f32_16x16x32_bf16 v[36:39], v[144:147], v[190:193], v[36:39]
	v_mfma_f32_16x16x32_bf16 v[32:35], v[152:155], v[190:193], v[32:35]
	v_mfma_f32_16x16x32_bf16 v[20:23], v[144:147], v[202:205], v[20:23]
	v_mfma_f32_16x16x32_bf16 v[16:19], v[152:155], v[202:205], v[16:19]
	v_mfma_f32_16x16x32_bf16 v[4:7], v[144:147], v[210:213], v[4:7]
	v_mfma_f32_16x16x32_bf16 v[0:3], v[152:155], v[210:213], v[0:3]
	v_mfma_f32_16x16x32_bf16 v[52:55], v[148:151], v[186:189], v[52:55]
	v_mfma_f32_16x16x32_bf16 v[48:51], v[166:169], v[186:189], v[48:51]
	v_mfma_f32_16x16x32_bf16 v[36:39], v[148:151], v[198:201], v[36:39]
	v_mfma_f32_16x16x32_bf16 v[32:35], v[166:169], v[198:201], v[32:35]
	v_mfma_f32_16x16x32_bf16 v[20:23], v[148:151], v[206:209], v[20:23]
	v_mfma_f32_16x16x32_bf16 v[16:19], v[166:169], v[206:209], v[16:19]
	v_mfma_f32_16x16x32_bf16 v[4:7], v[148:151], v[214:217], v[4:7]
	v_mfma_f32_16x16x32_bf16 v[0:3], v[166:169], v[214:217], v[0:3]
	s_barrier
	s_cmp_lg_u32 s99, 0
	s_cbranch_scc1 .Lpeelx_8
.LBB0_475:
	v_lshl_add_u64 v[174:175], s[28:29], 0, v[162:163]
	s_add_i32 m0, s38, 0xc000
	global_load_lds_dwordx4 v[174:175], off
	v_lshl_add_u64 v[174:175], s[28:29], 0, v[164:165]
	s_add_i32 m0, s38, 0xe000
	s_nop 0
	global_load_lds_dwordx4 v[174:175], off
	v_add_u32_e32 v140, s45, v195
	v_add_u32_e32 v166, s54, v195
	ds_read_b128 v[128:131], v140
	ds_read_b128 v[132:135], v140 offset:1024
	ds_read_b128 v[136:139], v140 offset:2048
	ds_read_b128 v[140:143], v140 offset:3072
	ds_read_b128 v[144:147], v166
	ds_read_b128 v[148:151], v166 offset:1024
	ds_read_b128 v[152:155], v166 offset:2048
	ds_read_b128 v[166:169], v166 offset:3072
	ds_read_b128 v[170:173], v197
	ds_read_b128 v[186:189], v197 offset:1024
	ds_read_b128 v[190:193], v197 offset:2048
	ds_read_b128 v[198:201], v197 offset:3072
	ds_read_b128 v[202:205], v197 offset:4096
	ds_read_b128 v[206:209], v197 offset:5120
	ds_read_b128 v[210:213], v197 offset:6144
	ds_read_b128 v[214:217], v197 offset:7168
	s_waitcnt vmcnt(8)
	s_waitcnt lgkmcnt(0)
	s_barrier
	s_waitcnt lgkmcnt(0)
	v_mfma_f32_16x16x32_bf16 v[120:123], v[128:131], v[170:173], v[120:123]
	v_mfma_f32_16x16x32_bf16 v[124:127], v[136:139], v[170:173], v[124:127]
	v_mfma_f32_16x16x32_bf16 v[108:111], v[128:131], v[190:193], v[108:111]
	v_mfma_f32_16x16x32_bf16 v[104:107], v[136:139], v[190:193], v[104:107]
	v_mfma_f32_16x16x32_bf16 v[92:95], v[128:131], v[202:205], v[92:95]
	v_mfma_f32_16x16x32_bf16 v[88:91], v[136:139], v[202:205], v[88:91]
	v_mfma_f32_16x16x32_bf16 v[76:79], v[128:131], v[210:213], v[76:79]
	v_mfma_f32_16x16x32_bf16 v[72:75], v[136:139], v[210:213], v[72:75]
	v_mfma_f32_16x16x32_bf16 v[120:123], v[132:135], v[186:189], v[120:123]
	v_mfma_f32_16x16x32_bf16 v[124:127], v[140:143], v[186:189], v[124:127]
	v_mfma_f32_16x16x32_bf16 v[108:111], v[132:135], v[198:201], v[108:111]
	v_mfma_f32_16x16x32_bf16 v[104:107], v[140:143], v[198:201], v[104:107]
	v_mfma_f32_16x16x32_bf16 v[92:95], v[132:135], v[206:209], v[92:95]
	v_mfma_f32_16x16x32_bf16 v[88:91], v[140:143], v[206:209], v[88:91]
	v_mfma_f32_16x16x32_bf16 v[76:79], v[132:135], v[214:217], v[76:79]
	v_mfma_f32_16x16x32_bf16 v[72:75], v[140:143], v[214:217], v[72:75]
	v_mfma_f32_16x16x32_bf16 v[116:119], v[144:147], v[170:173], v[116:119]
	v_mfma_f32_16x16x32_bf16 v[112:115], v[152:155], v[170:173], v[112:115]
	v_mfma_f32_16x16x32_bf16 v[100:103], v[144:147], v[190:193], v[100:103]
	v_mfma_f32_16x16x32_bf16 v[96:99], v[152:155], v[190:193], v[96:99]
	v_mfma_f32_16x16x32_bf16 v[84:87], v[144:147], v[202:205], v[84:87]
	v_mfma_f32_16x16x32_bf16 v[80:83], v[152:155], v[202:205], v[80:83]
	v_mfma_f32_16x16x32_bf16 v[68:71], v[144:147], v[210:213], v[68:71]
	v_mfma_f32_16x16x32_bf16 v[64:67], v[152:155], v[210:213], v[64:67]
	v_mfma_f32_16x16x32_bf16 v[116:119], v[148:151], v[186:189], v[116:119]
	v_mfma_f32_16x16x32_bf16 v[112:115], v[166:169], v[186:189], v[112:115]
	v_mfma_f32_16x16x32_bf16 v[100:103], v[148:151], v[198:201], v[100:103]
	v_mfma_f32_16x16x32_bf16 v[96:99], v[166:169], v[198:201], v[96:99]
	v_mfma_f32_16x16x32_bf16 v[84:87], v[148:151], v[206:209], v[84:87]
	v_mfma_f32_16x16x32_bf16 v[80:83], v[166:169], v[206:209], v[80:83]
	v_mfma_f32_16x16x32_bf16 v[68:71], v[148:151], v[214:217], v[68:71]
	v_mfma_f32_16x16x32_bf16 v[64:67], v[166:169], v[214:217], v[64:67]
	s_barrier
	s_add_i32 s45, s45, s37
	v_lshl_add_u64 v[174:175], s[4:5], 0, v[176:177]
	s_mov_b32 m0, s45
	global_load_lds_dwordx4 v[174:175], off
	s_add_i32 m0, s45, 0x2000
	v_lshl_add_u64 v[222:223], s[4:5], 0, v[156:157]
	s_add_u32 s4, s4, s6
	s_addc_u32 s5, s5, s7
	s_add_i32 s45, s54, s37
	global_load_lds_dwordx4 v[222:223], off
	v_lshl_add_u64 v[224:225], s[4:5], 0, v[176:177]
	s_mov_b32 m0, s45
	v_lshl_add_u64 v[226:227], s[4:5], 0, v[156:157]
	global_load_lds_dwordx4 v[224:225], off
	s_add_i32 m0, s45, 0x2000
	v_lshl_add_u64 v[228:229], s[30:31], 0, v[160:161]
	global_load_lds_dwordx4 v[226:227], off
	s_mov_b32 m0, s38
	v_lshl_add_u64 v[230:231], s[30:31], 0, v[158:159]
	global_load_lds_dwordx4 v[228:229], off
	s_mov_b32 m0, s39
	s_nop 0
	global_load_lds_dwordx4 v[230:231], off
	ds_read_b128 v[170:173], v197 offset:16384
	ds_read_b128 v[186:189], v197 offset:17408
	ds_read_b128 v[190:193], v197 offset:18432
	ds_read_b128 v[198:201], v197 offset:19456
	ds_read_b128 v[202:205], v197 offset:20480
	ds_read_b128 v[206:209], v197 offset:21504
	ds_read_b128 v[210:213], v197 offset:22528
	ds_read_b128 v[214:217], v197 offset:23552
	s_waitcnt vmcnt(8)
	s_waitcnt lgkmcnt(0)
	s_barrier
	s_waitcnt lgkmcnt(0)
	v_mfma_f32_16x16x32_bf16 v[60:63], v[128:131], v[170:173], v[60:63]
	v_mfma_f32_16x16x32_bf16 v[56:59], v[136:139], v[170:173], v[56:59]
	v_mfma_f32_16x16x32_bf16 v[44:47], v[128:131], v[190:193], v[44:47]
	v_mfma_f32_16x16x32_bf16 v[40:43], v[136:139], v[190:193], v[40:43]
	v_mfma_f32_16x16x32_bf16 v[28:31], v[128:131], v[202:205], v[28:31]
	v_mfma_f32_16x16x32_bf16 v[24:27], v[136:139], v[202:205], v[24:27]
	v_mfma_f32_16x16x32_bf16 v[12:15], v[128:131], v[210:213], v[12:15]
	v_mfma_f32_16x16x32_bf16 v[8:11], v[136:139], v[210:213], v[8:11]
	v_mfma_f32_16x16x32_bf16 v[60:63], v[132:135], v[186:189], v[60:63]
	v_mfma_f32_16x16x32_bf16 v[56:59], v[140:143], v[186:189], v[56:59]
	v_mfma_f32_16x16x32_bf16 v[44:47], v[132:135], v[198:201], v[44:47]
	v_mfma_f32_16x16x32_bf16 v[40:43], v[140:143], v[198:201], v[40:43]
	v_mfma_f32_16x16x32_bf16 v[28:31], v[132:135], v[206:209], v[28:31]
	v_mfma_f32_16x16x32_bf16 v[24:27], v[140:143], v[206:209], v[24:27]
	v_mfma_f32_16x16x32_bf16 v[12:15], v[132:135], v[214:217], v[12:15]
	v_mfma_f32_16x16x32_bf16 v[8:11], v[140:143], v[214:217], v[8:11]
	v_mfma_f32_16x16x32_bf16 v[52:55], v[144:147], v[170:173], v[52:55]
	v_mfma_f32_16x16x32_bf16 v[48:51], v[152:155], v[170:173], v[48:51]
	v_mfma_f32_16x16x32_bf16 v[36:39], v[144:147], v[190:193], v[36:39]
	v_mfma_f32_16x16x32_bf16 v[32:35], v[152:155], v[190:193], v[32:35]
	v_mfma_f32_16x16x32_bf16 v[20:23], v[144:147], v[202:205], v[20:23]
	v_mfma_f32_16x16x32_bf16 v[16:19], v[152:155], v[202:205], v[16:19]
	v_mfma_f32_16x16x32_bf16 v[4:7], v[144:147], v[210:213], v[4:7]
	v_mfma_f32_16x16x32_bf16 v[0:3], v[152:155], v[210:213], v[0:3]
	v_mfma_f32_16x16x32_bf16 v[52:55], v[148:151], v[186:189], v[52:55]
	v_mfma_f32_16x16x32_bf16 v[48:51], v[166:169], v[186:189], v[48:51]
	v_mfma_f32_16x16x32_bf16 v[36:39], v[148:151], v[198:201], v[36:39]
	v_mfma_f32_16x16x32_bf16 v[32:35], v[166:169], v[198:201], v[32:35]
	v_mfma_f32_16x16x32_bf16 v[20:23], v[148:151], v[206:209], v[20:23]
	v_mfma_f32_16x16x32_bf16 v[16:19], v[166:169], v[206:209], v[16:19]
	v_mfma_f32_16x16x32_bf16 v[4:7], v[148:151], v[214:217], v[4:7]
	v_mfma_f32_16x16x32_bf16 v[0:3], v[166:169], v[214:217], v[0:3]
	s_barrier
	s_add_i32 s45, 0, 0x18000
	s_add_i32 s54, 0, 0x1c000
	s_add_u32 s4, s30, s6
	s_addc_u32 s5, s31, s7
	s_mov_b32 m0, s48
	v_lshl_add_u64 v[232:233], s[4:5], 0, v[160:161]
	global_load_lds_dwordx4 v[232:233], off
	v_lshl_add_u64 v[232:233], s[4:5], 0, v[158:159]
	s_mov_b32 m0, s49
	s_nop 0
	global_load_lds_dwordx4 v[232:233], off
	v_add_u32_e32 v140, s45, v195
	v_add_u32_e32 v166, s54, v195
	ds_read_b128 v[128:131], v140
	ds_read_b128 v[132:135], v140 offset:1024
	ds_read_b128 v[136:139], v140 offset:2048
	ds_read_b128 v[140:143], v140 offset:3072
	ds_read_b128 v[144:147], v166
	ds_read_b128 v[148:151], v166 offset:1024
	ds_read_b128 v[152:155], v166 offset:2048
	ds_read_b128 v[166:169], v166 offset:3072
	ds_read_b128 v[170:173], v197 offset:32768
	ds_read_b128 v[186:189], v197 offset:33792
	ds_read_b128 v[190:193], v197 offset:34816
	ds_read_b128 v[198:201], v197 offset:35840
	ds_read_b128 v[202:205], v197 offset:36864
	ds_read_b128 v[206:209], v197 offset:37888
	ds_read_b128 v[210:213], v197 offset:38912
	ds_read_b128 v[214:217], v197 offset:39936
	s_waitcnt vmcnt(8)
	s_waitcnt lgkmcnt(0)
	s_barrier
	s_waitcnt lgkmcnt(0)
	v_mfma_f32_16x16x32_bf16 v[120:123], v[128:131], v[170:173], v[120:123]
	v_mfma_f32_16x16x32_bf16 v[124:127], v[136:139], v[170:173], v[124:127]
	v_mfma_f32_16x16x32_bf16 v[108:111], v[128:131], v[190:193], v[108:111]
	v_mfma_f32_16x16x32_bf16 v[104:107], v[136:139], v[190:193], v[104:107]
	v_mfma_f32_16x16x32_bf16 v[92:95], v[128:131], v[202:205], v[92:95]
	v_mfma_f32_16x16x32_bf16 v[88:91], v[136:139], v[202:205], v[88:91]
	v_mfma_f32_16x16x32_bf16 v[76:79], v[128:131], v[210:213], v[76:79]
	v_mfma_f32_16x16x32_bf16 v[72:75], v[136:139], v[210:213], v[72:75]
	v_mfma_f32_16x16x32_bf16 v[120:123], v[132:135], v[186:189], v[120:123]
	v_mfma_f32_16x16x32_bf16 v[124:127], v[140:143], v[186:189], v[124:127]
	v_mfma_f32_16x16x32_bf16 v[108:111], v[132:135], v[198:201], v[108:111]
	v_mfma_f32_16x16x32_bf16 v[104:107], v[140:143], v[198:201], v[104:107]
	v_mfma_f32_16x16x32_bf16 v[92:95], v[132:135], v[206:209], v[92:95]
	v_mfma_f32_16x16x32_bf16 v[88:91], v[140:143], v[206:209], v[88:91]
	v_mfma_f32_16x16x32_bf16 v[76:79], v[132:135], v[214:217], v[76:79]
	v_mfma_f32_16x16x32_bf16 v[72:75], v[140:143], v[214:217], v[72:75]
	v_mfma_f32_16x16x32_bf16 v[116:119], v[144:147], v[170:173], v[116:119]
	v_mfma_f32_16x16x32_bf16 v[112:115], v[152:155], v[170:173], v[112:115]
	v_mfma_f32_16x16x32_bf16 v[100:103], v[144:147], v[190:193], v[100:103]
	v_mfma_f32_16x16x32_bf16 v[96:99], v[152:155], v[190:193], v[96:99]
	v_mfma_f32_16x16x32_bf16 v[84:87], v[144:147], v[202:205], v[84:87]
	v_mfma_f32_16x16x32_bf16 v[80:83], v[152:155], v[202:205], v[80:83]
	v_mfma_f32_16x16x32_bf16 v[68:71], v[144:147], v[210:213], v[68:71]
	v_mfma_f32_16x16x32_bf16 v[64:67], v[152:155], v[210:213], v[64:67]
	v_mfma_f32_16x16x32_bf16 v[116:119], v[148:151], v[186:189], v[116:119]
	v_mfma_f32_16x16x32_bf16 v[112:115], v[166:169], v[186:189], v[112:115]
	v_mfma_f32_16x16x32_bf16 v[100:103], v[148:151], v[198:201], v[100:103]
	v_mfma_f32_16x16x32_bf16 v[96:99], v[166:169], v[198:201], v[96:99]
	v_mfma_f32_16x16x32_bf16 v[84:87], v[148:151], v[206:209], v[84:87]
	v_mfma_f32_16x16x32_bf16 v[80:83], v[166:169], v[206:209], v[80:83]
	v_mfma_f32_16x16x32_bf16 v[68:71], v[148:151], v[214:217], v[68:71]
	v_mfma_f32_16x16x32_bf16 v[64:67], v[166:169], v[214:217], v[64:67]
	s_barrier
	s_add_i32 s4, s45, s37
	v_lshl_add_u64 v[174:175], v[174:175], 0, s[14:15]
	s_mov_b32 m0, s4
	global_load_lds_dwordx4 v[174:175], off
	v_lshl_add_u64 v[174:175], v[222:223], 0, s[14:15]
	s_add_i32 m0, s4, 0x2000
	s_add_i32 s4, s54, s37
	global_load_lds_dwordx4 v[174:175], off
	v_lshl_add_u64 v[174:175], v[224:225], 0, s[14:15]
	s_mov_b32 m0, s4
	s_nop 0
	global_load_lds_dwordx4 v[174:175], off
	v_lshl_add_u64 v[174:175], v[226:227], 0, s[14:15]
	s_add_i32 m0, s4, 0x2000
	s_nop 0
	global_load_lds_dwordx4 v[174:175], off
	v_lshl_add_u64 v[174:175], v[228:229], 0, s[14:15]
	s_mov_b32 m0, s59
	s_nop 0
	global_load_lds_dwordx4 v[174:175], off
	v_lshl_add_u64 v[174:175], v[230:231], 0, s[14:15]
	s_mov_b32 m0, s60
	s_nop 0
	global_load_lds_dwordx4 v[174:175], off
	ds_read_b128 v[170:173], v197 offset:49152
	ds_read_b128 v[186:189], v197 offset:50176
	ds_read_b128 v[190:193], v197 offset:51200
	ds_read_b128 v[198:201], v197 offset:52224
	ds_read_b128 v[202:205], v197 offset:53248
	ds_read_b128 v[206:209], v197 offset:54272
	ds_read_b128 v[210:213], v197 offset:55296
	ds_read_b128 v[214:217], v197 offset:56320
	s_waitcnt vmcnt(8)
	s_waitcnt lgkmcnt(0)
	s_barrier
	s_waitcnt lgkmcnt(0)
	v_mfma_f32_16x16x32_bf16 v[60:63], v[128:131], v[170:173], v[60:63]
	s_add_u32 s28, s28, 0x100
	v_mfma_f32_16x16x32_bf16 v[56:59], v[136:139], v[170:173], v[56:59]
	s_addc_u32 s29, s29, 0
	v_mfma_f32_16x16x32_bf16 v[44:47], v[128:131], v[190:193], v[44:47]
	s_add_u32 s10, s10, 0x100
	v_mfma_f32_16x16x32_bf16 v[40:43], v[136:139], v[190:193], v[40:43]
	s_addc_u32 s11, s11, 0
	v_mfma_f32_16x16x32_bf16 v[28:31], v[128:131], v[202:205], v[28:31]
	s_mov_b32 s30, s44
	v_mfma_f32_16x16x32_bf16 v[24:27], v[136:139], v[202:205], v[24:27]
	s_cmp_ge_i32 s44, s58
	v_mfma_f32_16x16x32_bf16 v[12:15], v[128:131], v[210:213], v[12:15]
	s_cselect_b32 s99, 1, 0
	v_mfma_f32_16x16x32_bf16 v[8:11], v[136:139], v[210:213], v[8:11]
	s_add_i32 s44, s30, 2
	v_mfma_f32_16x16x32_bf16 v[60:63], v[132:135], v[186:189], v[60:63]
	s_add_u32 s4, s28, 0x80
	v_mfma_f32_16x16x32_bf16 v[56:59], v[140:143], v[186:189], v[56:59]
	s_addc_u32 s5, s29, 0
	v_mfma_f32_16x16x32_bf16 v[44:47], v[132:135], v[198:201], v[44:47]
	s_add_i32 s45, 0, 0x10000
	v_mfma_f32_16x16x32_bf16 v[40:43], v[140:143], v[198:201], v[40:43]
	s_cmp_eq_u32 s61, s30
	v_mfma_f32_16x16x32_bf16 v[28:31], v[132:135], v[206:209], v[28:31]
	s_cselect_b32 s31, s25, s5
	v_mfma_f32_16x16x32_bf16 v[24:27], v[140:143], v[206:209], v[24:27]
	s_cselect_b32 s30, s24, s4
	v_mfma_f32_16x16x32_bf16 v[12:15], v[132:135], v[214:217], v[12:15]
	s_cselect_b32 s5, s27, s11
	v_mfma_f32_16x16x32_bf16 v[8:11], v[140:143], v[214:217], v[8:11]
	s_cselect_b32 s4, s26, s10
	v_mfma_f32_16x16x32_bf16 v[52:55], v[144:147], v[170:173], v[52:55]
	s_add_i32 s54, 0, 0x14000
	v_mfma_f32_16x16x32_bf16 v[48:51], v[152:155], v[170:173], v[48:51]
	v_mfma_f32_16x16x32_bf16 v[36:39], v[144:147], v[190:193], v[36:39]
	v_mfma_f32_16x16x32_bf16 v[32:35], v[152:155], v[190:193], v[32:35]
	v_mfma_f32_16x16x32_bf16 v[20:23], v[144:147], v[202:205], v[20:23]
	v_mfma_f32_16x16x32_bf16 v[16:19], v[152:155], v[202:205], v[16:19]
	v_mfma_f32_16x16x32_bf16 v[4:7], v[144:147], v[210:213], v[4:7]
	v_mfma_f32_16x16x32_bf16 v[0:3], v[152:155], v[210:213], v[0:3]
	v_mfma_f32_16x16x32_bf16 v[52:55], v[148:151], v[186:189], v[52:55]
	v_mfma_f32_16x16x32_bf16 v[48:51], v[166:169], v[186:189], v[48:51]
	v_mfma_f32_16x16x32_bf16 v[36:39], v[148:151], v[198:201], v[36:39]
	v_mfma_f32_16x16x32_bf16 v[32:35], v[166:169], v[198:201], v[32:35]
	v_mfma_f32_16x16x32_bf16 v[20:23], v[148:151], v[206:209], v[20:23]
	v_mfma_f32_16x16x32_bf16 v[16:19], v[166:169], v[206:209], v[16:19]
	v_mfma_f32_16x16x32_bf16 v[4:7], v[148:151], v[214:217], v[4:7]
	v_mfma_f32_16x16x32_bf16 v[0:3], v[166:169], v[214:217], v[0:3]
	s_barrier
	s_cmp_lg_u32 s99, 0
	s_cbranch_scc0 .LBB0_475

.Llbb_5:
	s_add_i32 s44, s16, 2
	s_add_u32 s45, s0, 0x80
	s_addc_u32 s17, s1, 0
	s_add_i32 s64, 0, 0x10000
	s_cmp_eq_u32 s63, s16
	s_cselect_b32 s17, s57, s17
	s_cselect_b32 s16, s56, s45
	s_cselect_b32 s47, s9, s39
	s_cselect_b32 s46, s8, s38
	s_add_i32 s45, 0, 0x14000
	v_lshl_add_u64 v[178:179], s[0:1], 0, v[148:149]
	s_add_i32 m0, s52, 0xc000
	global_load_lds_dwordx4 v[178:179], off
	v_lshl_add_u64 v[178:179], s[0:1], 0, v[150:151]
	s_add_i32 m0, s52, 0xe000
	s_nop 0
	global_load_lds_dwordx4 v[178:179], off
	v_add_u32_e32 v152, s64, v153
	ds_read_b128 v[128:131], v152
	ds_read_b128 v[158:161], v152 offset:1024
	ds_read_b128 v[162:165], v152 offset:2048
	ds_read_b128 v[166:169], v152 offset:3072
	v_add_u32_e32 v152, s45, v153
	ds_read_b128 v[170:173], v152
	ds_read_b128 v[174:177], v152 offset:1024
	ds_read_b128 v[194:197], v152 offset:2048
	ds_read_b128 v[206:209], v152 offset:3072
	ds_read_b128 v[210:213], v157
	ds_read_b128 v[214:217], v157 offset:1024
	ds_read_b128 v[220:223], v157 offset:2048
	ds_read_b128 v[224:227], v157 offset:3072
	ds_read_b128 v[228:231], v157 offset:4096
	ds_read_b128 v[232:235], v157 offset:5120
	ds_read_b128 v[236:239], v157 offset:6144
	ds_read_b128 v[240:243], v157 offset:7168
	s_waitcnt vmcnt(8)
	s_waitcnt lgkmcnt(0)
	s_barrier
	s_waitcnt lgkmcnt(0)
	v_mfma_f32_16x16x32_bf16 v[124:127], v[128:131], v[210:213], 0
	v_mfma_f32_16x16x32_bf16 v[120:123], v[162:165], v[210:213], 0
	v_mfma_f32_16x16x32_bf16 v[108:111], v[128:131], v[220:223], 0
	v_mfma_f32_16x16x32_bf16 v[104:107], v[162:165], v[220:223], 0
	v_mfma_f32_16x16x32_bf16 v[92:95], v[128:131], v[228:231], 0
	v_mfma_f32_16x16x32_bf16 v[88:91], v[162:165], v[228:231], 0
	v_mfma_f32_16x16x32_bf16 v[76:79], v[128:131], v[236:239], 0
	v_mfma_f32_16x16x32_bf16 v[72:75], v[162:165], v[236:239], 0
	v_mfma_f32_16x16x32_bf16 v[124:127], v[158:161], v[214:217], v[124:127]
	v_mfma_f32_16x16x32_bf16 v[120:123], v[166:169], v[214:217], v[120:123]
	v_mfma_f32_16x16x32_bf16 v[108:111], v[158:161], v[224:227], v[108:111]
	v_mfma_f32_16x16x32_bf16 v[104:107], v[166:169], v[224:227], v[104:107]
	v_mfma_f32_16x16x32_bf16 v[92:95], v[158:161], v[232:235], v[92:95]
	v_mfma_f32_16x16x32_bf16 v[88:91], v[166:169], v[232:235], v[88:91]
	v_mfma_f32_16x16x32_bf16 v[76:79], v[158:161], v[240:243], v[76:79]
	v_mfma_f32_16x16x32_bf16 v[72:75], v[166:169], v[240:243], v[72:75]
	v_mfma_f32_16x16x32_bf16 v[116:119], v[170:173], v[210:213], 0
	v_mfma_f32_16x16x32_bf16 v[112:115], v[194:197], v[210:213], 0
	v_mfma_f32_16x16x32_bf16 v[100:103], v[170:173], v[220:223], 0
	v_mfma_f32_16x16x32_bf16 v[96:99], v[194:197], v[220:223], 0
	v_mfma_f32_16x16x32_bf16 v[84:87], v[170:173], v[228:231], 0
	v_mfma_f32_16x16x32_bf16 v[80:83], v[194:197], v[228:231], 0
	v_mfma_f32_16x16x32_bf16 v[68:71], v[170:173], v[236:239], 0
	v_mfma_f32_16x16x32_bf16 v[64:67], v[194:197], v[236:239], 0
	v_mfma_f32_16x16x32_bf16 v[116:119], v[174:177], v[214:217], v[116:119]
	v_mfma_f32_16x16x32_bf16 v[112:115], v[206:209], v[214:217], v[112:115]
	v_mfma_f32_16x16x32_bf16 v[100:103], v[174:177], v[224:227], v[100:103]
	v_mfma_f32_16x16x32_bf16 v[96:99], v[206:209], v[224:227], v[96:99]
	v_mfma_f32_16x16x32_bf16 v[84:87], v[174:177], v[232:235], v[84:87]
	v_mfma_f32_16x16x32_bf16 v[80:83], v[206:209], v[232:235], v[80:83]
	v_mfma_f32_16x16x32_bf16 v[68:71], v[174:177], v[240:243], v[68:71]
	v_mfma_f32_16x16x32_bf16 v[64:67], v[206:209], v[240:243], v[64:67]
	s_barrier
	s_add_i32 s64, s64, s4
	v_lshl_add_u64 v[178:179], s[46:47], 0, v[134:135]
	s_mov_b32 m0, s64
	global_load_lds_dwordx4 v[178:179], off
	s_add_i32 m0, s64, 0x2000
	v_lshl_add_u64 v[198:199], s[46:47], 0, v[138:139]
	s_add_u32 s46, s46, s24
	s_addc_u32 s47, s47, s25
	s_add_i32 s45, s45, s4
	global_load_lds_dwordx4 v[198:199], off
	v_lshl_add_u64 v[244:245], s[46:47], 0, v[134:135]
	s_mov_b32 m0, s45
	v_lshl_add_u64 v[246:247], s[46:47], 0, v[138:139]
	global_load_lds_dwordx4 v[244:245], off
	s_add_i32 m0, s45, 0x2000
	v_lshl_add_u64 v[248:249], s[16:17], 0, v[132:133]
	global_load_lds_dwordx4 v[246:247], off
	s_mov_b32 m0, s52
	v_lshl_add_u64 v[250:251], s[16:17], 0, v[136:137]
	global_load_lds_dwordx4 v[248:249], off
	s_mov_b32 m0, s18
	s_nop 0
	global_load_lds_dwordx4 v[250:251], off
	ds_read_b128 v[210:213], v157 offset:16384
	ds_read_b128 v[214:217], v157 offset:17408
	ds_read_b128 v[220:223], v157 offset:18432
	ds_read_b128 v[224:227], v157 offset:19456
	ds_read_b128 v[228:231], v157 offset:20480
	ds_read_b128 v[232:235], v157 offset:21504
	ds_read_b128 v[236:239], v157 offset:22528
	ds_read_b128 v[240:243], v157 offset:23552
	s_waitcnt vmcnt(8)
	s_waitcnt lgkmcnt(0)
	s_barrier
	s_waitcnt lgkmcnt(0)
	v_mfma_f32_16x16x32_bf16 v[60:63], v[128:131], v[210:213], 0
	v_mfma_f32_16x16x32_bf16 v[56:59], v[162:165], v[210:213], 0
	v_mfma_f32_16x16x32_bf16 v[44:47], v[128:131], v[220:223], 0
	v_mfma_f32_16x16x32_bf16 v[40:43], v[162:165], v[220:223], 0
	v_mfma_f32_16x16x32_bf16 v[28:31], v[128:131], v[228:231], 0
	v_mfma_f32_16x16x32_bf16 v[24:27], v[162:165], v[228:231], 0
	v_mfma_f32_16x16x32_bf16 v[12:15], v[128:131], v[236:239], 0
	v_mfma_f32_16x16x32_bf16 v[8:11], v[162:165], v[236:239], 0
	v_mfma_f32_16x16x32_bf16 v[60:63], v[158:161], v[214:217], v[60:63]
	v_mfma_f32_16x16x32_bf16 v[56:59], v[166:169], v[214:217], v[56:59]
	v_mfma_f32_16x16x32_bf16 v[44:47], v[158:161], v[224:227], v[44:47]
	v_mfma_f32_16x16x32_bf16 v[40:43], v[166:169], v[224:227], v[40:43]
	v_mfma_f32_16x16x32_bf16 v[28:31], v[158:161], v[232:235], v[28:31]
	v_mfma_f32_16x16x32_bf16 v[24:27], v[166:169], v[232:235], v[24:27]
	v_mfma_f32_16x16x32_bf16 v[12:15], v[158:161], v[240:243], v[12:15]
	v_mfma_f32_16x16x32_bf16 v[8:11], v[166:169], v[240:243], v[8:11]
	v_mfma_f32_16x16x32_bf16 v[52:55], v[170:173], v[210:213], 0
	v_mfma_f32_16x16x32_bf16 v[48:51], v[194:197], v[210:213], 0
	v_mfma_f32_16x16x32_bf16 v[36:39], v[170:173], v[220:223], 0
	v_mfma_f32_16x16x32_bf16 v[32:35], v[194:197], v[220:223], 0
	v_mfma_f32_16x16x32_bf16 v[20:23], v[170:173], v[228:231], 0
	v_mfma_f32_16x16x32_bf16 v[16:19], v[194:197], v[228:231], 0
	v_mfma_f32_16x16x32_bf16 v[4:7], v[170:173], v[236:239], 0
	v_mfma_f32_16x16x32_bf16 v[0:3], v[194:197], v[236:239], 0
	v_mfma_f32_16x16x32_bf16 v[52:55], v[174:177], v[214:217], v[52:55]
	v_mfma_f32_16x16x32_bf16 v[48:51], v[206:209], v[214:217], v[48:51]
	v_mfma_f32_16x16x32_bf16 v[36:39], v[174:177], v[224:227], v[36:39]
	v_mfma_f32_16x16x32_bf16 v[32:35], v[206:209], v[224:227], v[32:35]
	v_mfma_f32_16x16x32_bf16 v[20:23], v[174:177], v[232:235], v[20:23]
	v_mfma_f32_16x16x32_bf16 v[16:19], v[206:209], v[232:235], v[16:19]
	v_mfma_f32_16x16x32_bf16 v[4:7], v[174:177], v[240:243], v[4:7]
	v_mfma_f32_16x16x32_bf16 v[0:3], v[206:209], v[240:243], v[0:3]
	s_barrier
	s_add_i32 s45, 0, 0x18000
	s_add_i32 s46, 0, 0x1c000
	s_add_u32 s16, s16, s24
	s_addc_u32 s17, s17, s25
	s_mov_b32 m0, s19
	v_lshl_add_u64 v[202:203], s[16:17], 0, v[132:133]
	global_load_lds_dwordx4 v[202:203], off
	v_lshl_add_u64 v[202:203], s[16:17], 0, v[136:137]
	s_mov_b32 m0, s33
	s_nop 0
	global_load_lds_dwordx4 v[202:203], off
	v_add_u32_e32 v152, s45, v153
	ds_read_b128 v[128:131], v152
	ds_read_b128 v[158:161], v152 offset:1024
	ds_read_b128 v[162:165], v152 offset:2048
	ds_read_b128 v[166:169], v152 offset:3072
	v_add_u32_e32 v152, s46, v153
	ds_read_b128 v[170:173], v152
	ds_read_b128 v[174:177], v152 offset:1024
	ds_read_b128 v[194:197], v152 offset:2048
	ds_read_b128 v[206:209], v152 offset:3072
	ds_read_b128 v[210:213], v157 offset:32768
	ds_read_b128 v[214:217], v157 offset:33792
	ds_read_b128 v[220:223], v157 offset:34816
	ds_read_b128 v[224:227], v157 offset:35840
	ds_read_b128 v[228:231], v157 offset:36864
	ds_read_b128 v[232:235], v157 offset:37888
	ds_read_b128 v[236:239], v157 offset:38912
	ds_read_b128 v[240:243], v157 offset:39936
	s_waitcnt vmcnt(8)
	s_waitcnt lgkmcnt(0)
	s_barrier
	s_waitcnt lgkmcnt(0)
	v_mfma_f32_16x16x32_bf16 v[124:127], v[128:131], v[210:213], v[124:127]
	v_mfma_f32_16x16x32_bf16 v[120:123], v[162:165], v[210:213], v[120:123]
	v_mfma_f32_16x16x32_bf16 v[108:111], v[128:131], v[220:223], v[108:111]
	v_mfma_f32_16x16x32_bf16 v[104:107], v[162:165], v[220:223], v[104:107]
	v_mfma_f32_16x16x32_bf16 v[92:95], v[128:131], v[228:231], v[92:95]
	v_mfma_f32_16x16x32_bf16 v[88:91], v[162:165], v[228:231], v[88:91]
	v_mfma_f32_16x16x32_bf16 v[76:79], v[128:131], v[236:239], v[76:79]
	v_mfma_f32_16x16x32_bf16 v[72:75], v[162:165], v[236:239], v[72:75]
	v_mfma_f32_16x16x32_bf16 v[124:127], v[158:161], v[214:217], v[124:127]
	v_mfma_f32_16x16x32_bf16 v[120:123], v[166:169], v[214:217], v[120:123]
	v_mfma_f32_16x16x32_bf16 v[108:111], v[158:161], v[224:227], v[108:111]
	v_mfma_f32_16x16x32_bf16 v[104:107], v[166:169], v[224:227], v[104:107]
	v_mfma_f32_16x16x32_bf16 v[92:95], v[158:161], v[232:235], v[92:95]
	v_mfma_f32_16x16x32_bf16 v[88:91], v[166:169], v[232:235], v[88:91]
	v_mfma_f32_16x16x32_bf16 v[76:79], v[158:161], v[240:243], v[76:79]
	v_mfma_f32_16x16x32_bf16 v[72:75], v[166:169], v[240:243], v[72:75]
	v_mfma_f32_16x16x32_bf16 v[116:119], v[170:173], v[210:213], v[116:119]
	v_mfma_f32_16x16x32_bf16 v[112:115], v[194:197], v[210:213], v[112:115]
	v_mfma_f32_16x16x32_bf16 v[100:103], v[170:173], v[220:223], v[100:103]
	v_mfma_f32_16x16x32_bf16 v[96:99], v[194:197], v[220:223], v[96:99]
	v_mfma_f32_16x16x32_bf16 v[84:87], v[170:173], v[228:231], v[84:87]
	v_mfma_f32_16x16x32_bf16 v[80:83], v[194:197], v[228:231], v[80:83]
	v_mfma_f32_16x16x32_bf16 v[68:71], v[170:173], v[236:239], v[68:71]
	v_mfma_f32_16x16x32_bf16 v[64:67], v[194:197], v[236:239], v[64:67]
	v_mfma_f32_16x16x32_bf16 v[116:119], v[174:177], v[214:217], v[116:119]
	v_mfma_f32_16x16x32_bf16 v[112:115], v[206:209], v[214:217], v[112:115]
	v_mfma_f32_16x16x32_bf16 v[100:103], v[174:177], v[224:227], v[100:103]
	v_mfma_f32_16x16x32_bf16 v[96:99], v[206:209], v[224:227], v[96:99]
	v_mfma_f32_16x16x32_bf16 v[84:87], v[174:177], v[232:235], v[84:87]
	v_mfma_f32_16x16x32_bf16 v[80:83], v[206:209], v[232:235], v[80:83]
	v_mfma_f32_16x16x32_bf16 v[68:71], v[174:177], v[240:243], v[68:71]
	v_mfma_f32_16x16x32_bf16 v[64:67], v[206:209], v[240:243], v[64:67]
	s_barrier
	s_add_i32 s16, s45, s4
	v_lshl_add_u64 v[178:179], v[178:179], 0, s[12:13]
	s_mov_b32 m0, s16
	global_load_lds_dwordx4 v[178:179], off
	v_lshl_add_u64 v[178:179], v[198:199], 0, s[12:13]
	s_add_i32 m0, s16, 0x2000
	s_add_i32 s16, s46, s4
	global_load_lds_dwordx4 v[178:179], off
	v_lshl_add_u64 v[178:179], v[244:245], 0, s[12:13]
	s_mov_b32 m0, s16
	s_nop 0
	global_load_lds_dwordx4 v[178:179], off
	v_lshl_add_u64 v[178:179], v[246:247], 0, s[12:13]
	s_add_i32 m0, s16, 0x2000
	s_nop 0
	global_load_lds_dwordx4 v[178:179], off
	v_lshl_add_u64 v[178:179], v[248:249], 0, s[12:13]
	s_mov_b32 m0, s59
	s_nop 0
	global_load_lds_dwordx4 v[178:179], off
	v_lshl_add_u64 v[178:179], v[250:251], 0, s[12:13]
	s_mov_b32 m0, s60
	s_nop 0
	global_load_lds_dwordx4 v[178:179], off
	ds_read_b128 v[210:213], v157 offset:49152
	ds_read_b128 v[214:217], v157 offset:50176
	ds_read_b128 v[220:223], v157 offset:51200
	ds_read_b128 v[224:227], v157 offset:52224
	ds_read_b128 v[228:231], v157 offset:53248
	ds_read_b128 v[232:235], v157 offset:54272
	ds_read_b128 v[236:239], v157 offset:55296
	ds_read_b128 v[240:243], v157 offset:56320
	s_waitcnt vmcnt(8)
	s_waitcnt lgkmcnt(0)
	s_barrier
	s_waitcnt lgkmcnt(0)
	v_mfma_f32_16x16x32_bf16 v[60:63], v[128:131], v[210:213], v[60:63]
	s_add_u32 s0, s0, 0x100
	v_mfma_f32_16x16x32_bf16 v[56:59], v[162:165], v[210:213], v[56:59]
	s_addc_u32 s1, s1, 0
	v_mfma_f32_16x16x32_bf16 v[44:47], v[128:131], v[220:223], v[44:47]
	s_add_u32 s38, s38, 0x100
	v_mfma_f32_16x16x32_bf16 v[40:43], v[162:165], v[220:223], v[40:43]
	s_addc_u32 s39, s39, 0
	v_mfma_f32_16x16x32_bf16 v[28:31], v[128:131], v[228:231], v[28:31]
	s_mov_b32 s16, s44
	v_mfma_f32_16x16x32_bf16 v[24:27], v[162:165], v[228:231], v[24:27]
	s_cmp_ge_i32 s44, s68
	v_mfma_f32_16x16x32_bf16 v[12:15], v[128:131], v[236:239], v[12:15]
	s_cselect_b32 s99, 1, 0
	v_mfma_f32_16x16x32_bf16 v[8:11], v[162:165], v[236:239], v[8:11]
	s_add_i32 s44, s16, 2
	v_mfma_f32_16x16x32_bf16 v[60:63], v[158:161], v[214:217], v[60:63]
	s_add_u32 s45, s0, 0x80
	v_mfma_f32_16x16x32_bf16 v[56:59], v[166:169], v[214:217], v[56:59]
	s_addc_u32 s17, s1, 0
	v_mfma_f32_16x16x32_bf16 v[44:47], v[158:161], v[224:227], v[44:47]
	s_add_i32 s64, 0, 0x10000
	v_mfma_f32_16x16x32_bf16 v[40:43], v[166:169], v[224:227], v[40:43]
	s_cmp_eq_u32 s63, s16
	v_mfma_f32_16x16x32_bf16 v[28:31], v[158:161], v[232:235], v[28:31]
	s_cselect_b32 s17, s57, s17
	v_mfma_f32_16x16x32_bf16 v[24:27], v[166:169], v[232:235], v[24:27]
	s_cselect_b32 s16, s56, s45
	v_mfma_f32_16x16x32_bf16 v[12:15], v[158:161], v[240:243], v[12:15]
	s_cselect_b32 s47, s9, s39
	v_mfma_f32_16x16x32_bf16 v[8:11], v[166:169], v[240:243], v[8:11]
	s_cselect_b32 s46, s8, s38
	v_mfma_f32_16x16x32_bf16 v[52:55], v[170:173], v[210:213], v[52:55]
	s_add_i32 s45, 0, 0x14000
	v_mfma_f32_16x16x32_bf16 v[48:51], v[194:197], v[210:213], v[48:51]
	v_mfma_f32_16x16x32_bf16 v[36:39], v[170:173], v[220:223], v[36:39]
	v_mfma_f32_16x16x32_bf16 v[32:35], v[194:197], v[220:223], v[32:35]
	v_mfma_f32_16x16x32_bf16 v[20:23], v[170:173], v[228:231], v[20:23]
	v_mfma_f32_16x16x32_bf16 v[16:19], v[194:197], v[228:231], v[16:19]
	v_mfma_f32_16x16x32_bf16 v[4:7], v[170:173], v[236:239], v[4:7]
	v_mfma_f32_16x16x32_bf16 v[0:3], v[194:197], v[236:239], v[0:3]
	v_mfma_f32_16x16x32_bf16 v[52:55], v[174:177], v[214:217], v[52:55]
	v_mfma_f32_16x16x32_bf16 v[48:51], v[206:209], v[214:217], v[48:51]
	v_mfma_f32_16x16x32_bf16 v[36:39], v[174:177], v[224:227], v[36:39]
	v_mfma_f32_16x16x32_bf16 v[32:35], v[206:209], v[224:227], v[32:35]
	v_mfma_f32_16x16x32_bf16 v[20:23], v[174:177], v[232:235], v[20:23]
	v_mfma_f32_16x16x32_bf16 v[16:19], v[206:209], v[232:235], v[16:19]
	v_mfma_f32_16x16x32_bf16 v[4:7], v[174:177], v[240:243], v[4:7]
	v_mfma_f32_16x16x32_bf16 v[0:3], v[206:209], v[240:243], v[0:3]
	s_barrier
	s_cmp_lg_u32 s99, 0
	s_cbranch_scc1 .Lpeelx_9
.LBB0_576:
	v_lshl_add_u64 v[178:179], s[0:1], 0, v[148:149]
	s_add_i32 m0, s52, 0xc000
	global_load_lds_dwordx4 v[178:179], off
	v_lshl_add_u64 v[178:179], s[0:1], 0, v[150:151]
	s_add_i32 m0, s52, 0xe000
	s_nop 0
	global_load_lds_dwordx4 v[178:179], off
	v_add_u32_e32 v152, s64, v153
	ds_read_b128 v[128:131], v152
	ds_read_b128 v[158:161], v152 offset:1024
	ds_read_b128 v[162:165], v152 offset:2048
	ds_read_b128 v[166:169], v152 offset:3072
	v_add_u32_e32 v152, s45, v153
	ds_read_b128 v[170:173], v152
	ds_read_b128 v[174:177], v152 offset:1024
	ds_read_b128 v[194:197], v152 offset:2048
	ds_read_b128 v[206:209], v152 offset:3072
	ds_read_b128 v[210:213], v157
	ds_read_b128 v[214:217], v157 offset:1024
	ds_read_b128 v[220:223], v157 offset:2048
	ds_read_b128 v[224:227], v157 offset:3072
	ds_read_b128 v[228:231], v157 offset:4096
	ds_read_b128 v[232:235], v157 offset:5120
	ds_read_b128 v[236:239], v157 offset:6144
	ds_read_b128 v[240:243], v157 offset:7168
	s_waitcnt vmcnt(8)
	s_waitcnt lgkmcnt(0)
	s_barrier
	s_waitcnt lgkmcnt(0)
	v_mfma_f32_16x16x32_bf16 v[124:127], v[128:131], v[210:213], v[124:127]
	v_mfma_f32_16x16x32_bf16 v[120:123], v[162:165], v[210:213], v[120:123]
	v_mfma_f32_16x16x32_bf16 v[108:111], v[128:131], v[220:223], v[108:111]
	v_mfma_f32_16x16x32_bf16 v[104:107], v[162:165], v[220:223], v[104:107]
	v_mfma_f32_16x16x32_bf16 v[92:95], v[128:131], v[228:231], v[92:95]
	v_mfma_f32_16x16x32_bf16 v[88:91], v[162:165], v[228:231], v[88:91]
	v_mfma_f32_16x16x32_bf16 v[76:79], v[128:131], v[236:239], v[76:79]
	v_mfma_f32_16x16x32_bf16 v[72:75], v[162:165], v[236:239], v[72:75]
	v_mfma_f32_16x16x32_bf16 v[124:127], v[158:161], v[214:217], v[124:127]
	v_mfma_f32_16x16x32_bf16 v[120:123], v[166:169], v[214:217], v[120:123]
	v_mfma_f32_16x16x32_bf16 v[108:111], v[158:161], v[224:227], v[108:111]
	v_mfma_f32_16x16x32_bf16 v[104:107], v[166:169], v[224:227], v[104:107]
	v_mfma_f32_16x16x32_bf16 v[92:95], v[158:161], v[232:235], v[92:95]
	v_mfma_f32_16x16x32_bf16 v[88:91], v[166:169], v[232:235], v[88:91]
	v_mfma_f32_16x16x32_bf16 v[76:79], v[158:161], v[240:243], v[76:79]
	v_mfma_f32_16x16x32_bf16 v[72:75], v[166:169], v[240:243], v[72:75]
	v_mfma_f32_16x16x32_bf16 v[116:119], v[170:173], v[210:213], v[116:119]
	v_mfma_f32_16x16x32_bf16 v[112:115], v[194:197], v[210:213], v[112:115]
	v_mfma_f32_16x16x32_bf16 v[100:103], v[170:173], v[220:223], v[100:103]
	v_mfma_f32_16x16x32_bf16 v[96:99], v[194:197], v[220:223], v[96:99]
	v_mfma_f32_16x16x32_bf16 v[84:87], v[170:173], v[228:231], v[84:87]
	v_mfma_f32_16x16x32_bf16 v[80:83], v[194:197], v[228:231], v[80:83]
	v_mfma_f32_16x16x32_bf16 v[68:71], v[170:173], v[236:239], v[68:71]
	v_mfma_f32_16x16x32_bf16 v[64:67], v[194:197], v[236:239], v[64:67]
	v_mfma_f32_16x16x32_bf16 v[116:119], v[174:177], v[214:217], v[116:119]
	v_mfma_f32_16x16x32_bf16 v[112:115], v[206:209], v[214:217], v[112:115]
	v_mfma_f32_16x16x32_bf16 v[100:103], v[174:177], v[224:227], v[100:103]
	v_mfma_f32_16x16x32_bf16 v[96:99], v[206:209], v[224:227], v[96:99]
	v_mfma_f32_16x16x32_bf16 v[84:87], v[174:177], v[232:235], v[84:87]
	v_mfma_f32_16x16x32_bf16 v[80:83], v[206:209], v[232:235], v[80:83]
	v_mfma_f32_16x16x32_bf16 v[68:71], v[174:177], v[240:243], v[68:71]
	v_mfma_f32_16x16x32_bf16 v[64:67], v[206:209], v[240:243], v[64:67]
	s_barrier
	s_add_i32 s64, s64, s4
	v_lshl_add_u64 v[178:179], s[46:47], 0, v[134:135]
	s_mov_b32 m0, s64
	global_load_lds_dwordx4 v[178:179], off
	s_add_i32 m0, s64, 0x2000
	v_lshl_add_u64 v[198:199], s[46:47], 0, v[138:139]
	s_add_u32 s46, s46, s24
	s_addc_u32 s47, s47, s25
	s_add_i32 s45, s45, s4
	global_load_lds_dwordx4 v[198:199], off
	v_lshl_add_u64 v[244:245], s[46:47], 0, v[134:135]
	s_mov_b32 m0, s45
	v_lshl_add_u64 v[246:247], s[46:47], 0, v[138:139]
	global_load_lds_dwordx4 v[244:245], off
	s_add_i32 m0, s45, 0x2000
	v_lshl_add_u64 v[248:249], s[16:17], 0, v[132:133]
	global_load_lds_dwordx4 v[246:247], off
	s_mov_b32 m0, s52
	v_lshl_add_u64 v[250:251], s[16:17], 0, v[136:137]
	global_load_lds_dwordx4 v[248:249], off
	s_mov_b32 m0, s18
	s_nop 0
	global_load_lds_dwordx4 v[250:251], off
	ds_read_b128 v[210:213], v157 offset:16384
	ds_read_b128 v[214:217], v157 offset:17408
	ds_read_b128 v[220:223], v157 offset:18432
	ds_read_b128 v[224:227], v157 offset:19456
	ds_read_b128 v[228:231], v157 offset:20480
	ds_read_b128 v[232:235], v157 offset:21504
	ds_read_b128 v[236:239], v157 offset:22528
	ds_read_b128 v[240:243], v157 offset:23552
	s_waitcnt vmcnt(8)
	s_waitcnt lgkmcnt(0)
	s_barrier
	s_waitcnt lgkmcnt(0)
	v_mfma_f32_16x16x32_bf16 v[60:63], v[128:131], v[210:213], v[60:63]
	v_mfma_f32_16x16x32_bf16 v[56:59], v[162:165], v[210:213], v[56:59]
	v_mfma_f32_16x16x32_bf16 v[44:47], v[128:131], v[220:223], v[44:47]
	v_mfma_f32_16x16x32_bf16 v[40:43], v[162:165], v[220:223], v[40:43]
	v_mfma_f32_16x16x32_bf16 v[28:31], v[128:131], v[228:231], v[28:31]
	v_mfma_f32_16x16x32_bf16 v[24:27], v[162:165], v[228:231], v[24:27]
	v_mfma_f32_16x16x32_bf16 v[12:15], v[128:131], v[236:239], v[12:15]
	v_mfma_f32_16x16x32_bf16 v[8:11], v[162:165], v[236:239], v[8:11]
	v_mfma_f32_16x16x32_bf16 v[60:63], v[158:161], v[214:217], v[60:63]
	v_mfma_f32_16x16x32_bf16 v[56:59], v[166:169], v[214:217], v[56:59]
	v_mfma_f32_16x16x32_bf16 v[44:47], v[158:161], v[224:227], v[44:47]
	v_mfma_f32_16x16x32_bf16 v[40:43], v[166:169], v[224:227], v[40:43]
	v_mfma_f32_16x16x32_bf16 v[28:31], v[158:161], v[232:235], v[28:31]
	v_mfma_f32_16x16x32_bf16 v[24:27], v[166:169], v[232:235], v[24:27]
	v_mfma_f32_16x16x32_bf16 v[12:15], v[158:161], v[240:243], v[12:15]
	v_mfma_f32_16x16x32_bf16 v[8:11], v[166:169], v[240:243], v[8:11]
	v_mfma_f32_16x16x32_bf16 v[52:55], v[170:173], v[210:213], v[52:55]
	v_mfma_f32_16x16x32_bf16 v[48:51], v[194:197], v[210:213], v[48:51]
	v_mfma_f32_16x16x32_bf16 v[36:39], v[170:173], v[220:223], v[36:39]
	v_mfma_f32_16x16x32_bf16 v[32:35], v[194:197], v[220:223], v[32:35]
	v_mfma_f32_16x16x32_bf16 v[20:23], v[170:173], v[228:231], v[20:23]
	v_mfma_f32_16x16x32_bf16 v[16:19], v[194:197], v[228:231], v[16:19]
	v_mfma_f32_16x16x32_bf16 v[4:7], v[170:173], v[236:239], v[4:7]
	v_mfma_f32_16x16x32_bf16 v[0:3], v[194:197], v[236:239], v[0:3]
	v_mfma_f32_16x16x32_bf16 v[52:55], v[174:177], v[214:217], v[52:55]
	v_mfma_f32_16x16x32_bf16 v[48:51], v[206:209], v[214:217], v[48:51]
	v_mfma_f32_16x16x32_bf16 v[36:39], v[174:177], v[224:227], v[36:39]
	v_mfma_f32_16x16x32_bf16 v[32:35], v[206:209], v[224:227], v[32:35]
	v_mfma_f32_16x16x32_bf16 v[20:23], v[174:177], v[232:235], v[20:23]
	v_mfma_f32_16x16x32_bf16 v[16:19], v[206:209], v[232:235], v[16:19]
	v_mfma_f32_16x16x32_bf16 v[4:7], v[174:177], v[240:243], v[4:7]
	v_mfma_f32_16x16x32_bf16 v[0:3], v[206:209], v[240:243], v[0:3]
	s_barrier
	s_add_i32 s45, 0, 0x18000
	s_add_i32 s46, 0, 0x1c000
	s_add_u32 s16, s16, s24
	s_addc_u32 s17, s17, s25
	s_mov_b32 m0, s19
	v_lshl_add_u64 v[202:203], s[16:17], 0, v[132:133]
	global_load_lds_dwordx4 v[202:203], off
	v_lshl_add_u64 v[202:203], s[16:17], 0, v[136:137]
	s_mov_b32 m0, s33
	s_nop 0
	global_load_lds_dwordx4 v[202:203], off
	v_add_u32_e32 v152, s45, v153
	ds_read_b128 v[128:131], v152
	ds_read_b128 v[158:161], v152 offset:1024
	ds_read_b128 v[162:165], v152 offset:2048
	ds_read_b128 v[166:169], v152 offset:3072
	v_add_u32_e32 v152, s46, v153
	ds_read_b128 v[170:173], v152
	ds_read_b128 v[174:177], v152 offset:1024
	ds_read_b128 v[194:197], v152 offset:2048
	ds_read_b128 v[206:209], v152 offset:3072
	ds_read_b128 v[210:213], v157 offset:32768
	ds_read_b128 v[214:217], v157 offset:33792
	ds_read_b128 v[220:223], v157 offset:34816
	ds_read_b128 v[224:227], v157 offset:35840
	ds_read_b128 v[228:231], v157 offset:36864
	ds_read_b128 v[232:235], v157 offset:37888
	ds_read_b128 v[236:239], v157 offset:38912
	ds_read_b128 v[240:243], v157 offset:39936
	s_waitcnt vmcnt(8)
	s_waitcnt lgkmcnt(0)
	s_barrier
	s_waitcnt lgkmcnt(0)
	v_mfma_f32_16x16x32_bf16 v[124:127], v[128:131], v[210:213], v[124:127]
	v_mfma_f32_16x16x32_bf16 v[120:123], v[162:165], v[210:213], v[120:123]
	v_mfma_f32_16x16x32_bf16 v[108:111], v[128:131], v[220:223], v[108:111]
	v_mfma_f32_16x16x32_bf16 v[104:107], v[162:165], v[220:223], v[104:107]
	v_mfma_f32_16x16x32_bf16 v[92:95], v[128:131], v[228:231], v[92:95]
	v_mfma_f32_16x16x32_bf16 v[88:91], v[162:165], v[228:231], v[88:91]
	v_mfma_f32_16x16x32_bf16 v[76:79], v[128:131], v[236:239], v[76:79]
	v_mfma_f32_16x16x32_bf16 v[72:75], v[162:165], v[236:239], v[72:75]
	v_mfma_f32_16x16x32_bf16 v[124:127], v[158:161], v[214:217], v[124:127]
	v_mfma_f32_16x16x32_bf16 v[120:123], v[166:169], v[214:217], v[120:123]
	v_mfma_f32_16x16x32_bf16 v[108:111], v[158:161], v[224:227], v[108:111]
	v_mfma_f32_16x16x32_bf16 v[104:107], v[166:169], v[224:227], v[104:107]
	v_mfma_f32_16x16x32_bf16 v[92:95], v[158:161], v[232:235], v[92:95]
	v_mfma_f32_16x16x32_bf16 v[88:91], v[166:169], v[232:235], v[88:91]
	v_mfma_f32_16x16x32_bf16 v[76:79], v[158:161], v[240:243], v[76:79]
	v_mfma_f32_16x16x32_bf16 v[72:75], v[166:169], v[240:243], v[72:75]
	v_mfma_f32_16x16x32_bf16 v[116:119], v[170:173], v[210:213], v[116:119]
	v_mfma_f32_16x16x32_bf16 v[112:115], v[194:197], v[210:213], v[112:115]
	v_mfma_f32_16x16x32_bf16 v[100:103], v[170:173], v[220:223], v[100:103]
	v_mfma_f32_16x16x32_bf16 v[96:99], v[194:197], v[220:223], v[96:99]
	v_mfma_f32_16x16x32_bf16 v[84:87], v[170:173], v[228:231], v[84:87]
	v_mfma_f32_16x16x32_bf16 v[80:83], v[194:197], v[228:231], v[80:83]
	v_mfma_f32_16x16x32_bf16 v[68:71], v[170:173], v[236:239], v[68:71]
	v_mfma_f32_16x16x32_bf16 v[64:67], v[194:197], v[236:239], v[64:67]
	v_mfma_f32_16x16x32_bf16 v[116:119], v[174:177], v[214:217], v[116:119]
	v_mfma_f32_16x16x32_bf16 v[112:115], v[206:209], v[214:217], v[112:115]
	v_mfma_f32_16x16x32_bf16 v[100:103], v[174:177], v[224:227], v[100:103]
	v_mfma_f32_16x16x32_bf16 v[96:99], v[206:209], v[224:227], v[96:99]
	v_mfma_f32_16x16x32_bf16 v[84:87], v[174:177], v[232:235], v[84:87]
	v_mfma_f32_16x16x32_bf16 v[80:83], v[206:209], v[232:235], v[80:83]
	v_mfma_f32_16x16x32_bf16 v[68:71], v[174:177], v[240:243], v[68:71]
	v_mfma_f32_16x16x32_bf16 v[64:67], v[206:209], v[240:243], v[64:67]
	s_barrier
	s_add_i32 s16, s45, s4
	v_lshl_add_u64 v[178:179], v[178:179], 0, s[12:13]
	s_mov_b32 m0, s16
	global_load_lds_dwordx4 v[178:179], off
	v_lshl_add_u64 v[178:179], v[198:199], 0, s[12:13]
	s_add_i32 m0, s16, 0x2000
	s_add_i32 s16, s46, s4
	global_load_lds_dwordx4 v[178:179], off
	v_lshl_add_u64 v[178:179], v[244:245], 0, s[12:13]
	s_mov_b32 m0, s16
	s_nop 0
	global_load_lds_dwordx4 v[178:179], off
	v_lshl_add_u64 v[178:179], v[246:247], 0, s[12:13]
	s_add_i32 m0, s16, 0x2000
	s_nop 0
	global_load_lds_dwordx4 v[178:179], off
	v_lshl_add_u64 v[178:179], v[248:249], 0, s[12:13]
	s_mov_b32 m0, s59
	s_nop 0
	global_load_lds_dwordx4 v[178:179], off
	v_lshl_add_u64 v[178:179], v[250:251], 0, s[12:13]
	s_mov_b32 m0, s60
	s_nop 0
	global_load_lds_dwordx4 v[178:179], off
	ds_read_b128 v[210:213], v157 offset:49152
	ds_read_b128 v[214:217], v157 offset:50176
	ds_read_b128 v[220:223], v157 offset:51200
	ds_read_b128 v[224:227], v157 offset:52224
	ds_read_b128 v[228:231], v157 offset:53248
	ds_read_b128 v[232:235], v157 offset:54272
	ds_read_b128 v[236:239], v157 offset:55296
	ds_read_b128 v[240:243], v157 offset:56320
	s_waitcnt vmcnt(8)
	s_waitcnt lgkmcnt(0)
	s_barrier
	s_waitcnt lgkmcnt(0)
	v_mfma_f32_16x16x32_bf16 v[60:63], v[128:131], v[210:213], v[60:63]
	s_add_u32 s0, s0, 0x100
	v_mfma_f32_16x16x32_bf16 v[56:59], v[162:165], v[210:213], v[56:59]
	s_addc_u32 s1, s1, 0
	v_mfma_f32_16x16x32_bf16 v[44:47], v[128:131], v[220:223], v[44:47]
	s_add_u32 s38, s38, 0x100
	v_mfma_f32_16x16x32_bf16 v[40:43], v[162:165], v[220:223], v[40:43]
	s_addc_u32 s39, s39, 0
	v_mfma_f32_16x16x32_bf16 v[28:31], v[128:131], v[228:231], v[28:31]
	s_mov_b32 s16, s44
	v_mfma_f32_16x16x32_bf16 v[24:27], v[162:165], v[228:231], v[24:27]
	s_cmp_ge_i32 s44, s68
	v_mfma_f32_16x16x32_bf16 v[12:15], v[128:131], v[236:239], v[12:15]
	s_cselect_b32 s99, 1, 0
	v_mfma_f32_16x16x32_bf16 v[8:11], v[162:165], v[236:239], v[8:11]
	s_add_i32 s44, s16, 2
	v_mfma_f32_16x16x32_bf16 v[60:63], v[158:161], v[214:217], v[60:63]
	s_add_u32 s45, s0, 0x80
	v_mfma_f32_16x16x32_bf16 v[56:59], v[166:169], v[214:217], v[56:59]
	s_addc_u32 s17, s1, 0
	v_mfma_f32_16x16x32_bf16 v[44:47], v[158:161], v[224:227], v[44:47]
	s_add_i32 s64, 0, 0x10000
	v_mfma_f32_16x16x32_bf16 v[40:43], v[166:169], v[224:227], v[40:43]
	s_cmp_eq_u32 s63, s16
	v_mfma_f32_16x16x32_bf16 v[28:31], v[158:161], v[232:235], v[28:31]
	s_cselect_b32 s17, s57, s17
	v_mfma_f32_16x16x32_bf16 v[24:27], v[166:169], v[232:235], v[24:27]
	s_cselect_b32 s16, s56, s45
	v_mfma_f32_16x16x32_bf16 v[12:15], v[158:161], v[240:243], v[12:15]
	s_cselect_b32 s47, s9, s39
	v_mfma_f32_16x16x32_bf16 v[8:11], v[166:169], v[240:243], v[8:11]
	s_cselect_b32 s46, s8, s38
	v_mfma_f32_16x16x32_bf16 v[52:55], v[170:173], v[210:213], v[52:55]
	s_add_i32 s45, 0, 0x14000
	v_mfma_f32_16x16x32_bf16 v[48:51], v[194:197], v[210:213], v[48:51]
	v_mfma_f32_16x16x32_bf16 v[36:39], v[170:173], v[220:223], v[36:39]
	v_mfma_f32_16x16x32_bf16 v[32:35], v[194:197], v[220:223], v[32:35]
	v_mfma_f32_16x16x32_bf16 v[20:23], v[170:173], v[228:231], v[20:23]
	v_mfma_f32_16x16x32_bf16 v[16:19], v[194:197], v[228:231], v[16:19]
	v_mfma_f32_16x16x32_bf16 v[4:7], v[170:173], v[236:239], v[4:7]
	v_mfma_f32_16x16x32_bf16 v[0:3], v[194:197], v[236:239], v[0:3]
	v_mfma_f32_16x16x32_bf16 v[52:55], v[174:177], v[214:217], v[52:55]
	v_mfma_f32_16x16x32_bf16 v[48:51], v[206:209], v[214:217], v[48:51]
	v_mfma_f32_16x16x32_bf16 v[36:39], v[174:177], v[224:227], v[36:39]
	v_mfma_f32_16x16x32_bf16 v[32:35], v[206:209], v[224:227], v[32:35]
	v_mfma_f32_16x16x32_bf16 v[20:23], v[174:177], v[232:235], v[20:23]
	v_mfma_f32_16x16x32_bf16 v[16:19], v[206:209], v[232:235], v[16:19]
	v_mfma_f32_16x16x32_bf16 v[4:7], v[174:177], v[240:243], v[4:7]
	v_mfma_f32_16x16x32_bf16 v[0:3], v[206:209], v[240:243], v[0:3]
	s_barrier
	s_cmp_lg_u32 s99, 0
	s_cbranch_scc0 .LBB0_576

.Llbb_6:
	s_add_i32 s30, s16, 2
	s_add_u32 s31, s28, 0x80
	s_addc_u32 s17, s29, 0
	s_add_i32 s59, 0, 0x10000
	s_cmp_eq_u32 s48, s16
	s_cselect_b32 s17, s25, s17
	s_cselect_b32 s16, s24, s31
	s_cselect_b32 s43, s27, s11
	s_cselect_b32 s42, s26, s10
	s_add_i32 s31, 0, 0x14000
	v_lshl_add_u64 v[178:179], s[28:29], 0, v[136:137]
	s_add_i32 m0, s37, 0xc000
	global_load_lds_dwordx4 v[178:179], off
	v_lshl_add_u64 v[178:179], s[28:29], 0, v[138:139]
	s_add_i32 m0, s37, 0xe000
	s_nop 0
	global_load_lds_dwordx4 v[178:179], off
	v_add_u32_e32 v140, s59, v143
	ds_read_b128 v[146:149], v140
	ds_read_b128 v[150:153], v140 offset:1024
	ds_read_b128 v[154:157], v140 offset:2048
	ds_read_b128 v[158:161], v140 offset:3072
	v_add_u32_e32 v140, s31, v143
	ds_read_b128 v[162:165], v140
	ds_read_b128 v[166:169], v140 offset:1024
	ds_read_b128 v[170:173], v140 offset:2048
	ds_read_b128 v[174:177], v140 offset:3072
	ds_read_b128 v[194:197], v145
	ds_read_b128 v[206:209], v145 offset:1024
	ds_read_b128 v[210:213], v145 offset:2048
	ds_read_b128 v[214:217], v145 offset:3072
	ds_read_b128 v[220:223], v145 offset:4096
	ds_read_b128 v[224:227], v145 offset:5120
	ds_read_b128 v[228:231], v145 offset:6144
	ds_read_b128 v[232:235], v145 offset:7168
	s_waitcnt vmcnt(8)
	s_waitcnt lgkmcnt(0)
	s_barrier
	s_waitcnt lgkmcnt(0)
	v_mfma_f32_16x16x32_bf16 v[124:127], v[146:149], v[194:197], 0
	v_mfma_f32_16x16x32_bf16 v[120:123], v[154:157], v[194:197], 0
	v_mfma_f32_16x16x32_bf16 v[108:111], v[146:149], v[210:213], 0
	v_mfma_f32_16x16x32_bf16 v[104:107], v[154:157], v[210:213], 0
	v_mfma_f32_16x16x32_bf16 v[92:95], v[146:149], v[220:223], 0
	v_mfma_f32_16x16x32_bf16 v[88:91], v[154:157], v[220:223], 0
	v_mfma_f32_16x16x32_bf16 v[76:79], v[146:149], v[228:231], 0
	v_mfma_f32_16x16x32_bf16 v[72:75], v[154:157], v[228:231], 0
	v_mfma_f32_16x16x32_bf16 v[124:127], v[150:153], v[206:209], v[124:127]
	v_mfma_f32_16x16x32_bf16 v[120:123], v[158:161], v[206:209], v[120:123]
	v_mfma_f32_16x16x32_bf16 v[108:111], v[150:153], v[214:217], v[108:111]
	v_mfma_f32_16x16x32_bf16 v[104:107], v[158:161], v[214:217], v[104:107]
	v_mfma_f32_16x16x32_bf16 v[92:95], v[150:153], v[224:227], v[92:95]
	v_mfma_f32_16x16x32_bf16 v[88:91], v[158:161], v[224:227], v[88:91]
	v_mfma_f32_16x16x32_bf16 v[76:79], v[150:153], v[232:235], v[76:79]
	v_mfma_f32_16x16x32_bf16 v[72:75], v[158:161], v[232:235], v[72:75]
	v_mfma_f32_16x16x32_bf16 v[116:119], v[162:165], v[194:197], 0
	v_mfma_f32_16x16x32_bf16 v[112:115], v[170:173], v[194:197], 0
	v_mfma_f32_16x16x32_bf16 v[100:103], v[162:165], v[210:213], 0
	v_mfma_f32_16x16x32_bf16 v[96:99], v[170:173], v[210:213], 0
	v_mfma_f32_16x16x32_bf16 v[84:87], v[162:165], v[220:223], 0
	v_mfma_f32_16x16x32_bf16 v[80:83], v[170:173], v[220:223], 0
	v_mfma_f32_16x16x32_bf16 v[68:71], v[162:165], v[228:231], 0
	v_mfma_f32_16x16x32_bf16 v[64:67], v[170:173], v[228:231], 0
	v_mfma_f32_16x16x32_bf16 v[116:119], v[166:169], v[206:209], v[116:119]
	v_mfma_f32_16x16x32_bf16 v[112:115], v[174:177], v[206:209], v[112:115]
	v_mfma_f32_16x16x32_bf16 v[100:103], v[166:169], v[214:217], v[100:103]
	v_mfma_f32_16x16x32_bf16 v[96:99], v[174:177], v[214:217], v[96:99]
	v_mfma_f32_16x16x32_bf16 v[84:87], v[166:169], v[224:227], v[84:87]
	v_mfma_f32_16x16x32_bf16 v[80:83], v[174:177], v[224:227], v[80:83]
	v_mfma_f32_16x16x32_bf16 v[68:71], v[166:169], v[232:235], v[68:71]
	v_mfma_f32_16x16x32_bf16 v[64:67], v[174:177], v[232:235], v[64:67]
	s_barrier
	s_add_i32 s59, s59, s36
	v_lshl_add_u64 v[178:179], s[42:43], 0, v[132:133]
	s_mov_b32 m0, s59
	global_load_lds_dwordx4 v[178:179], off
	s_add_i32 m0, s59, 0x2000
	v_lshl_add_u64 v[198:199], s[42:43], 0, v[128:129]
	s_add_u32 s42, s42, s0
	s_addc_u32 s43, s43, s1
	s_add_i32 s31, s31, s36
	global_load_lds_dwordx4 v[198:199], off
	v_lshl_add_u64 v[202:203], s[42:43], 0, v[132:133]
	s_mov_b32 m0, s31
	v_lshl_add_u64 v[236:237], s[42:43], 0, v[128:129]
	global_load_lds_dwordx4 v[202:203], off
	s_add_i32 m0, s31, 0x2000
	v_lshl_add_u64 v[238:239], s[16:17], 0, v[134:135]
	global_load_lds_dwordx4 v[236:237], off
	s_mov_b32 m0, s37
	v_lshl_add_u64 v[240:241], s[16:17], 0, v[130:131]
	global_load_lds_dwordx4 v[238:239], off
	s_mov_b32 m0, s38
	s_nop 0
	global_load_lds_dwordx4 v[240:241], off
	ds_read_b128 v[194:197], v145 offset:16384
	ds_read_b128 v[206:209], v145 offset:17408
	ds_read_b128 v[210:213], v145 offset:18432
	ds_read_b128 v[214:217], v145 offset:19456
	ds_read_b128 v[220:223], v145 offset:20480
	ds_read_b128 v[224:227], v145 offset:21504
	ds_read_b128 v[228:231], v145 offset:22528
	ds_read_b128 v[232:235], v145 offset:23552
	s_waitcnt vmcnt(8)
	s_waitcnt lgkmcnt(0)
	s_barrier
	s_waitcnt lgkmcnt(0)
	v_mfma_f32_16x16x32_bf16 v[60:63], v[146:149], v[194:197], 0
	v_mfma_f32_16x16x32_bf16 v[56:59], v[154:157], v[194:197], 0
	v_mfma_f32_16x16x32_bf16 v[44:47], v[146:149], v[210:213], 0
	v_mfma_f32_16x16x32_bf16 v[40:43], v[154:157], v[210:213], 0
	v_mfma_f32_16x16x32_bf16 v[28:31], v[146:149], v[220:223], 0
	v_mfma_f32_16x16x32_bf16 v[24:27], v[154:157], v[220:223], 0
	v_mfma_f32_16x16x32_bf16 v[12:15], v[146:149], v[228:231], 0
	v_mfma_f32_16x16x32_bf16 v[8:11], v[154:157], v[228:231], 0
	v_mfma_f32_16x16x32_bf16 v[60:63], v[150:153], v[206:209], v[60:63]
	v_mfma_f32_16x16x32_bf16 v[56:59], v[158:161], v[206:209], v[56:59]
	v_mfma_f32_16x16x32_bf16 v[44:47], v[150:153], v[214:217], v[44:47]
	v_mfma_f32_16x16x32_bf16 v[40:43], v[158:161], v[214:217], v[40:43]
	v_mfma_f32_16x16x32_bf16 v[28:31], v[150:153], v[224:227], v[28:31]
	v_mfma_f32_16x16x32_bf16 v[24:27], v[158:161], v[224:227], v[24:27]
	v_mfma_f32_16x16x32_bf16 v[12:15], v[150:153], v[232:235], v[12:15]
	v_mfma_f32_16x16x32_bf16 v[8:11], v[158:161], v[232:235], v[8:11]
	v_mfma_f32_16x16x32_bf16 v[52:55], v[162:165], v[194:197], 0
	v_mfma_f32_16x16x32_bf16 v[48:51], v[170:173], v[194:197], 0
	v_mfma_f32_16x16x32_bf16 v[36:39], v[162:165], v[210:213], 0
	v_mfma_f32_16x16x32_bf16 v[32:35], v[170:173], v[210:213], 0
	v_mfma_f32_16x16x32_bf16 v[20:23], v[162:165], v[220:223], 0
	v_mfma_f32_16x16x32_bf16 v[16:19], v[170:173], v[220:223], 0
	v_mfma_f32_16x16x32_bf16 v[4:7], v[162:165], v[228:231], 0
	v_mfma_f32_16x16x32_bf16 v[0:3], v[170:173], v[228:231], 0
	v_mfma_f32_16x16x32_bf16 v[52:55], v[166:169], v[206:209], v[52:55]
	v_mfma_f32_16x16x32_bf16 v[48:51], v[174:177], v[206:209], v[48:51]
	v_mfma_f32_16x16x32_bf16 v[36:39], v[166:169], v[214:217], v[36:39]
	v_mfma_f32_16x16x32_bf16 v[32:35], v[174:177], v[214:217], v[32:35]
	v_mfma_f32_16x16x32_bf16 v[20:23], v[166:169], v[224:227], v[20:23]
	v_mfma_f32_16x16x32_bf16 v[16:19], v[174:177], v[224:227], v[16:19]
	v_mfma_f32_16x16x32_bf16 v[4:7], v[166:169], v[232:235], v[4:7]
	v_mfma_f32_16x16x32_bf16 v[0:3], v[174:177], v[232:235], v[0:3]
	s_barrier
	s_add_i32 s31, 0, 0x18000
	s_add_i32 s42, 0, 0x1c000
	s_add_u32 s16, s16, s0
	s_addc_u32 s17, s17, s1
	s_mov_b32 m0, s39
	v_lshl_add_u64 v[242:243], s[16:17], 0, v[134:135]
	global_load_lds_dwordx4 v[242:243], off
	v_lshl_add_u64 v[242:243], s[16:17], 0, v[130:131]
	s_mov_b32 m0, s44
	s_nop 0
	global_load_lds_dwordx4 v[242:243], off
	v_add_u32_e32 v140, s31, v143
	ds_read_b128 v[146:149], v140
	ds_read_b128 v[150:153], v140 offset:1024
	ds_read_b128 v[154:157], v140 offset:2048
	ds_read_b128 v[158:161], v140 offset:3072
	v_add_u32_e32 v140, s42, v143
	ds_read_b128 v[162:165], v140
	ds_read_b128 v[166:169], v140 offset:1024
	ds_read_b128 v[170:173], v140 offset:2048
	ds_read_b128 v[174:177], v140 offset:3072
	ds_read_b128 v[194:197], v145 offset:32768
	ds_read_b128 v[206:209], v145 offset:33792
	ds_read_b128 v[210:213], v145 offset:34816
	ds_read_b128 v[214:217], v145 offset:35840
	ds_read_b128 v[220:223], v145 offset:36864
	ds_read_b128 v[224:227], v145 offset:37888
	ds_read_b128 v[228:231], v145 offset:38912
	ds_read_b128 v[232:235], v145 offset:39936
	s_waitcnt vmcnt(8)
	s_waitcnt lgkmcnt(0)
	s_barrier
	s_waitcnt lgkmcnt(0)
	v_mfma_f32_16x16x32_bf16 v[124:127], v[146:149], v[194:197], v[124:127]
	v_mfma_f32_16x16x32_bf16 v[120:123], v[154:157], v[194:197], v[120:123]
	v_mfma_f32_16x16x32_bf16 v[108:111], v[146:149], v[210:213], v[108:111]
	v_mfma_f32_16x16x32_bf16 v[104:107], v[154:157], v[210:213], v[104:107]
	v_mfma_f32_16x16x32_bf16 v[92:95], v[146:149], v[220:223], v[92:95]
	v_mfma_f32_16x16x32_bf16 v[88:91], v[154:157], v[220:223], v[88:91]
	v_mfma_f32_16x16x32_bf16 v[76:79], v[146:149], v[228:231], v[76:79]
	v_mfma_f32_16x16x32_bf16 v[72:75], v[154:157], v[228:231], v[72:75]
	v_mfma_f32_16x16x32_bf16 v[124:127], v[150:153], v[206:209], v[124:127]
	v_mfma_f32_16x16x32_bf16 v[120:123], v[158:161], v[206:209], v[120:123]
	v_mfma_f32_16x16x32_bf16 v[108:111], v[150:153], v[214:217], v[108:111]
	v_mfma_f32_16x16x32_bf16 v[104:107], v[158:161], v[214:217], v[104:107]
	v_mfma_f32_16x16x32_bf16 v[92:95], v[150:153], v[224:227], v[92:95]
	v_mfma_f32_16x16x32_bf16 v[88:91], v[158:161], v[224:227], v[88:91]
	v_mfma_f32_16x16x32_bf16 v[76:79], v[150:153], v[232:235], v[76:79]
	v_mfma_f32_16x16x32_bf16 v[72:75], v[158:161], v[232:235], v[72:75]
	v_mfma_f32_16x16x32_bf16 v[116:119], v[162:165], v[194:197], v[116:119]
	v_mfma_f32_16x16x32_bf16 v[112:115], v[170:173], v[194:197], v[112:115]
	v_mfma_f32_16x16x32_bf16 v[100:103], v[162:165], v[210:213], v[100:103]
	v_mfma_f32_16x16x32_bf16 v[96:99], v[170:173], v[210:213], v[96:99]
	v_mfma_f32_16x16x32_bf16 v[84:87], v[162:165], v[220:223], v[84:87]
	v_mfma_f32_16x16x32_bf16 v[80:83], v[170:173], v[220:223], v[80:83]
	v_mfma_f32_16x16x32_bf16 v[68:71], v[162:165], v[228:231], v[68:71]
	v_mfma_f32_16x16x32_bf16 v[64:67], v[170:173], v[228:231], v[64:67]
	v_mfma_f32_16x16x32_bf16 v[116:119], v[166:169], v[206:209], v[116:119]
	v_mfma_f32_16x16x32_bf16 v[112:115], v[174:177], v[206:209], v[112:115]
	v_mfma_f32_16x16x32_bf16 v[100:103], v[166:169], v[214:217], v[100:103]
	v_mfma_f32_16x16x32_bf16 v[96:99], v[174:177], v[214:217], v[96:99]
	v_mfma_f32_16x16x32_bf16 v[84:87], v[166:169], v[224:227], v[84:87]
	v_mfma_f32_16x16x32_bf16 v[80:83], v[174:177], v[224:227], v[80:83]
	v_mfma_f32_16x16x32_bf16 v[68:71], v[166:169], v[232:235], v[68:71]
	v_mfma_f32_16x16x32_bf16 v[64:67], v[174:177], v[232:235], v[64:67]
	s_barrier
	s_add_i32 s16, s31, s36
	v_lshl_add_u64 v[178:179], v[178:179], 0, s[12:13]
	s_mov_b32 m0, s16
	global_load_lds_dwordx4 v[178:179], off
	v_lshl_add_u64 v[178:179], v[198:199], 0, s[12:13]
	s_add_i32 m0, s16, 0x2000
	s_add_i32 s16, s42, s36
	global_load_lds_dwordx4 v[178:179], off
	v_lshl_add_u64 v[178:179], v[202:203], 0, s[12:13]
	s_mov_b32 m0, s16
	s_nop 0
	global_load_lds_dwordx4 v[178:179], off
	v_lshl_add_u64 v[178:179], v[236:237], 0, s[12:13]
	s_add_i32 m0, s16, 0x2000
	s_nop 0
	global_load_lds_dwordx4 v[178:179], off
	v_lshl_add_u64 v[178:179], v[238:239], 0, s[12:13]
	s_mov_b32 m0, s45
	s_nop 0
	global_load_lds_dwordx4 v[178:179], off
	v_lshl_add_u64 v[178:179], v[240:241], 0, s[12:13]
	s_mov_b32 m0, s46
	s_nop 0
	global_load_lds_dwordx4 v[178:179], off
	ds_read_b128 v[194:197], v145 offset:49152
	ds_read_b128 v[206:209], v145 offset:50176
	ds_read_b128 v[210:213], v145 offset:51200
	ds_read_b128 v[214:217], v145 offset:52224
	ds_read_b128 v[220:223], v145 offset:53248
	ds_read_b128 v[224:227], v145 offset:54272
	ds_read_b128 v[228:231], v145 offset:55296
	ds_read_b128 v[232:235], v145 offset:56320
	s_waitcnt vmcnt(8)
	s_waitcnt lgkmcnt(0)
	s_barrier
	s_waitcnt lgkmcnt(0)
	v_mfma_f32_16x16x32_bf16 v[60:63], v[146:149], v[194:197], v[60:63]
	s_add_u32 s28, s28, 0x100
	v_mfma_f32_16x16x32_bf16 v[56:59], v[154:157], v[194:197], v[56:59]
	s_addc_u32 s29, s29, 0
	v_mfma_f32_16x16x32_bf16 v[44:47], v[146:149], v[210:213], v[44:47]
	s_add_u32 s10, s10, 0x100
	v_mfma_f32_16x16x32_bf16 v[40:43], v[154:157], v[210:213], v[40:43]
	s_addc_u32 s11, s11, 0
	v_mfma_f32_16x16x32_bf16 v[28:31], v[146:149], v[220:223], v[28:31]
	s_mov_b32 s16, s30
	v_mfma_f32_16x16x32_bf16 v[24:27], v[154:157], v[220:223], v[24:27]
	s_cmp_ge_i32 s30, s47
	v_mfma_f32_16x16x32_bf16 v[12:15], v[146:149], v[228:231], v[12:15]
	s_cselect_b32 s99, 1, 0
	v_mfma_f32_16x16x32_bf16 v[8:11], v[154:157], v[228:231], v[8:11]
	s_add_i32 s30, s16, 2
	v_mfma_f32_16x16x32_bf16 v[60:63], v[150:153], v[206:209], v[60:63]
	s_add_u32 s31, s28, 0x80
	v_mfma_f32_16x16x32_bf16 v[56:59], v[158:161], v[206:209], v[56:59]
	s_addc_u32 s17, s29, 0
	v_mfma_f32_16x16x32_bf16 v[44:47], v[150:153], v[214:217], v[44:47]
	s_add_i32 s59, 0, 0x10000
	v_mfma_f32_16x16x32_bf16 v[40:43], v[158:161], v[214:217], v[40:43]
	s_cmp_eq_u32 s48, s16
	v_mfma_f32_16x16x32_bf16 v[28:31], v[150:153], v[224:227], v[28:31]
	s_cselect_b32 s17, s25, s17
	v_mfma_f32_16x16x32_bf16 v[24:27], v[158:161], v[224:227], v[24:27]
	s_cselect_b32 s16, s24, s31
	v_mfma_f32_16x16x32_bf16 v[12:15], v[150:153], v[232:235], v[12:15]
	s_cselect_b32 s43, s27, s11
	v_mfma_f32_16x16x32_bf16 v[8:11], v[158:161], v[232:235], v[8:11]
	s_cselect_b32 s42, s26, s10
	v_mfma_f32_16x16x32_bf16 v[52:55], v[162:165], v[194:197], v[52:55]
	s_add_i32 s31, 0, 0x14000
	v_mfma_f32_16x16x32_bf16 v[48:51], v[170:173], v[194:197], v[48:51]
	v_mfma_f32_16x16x32_bf16 v[36:39], v[162:165], v[210:213], v[36:39]
	v_mfma_f32_16x16x32_bf16 v[32:35], v[170:173], v[210:213], v[32:35]
	v_mfma_f32_16x16x32_bf16 v[20:23], v[162:165], v[220:223], v[20:23]
	v_mfma_f32_16x16x32_bf16 v[16:19], v[170:173], v[220:223], v[16:19]
	v_mfma_f32_16x16x32_bf16 v[4:7], v[162:165], v[228:231], v[4:7]
	v_mfma_f32_16x16x32_bf16 v[0:3], v[170:173], v[228:231], v[0:3]
	v_mfma_f32_16x16x32_bf16 v[52:55], v[166:169], v[206:209], v[52:55]
	v_mfma_f32_16x16x32_bf16 v[48:51], v[174:177], v[206:209], v[48:51]
	v_mfma_f32_16x16x32_bf16 v[36:39], v[166:169], v[214:217], v[36:39]
	v_mfma_f32_16x16x32_bf16 v[32:35], v[174:177], v[214:217], v[32:35]
	v_mfma_f32_16x16x32_bf16 v[20:23], v[166:169], v[224:227], v[20:23]
	v_mfma_f32_16x16x32_bf16 v[16:19], v[174:177], v[224:227], v[16:19]
	v_mfma_f32_16x16x32_bf16 v[4:7], v[166:169], v[232:235], v[4:7]
	v_mfma_f32_16x16x32_bf16 v[0:3], v[174:177], v[232:235], v[0:3]
	s_barrier
	s_cmp_lg_u32 s99, 0
	s_cbranch_scc1 .Lpeelx_10
.LBB0_798:
	v_lshl_add_u64 v[178:179], s[28:29], 0, v[136:137]
	s_add_i32 m0, s37, 0xc000
	global_load_lds_dwordx4 v[178:179], off
	v_lshl_add_u64 v[178:179], s[28:29], 0, v[138:139]
	s_add_i32 m0, s37, 0xe000
	s_nop 0
	global_load_lds_dwordx4 v[178:179], off
	v_add_u32_e32 v140, s59, v143
	ds_read_b128 v[146:149], v140
	ds_read_b128 v[150:153], v140 offset:1024
	ds_read_b128 v[154:157], v140 offset:2048
	ds_read_b128 v[158:161], v140 offset:3072
	v_add_u32_e32 v140, s31, v143
	ds_read_b128 v[162:165], v140
	ds_read_b128 v[166:169], v140 offset:1024
	ds_read_b128 v[170:173], v140 offset:2048
	ds_read_b128 v[174:177], v140 offset:3072
	ds_read_b128 v[194:197], v145
	ds_read_b128 v[206:209], v145 offset:1024
	ds_read_b128 v[210:213], v145 offset:2048
	ds_read_b128 v[214:217], v145 offset:3072
	ds_read_b128 v[220:223], v145 offset:4096
	ds_read_b128 v[224:227], v145 offset:5120
	ds_read_b128 v[228:231], v145 offset:6144
	ds_read_b128 v[232:235], v145 offset:7168
	s_waitcnt vmcnt(8)
	s_waitcnt lgkmcnt(0)
	s_barrier
	s_waitcnt lgkmcnt(0)
	v_mfma_f32_16x16x32_bf16 v[124:127], v[146:149], v[194:197], v[124:127]
	v_mfma_f32_16x16x32_bf16 v[120:123], v[154:157], v[194:197], v[120:123]
	v_mfma_f32_16x16x32_bf16 v[108:111], v[146:149], v[210:213], v[108:111]
	v_mfma_f32_16x16x32_bf16 v[104:107], v[154:157], v[210:213], v[104:107]
	v_mfma_f32_16x16x32_bf16 v[92:95], v[146:149], v[220:223], v[92:95]
	v_mfma_f32_16x16x32_bf16 v[88:91], v[154:157], v[220:223], v[88:91]
	v_mfma_f32_16x16x32_bf16 v[76:79], v[146:149], v[228:231], v[76:79]
	v_mfma_f32_16x16x32_bf16 v[72:75], v[154:157], v[228:231], v[72:75]
	v_mfma_f32_16x16x32_bf16 v[124:127], v[150:153], v[206:209], v[124:127]
	v_mfma_f32_16x16x32_bf16 v[120:123], v[158:161], v[206:209], v[120:123]
	v_mfma_f32_16x16x32_bf16 v[108:111], v[150:153], v[214:217], v[108:111]
	v_mfma_f32_16x16x32_bf16 v[104:107], v[158:161], v[214:217], v[104:107]
	v_mfma_f32_16x16x32_bf16 v[92:95], v[150:153], v[224:227], v[92:95]
	v_mfma_f32_16x16x32_bf16 v[88:91], v[158:161], v[224:227], v[88:91]
	v_mfma_f32_16x16x32_bf16 v[76:79], v[150:153], v[232:235], v[76:79]
	v_mfma_f32_16x16x32_bf16 v[72:75], v[158:161], v[232:235], v[72:75]
	v_mfma_f32_16x16x32_bf16 v[116:119], v[162:165], v[194:197], v[116:119]
	v_mfma_f32_16x16x32_bf16 v[112:115], v[170:173], v[194:197], v[112:115]
	v_mfma_f32_16x16x32_bf16 v[100:103], v[162:165], v[210:213], v[100:103]
	v_mfma_f32_16x16x32_bf16 v[96:99], v[170:173], v[210:213], v[96:99]
	v_mfma_f32_16x16x32_bf16 v[84:87], v[162:165], v[220:223], v[84:87]
	v_mfma_f32_16x16x32_bf16 v[80:83], v[170:173], v[220:223], v[80:83]
	v_mfma_f32_16x16x32_bf16 v[68:71], v[162:165], v[228:231], v[68:71]
	v_mfma_f32_16x16x32_bf16 v[64:67], v[170:173], v[228:231], v[64:67]
	v_mfma_f32_16x16x32_bf16 v[116:119], v[166:169], v[206:209], v[116:119]
	v_mfma_f32_16x16x32_bf16 v[112:115], v[174:177], v[206:209], v[112:115]
	v_mfma_f32_16x16x32_bf16 v[100:103], v[166:169], v[214:217], v[100:103]
	v_mfma_f32_16x16x32_bf16 v[96:99], v[174:177], v[214:217], v[96:99]
	v_mfma_f32_16x16x32_bf16 v[84:87], v[166:169], v[224:227], v[84:87]
	v_mfma_f32_16x16x32_bf16 v[80:83], v[174:177], v[224:227], v[80:83]
	v_mfma_f32_16x16x32_bf16 v[68:71], v[166:169], v[232:235], v[68:71]
	v_mfma_f32_16x16x32_bf16 v[64:67], v[174:177], v[232:235], v[64:67]
	s_barrier
	s_add_i32 s59, s59, s36
	v_lshl_add_u64 v[178:179], s[42:43], 0, v[132:133]
	s_mov_b32 m0, s59
	global_load_lds_dwordx4 v[178:179], off
	s_add_i32 m0, s59, 0x2000
	v_lshl_add_u64 v[198:199], s[42:43], 0, v[128:129]
	s_add_u32 s42, s42, s0
	s_addc_u32 s43, s43, s1
	s_add_i32 s31, s31, s36
	global_load_lds_dwordx4 v[198:199], off
	v_lshl_add_u64 v[202:203], s[42:43], 0, v[132:133]
	s_mov_b32 m0, s31
	v_lshl_add_u64 v[236:237], s[42:43], 0, v[128:129]
	global_load_lds_dwordx4 v[202:203], off
	s_add_i32 m0, s31, 0x2000
	v_lshl_add_u64 v[238:239], s[16:17], 0, v[134:135]
	global_load_lds_dwordx4 v[236:237], off
	s_mov_b32 m0, s37
	v_lshl_add_u64 v[240:241], s[16:17], 0, v[130:131]
	global_load_lds_dwordx4 v[238:239], off
	s_mov_b32 m0, s38
	s_nop 0
	global_load_lds_dwordx4 v[240:241], off
	ds_read_b128 v[194:197], v145 offset:16384
	ds_read_b128 v[206:209], v145 offset:17408
	ds_read_b128 v[210:213], v145 offset:18432
	ds_read_b128 v[214:217], v145 offset:19456
	ds_read_b128 v[220:223], v145 offset:20480
	ds_read_b128 v[224:227], v145 offset:21504
	ds_read_b128 v[228:231], v145 offset:22528
	ds_read_b128 v[232:235], v145 offset:23552
	s_waitcnt vmcnt(8)
	s_waitcnt lgkmcnt(0)
	s_barrier
	s_waitcnt lgkmcnt(0)
	v_mfma_f32_16x16x32_bf16 v[60:63], v[146:149], v[194:197], v[60:63]
	v_mfma_f32_16x16x32_bf16 v[56:59], v[154:157], v[194:197], v[56:59]
	v_mfma_f32_16x16x32_bf16 v[44:47], v[146:149], v[210:213], v[44:47]
	v_mfma_f32_16x16x32_bf16 v[40:43], v[154:157], v[210:213], v[40:43]
	v_mfma_f32_16x16x32_bf16 v[28:31], v[146:149], v[220:223], v[28:31]
	v_mfma_f32_16x16x32_bf16 v[24:27], v[154:157], v[220:223], v[24:27]
	v_mfma_f32_16x16x32_bf16 v[12:15], v[146:149], v[228:231], v[12:15]
	v_mfma_f32_16x16x32_bf16 v[8:11], v[154:157], v[228:231], v[8:11]
	v_mfma_f32_16x16x32_bf16 v[60:63], v[150:153], v[206:209], v[60:63]
	v_mfma_f32_16x16x32_bf16 v[56:59], v[158:161], v[206:209], v[56:59]
	v_mfma_f32_16x16x32_bf16 v[44:47], v[150:153], v[214:217], v[44:47]
	v_mfma_f32_16x16x32_bf16 v[40:43], v[158:161], v[214:217], v[40:43]
	v_mfma_f32_16x16x32_bf16 v[28:31], v[150:153], v[224:227], v[28:31]
	v_mfma_f32_16x16x32_bf16 v[24:27], v[158:161], v[224:227], v[24:27]
	v_mfma_f32_16x16x32_bf16 v[12:15], v[150:153], v[232:235], v[12:15]
	v_mfma_f32_16x16x32_bf16 v[8:11], v[158:161], v[232:235], v[8:11]
	v_mfma_f32_16x16x32_bf16 v[52:55], v[162:165], v[194:197], v[52:55]
	v_mfma_f32_16x16x32_bf16 v[48:51], v[170:173], v[194:197], v[48:51]
	v_mfma_f32_16x16x32_bf16 v[36:39], v[162:165], v[210:213], v[36:39]
	v_mfma_f32_16x16x32_bf16 v[32:35], v[170:173], v[210:213], v[32:35]
	v_mfma_f32_16x16x32_bf16 v[20:23], v[162:165], v[220:223], v[20:23]
	v_mfma_f32_16x16x32_bf16 v[16:19], v[170:173], v[220:223], v[16:19]
	v_mfma_f32_16x16x32_bf16 v[4:7], v[162:165], v[228:231], v[4:7]
	v_mfma_f32_16x16x32_bf16 v[0:3], v[170:173], v[228:231], v[0:3]
	v_mfma_f32_16x16x32_bf16 v[52:55], v[166:169], v[206:209], v[52:55]
	v_mfma_f32_16x16x32_bf16 v[48:51], v[174:177], v[206:209], v[48:51]
	v_mfma_f32_16x16x32_bf16 v[36:39], v[166:169], v[214:217], v[36:39]
	v_mfma_f32_16x16x32_bf16 v[32:35], v[174:177], v[214:217], v[32:35]
	v_mfma_f32_16x16x32_bf16 v[20:23], v[166:169], v[224:227], v[20:23]
	v_mfma_f32_16x16x32_bf16 v[16:19], v[174:177], v[224:227], v[16:19]
	v_mfma_f32_16x16x32_bf16 v[4:7], v[166:169], v[232:235], v[4:7]
	v_mfma_f32_16x16x32_bf16 v[0:3], v[174:177], v[232:235], v[0:3]
	s_barrier
	s_add_i32 s31, 0, 0x18000
	s_add_i32 s42, 0, 0x1c000
	s_add_u32 s16, s16, s0
	s_addc_u32 s17, s17, s1
	s_mov_b32 m0, s39
	v_lshl_add_u64 v[242:243], s[16:17], 0, v[134:135]
	global_load_lds_dwordx4 v[242:243], off
	v_lshl_add_u64 v[242:243], s[16:17], 0, v[130:131]
	s_mov_b32 m0, s44
	s_nop 0
	global_load_lds_dwordx4 v[242:243], off
	v_add_u32_e32 v140, s31, v143
	ds_read_b128 v[146:149], v140
	ds_read_b128 v[150:153], v140 offset:1024
	ds_read_b128 v[154:157], v140 offset:2048
	ds_read_b128 v[158:161], v140 offset:3072
	v_add_u32_e32 v140, s42, v143
	ds_read_b128 v[162:165], v140
	ds_read_b128 v[166:169], v140 offset:1024
	ds_read_b128 v[170:173], v140 offset:2048
	ds_read_b128 v[174:177], v140 offset:3072
	ds_read_b128 v[194:197], v145 offset:32768
	ds_read_b128 v[206:209], v145 offset:33792
	ds_read_b128 v[210:213], v145 offset:34816
	ds_read_b128 v[214:217], v145 offset:35840
	ds_read_b128 v[220:223], v145 offset:36864
	ds_read_b128 v[224:227], v145 offset:37888
	ds_read_b128 v[228:231], v145 offset:38912
	ds_read_b128 v[232:235], v145 offset:39936
	s_waitcnt vmcnt(8)
	s_waitcnt lgkmcnt(0)
	s_barrier
	s_waitcnt lgkmcnt(0)
	v_mfma_f32_16x16x32_bf16 v[124:127], v[146:149], v[194:197], v[124:127]
	v_mfma_f32_16x16x32_bf16 v[120:123], v[154:157], v[194:197], v[120:123]
	v_mfma_f32_16x16x32_bf16 v[108:111], v[146:149], v[210:213], v[108:111]
	v_mfma_f32_16x16x32_bf16 v[104:107], v[154:157], v[210:213], v[104:107]
	v_mfma_f32_16x16x32_bf16 v[92:95], v[146:149], v[220:223], v[92:95]
	v_mfma_f32_16x16x32_bf16 v[88:91], v[154:157], v[220:223], v[88:91]
	v_mfma_f32_16x16x32_bf16 v[76:79], v[146:149], v[228:231], v[76:79]
	v_mfma_f32_16x16x32_bf16 v[72:75], v[154:157], v[228:231], v[72:75]
	v_mfma_f32_16x16x32_bf16 v[124:127], v[150:153], v[206:209], v[124:127]
	v_mfma_f32_16x16x32_bf16 v[120:123], v[158:161], v[206:209], v[120:123]
	v_mfma_f32_16x16x32_bf16 v[108:111], v[150:153], v[214:217], v[108:111]
	v_mfma_f32_16x16x32_bf16 v[104:107], v[158:161], v[214:217], v[104:107]
	v_mfma_f32_16x16x32_bf16 v[92:95], v[150:153], v[224:227], v[92:95]
	v_mfma_f32_16x16x32_bf16 v[88:91], v[158:161], v[224:227], v[88:91]
	v_mfma_f32_16x16x32_bf16 v[76:79], v[150:153], v[232:235], v[76:79]
	v_mfma_f32_16x16x32_bf16 v[72:75], v[158:161], v[232:235], v[72:75]
	v_mfma_f32_16x16x32_bf16 v[116:119], v[162:165], v[194:197], v[116:119]
	v_mfma_f32_16x16x32_bf16 v[112:115], v[170:173], v[194:197], v[112:115]
	v_mfma_f32_16x16x32_bf16 v[100:103], v[162:165], v[210:213], v[100:103]
	v_mfma_f32_16x16x32_bf16 v[96:99], v[170:173], v[210:213], v[96:99]
	v_mfma_f32_16x16x32_bf16 v[84:87], v[162:165], v[220:223], v[84:87]
	v_mfma_f32_16x16x32_bf16 v[80:83], v[170:173], v[220:223], v[80:83]
	v_mfma_f32_16x16x32_bf16 v[68:71], v[162:165], v[228:231], v[68:71]
	v_mfma_f32_16x16x32_bf16 v[64:67], v[170:173], v[228:231], v[64:67]
	v_mfma_f32_16x16x32_bf16 v[116:119], v[166:169], v[206:209], v[116:119]
	v_mfma_f32_16x16x32_bf16 v[112:115], v[174:177], v[206:209], v[112:115]
	v_mfma_f32_16x16x32_bf16 v[100:103], v[166:169], v[214:217], v[100:103]
	v_mfma_f32_16x16x32_bf16 v[96:99], v[174:177], v[214:217], v[96:99]
	v_mfma_f32_16x16x32_bf16 v[84:87], v[166:169], v[224:227], v[84:87]
	v_mfma_f32_16x16x32_bf16 v[80:83], v[174:177], v[224:227], v[80:83]
	v_mfma_f32_16x16x32_bf16 v[68:71], v[166:169], v[232:235], v[68:71]
	v_mfma_f32_16x16x32_bf16 v[64:67], v[174:177], v[232:235], v[64:67]
	s_barrier
	s_add_i32 s16, s31, s36
	v_lshl_add_u64 v[178:179], v[178:179], 0, s[12:13]
	s_mov_b32 m0, s16
	global_load_lds_dwordx4 v[178:179], off
	v_lshl_add_u64 v[178:179], v[198:199], 0, s[12:13]
	s_add_i32 m0, s16, 0x2000
	s_add_i32 s16, s42, s36
	global_load_lds_dwordx4 v[178:179], off
	v_lshl_add_u64 v[178:179], v[202:203], 0, s[12:13]
	s_mov_b32 m0, s16
	s_nop 0
	global_load_lds_dwordx4 v[178:179], off
	v_lshl_add_u64 v[178:179], v[236:237], 0, s[12:13]
	s_add_i32 m0, s16, 0x2000
	s_nop 0
	global_load_lds_dwordx4 v[178:179], off
	v_lshl_add_u64 v[178:179], v[238:239], 0, s[12:13]
	s_mov_b32 m0, s45
	s_nop 0
	global_load_lds_dwordx4 v[178:179], off
	v_lshl_add_u64 v[178:179], v[240:241], 0, s[12:13]
	s_mov_b32 m0, s46
	s_nop 0
	global_load_lds_dwordx4 v[178:179], off
	ds_read_b128 v[194:197], v145 offset:49152
	ds_read_b128 v[206:209], v145 offset:50176
	ds_read_b128 v[210:213], v145 offset:51200
	ds_read_b128 v[214:217], v145 offset:52224
	ds_read_b128 v[220:223], v145 offset:53248
	ds_read_b128 v[224:227], v145 offset:54272
	ds_read_b128 v[228:231], v145 offset:55296
	ds_read_b128 v[232:235], v145 offset:56320
	s_waitcnt vmcnt(8)
	s_waitcnt lgkmcnt(0)
	s_barrier
	s_waitcnt lgkmcnt(0)
	v_mfma_f32_16x16x32_bf16 v[60:63], v[146:149], v[194:197], v[60:63]
	s_add_u32 s28, s28, 0x100
	v_mfma_f32_16x16x32_bf16 v[56:59], v[154:157], v[194:197], v[56:59]
	s_addc_u32 s29, s29, 0
	v_mfma_f32_16x16x32_bf16 v[44:47], v[146:149], v[210:213], v[44:47]
	s_add_u32 s10, s10, 0x100
	v_mfma_f32_16x16x32_bf16 v[40:43], v[154:157], v[210:213], v[40:43]
	s_addc_u32 s11, s11, 0
	v_mfma_f32_16x16x32_bf16 v[28:31], v[146:149], v[220:223], v[28:31]
	s_mov_b32 s16, s30
	v_mfma_f32_16x16x32_bf16 v[24:27], v[154:157], v[220:223], v[24:27]
	s_cmp_ge_i32 s30, s47
	v_mfma_f32_16x16x32_bf16 v[12:15], v[146:149], v[228:231], v[12:15]
	s_cselect_b32 s99, 1, 0
	v_mfma_f32_16x16x32_bf16 v[8:11], v[154:157], v[228:231], v[8:11]
	s_add_i32 s30, s16, 2
	v_mfma_f32_16x16x32_bf16 v[60:63], v[150:153], v[206:209], v[60:63]
	s_add_u32 s31, s28, 0x80
	v_mfma_f32_16x16x32_bf16 v[56:59], v[158:161], v[206:209], v[56:59]
	s_addc_u32 s17, s29, 0
	v_mfma_f32_16x16x32_bf16 v[44:47], v[150:153], v[214:217], v[44:47]
	s_add_i32 s59, 0, 0x10000
	v_mfma_f32_16x16x32_bf16 v[40:43], v[158:161], v[214:217], v[40:43]
	s_cmp_eq_u32 s48, s16
	v_mfma_f32_16x16x32_bf16 v[28:31], v[150:153], v[224:227], v[28:31]
	s_cselect_b32 s17, s25, s17
	v_mfma_f32_16x16x32_bf16 v[24:27], v[158:161], v[224:227], v[24:27]
	s_cselect_b32 s16, s24, s31
	v_mfma_f32_16x16x32_bf16 v[12:15], v[150:153], v[232:235], v[12:15]
	s_cselect_b32 s43, s27, s11
	v_mfma_f32_16x16x32_bf16 v[8:11], v[158:161], v[232:235], v[8:11]
	s_cselect_b32 s42, s26, s10
	v_mfma_f32_16x16x32_bf16 v[52:55], v[162:165], v[194:197], v[52:55]
	s_add_i32 s31, 0, 0x14000
	v_mfma_f32_16x16x32_bf16 v[48:51], v[170:173], v[194:197], v[48:51]
	v_mfma_f32_16x16x32_bf16 v[36:39], v[162:165], v[210:213], v[36:39]
	v_mfma_f32_16x16x32_bf16 v[32:35], v[170:173], v[210:213], v[32:35]
	v_mfma_f32_16x16x32_bf16 v[20:23], v[162:165], v[220:223], v[20:23]
	v_mfma_f32_16x16x32_bf16 v[16:19], v[170:173], v[220:223], v[16:19]
	v_mfma_f32_16x16x32_bf16 v[4:7], v[162:165], v[228:231], v[4:7]
	v_mfma_f32_16x16x32_bf16 v[0:3], v[170:173], v[228:231], v[0:3]
	v_mfma_f32_16x16x32_bf16 v[52:55], v[166:169], v[206:209], v[52:55]
	v_mfma_f32_16x16x32_bf16 v[48:51], v[174:177], v[206:209], v[48:51]
	v_mfma_f32_16x16x32_bf16 v[36:39], v[166:169], v[214:217], v[36:39]
	v_mfma_f32_16x16x32_bf16 v[32:35], v[174:177], v[214:217], v[32:35]
	v_mfma_f32_16x16x32_bf16 v[20:23], v[166:169], v[224:227], v[20:23]
	v_mfma_f32_16x16x32_bf16 v[16:19], v[174:177], v[224:227], v[16:19]
	v_mfma_f32_16x16x32_bf16 v[4:7], v[166:169], v[232:235], v[4:7]
	v_mfma_f32_16x16x32_bf16 v[0:3], v[174:177], v[232:235], v[0:3]
	s_barrier
	s_cmp_lg_u32 s99, 0
	s_cbranch_scc0 .LBB0_798

.Llbb_7:
	s_add_i32 s28, s16, 2
	s_add_u32 s29, s26, 0x80
	s_addc_u32 s17, s27, 0
	s_add_i32 s59, 0, 0x10000
	s_cmp_eq_u32 s48, s16
	s_cselect_b32 s17, s23, s17
	s_cselect_b32 s16, s22, s29
	v_add_u32_e32 v140, s59, v143
	s_cselect_b32 s43, s25, s11
	s_cselect_b32 s42, s24, s10
	s_add_i32 s29, 0, 0x14000
	ds_read_b128 v[146:149], v140
	ds_read_b128 v[150:153], v140 offset:1024
	ds_read_b128 v[154:157], v140 offset:2048
	ds_read_b128 v[158:161], v140 offset:3072
	v_add_u32_e32 v140, s29, v143
	ds_read_b128 v[162:165], v140
	ds_read_b128 v[166:169], v140 offset:1024
	ds_read_b128 v[170:173], v140 offset:2048
	ds_read_b128 v[174:177], v140 offset:3072
	v_lshl_add_u64 v[140:141], s[26:27], 0, v[136:137]
	s_add_i32 m0, s35, 0xc000
	global_load_lds_dwordx4 v[140:141], off
	v_lshl_add_u64 v[140:141], s[26:27], 0, v[138:139]
	s_add_i32 m0, s35, 0xe000
	s_nop 0
	global_load_lds_dwordx4 v[140:141], off
	ds_read_b128 v[194:197], v145
	ds_read_b128 v[206:209], v145 offset:1024
	ds_read_b128 v[210:213], v145 offset:2048
	ds_read_b128 v[214:217], v145 offset:3072
	ds_read_b128 v[220:223], v145 offset:4096
	ds_read_b128 v[224:227], v145 offset:5120
	ds_read_b128 v[228:231], v145 offset:6144
	ds_read_b128 v[232:235], v145 offset:7168
	s_waitcnt vmcnt(8)
	s_waitcnt lgkmcnt(0)
	s_barrier
	s_waitcnt lgkmcnt(0)
	v_mfma_f32_16x16x32_bf16 v[120:123], v[146:149], v[194:197], 0
	v_mfma_f32_16x16x32_bf16 v[124:127], v[154:157], v[194:197], 0
	v_mfma_f32_16x16x32_bf16 v[116:119], v[146:149], v[210:213], 0
	v_mfma_f32_16x16x32_bf16 v[112:115], v[154:157], v[210:213], 0
	v_mfma_f32_16x16x32_bf16 v[108:111], v[146:149], v[220:223], 0
	v_mfma_f32_16x16x32_bf16 v[104:107], v[154:157], v[220:223], 0
	v_mfma_f32_16x16x32_bf16 v[100:103], v[146:149], v[228:231], 0
	v_mfma_f32_16x16x32_bf16 v[96:99], v[154:157], v[228:231], 0
	v_mfma_f32_16x16x32_bf16 v[120:123], v[150:153], v[206:209], v[120:123]
	v_mfma_f32_16x16x32_bf16 v[124:127], v[158:161], v[206:209], v[124:127]
	v_mfma_f32_16x16x32_bf16 v[116:119], v[150:153], v[214:217], v[116:119]
	v_mfma_f32_16x16x32_bf16 v[112:115], v[158:161], v[214:217], v[112:115]
	v_mfma_f32_16x16x32_bf16 v[108:111], v[150:153], v[224:227], v[108:111]
	v_mfma_f32_16x16x32_bf16 v[104:107], v[158:161], v[224:227], v[104:107]
	v_mfma_f32_16x16x32_bf16 v[100:103], v[150:153], v[232:235], v[100:103]
	v_mfma_f32_16x16x32_bf16 v[96:99], v[158:161], v[232:235], v[96:99]
	v_mfma_f32_16x16x32_bf16 v[60:63], v[162:165], v[194:197], 0
	v_mfma_f32_16x16x32_bf16 v[56:59], v[170:173], v[194:197], 0
	v_mfma_f32_16x16x32_bf16 v[52:55], v[162:165], v[210:213], 0
	v_mfma_f32_16x16x32_bf16 v[48:51], v[170:173], v[210:213], 0
	v_mfma_f32_16x16x32_bf16 v[44:47], v[162:165], v[220:223], 0
	v_mfma_f32_16x16x32_bf16 v[40:43], v[170:173], v[220:223], 0
	v_mfma_f32_16x16x32_bf16 v[36:39], v[162:165], v[228:231], 0
	v_mfma_f32_16x16x32_bf16 v[32:35], v[170:173], v[228:231], 0
	v_mfma_f32_16x16x32_bf16 v[60:63], v[166:169], v[206:209], v[60:63]
	v_mfma_f32_16x16x32_bf16 v[56:59], v[174:177], v[206:209], v[56:59]
	v_mfma_f32_16x16x32_bf16 v[52:55], v[166:169], v[214:217], v[52:55]
	v_mfma_f32_16x16x32_bf16 v[48:51], v[174:177], v[214:217], v[48:51]
	v_mfma_f32_16x16x32_bf16 v[44:47], v[166:169], v[224:227], v[44:47]
	v_mfma_f32_16x16x32_bf16 v[40:43], v[174:177], v[224:227], v[40:43]
	v_mfma_f32_16x16x32_bf16 v[36:39], v[166:169], v[232:235], v[36:39]
	v_mfma_f32_16x16x32_bf16 v[32:35], v[174:177], v[232:235], v[32:35]
	s_barrier
	s_add_i32 s59, s59, s34
	v_lshl_add_u64 v[140:141], s[42:43], 0, v[132:133]
	s_mov_b32 m0, s59
	global_load_lds_dwordx4 v[140:141], off
	s_add_i32 m0, s59, 0x2000
	v_lshl_add_u64 v[178:179], s[42:43], 0, v[128:129]
	s_add_u32 s42, s42, s0
	s_addc_u32 s43, s43, s1
	s_add_i32 s29, s29, s34
	global_load_lds_dwordx4 v[178:179], off
	v_lshl_add_u64 v[198:199], s[42:43], 0, v[132:133]
	s_mov_b32 m0, s29
	v_lshl_add_u64 v[202:203], s[42:43], 0, v[128:129]
	global_load_lds_dwordx4 v[198:199], off
	s_add_i32 m0, s29, 0x2000
	v_lshl_add_u64 v[236:237], s[16:17], 0, v[134:135]
	global_load_lds_dwordx4 v[202:203], off
	s_mov_b32 m0, s35
	v_lshl_add_u64 v[238:239], s[16:17], 0, v[130:131]
	global_load_lds_dwordx4 v[236:237], off
	s_mov_b32 m0, s36
	s_nop 0
	global_load_lds_dwordx4 v[238:239], off
	ds_read_b128 v[194:197], v145 offset:16384
	ds_read_b128 v[206:209], v145 offset:17408
	ds_read_b128 v[210:213], v145 offset:18432
	ds_read_b128 v[214:217], v145 offset:19456
	ds_read_b128 v[220:223], v145 offset:20480
	ds_read_b128 v[224:227], v145 offset:21504
	ds_read_b128 v[228:231], v145 offset:22528
	ds_read_b128 v[232:235], v145 offset:23552
	s_waitcnt vmcnt(8)
	s_waitcnt lgkmcnt(0)
	s_barrier
	s_waitcnt lgkmcnt(0)
	v_mfma_f32_16x16x32_bf16 v[92:95], v[146:149], v[194:197], 0
	v_mfma_f32_16x16x32_bf16 v[88:91], v[154:157], v[194:197], 0
	v_mfma_f32_16x16x32_bf16 v[84:87], v[146:149], v[210:213], 0
	v_mfma_f32_16x16x32_bf16 v[80:83], v[154:157], v[210:213], 0
	v_mfma_f32_16x16x32_bf16 v[76:79], v[146:149], v[220:223], 0
	v_mfma_f32_16x16x32_bf16 v[72:75], v[154:157], v[220:223], 0
	v_mfma_f32_16x16x32_bf16 v[68:71], v[146:149], v[228:231], 0
	v_mfma_f32_16x16x32_bf16 v[64:67], v[154:157], v[228:231], 0
	v_mfma_f32_16x16x32_bf16 v[92:95], v[150:153], v[206:209], v[92:95]
	v_mfma_f32_16x16x32_bf16 v[88:91], v[158:161], v[206:209], v[88:91]
	v_mfma_f32_16x16x32_bf16 v[84:87], v[150:153], v[214:217], v[84:87]
	v_mfma_f32_16x16x32_bf16 v[80:83], v[158:161], v[214:217], v[80:83]
	v_mfma_f32_16x16x32_bf16 v[76:79], v[150:153], v[224:227], v[76:79]
	v_mfma_f32_16x16x32_bf16 v[72:75], v[158:161], v[224:227], v[72:75]
	v_mfma_f32_16x16x32_bf16 v[68:71], v[150:153], v[232:235], v[68:71]
	v_mfma_f32_16x16x32_bf16 v[64:67], v[158:161], v[232:235], v[64:67]
	v_mfma_f32_16x16x32_bf16 v[28:31], v[162:165], v[194:197], 0
	v_mfma_f32_16x16x32_bf16 v[24:27], v[170:173], v[194:197], 0
	v_mfma_f32_16x16x32_bf16 v[20:23], v[162:165], v[210:213], 0
	v_mfma_f32_16x16x32_bf16 v[16:19], v[170:173], v[210:213], 0
	v_mfma_f32_16x16x32_bf16 v[12:15], v[162:165], v[220:223], 0
	v_mfma_f32_16x16x32_bf16 v[8:11], v[170:173], v[220:223], 0
	v_mfma_f32_16x16x32_bf16 v[4:7], v[162:165], v[228:231], 0
	v_mfma_f32_16x16x32_bf16 v[0:3], v[170:173], v[228:231], 0
	v_mfma_f32_16x16x32_bf16 v[28:31], v[166:169], v[206:209], v[28:31]
	v_mfma_f32_16x16x32_bf16 v[24:27], v[174:177], v[206:209], v[24:27]
	v_mfma_f32_16x16x32_bf16 v[20:23], v[166:169], v[214:217], v[20:23]
	v_mfma_f32_16x16x32_bf16 v[16:19], v[174:177], v[214:217], v[16:19]
	v_mfma_f32_16x16x32_bf16 v[12:15], v[166:169], v[224:227], v[12:15]
	v_mfma_f32_16x16x32_bf16 v[8:11], v[174:177], v[224:227], v[8:11]
	v_mfma_f32_16x16x32_bf16 v[4:7], v[166:169], v[232:235], v[4:7]
	v_mfma_f32_16x16x32_bf16 v[0:3], v[174:177], v[232:235], v[0:3]
	s_barrier
	s_add_i32 s29, 0, 0x18000
	s_add_i32 s42, 0, 0x1c000
	s_add_u32 s16, s16, s0
	s_addc_u32 s17, s17, s1
	s_mov_b32 m0, s37
	v_lshl_add_u64 v[240:241], s[16:17], 0, v[134:135]
	global_load_lds_dwordx4 v[240:241], off
	v_lshl_add_u64 v[240:241], s[16:17], 0, v[130:131]
	s_mov_b32 m0, s38
	s_nop 0
	global_load_lds_dwordx4 v[240:241], off
	v_add_u32_e32 v158, s29, v143
	v_add_u32_e32 v174, s42, v143
	ds_read_b128 v[146:149], v158
	ds_read_b128 v[150:153], v158 offset:1024
	ds_read_b128 v[154:157], v158 offset:2048
	ds_read_b128 v[158:161], v158 offset:3072
	ds_read_b128 v[162:165], v174
	ds_read_b128 v[166:169], v174 offset:1024
	ds_read_b128 v[170:173], v174 offset:2048
	ds_read_b128 v[174:177], v174 offset:3072
	ds_read_b128 v[194:197], v145 offset:32768
	ds_read_b128 v[206:209], v145 offset:33792
	ds_read_b128 v[210:213], v145 offset:34816
	ds_read_b128 v[214:217], v145 offset:35840
	ds_read_b128 v[220:223], v145 offset:36864
	ds_read_b128 v[224:227], v145 offset:37888
	ds_read_b128 v[228:231], v145 offset:38912
	ds_read_b128 v[232:235], v145 offset:39936
	s_waitcnt vmcnt(8)
	s_waitcnt lgkmcnt(0)
	s_barrier
	s_waitcnt lgkmcnt(0)
	v_mfma_f32_16x16x32_bf16 v[120:123], v[146:149], v[194:197], v[120:123]
	v_mfma_f32_16x16x32_bf16 v[124:127], v[154:157], v[194:197], v[124:127]
	v_mfma_f32_16x16x32_bf16 v[116:119], v[146:149], v[210:213], v[116:119]
	v_mfma_f32_16x16x32_bf16 v[112:115], v[154:157], v[210:213], v[112:115]
	v_mfma_f32_16x16x32_bf16 v[108:111], v[146:149], v[220:223], v[108:111]
	v_mfma_f32_16x16x32_bf16 v[104:107], v[154:157], v[220:223], v[104:107]
	v_mfma_f32_16x16x32_bf16 v[100:103], v[146:149], v[228:231], v[100:103]
	v_mfma_f32_16x16x32_bf16 v[96:99], v[154:157], v[228:231], v[96:99]
	v_mfma_f32_16x16x32_bf16 v[120:123], v[150:153], v[206:209], v[120:123]
	v_mfma_f32_16x16x32_bf16 v[124:127], v[158:161], v[206:209], v[124:127]
	v_mfma_f32_16x16x32_bf16 v[116:119], v[150:153], v[214:217], v[116:119]
	v_mfma_f32_16x16x32_bf16 v[112:115], v[158:161], v[214:217], v[112:115]
	v_mfma_f32_16x16x32_bf16 v[108:111], v[150:153], v[224:227], v[108:111]
	v_mfma_f32_16x16x32_bf16 v[104:107], v[158:161], v[224:227], v[104:107]
	v_mfma_f32_16x16x32_bf16 v[100:103], v[150:153], v[232:235], v[100:103]
	v_mfma_f32_16x16x32_bf16 v[96:99], v[158:161], v[232:235], v[96:99]
	v_mfma_f32_16x16x32_bf16 v[60:63], v[162:165], v[194:197], v[60:63]
	v_mfma_f32_16x16x32_bf16 v[56:59], v[170:173], v[194:197], v[56:59]
	v_mfma_f32_16x16x32_bf16 v[52:55], v[162:165], v[210:213], v[52:55]
	v_mfma_f32_16x16x32_bf16 v[48:51], v[170:173], v[210:213], v[48:51]
	v_mfma_f32_16x16x32_bf16 v[44:47], v[162:165], v[220:223], v[44:47]
	v_mfma_f32_16x16x32_bf16 v[40:43], v[170:173], v[220:223], v[40:43]
	v_mfma_f32_16x16x32_bf16 v[36:39], v[162:165], v[228:231], v[36:39]
	v_mfma_f32_16x16x32_bf16 v[32:35], v[170:173], v[228:231], v[32:35]
	v_mfma_f32_16x16x32_bf16 v[60:63], v[166:169], v[206:209], v[60:63]
	v_mfma_f32_16x16x32_bf16 v[56:59], v[174:177], v[206:209], v[56:59]
	v_mfma_f32_16x16x32_bf16 v[52:55], v[166:169], v[214:217], v[52:55]
	v_mfma_f32_16x16x32_bf16 v[48:51], v[174:177], v[214:217], v[48:51]
	v_mfma_f32_16x16x32_bf16 v[44:47], v[166:169], v[224:227], v[44:47]
	v_mfma_f32_16x16x32_bf16 v[40:43], v[174:177], v[224:227], v[40:43]
	v_mfma_f32_16x16x32_bf16 v[36:39], v[166:169], v[232:235], v[36:39]
	v_mfma_f32_16x16x32_bf16 v[32:35], v[174:177], v[232:235], v[32:35]
	s_barrier
	s_add_i32 s16, s29, s34
	v_lshl_add_u64 v[140:141], v[140:141], 0, s[12:13]
	s_mov_b32 m0, s16
	global_load_lds_dwordx4 v[140:141], off
	v_lshl_add_u64 v[140:141], v[178:179], 0, s[12:13]
	s_add_i32 m0, s16, 0x2000
	s_add_i32 s16, s42, s34
	global_load_lds_dwordx4 v[140:141], off
	v_lshl_add_u64 v[140:141], v[198:199], 0, s[12:13]
	s_mov_b32 m0, s16
	s_nop 0
	global_load_lds_dwordx4 v[140:141], off
	v_lshl_add_u64 v[140:141], v[202:203], 0, s[12:13]
	s_add_i32 m0, s16, 0x2000
	s_nop 0
	global_load_lds_dwordx4 v[140:141], off
	v_lshl_add_u64 v[140:141], v[236:237], 0, s[12:13]
	s_mov_b32 m0, s46
	s_nop 0
	global_load_lds_dwordx4 v[140:141], off
	v_lshl_add_u64 v[140:141], v[238:239], 0, s[12:13]
	s_mov_b32 m0, s47
	s_nop 0
	global_load_lds_dwordx4 v[140:141], off
	ds_read_b128 v[194:197], v145 offset:49152
	ds_read_b128 v[206:209], v145 offset:50176
	ds_read_b128 v[210:213], v145 offset:51200
	ds_read_b128 v[214:217], v145 offset:52224
	ds_read_b128 v[220:223], v145 offset:53248
	ds_read_b128 v[224:227], v145 offset:54272
	ds_read_b128 v[228:231], v145 offset:55296
	ds_read_b128 v[232:235], v145 offset:56320
	s_waitcnt vmcnt(8)
	s_waitcnt lgkmcnt(0)
	s_barrier
	s_waitcnt lgkmcnt(0)
	v_mfma_f32_16x16x32_bf16 v[92:95], v[146:149], v[194:197], v[92:95]
	s_add_u32 s26, s26, 0x100
	v_mfma_f32_16x16x32_bf16 v[88:91], v[154:157], v[194:197], v[88:91]
	s_addc_u32 s27, s27, 0
	v_mfma_f32_16x16x32_bf16 v[84:87], v[146:149], v[210:213], v[84:87]
	s_add_u32 s10, s10, 0x100
	v_mfma_f32_16x16x32_bf16 v[80:83], v[154:157], v[210:213], v[80:83]
	s_addc_u32 s11, s11, 0
	v_mfma_f32_16x16x32_bf16 v[76:79], v[146:149], v[220:223], v[76:79]
	s_mov_b32 s16, s28
	v_mfma_f32_16x16x32_bf16 v[72:75], v[154:157], v[220:223], v[72:75]
	s_cmp_ge_i32 s28, s45
	v_mfma_f32_16x16x32_bf16 v[68:71], v[146:149], v[228:231], v[68:71]
	s_cselect_b32 s99, 1, 0
	v_mfma_f32_16x16x32_bf16 v[64:67], v[154:157], v[228:231], v[64:67]
	s_add_i32 s28, s16, 2
	v_mfma_f32_16x16x32_bf16 v[92:95], v[150:153], v[206:209], v[92:95]
	s_add_u32 s29, s26, 0x80
	v_mfma_f32_16x16x32_bf16 v[88:91], v[158:161], v[206:209], v[88:91]
	s_addc_u32 s17, s27, 0
	v_mfma_f32_16x16x32_bf16 v[84:87], v[150:153], v[214:217], v[84:87]
	s_add_i32 s59, 0, 0x10000
	v_mfma_f32_16x16x32_bf16 v[80:83], v[158:161], v[214:217], v[80:83]
	s_cmp_eq_u32 s48, s16
	v_mfma_f32_16x16x32_bf16 v[76:79], v[150:153], v[224:227], v[76:79]
	s_cselect_b32 s17, s23, s17
	v_mfma_f32_16x16x32_bf16 v[72:75], v[158:161], v[224:227], v[72:75]
	s_cselect_b32 s16, s22, s29
	v_mfma_f32_16x16x32_bf16 v[68:71], v[150:153], v[232:235], v[68:71]
	s_cselect_b32 s43, s25, s11
	v_mfma_f32_16x16x32_bf16 v[64:67], v[158:161], v[232:235], v[64:67]
	s_cselect_b32 s42, s24, s10
	v_mfma_f32_16x16x32_bf16 v[28:31], v[162:165], v[194:197], v[28:31]
	s_add_i32 s29, 0, 0x14000
	v_mfma_f32_16x16x32_bf16 v[24:27], v[170:173], v[194:197], v[24:27]
	v_mfma_f32_16x16x32_bf16 v[20:23], v[162:165], v[210:213], v[20:23]
	v_mfma_f32_16x16x32_bf16 v[16:19], v[170:173], v[210:213], v[16:19]
	v_mfma_f32_16x16x32_bf16 v[12:15], v[162:165], v[220:223], v[12:15]
	v_mfma_f32_16x16x32_bf16 v[8:11], v[170:173], v[220:223], v[8:11]
	v_mfma_f32_16x16x32_bf16 v[4:7], v[162:165], v[228:231], v[4:7]
	v_mfma_f32_16x16x32_bf16 v[0:3], v[170:173], v[228:231], v[0:3]
	v_mfma_f32_16x16x32_bf16 v[28:31], v[166:169], v[206:209], v[28:31]
	v_mfma_f32_16x16x32_bf16 v[24:27], v[174:177], v[206:209], v[24:27]
	v_mfma_f32_16x16x32_bf16 v[20:23], v[166:169], v[214:217], v[20:23]
	v_mfma_f32_16x16x32_bf16 v[16:19], v[174:177], v[214:217], v[16:19]
	v_mfma_f32_16x16x32_bf16 v[12:15], v[166:169], v[224:227], v[12:15]
	v_mfma_f32_16x16x32_bf16 v[8:11], v[174:177], v[224:227], v[8:11]
	v_mfma_f32_16x16x32_bf16 v[4:7], v[166:169], v[232:235], v[4:7]
	v_mfma_f32_16x16x32_bf16 v[0:3], v[174:177], v[232:235], v[0:3]
	s_barrier
	s_cmp_lg_u32 s99, 0
	s_cbranch_scc1 .Lpeelx_11
.LBB0_823:
	v_add_u32_e32 v140, s59, v143
	ds_read_b128 v[146:149], v140
	ds_read_b128 v[150:153], v140 offset:1024
	ds_read_b128 v[154:157], v140 offset:2048
	ds_read_b128 v[158:161], v140 offset:3072
	v_add_u32_e32 v140, s29, v143
	ds_read_b128 v[162:165], v140
	ds_read_b128 v[166:169], v140 offset:1024
	ds_read_b128 v[170:173], v140 offset:2048
	ds_read_b128 v[174:177], v140 offset:3072
	v_lshl_add_u64 v[140:141], s[26:27], 0, v[136:137]
	s_add_i32 m0, s35, 0xc000
	global_load_lds_dwordx4 v[140:141], off
	v_lshl_add_u64 v[140:141], s[26:27], 0, v[138:139]
	s_add_i32 m0, s35, 0xe000
	s_nop 0
	global_load_lds_dwordx4 v[140:141], off
	ds_read_b128 v[194:197], v145
	ds_read_b128 v[206:209], v145 offset:1024
	ds_read_b128 v[210:213], v145 offset:2048
	ds_read_b128 v[214:217], v145 offset:3072
	ds_read_b128 v[220:223], v145 offset:4096
	ds_read_b128 v[224:227], v145 offset:5120
	ds_read_b128 v[228:231], v145 offset:6144
	ds_read_b128 v[232:235], v145 offset:7168
	s_waitcnt vmcnt(8)
	s_waitcnt lgkmcnt(0)
	s_barrier
	s_waitcnt lgkmcnt(0)
	v_mfma_f32_16x16x32_bf16 v[120:123], v[146:149], v[194:197], v[120:123]
	v_mfma_f32_16x16x32_bf16 v[124:127], v[154:157], v[194:197], v[124:127]
	v_mfma_f32_16x16x32_bf16 v[116:119], v[146:149], v[210:213], v[116:119]
	v_mfma_f32_16x16x32_bf16 v[112:115], v[154:157], v[210:213], v[112:115]
	v_mfma_f32_16x16x32_bf16 v[108:111], v[146:149], v[220:223], v[108:111]
	v_mfma_f32_16x16x32_bf16 v[104:107], v[154:157], v[220:223], v[104:107]
	v_mfma_f32_16x16x32_bf16 v[100:103], v[146:149], v[228:231], v[100:103]
	v_mfma_f32_16x16x32_bf16 v[96:99], v[154:157], v[228:231], v[96:99]
	v_mfma_f32_16x16x32_bf16 v[120:123], v[150:153], v[206:209], v[120:123]
	v_mfma_f32_16x16x32_bf16 v[124:127], v[158:161], v[206:209], v[124:127]
	v_mfma_f32_16x16x32_bf16 v[116:119], v[150:153], v[214:217], v[116:119]
	v_mfma_f32_16x16x32_bf16 v[112:115], v[158:161], v[214:217], v[112:115]
	v_mfma_f32_16x16x32_bf16 v[108:111], v[150:153], v[224:227], v[108:111]
	v_mfma_f32_16x16x32_bf16 v[104:107], v[158:161], v[224:227], v[104:107]
	v_mfma_f32_16x16x32_bf16 v[100:103], v[150:153], v[232:235], v[100:103]
	v_mfma_f32_16x16x32_bf16 v[96:99], v[158:161], v[232:235], v[96:99]
	v_mfma_f32_16x16x32_bf16 v[60:63], v[162:165], v[194:197], v[60:63]
	v_mfma_f32_16x16x32_bf16 v[56:59], v[170:173], v[194:197], v[56:59]
	v_mfma_f32_16x16x32_bf16 v[52:55], v[162:165], v[210:213], v[52:55]
	v_mfma_f32_16x16x32_bf16 v[48:51], v[170:173], v[210:213], v[48:51]
	v_mfma_f32_16x16x32_bf16 v[44:47], v[162:165], v[220:223], v[44:47]
	v_mfma_f32_16x16x32_bf16 v[40:43], v[170:173], v[220:223], v[40:43]
	v_mfma_f32_16x16x32_bf16 v[36:39], v[162:165], v[228:231], v[36:39]
	v_mfma_f32_16x16x32_bf16 v[32:35], v[170:173], v[228:231], v[32:35]
	v_mfma_f32_16x16x32_bf16 v[60:63], v[166:169], v[206:209], v[60:63]
	v_mfma_f32_16x16x32_bf16 v[56:59], v[174:177], v[206:209], v[56:59]
	v_mfma_f32_16x16x32_bf16 v[52:55], v[166:169], v[214:217], v[52:55]
	v_mfma_f32_16x16x32_bf16 v[48:51], v[174:177], v[214:217], v[48:51]
	v_mfma_f32_16x16x32_bf16 v[44:47], v[166:169], v[224:227], v[44:47]
	v_mfma_f32_16x16x32_bf16 v[40:43], v[174:177], v[224:227], v[40:43]
	v_mfma_f32_16x16x32_bf16 v[36:39], v[166:169], v[232:235], v[36:39]
	v_mfma_f32_16x16x32_bf16 v[32:35], v[174:177], v[232:235], v[32:35]
	s_barrier
	s_add_i32 s59, s59, s34
	v_lshl_add_u64 v[140:141], s[42:43], 0, v[132:133]
	s_mov_b32 m0, s59
	global_load_lds_dwordx4 v[140:141], off
	s_add_i32 m0, s59, 0x2000
	v_lshl_add_u64 v[178:179], s[42:43], 0, v[128:129]
	s_add_u32 s42, s42, s0
	s_addc_u32 s43, s43, s1
	s_add_i32 s29, s29, s34
	global_load_lds_dwordx4 v[178:179], off
	v_lshl_add_u64 v[198:199], s[42:43], 0, v[132:133]
	s_mov_b32 m0, s29
	v_lshl_add_u64 v[202:203], s[42:43], 0, v[128:129]
	global_load_lds_dwordx4 v[198:199], off
	s_add_i32 m0, s29, 0x2000
	v_lshl_add_u64 v[236:237], s[16:17], 0, v[134:135]
	global_load_lds_dwordx4 v[202:203], off
	s_mov_b32 m0, s35
	v_lshl_add_u64 v[238:239], s[16:17], 0, v[130:131]
	global_load_lds_dwordx4 v[236:237], off
	s_mov_b32 m0, s36
	s_nop 0
	global_load_lds_dwordx4 v[238:239], off
	ds_read_b128 v[194:197], v145 offset:16384
	ds_read_b128 v[206:209], v145 offset:17408
	ds_read_b128 v[210:213], v145 offset:18432
	ds_read_b128 v[214:217], v145 offset:19456
	ds_read_b128 v[220:223], v145 offset:20480
	ds_read_b128 v[224:227], v145 offset:21504
	ds_read_b128 v[228:231], v145 offset:22528
	ds_read_b128 v[232:235], v145 offset:23552
	s_waitcnt vmcnt(8)
	s_waitcnt lgkmcnt(0)
	s_barrier
	s_waitcnt lgkmcnt(0)
	v_mfma_f32_16x16x32_bf16 v[92:95], v[146:149], v[194:197], v[92:95]
	v_mfma_f32_16x16x32_bf16 v[88:91], v[154:157], v[194:197], v[88:91]
	v_mfma_f32_16x16x32_bf16 v[84:87], v[146:149], v[210:213], v[84:87]
	v_mfma_f32_16x16x32_bf16 v[80:83], v[154:157], v[210:213], v[80:83]
	v_mfma_f32_16x16x32_bf16 v[76:79], v[146:149], v[220:223], v[76:79]
	v_mfma_f32_16x16x32_bf16 v[72:75], v[154:157], v[220:223], v[72:75]
	v_mfma_f32_16x16x32_bf16 v[68:71], v[146:149], v[228:231], v[68:71]
	v_mfma_f32_16x16x32_bf16 v[64:67], v[154:157], v[228:231], v[64:67]
	v_mfma_f32_16x16x32_bf16 v[92:95], v[150:153], v[206:209], v[92:95]
	v_mfma_f32_16x16x32_bf16 v[88:91], v[158:161], v[206:209], v[88:91]
	v_mfma_f32_16x16x32_bf16 v[84:87], v[150:153], v[214:217], v[84:87]
	v_mfma_f32_16x16x32_bf16 v[80:83], v[158:161], v[214:217], v[80:83]
	v_mfma_f32_16x16x32_bf16 v[76:79], v[150:153], v[224:227], v[76:79]
	v_mfma_f32_16x16x32_bf16 v[72:75], v[158:161], v[224:227], v[72:75]
	v_mfma_f32_16x16x32_bf16 v[68:71], v[150:153], v[232:235], v[68:71]
	v_mfma_f32_16x16x32_bf16 v[64:67], v[158:161], v[232:235], v[64:67]
	v_mfma_f32_16x16x32_bf16 v[28:31], v[162:165], v[194:197], v[28:31]
	v_mfma_f32_16x16x32_bf16 v[24:27], v[170:173], v[194:197], v[24:27]
	v_mfma_f32_16x16x32_bf16 v[20:23], v[162:165], v[210:213], v[20:23]
	v_mfma_f32_16x16x32_bf16 v[16:19], v[170:173], v[210:213], v[16:19]
	v_mfma_f32_16x16x32_bf16 v[12:15], v[162:165], v[220:223], v[12:15]
	v_mfma_f32_16x16x32_bf16 v[8:11], v[170:173], v[220:223], v[8:11]
	v_mfma_f32_16x16x32_bf16 v[4:7], v[162:165], v[228:231], v[4:7]
	v_mfma_f32_16x16x32_bf16 v[0:3], v[170:173], v[228:231], v[0:3]
	v_mfma_f32_16x16x32_bf16 v[28:31], v[166:169], v[206:209], v[28:31]
	v_mfma_f32_16x16x32_bf16 v[24:27], v[174:177], v[206:209], v[24:27]
	v_mfma_f32_16x16x32_bf16 v[20:23], v[166:169], v[214:217], v[20:23]
	v_mfma_f32_16x16x32_bf16 v[16:19], v[174:177], v[214:217], v[16:19]
	v_mfma_f32_16x16x32_bf16 v[12:15], v[166:169], v[224:227], v[12:15]
	v_mfma_f32_16x16x32_bf16 v[8:11], v[174:177], v[224:227], v[8:11]
	v_mfma_f32_16x16x32_bf16 v[4:7], v[166:169], v[232:235], v[4:7]
	v_mfma_f32_16x16x32_bf16 v[0:3], v[174:177], v[232:235], v[0:3]
	s_barrier
	s_add_i32 s29, 0, 0x18000
	s_add_i32 s42, 0, 0x1c000
	s_add_u32 s16, s16, s0
	s_addc_u32 s17, s17, s1
	s_mov_b32 m0, s37
	v_lshl_add_u64 v[240:241], s[16:17], 0, v[134:135]
	global_load_lds_dwordx4 v[240:241], off
	v_lshl_add_u64 v[240:241], s[16:17], 0, v[130:131]
	s_mov_b32 m0, s38
	s_nop 0
	global_load_lds_dwordx4 v[240:241], off
	v_add_u32_e32 v158, s29, v143
	v_add_u32_e32 v174, s42, v143
	ds_read_b128 v[146:149], v158
	ds_read_b128 v[150:153], v158 offset:1024
	ds_read_b128 v[154:157], v158 offset:2048
	ds_read_b128 v[158:161], v158 offset:3072
	ds_read_b128 v[162:165], v174
	ds_read_b128 v[166:169], v174 offset:1024
	ds_read_b128 v[170:173], v174 offset:2048
	ds_read_b128 v[174:177], v174 offset:3072
	ds_read_b128 v[194:197], v145 offset:32768
	ds_read_b128 v[206:209], v145 offset:33792
	ds_read_b128 v[210:213], v145 offset:34816
	ds_read_b128 v[214:217], v145 offset:35840
	ds_read_b128 v[220:223], v145 offset:36864
	ds_read_b128 v[224:227], v145 offset:37888
	ds_read_b128 v[228:231], v145 offset:38912
	ds_read_b128 v[232:235], v145 offset:39936
	s_waitcnt vmcnt(8)
	s_waitcnt lgkmcnt(0)
	s_barrier
	s_waitcnt lgkmcnt(0)
	v_mfma_f32_16x16x32_bf16 v[120:123], v[146:149], v[194:197], v[120:123]
	v_mfma_f32_16x16x32_bf16 v[124:127], v[154:157], v[194:197], v[124:127]
	v_mfma_f32_16x16x32_bf16 v[116:119], v[146:149], v[210:213], v[116:119]
	v_mfma_f32_16x16x32_bf16 v[112:115], v[154:157], v[210:213], v[112:115]
	v_mfma_f32_16x16x32_bf16 v[108:111], v[146:149], v[220:223], v[108:111]
	v_mfma_f32_16x16x32_bf16 v[104:107], v[154:157], v[220:223], v[104:107]
	v_mfma_f32_16x16x32_bf16 v[100:103], v[146:149], v[228:231], v[100:103]
	v_mfma_f32_16x16x32_bf16 v[96:99], v[154:157], v[228:231], v[96:99]
	v_mfma_f32_16x16x32_bf16 v[120:123], v[150:153], v[206:209], v[120:123]
	v_mfma_f32_16x16x32_bf16 v[124:127], v[158:161], v[206:209], v[124:127]
	v_mfma_f32_16x16x32_bf16 v[116:119], v[150:153], v[214:217], v[116:119]
	v_mfma_f32_16x16x32_bf16 v[112:115], v[158:161], v[214:217], v[112:115]
	v_mfma_f32_16x16x32_bf16 v[108:111], v[150:153], v[224:227], v[108:111]
	v_mfma_f32_16x16x32_bf16 v[104:107], v[158:161], v[224:227], v[104:107]
	v_mfma_f32_16x16x32_bf16 v[100:103], v[150:153], v[232:235], v[100:103]
	v_mfma_f32_16x16x32_bf16 v[96:99], v[158:161], v[232:235], v[96:99]
	v_mfma_f32_16x16x32_bf16 v[60:63], v[162:165], v[194:197], v[60:63]
	v_mfma_f32_16x16x32_bf16 v[56:59], v[170:173], v[194:197], v[56:59]
	v_mfma_f32_16x16x32_bf16 v[52:55], v[162:165], v[210:213], v[52:55]
	v_mfma_f32_16x16x32_bf16 v[48:51], v[170:173], v[210:213], v[48:51]
	v_mfma_f32_16x16x32_bf16 v[44:47], v[162:165], v[220:223], v[44:47]
	v_mfma_f32_16x16x32_bf16 v[40:43], v[170:173], v[220:223], v[40:43]
	v_mfma_f32_16x16x32_bf16 v[36:39], v[162:165], v[228:231], v[36:39]
	v_mfma_f32_16x16x32_bf16 v[32:35], v[170:173], v[228:231], v[32:35]
	v_mfma_f32_16x16x32_bf16 v[60:63], v[166:169], v[206:209], v[60:63]
	v_mfma_f32_16x16x32_bf16 v[56:59], v[174:177], v[206:209], v[56:59]
	v_mfma_f32_16x16x32_bf16 v[52:55], v[166:169], v[214:217], v[52:55]
	v_mfma_f32_16x16x32_bf16 v[48:51], v[174:177], v[214:217], v[48:51]
	v_mfma_f32_16x16x32_bf16 v[44:47], v[166:169], v[224:227], v[44:47]
	v_mfma_f32_16x16x32_bf16 v[40:43], v[174:177], v[224:227], v[40:43]
	v_mfma_f32_16x16x32_bf16 v[36:39], v[166:169], v[232:235], v[36:39]
	v_mfma_f32_16x16x32_bf16 v[32:35], v[174:177], v[232:235], v[32:35]
	s_barrier
	s_add_i32 s16, s29, s34
	v_lshl_add_u64 v[140:141], v[140:141], 0, s[12:13]
	s_mov_b32 m0, s16
	global_load_lds_dwordx4 v[140:141], off
	v_lshl_add_u64 v[140:141], v[178:179], 0, s[12:13]
	s_add_i32 m0, s16, 0x2000
	s_add_i32 s16, s42, s34
	global_load_lds_dwordx4 v[140:141], off
	v_lshl_add_u64 v[140:141], v[198:199], 0, s[12:13]
	s_mov_b32 m0, s16
	s_nop 0
	global_load_lds_dwordx4 v[140:141], off
	v_lshl_add_u64 v[140:141], v[202:203], 0, s[12:13]
	s_add_i32 m0, s16, 0x2000
	s_nop 0
	global_load_lds_dwordx4 v[140:141], off
	v_lshl_add_u64 v[140:141], v[236:237], 0, s[12:13]
	s_mov_b32 m0, s46
	s_nop 0
	global_load_lds_dwordx4 v[140:141], off
	v_lshl_add_u64 v[140:141], v[238:239], 0, s[12:13]
	s_mov_b32 m0, s47
	s_nop 0
	global_load_lds_dwordx4 v[140:141], off
	ds_read_b128 v[194:197], v145 offset:49152
	ds_read_b128 v[206:209], v145 offset:50176
	ds_read_b128 v[210:213], v145 offset:51200
	ds_read_b128 v[214:217], v145 offset:52224
	ds_read_b128 v[220:223], v145 offset:53248
	ds_read_b128 v[224:227], v145 offset:54272
	ds_read_b128 v[228:231], v145 offset:55296
	ds_read_b128 v[232:235], v145 offset:56320
	s_waitcnt vmcnt(8)
	s_waitcnt lgkmcnt(0)
	s_barrier
	s_waitcnt lgkmcnt(0)
	v_mfma_f32_16x16x32_bf16 v[92:95], v[146:149], v[194:197], v[92:95]
	s_add_u32 s26, s26, 0x100
	v_mfma_f32_16x16x32_bf16 v[88:91], v[154:157], v[194:197], v[88:91]
	s_addc_u32 s27, s27, 0
	v_mfma_f32_16x16x32_bf16 v[84:87], v[146:149], v[210:213], v[84:87]
	s_add_u32 s10, s10, 0x100
	v_mfma_f32_16x16x32_bf16 v[80:83], v[154:157], v[210:213], v[80:83]
	s_addc_u32 s11, s11, 0
	v_mfma_f32_16x16x32_bf16 v[76:79], v[146:149], v[220:223], v[76:79]
	s_mov_b32 s16, s28
	v_mfma_f32_16x16x32_bf16 v[72:75], v[154:157], v[220:223], v[72:75]
	s_cmp_ge_i32 s28, s45
	v_mfma_f32_16x16x32_bf16 v[68:71], v[146:149], v[228:231], v[68:71]
	s_cselect_b32 s99, 1, 0
	v_mfma_f32_16x16x32_bf16 v[64:67], v[154:157], v[228:231], v[64:67]
	s_add_i32 s28, s16, 2
	v_mfma_f32_16x16x32_bf16 v[92:95], v[150:153], v[206:209], v[92:95]
	s_add_u32 s29, s26, 0x80
	v_mfma_f32_16x16x32_bf16 v[88:91], v[158:161], v[206:209], v[88:91]
	s_addc_u32 s17, s27, 0
	v_mfma_f32_16x16x32_bf16 v[84:87], v[150:153], v[214:217], v[84:87]
	s_add_i32 s59, 0, 0x10000
	v_mfma_f32_16x16x32_bf16 v[80:83], v[158:161], v[214:217], v[80:83]
	s_cmp_eq_u32 s48, s16
	v_mfma_f32_16x16x32_bf16 v[76:79], v[150:153], v[224:227], v[76:79]
	s_cselect_b32 s17, s23, s17
	v_mfma_f32_16x16x32_bf16 v[72:75], v[158:161], v[224:227], v[72:75]
	s_cselect_b32 s16, s22, s29
	v_mfma_f32_16x16x32_bf16 v[68:71], v[150:153], v[232:235], v[68:71]
	s_cselect_b32 s43, s25, s11
	v_mfma_f32_16x16x32_bf16 v[64:67], v[158:161], v[232:235], v[64:67]
	s_cselect_b32 s42, s24, s10
	v_mfma_f32_16x16x32_bf16 v[28:31], v[162:165], v[194:197], v[28:31]
	s_add_i32 s29, 0, 0x14000
	v_mfma_f32_16x16x32_bf16 v[24:27], v[170:173], v[194:197], v[24:27]
	v_mfma_f32_16x16x32_bf16 v[20:23], v[162:165], v[210:213], v[20:23]
	v_mfma_f32_16x16x32_bf16 v[16:19], v[170:173], v[210:213], v[16:19]
	v_mfma_f32_16x16x32_bf16 v[12:15], v[162:165], v[220:223], v[12:15]
	v_mfma_f32_16x16x32_bf16 v[8:11], v[170:173], v[220:223], v[8:11]
	v_mfma_f32_16x16x32_bf16 v[4:7], v[162:165], v[228:231], v[4:7]
	v_mfma_f32_16x16x32_bf16 v[0:3], v[170:173], v[228:231], v[0:3]
	v_mfma_f32_16x16x32_bf16 v[28:31], v[166:169], v[206:209], v[28:31]
	v_mfma_f32_16x16x32_bf16 v[24:27], v[174:177], v[206:209], v[24:27]
	v_mfma_f32_16x16x32_bf16 v[20:23], v[166:169], v[214:217], v[20:23]
	v_mfma_f32_16x16x32_bf16 v[16:19], v[174:177], v[214:217], v[16:19]
	v_mfma_f32_16x16x32_bf16 v[12:15], v[166:169], v[224:227], v[12:15]
	v_mfma_f32_16x16x32_bf16 v[8:11], v[174:177], v[224:227], v[8:11]
	v_mfma_f32_16x16x32_bf16 v[4:7], v[166:169], v[232:235], v[4:7]
	v_mfma_f32_16x16x32_bf16 v[0:3], v[174:177], v[232:235], v[0:3]
	s_barrier
	s_cmp_lg_u32 s99, 0
	s_cbranch_scc0 .LBB0_823

.Llbb_8:
	s_add_i32 s30, s16, 2
	s_add_u32 s31, s0, 0x80
	s_addc_u32 s17, s1, 0
	s_add_i32 s35, 0, 0x10000
	s_cmp_eq_u32 s57, s16
	s_cselect_b32 s17, s27, s17
	s_cselect_b32 s16, s26, s31
	s_cselect_b32 s43, s29, s11
	s_cselect_b32 s42, s28, s10
	s_add_i32 s31, 0, 0x14000
	v_lshl_add_u64 v[198:199], s[0:1], 0, v[140:141]
	s_add_i32 m0, s39, 0xc000
	global_load_lds_dwordx4 v[198:199], off
	v_lshl_add_u64 v[198:199], s[0:1], 0, v[142:143]
	s_add_i32 m0, s39, 0xe000
	s_nop 0
	global_load_lds_dwordx4 v[198:199], off
	v_add_u32_e32 v156, s35, v164
	v_add_u32_e32 v167, s31, v164
	ds_read_b128 v[144:147], v156
	ds_read_b128 v[148:151], v156 offset:1024
	ds_read_b128 v[152:155], v156 offset:2048
	ds_read_b128 v[156:159], v156 offset:3072
	ds_read_b128 v[160:163], v167
	ds_read_b128 v[168:171], v167 offset:1024
	ds_read_b128 v[172:175], v167 offset:2048
	ds_read_b128 v[176:179], v167 offset:3072
	ds_read_b128 v[194:197], v166
	ds_read_b128 v[206:209], v166 offset:1024
	ds_read_b128 v[210:213], v166 offset:2048
	ds_read_b128 v[214:217], v166 offset:3072
	ds_read_b128 v[220:223], v166 offset:4096
	ds_read_b128 v[224:227], v166 offset:5120
	ds_read_b128 v[228:231], v166 offset:6144
	ds_read_b128 v[232:235], v166 offset:7168
	s_waitcnt vmcnt(8)
	s_waitcnt lgkmcnt(0)
	s_barrier
	s_waitcnt lgkmcnt(0)
	v_mfma_f32_16x16x32_bf16 v[124:127], v[144:147], v[194:197], 0
	v_mfma_f32_16x16x32_bf16 v[120:123], v[152:155], v[194:197], 0
	v_mfma_f32_16x16x32_bf16 v[108:111], v[144:147], v[210:213], 0
	v_mfma_f32_16x16x32_bf16 v[104:107], v[152:155], v[210:213], 0
	v_mfma_f32_16x16x32_bf16 v[92:95], v[144:147], v[220:223], 0
	v_mfma_f32_16x16x32_bf16 v[88:91], v[152:155], v[220:223], 0
	v_mfma_f32_16x16x32_bf16 v[76:79], v[144:147], v[228:231], 0
	v_mfma_f32_16x16x32_bf16 v[72:75], v[152:155], v[228:231], 0
	v_mfma_f32_16x16x32_bf16 v[124:127], v[148:151], v[206:209], v[124:127]
	v_mfma_f32_16x16x32_bf16 v[120:123], v[156:159], v[206:209], v[120:123]
	v_mfma_f32_16x16x32_bf16 v[108:111], v[148:151], v[214:217], v[108:111]
	v_mfma_f32_16x16x32_bf16 v[104:107], v[156:159], v[214:217], v[104:107]
	v_mfma_f32_16x16x32_bf16 v[92:95], v[148:151], v[224:227], v[92:95]
	v_mfma_f32_16x16x32_bf16 v[88:91], v[156:159], v[224:227], v[88:91]
	v_mfma_f32_16x16x32_bf16 v[76:79], v[148:151], v[232:235], v[76:79]
	v_mfma_f32_16x16x32_bf16 v[72:75], v[156:159], v[232:235], v[72:75]
	v_mfma_f32_16x16x32_bf16 v[116:119], v[160:163], v[194:197], 0
	v_mfma_f32_16x16x32_bf16 v[112:115], v[172:175], v[194:197], 0
	v_mfma_f32_16x16x32_bf16 v[100:103], v[160:163], v[210:213], 0
	v_mfma_f32_16x16x32_bf16 v[96:99], v[172:175], v[210:213], 0
	v_mfma_f32_16x16x32_bf16 v[84:87], v[160:163], v[220:223], 0
	v_mfma_f32_16x16x32_bf16 v[80:83], v[172:175], v[220:223], 0
	v_mfma_f32_16x16x32_bf16 v[68:71], v[160:163], v[228:231], 0
	v_mfma_f32_16x16x32_bf16 v[64:67], v[172:175], v[228:231], 0
	v_mfma_f32_16x16x32_bf16 v[116:119], v[168:171], v[206:209], v[116:119]
	v_mfma_f32_16x16x32_bf16 v[112:115], v[176:179], v[206:209], v[112:115]
	v_mfma_f32_16x16x32_bf16 v[100:103], v[168:171], v[214:217], v[100:103]
	v_mfma_f32_16x16x32_bf16 v[96:99], v[176:179], v[214:217], v[96:99]
	v_mfma_f32_16x16x32_bf16 v[84:87], v[168:171], v[224:227], v[84:87]
	v_mfma_f32_16x16x32_bf16 v[80:83], v[176:179], v[224:227], v[80:83]
	v_mfma_f32_16x16x32_bf16 v[68:71], v[168:171], v[232:235], v[68:71]
	v_mfma_f32_16x16x32_bf16 v[64:67], v[176:179], v[232:235], v[64:67]
	s_barrier
	s_add_i32 s35, s35, s38
	v_lshl_add_u64 v[198:199], s[42:43], 0, v[132:133]
	s_mov_b32 m0, s35
	global_load_lds_dwordx4 v[198:199], off
	s_add_i32 m0, s35, 0x2000
	v_lshl_add_u64 v[202:203], s[42:43], 0, v[128:129]
	s_add_u32 s42, s42, s6
	s_addc_u32 s43, s43, s7
	s_add_i32 s31, s31, s38
	global_load_lds_dwordx4 v[202:203], off
	v_lshl_add_u64 v[236:237], s[42:43], 0, v[132:133]
	s_mov_b32 m0, s31
	v_lshl_add_u64 v[238:239], s[42:43], 0, v[128:129]
	global_load_lds_dwordx4 v[236:237], off
	s_add_i32 m0, s31, 0x2000
	v_lshl_add_u64 v[240:241], s[16:17], 0, v[134:135]
	global_load_lds_dwordx4 v[238:239], off
	s_mov_b32 m0, s39
	v_lshl_add_u64 v[242:243], s[16:17], 0, v[130:131]
	global_load_lds_dwordx4 v[240:241], off
	s_mov_b32 m0, s44
	s_nop 0
	global_load_lds_dwordx4 v[242:243], off
	ds_read_b128 v[194:197], v166 offset:16384
	ds_read_b128 v[206:209], v166 offset:17408
	ds_read_b128 v[210:213], v166 offset:18432
	ds_read_b128 v[214:217], v166 offset:19456
	ds_read_b128 v[220:223], v166 offset:20480
	ds_read_b128 v[224:227], v166 offset:21504
	ds_read_b128 v[228:231], v166 offset:22528
	ds_read_b128 v[232:235], v166 offset:23552
	s_waitcnt vmcnt(8)
	s_waitcnt lgkmcnt(0)
	s_barrier
	s_waitcnt lgkmcnt(0)
	v_mfma_f32_16x16x32_bf16 v[60:63], v[144:147], v[194:197], 0
	v_mfma_f32_16x16x32_bf16 v[56:59], v[152:155], v[194:197], 0
	v_mfma_f32_16x16x32_bf16 v[44:47], v[144:147], v[210:213], 0
	v_mfma_f32_16x16x32_bf16 v[40:43], v[152:155], v[210:213], 0
	v_mfma_f32_16x16x32_bf16 v[28:31], v[144:147], v[220:223], 0
	v_mfma_f32_16x16x32_bf16 v[24:27], v[152:155], v[220:223], 0
	v_mfma_f32_16x16x32_bf16 v[12:15], v[144:147], v[228:231], 0
	v_mfma_f32_16x16x32_bf16 v[8:11], v[152:155], v[228:231], 0
	v_mfma_f32_16x16x32_bf16 v[60:63], v[148:151], v[206:209], v[60:63]
	v_mfma_f32_16x16x32_bf16 v[56:59], v[156:159], v[206:209], v[56:59]
	v_mfma_f32_16x16x32_bf16 v[44:47], v[148:151], v[214:217], v[44:47]
	v_mfma_f32_16x16x32_bf16 v[40:43], v[156:159], v[214:217], v[40:43]
	v_mfma_f32_16x16x32_bf16 v[28:31], v[148:151], v[224:227], v[28:31]
	v_mfma_f32_16x16x32_bf16 v[24:27], v[156:159], v[224:227], v[24:27]
	v_mfma_f32_16x16x32_bf16 v[12:15], v[148:151], v[232:235], v[12:15]
	v_mfma_f32_16x16x32_bf16 v[8:11], v[156:159], v[232:235], v[8:11]
	v_mfma_f32_16x16x32_bf16 v[52:55], v[160:163], v[194:197], 0
	v_mfma_f32_16x16x32_bf16 v[48:51], v[172:175], v[194:197], 0
	v_mfma_f32_16x16x32_bf16 v[36:39], v[160:163], v[210:213], 0
	v_mfma_f32_16x16x32_bf16 v[32:35], v[172:175], v[210:213], 0
	v_mfma_f32_16x16x32_bf16 v[20:23], v[160:163], v[220:223], 0
	v_mfma_f32_16x16x32_bf16 v[16:19], v[172:175], v[220:223], 0
	v_mfma_f32_16x16x32_bf16 v[4:7], v[160:163], v[228:231], 0
	v_mfma_f32_16x16x32_bf16 v[0:3], v[172:175], v[228:231], 0
	v_mfma_f32_16x16x32_bf16 v[52:55], v[168:171], v[206:209], v[52:55]
	v_mfma_f32_16x16x32_bf16 v[48:51], v[176:179], v[206:209], v[48:51]
	v_mfma_f32_16x16x32_bf16 v[36:39], v[168:171], v[214:217], v[36:39]
	v_mfma_f32_16x16x32_bf16 v[32:35], v[176:179], v[214:217], v[32:35]
	v_mfma_f32_16x16x32_bf16 v[20:23], v[168:171], v[224:227], v[20:23]
	v_mfma_f32_16x16x32_bf16 v[16:19], v[176:179], v[224:227], v[16:19]
	v_mfma_f32_16x16x32_bf16 v[4:7], v[168:171], v[232:235], v[4:7]
	v_mfma_f32_16x16x32_bf16 v[0:3], v[176:179], v[232:235], v[0:3]
	s_barrier
	s_add_i32 s31, 0, 0x18000
	s_add_i32 s35, 0, 0x1c000
	s_add_u32 s16, s16, s6
	s_addc_u32 s17, s17, s7
	s_mov_b32 m0, s45
	v_lshl_add_u64 v[244:245], s[16:17], 0, v[134:135]
	global_load_lds_dwordx4 v[244:245], off
	v_lshl_add_u64 v[244:245], s[16:17], 0, v[130:131]
	s_mov_b32 m0, s46
	s_nop 0
	global_load_lds_dwordx4 v[244:245], off
	v_add_u32_e32 v156, s31, v164
	v_add_u32_e32 v167, s35, v164
	ds_read_b128 v[144:147], v156
	ds_read_b128 v[148:151], v156 offset:1024
	ds_read_b128 v[152:155], v156 offset:2048
	ds_read_b128 v[156:159], v156 offset:3072
	ds_read_b128 v[160:163], v167
	ds_read_b128 v[168:171], v167 offset:1024
	ds_read_b128 v[172:175], v167 offset:2048
	ds_read_b128 v[176:179], v167 offset:3072
	ds_read_b128 v[194:197], v166 offset:32768
	ds_read_b128 v[206:209], v166 offset:33792
	ds_read_b128 v[210:213], v166 offset:34816
	ds_read_b128 v[214:217], v166 offset:35840
	ds_read_b128 v[220:223], v166 offset:36864
	ds_read_b128 v[224:227], v166 offset:37888
	ds_read_b128 v[228:231], v166 offset:38912
	ds_read_b128 v[232:235], v166 offset:39936
	s_waitcnt vmcnt(8)
	s_waitcnt lgkmcnt(0)
	s_barrier
	s_waitcnt lgkmcnt(0)
	v_mfma_f32_16x16x32_bf16 v[124:127], v[144:147], v[194:197], v[124:127]
	v_mfma_f32_16x16x32_bf16 v[120:123], v[152:155], v[194:197], v[120:123]
	v_mfma_f32_16x16x32_bf16 v[108:111], v[144:147], v[210:213], v[108:111]
	v_mfma_f32_16x16x32_bf16 v[104:107], v[152:155], v[210:213], v[104:107]
	v_mfma_f32_16x16x32_bf16 v[92:95], v[144:147], v[220:223], v[92:95]
	v_mfma_f32_16x16x32_bf16 v[88:91], v[152:155], v[220:223], v[88:91]
	v_mfma_f32_16x16x32_bf16 v[76:79], v[144:147], v[228:231], v[76:79]
	v_mfma_f32_16x16x32_bf16 v[72:75], v[152:155], v[228:231], v[72:75]
	v_mfma_f32_16x16x32_bf16 v[124:127], v[148:151], v[206:209], v[124:127]
	v_mfma_f32_16x16x32_bf16 v[120:123], v[156:159], v[206:209], v[120:123]
	v_mfma_f32_16x16x32_bf16 v[108:111], v[148:151], v[214:217], v[108:111]
	v_mfma_f32_16x16x32_bf16 v[104:107], v[156:159], v[214:217], v[104:107]
	v_mfma_f32_16x16x32_bf16 v[92:95], v[148:151], v[224:227], v[92:95]
	v_mfma_f32_16x16x32_bf16 v[88:91], v[156:159], v[224:227], v[88:91]
	v_mfma_f32_16x16x32_bf16 v[76:79], v[148:151], v[232:235], v[76:79]
	v_mfma_f32_16x16x32_bf16 v[72:75], v[156:159], v[232:235], v[72:75]
	v_mfma_f32_16x16x32_bf16 v[116:119], v[160:163], v[194:197], v[116:119]
	v_mfma_f32_16x16x32_bf16 v[112:115], v[172:175], v[194:197], v[112:115]
	v_mfma_f32_16x16x32_bf16 v[100:103], v[160:163], v[210:213], v[100:103]
	v_mfma_f32_16x16x32_bf16 v[96:99], v[172:175], v[210:213], v[96:99]
	v_mfma_f32_16x16x32_bf16 v[84:87], v[160:163], v[220:223], v[84:87]
	v_mfma_f32_16x16x32_bf16 v[80:83], v[172:175], v[220:223], v[80:83]
	v_mfma_f32_16x16x32_bf16 v[68:71], v[160:163], v[228:231], v[68:71]
	v_mfma_f32_16x16x32_bf16 v[64:67], v[172:175], v[228:231], v[64:67]
	v_mfma_f32_16x16x32_bf16 v[116:119], v[168:171], v[206:209], v[116:119]
	v_mfma_f32_16x16x32_bf16 v[112:115], v[176:179], v[206:209], v[112:115]
	v_mfma_f32_16x16x32_bf16 v[100:103], v[168:171], v[214:217], v[100:103]
	v_mfma_f32_16x16x32_bf16 v[96:99], v[176:179], v[214:217], v[96:99]
	v_mfma_f32_16x16x32_bf16 v[84:87], v[168:171], v[224:227], v[84:87]
	v_mfma_f32_16x16x32_bf16 v[80:83], v[176:179], v[224:227], v[80:83]
	v_mfma_f32_16x16x32_bf16 v[68:71], v[168:171], v[232:235], v[68:71]
	v_mfma_f32_16x16x32_bf16 v[64:67], v[176:179], v[232:235], v[64:67]
	s_barrier
	s_add_i32 s16, s31, s38
	v_lshl_add_u64 v[198:199], v[198:199], 0, s[12:13]
	s_mov_b32 m0, s16
	global_load_lds_dwordx4 v[198:199], off
	v_lshl_add_u64 v[198:199], v[202:203], 0, s[12:13]
	s_add_i32 m0, s16, 0x2000
	s_add_i32 s16, s35, s38
	global_load_lds_dwordx4 v[198:199], off
	v_lshl_add_u64 v[198:199], v[236:237], 0, s[12:13]
	s_mov_b32 m0, s16
	s_nop 0
	global_load_lds_dwordx4 v[198:199], off
	v_lshl_add_u64 v[198:199], v[238:239], 0, s[12:13]
	s_add_i32 m0, s16, 0x2000
	s_nop 0
	global_load_lds_dwordx4 v[198:199], off
	v_lshl_add_u64 v[198:199], v[240:241], 0, s[12:13]
	s_mov_b32 m0, s47
	s_nop 0
	global_load_lds_dwordx4 v[198:199], off
	v_lshl_add_u64 v[198:199], v[242:243], 0, s[12:13]
	s_mov_b32 m0, s48
	s_nop 0
	global_load_lds_dwordx4 v[198:199], off
	ds_read_b128 v[194:197], v166 offset:49152
	ds_read_b128 v[206:209], v166 offset:50176
	ds_read_b128 v[210:213], v166 offset:51200
	ds_read_b128 v[214:217], v166 offset:52224
	ds_read_b128 v[220:223], v166 offset:53248
	ds_read_b128 v[224:227], v166 offset:54272
	ds_read_b128 v[228:231], v166 offset:55296
	ds_read_b128 v[232:235], v166 offset:56320
	s_waitcnt vmcnt(8)
	s_waitcnt lgkmcnt(0)
	s_barrier
	s_waitcnt lgkmcnt(0)
	v_mfma_f32_16x16x32_bf16 v[60:63], v[144:147], v[194:197], v[60:63]
	s_add_u32 s0, s0, 0x100
	v_mfma_f32_16x16x32_bf16 v[56:59], v[152:155], v[194:197], v[56:59]
	s_addc_u32 s1, s1, 0
	v_mfma_f32_16x16x32_bf16 v[44:47], v[144:147], v[210:213], v[44:47]
	s_add_u32 s10, s10, 0x100
	v_mfma_f32_16x16x32_bf16 v[40:43], v[152:155], v[210:213], v[40:43]
	s_addc_u32 s11, s11, 0
	v_mfma_f32_16x16x32_bf16 v[28:31], v[144:147], v[220:223], v[28:31]
	s_mov_b32 s16, s30
	v_mfma_f32_16x16x32_bf16 v[24:27], v[152:155], v[220:223], v[24:27]
	s_cmp_ge_i32 s30, s49
	v_mfma_f32_16x16x32_bf16 v[12:15], v[144:147], v[228:231], v[12:15]
	s_cselect_b32 s99, 1, 0
	v_mfma_f32_16x16x32_bf16 v[8:11], v[152:155], v[228:231], v[8:11]
	s_add_i32 s30, s16, 2
	v_mfma_f32_16x16x32_bf16 v[60:63], v[148:151], v[206:209], v[60:63]
	s_add_u32 s31, s0, 0x80
	v_mfma_f32_16x16x32_bf16 v[56:59], v[156:159], v[206:209], v[56:59]
	s_addc_u32 s17, s1, 0
	v_mfma_f32_16x16x32_bf16 v[44:47], v[148:151], v[214:217], v[44:47]
	s_add_i32 s35, 0, 0x10000
	v_mfma_f32_16x16x32_bf16 v[40:43], v[156:159], v[214:217], v[40:43]
	s_cmp_eq_u32 s57, s16
	v_mfma_f32_16x16x32_bf16 v[28:31], v[148:151], v[224:227], v[28:31]
	s_cselect_b32 s17, s27, s17
	v_mfma_f32_16x16x32_bf16 v[24:27], v[156:159], v[224:227], v[24:27]
	s_cselect_b32 s16, s26, s31
	v_mfma_f32_16x16x32_bf16 v[12:15], v[148:151], v[232:235], v[12:15]
	s_cselect_b32 s43, s29, s11
	v_mfma_f32_16x16x32_bf16 v[8:11], v[156:159], v[232:235], v[8:11]
	s_cselect_b32 s42, s28, s10
	v_mfma_f32_16x16x32_bf16 v[52:55], v[160:163], v[194:197], v[52:55]
	s_add_i32 s31, 0, 0x14000
	v_mfma_f32_16x16x32_bf16 v[48:51], v[172:175], v[194:197], v[48:51]
	v_mfma_f32_16x16x32_bf16 v[36:39], v[160:163], v[210:213], v[36:39]
	v_mfma_f32_16x16x32_bf16 v[32:35], v[172:175], v[210:213], v[32:35]
	v_mfma_f32_16x16x32_bf16 v[20:23], v[160:163], v[220:223], v[20:23]
	v_mfma_f32_16x16x32_bf16 v[16:19], v[172:175], v[220:223], v[16:19]
	v_mfma_f32_16x16x32_bf16 v[4:7], v[160:163], v[228:231], v[4:7]
	v_mfma_f32_16x16x32_bf16 v[0:3], v[172:175], v[228:231], v[0:3]
	v_mfma_f32_16x16x32_bf16 v[52:55], v[168:171], v[206:209], v[52:55]
	v_mfma_f32_16x16x32_bf16 v[48:51], v[176:179], v[206:209], v[48:51]
	v_mfma_f32_16x16x32_bf16 v[36:39], v[168:171], v[214:217], v[36:39]
	v_mfma_f32_16x16x32_bf16 v[32:35], v[176:179], v[214:217], v[32:35]
	v_mfma_f32_16x16x32_bf16 v[20:23], v[168:171], v[224:227], v[20:23]
	v_mfma_f32_16x16x32_bf16 v[16:19], v[176:179], v[224:227], v[16:19]
	v_mfma_f32_16x16x32_bf16 v[4:7], v[168:171], v[232:235], v[4:7]
	v_mfma_f32_16x16x32_bf16 v[0:3], v[176:179], v[232:235], v[0:3]
	s_barrier
	s_cmp_lg_u32 s99, 0
	s_cbranch_scc1 .Lpeelx_12
.LBB0_844:
	v_lshl_add_u64 v[198:199], s[0:1], 0, v[140:141]
	s_add_i32 m0, s39, 0xc000
	global_load_lds_dwordx4 v[198:199], off
	v_lshl_add_u64 v[198:199], s[0:1], 0, v[142:143]
	s_add_i32 m0, s39, 0xe000
	s_nop 0
	global_load_lds_dwordx4 v[198:199], off
	v_add_u32_e32 v156, s35, v164
	v_add_u32_e32 v167, s31, v164
	ds_read_b128 v[144:147], v156
	ds_read_b128 v[148:151], v156 offset:1024
	ds_read_b128 v[152:155], v156 offset:2048
	ds_read_b128 v[156:159], v156 offset:3072
	ds_read_b128 v[160:163], v167
	ds_read_b128 v[168:171], v167 offset:1024
	ds_read_b128 v[172:175], v167 offset:2048
	ds_read_b128 v[176:179], v167 offset:3072
	ds_read_b128 v[194:197], v166
	ds_read_b128 v[206:209], v166 offset:1024
	ds_read_b128 v[210:213], v166 offset:2048
	ds_read_b128 v[214:217], v166 offset:3072
	ds_read_b128 v[220:223], v166 offset:4096
	ds_read_b128 v[224:227], v166 offset:5120
	ds_read_b128 v[228:231], v166 offset:6144
	ds_read_b128 v[232:235], v166 offset:7168
	s_waitcnt vmcnt(8)
	s_waitcnt lgkmcnt(0)
	s_barrier
	s_waitcnt lgkmcnt(0)
	v_mfma_f32_16x16x32_bf16 v[124:127], v[144:147], v[194:197], v[124:127]
	v_mfma_f32_16x16x32_bf16 v[120:123], v[152:155], v[194:197], v[120:123]
	v_mfma_f32_16x16x32_bf16 v[108:111], v[144:147], v[210:213], v[108:111]
	v_mfma_f32_16x16x32_bf16 v[104:107], v[152:155], v[210:213], v[104:107]
	v_mfma_f32_16x16x32_bf16 v[92:95], v[144:147], v[220:223], v[92:95]
	v_mfma_f32_16x16x32_bf16 v[88:91], v[152:155], v[220:223], v[88:91]
	v_mfma_f32_16x16x32_bf16 v[76:79], v[144:147], v[228:231], v[76:79]
	v_mfma_f32_16x16x32_bf16 v[72:75], v[152:155], v[228:231], v[72:75]
	v_mfma_f32_16x16x32_bf16 v[124:127], v[148:151], v[206:209], v[124:127]
	v_mfma_f32_16x16x32_bf16 v[120:123], v[156:159], v[206:209], v[120:123]
	v_mfma_f32_16x16x32_bf16 v[108:111], v[148:151], v[214:217], v[108:111]
	v_mfma_f32_16x16x32_bf16 v[104:107], v[156:159], v[214:217], v[104:107]
	v_mfma_f32_16x16x32_bf16 v[92:95], v[148:151], v[224:227], v[92:95]
	v_mfma_f32_16x16x32_bf16 v[88:91], v[156:159], v[224:227], v[88:91]
	v_mfma_f32_16x16x32_bf16 v[76:79], v[148:151], v[232:235], v[76:79]
	v_mfma_f32_16x16x32_bf16 v[72:75], v[156:159], v[232:235], v[72:75]
	v_mfma_f32_16x16x32_bf16 v[116:119], v[160:163], v[194:197], v[116:119]
	v_mfma_f32_16x16x32_bf16 v[112:115], v[172:175], v[194:197], v[112:115]
	v_mfma_f32_16x16x32_bf16 v[100:103], v[160:163], v[210:213], v[100:103]
	v_mfma_f32_16x16x32_bf16 v[96:99], v[172:175], v[210:213], v[96:99]
	v_mfma_f32_16x16x32_bf16 v[84:87], v[160:163], v[220:223], v[84:87]
	v_mfma_f32_16x16x32_bf16 v[80:83], v[172:175], v[220:223], v[80:83]
	v_mfma_f32_16x16x32_bf16 v[68:71], v[160:163], v[228:231], v[68:71]
	v_mfma_f32_16x16x32_bf16 v[64:67], v[172:175], v[228:231], v[64:67]
	v_mfma_f32_16x16x32_bf16 v[116:119], v[168:171], v[206:209], v[116:119]
	v_mfma_f32_16x16x32_bf16 v[112:115], v[176:179], v[206:209], v[112:115]
	v_mfma_f32_16x16x32_bf16 v[100:103], v[168:171], v[214:217], v[100:103]
	v_mfma_f32_16x16x32_bf16 v[96:99], v[176:179], v[214:217], v[96:99]
	v_mfma_f32_16x16x32_bf16 v[84:87], v[168:171], v[224:227], v[84:87]
	v_mfma_f32_16x16x32_bf16 v[80:83], v[176:179], v[224:227], v[80:83]
	v_mfma_f32_16x16x32_bf16 v[68:71], v[168:171], v[232:235], v[68:71]
	v_mfma_f32_16x16x32_bf16 v[64:67], v[176:179], v[232:235], v[64:67]
	s_barrier
	s_add_i32 s35, s35, s38
	v_lshl_add_u64 v[198:199], s[42:43], 0, v[132:133]
	s_mov_b32 m0, s35
	global_load_lds_dwordx4 v[198:199], off
	s_add_i32 m0, s35, 0x2000
	v_lshl_add_u64 v[202:203], s[42:43], 0, v[128:129]
	s_add_u32 s42, s42, s6
	s_addc_u32 s43, s43, s7
	s_add_i32 s31, s31, s38
	global_load_lds_dwordx4 v[202:203], off
	v_lshl_add_u64 v[236:237], s[42:43], 0, v[132:133]
	s_mov_b32 m0, s31
	v_lshl_add_u64 v[238:239], s[42:43], 0, v[128:129]
	global_load_lds_dwordx4 v[236:237], off
	s_add_i32 m0, s31, 0x2000
	v_lshl_add_u64 v[240:241], s[16:17], 0, v[134:135]
	global_load_lds_dwordx4 v[238:239], off
	s_mov_b32 m0, s39
	v_lshl_add_u64 v[242:243], s[16:17], 0, v[130:131]
	global_load_lds_dwordx4 v[240:241], off
	s_mov_b32 m0, s44
	s_nop 0
	global_load_lds_dwordx4 v[242:243], off
	ds_read_b128 v[194:197], v166 offset:16384
	ds_read_b128 v[206:209], v166 offset:17408
	ds_read_b128 v[210:213], v166 offset:18432
	ds_read_b128 v[214:217], v166 offset:19456
	ds_read_b128 v[220:223], v166 offset:20480
	ds_read_b128 v[224:227], v166 offset:21504
	ds_read_b128 v[228:231], v166 offset:22528
	ds_read_b128 v[232:235], v166 offset:23552
	s_waitcnt vmcnt(8)
	s_waitcnt lgkmcnt(0)
	s_barrier
	s_waitcnt lgkmcnt(0)
	v_mfma_f32_16x16x32_bf16 v[60:63], v[144:147], v[194:197], v[60:63]
	v_mfma_f32_16x16x32_bf16 v[56:59], v[152:155], v[194:197], v[56:59]
	v_mfma_f32_16x16x32_bf16 v[44:47], v[144:147], v[210:213], v[44:47]
	v_mfma_f32_16x16x32_bf16 v[40:43], v[152:155], v[210:213], v[40:43]
	v_mfma_f32_16x16x32_bf16 v[28:31], v[144:147], v[220:223], v[28:31]
	v_mfma_f32_16x16x32_bf16 v[24:27], v[152:155], v[220:223], v[24:27]
	v_mfma_f32_16x16x32_bf16 v[12:15], v[144:147], v[228:231], v[12:15]
	v_mfma_f32_16x16x32_bf16 v[8:11], v[152:155], v[228:231], v[8:11]
	v_mfma_f32_16x16x32_bf16 v[60:63], v[148:151], v[206:209], v[60:63]
	v_mfma_f32_16x16x32_bf16 v[56:59], v[156:159], v[206:209], v[56:59]
	v_mfma_f32_16x16x32_bf16 v[44:47], v[148:151], v[214:217], v[44:47]
	v_mfma_f32_16x16x32_bf16 v[40:43], v[156:159], v[214:217], v[40:43]
	v_mfma_f32_16x16x32_bf16 v[28:31], v[148:151], v[224:227], v[28:31]
	v_mfma_f32_16x16x32_bf16 v[24:27], v[156:159], v[224:227], v[24:27]
	v_mfma_f32_16x16x32_bf16 v[12:15], v[148:151], v[232:235], v[12:15]
	v_mfma_f32_16x16x32_bf16 v[8:11], v[156:159], v[232:235], v[8:11]
	v_mfma_f32_16x16x32_bf16 v[52:55], v[160:163], v[194:197], v[52:55]
	v_mfma_f32_16x16x32_bf16 v[48:51], v[172:175], v[194:197], v[48:51]
	v_mfma_f32_16x16x32_bf16 v[36:39], v[160:163], v[210:213], v[36:39]
	v_mfma_f32_16x16x32_bf16 v[32:35], v[172:175], v[210:213], v[32:35]
	v_mfma_f32_16x16x32_bf16 v[20:23], v[160:163], v[220:223], v[20:23]
	v_mfma_f32_16x16x32_bf16 v[16:19], v[172:175], v[220:223], v[16:19]
	v_mfma_f32_16x16x32_bf16 v[4:7], v[160:163], v[228:231], v[4:7]
	v_mfma_f32_16x16x32_bf16 v[0:3], v[172:175], v[228:231], v[0:3]
	v_mfma_f32_16x16x32_bf16 v[52:55], v[168:171], v[206:209], v[52:55]
	v_mfma_f32_16x16x32_bf16 v[48:51], v[176:179], v[206:209], v[48:51]
	v_mfma_f32_16x16x32_bf16 v[36:39], v[168:171], v[214:217], v[36:39]
	v_mfma_f32_16x16x32_bf16 v[32:35], v[176:179], v[214:217], v[32:35]
	v_mfma_f32_16x16x32_bf16 v[20:23], v[168:171], v[224:227], v[20:23]
	v_mfma_f32_16x16x32_bf16 v[16:19], v[176:179], v[224:227], v[16:19]
	v_mfma_f32_16x16x32_bf16 v[4:7], v[168:171], v[232:235], v[4:7]
	v_mfma_f32_16x16x32_bf16 v[0:3], v[176:179], v[232:235], v[0:3]
	s_barrier
	s_add_i32 s31, 0, 0x18000
	s_add_i32 s35, 0, 0x1c000
	s_add_u32 s16, s16, s6
	s_addc_u32 s17, s17, s7
	s_mov_b32 m0, s45
	v_lshl_add_u64 v[244:245], s[16:17], 0, v[134:135]
	global_load_lds_dwordx4 v[244:245], off
	v_lshl_add_u64 v[244:245], s[16:17], 0, v[130:131]
	s_mov_b32 m0, s46
	s_nop 0
	global_load_lds_dwordx4 v[244:245], off
	v_add_u32_e32 v156, s31, v164
	v_add_u32_e32 v167, s35, v164
	ds_read_b128 v[144:147], v156
	ds_read_b128 v[148:151], v156 offset:1024
	ds_read_b128 v[152:155], v156 offset:2048
	ds_read_b128 v[156:159], v156 offset:3072
	ds_read_b128 v[160:163], v167
	ds_read_b128 v[168:171], v167 offset:1024
	ds_read_b128 v[172:175], v167 offset:2048
	ds_read_b128 v[176:179], v167 offset:3072
	ds_read_b128 v[194:197], v166 offset:32768
	ds_read_b128 v[206:209], v166 offset:33792
	ds_read_b128 v[210:213], v166 offset:34816
	ds_read_b128 v[214:217], v166 offset:35840
	ds_read_b128 v[220:223], v166 offset:36864
	ds_read_b128 v[224:227], v166 offset:37888
	ds_read_b128 v[228:231], v166 offset:38912
	ds_read_b128 v[232:235], v166 offset:39936
	s_waitcnt vmcnt(8)
	s_waitcnt lgkmcnt(0)
	s_barrier
	s_waitcnt lgkmcnt(0)
	v_mfma_f32_16x16x32_bf16 v[124:127], v[144:147], v[194:197], v[124:127]
	v_mfma_f32_16x16x32_bf16 v[120:123], v[152:155], v[194:197], v[120:123]
	v_mfma_f32_16x16x32_bf16 v[108:111], v[144:147], v[210:213], v[108:111]
	v_mfma_f32_16x16x32_bf16 v[104:107], v[152:155], v[210:213], v[104:107]
	v_mfma_f32_16x16x32_bf16 v[92:95], v[144:147], v[220:223], v[92:95]
	v_mfma_f32_16x16x32_bf16 v[88:91], v[152:155], v[220:223], v[88:91]
	v_mfma_f32_16x16x32_bf16 v[76:79], v[144:147], v[228:231], v[76:79]
	v_mfma_f32_16x16x32_bf16 v[72:75], v[152:155], v[228:231], v[72:75]
	v_mfma_f32_16x16x32_bf16 v[124:127], v[148:151], v[206:209], v[124:127]
	v_mfma_f32_16x16x32_bf16 v[120:123], v[156:159], v[206:209], v[120:123]
	v_mfma_f32_16x16x32_bf16 v[108:111], v[148:151], v[214:217], v[108:111]
	v_mfma_f32_16x16x32_bf16 v[104:107], v[156:159], v[214:217], v[104:107]
	v_mfma_f32_16x16x32_bf16 v[92:95], v[148:151], v[224:227], v[92:95]
	v_mfma_f32_16x16x32_bf16 v[88:91], v[156:159], v[224:227], v[88:91]
	v_mfma_f32_16x16x32_bf16 v[76:79], v[148:151], v[232:235], v[76:79]
	v_mfma_f32_16x16x32_bf16 v[72:75], v[156:159], v[232:235], v[72:75]
	v_mfma_f32_16x16x32_bf16 v[116:119], v[160:163], v[194:197], v[116:119]
	v_mfma_f32_16x16x32_bf16 v[112:115], v[172:175], v[194:197], v[112:115]
	v_mfma_f32_16x16x32_bf16 v[100:103], v[160:163], v[210:213], v[100:103]
	v_mfma_f32_16x16x32_bf16 v[96:99], v[172:175], v[210:213], v[96:99]
	v_mfma_f32_16x16x32_bf16 v[84:87], v[160:163], v[220:223], v[84:87]
	v_mfma_f32_16x16x32_bf16 v[80:83], v[172:175], v[220:223], v[80:83]
	v_mfma_f32_16x16x32_bf16 v[68:71], v[160:163], v[228:231], v[68:71]
	v_mfma_f32_16x16x32_bf16 v[64:67], v[172:175], v[228:231], v[64:67]
	v_mfma_f32_16x16x32_bf16 v[116:119], v[168:171], v[206:209], v[116:119]
	v_mfma_f32_16x16x32_bf16 v[112:115], v[176:179], v[206:209], v[112:115]
	v_mfma_f32_16x16x32_bf16 v[100:103], v[168:171], v[214:217], v[100:103]
	v_mfma_f32_16x16x32_bf16 v[96:99], v[176:179], v[214:217], v[96:99]
	v_mfma_f32_16x16x32_bf16 v[84:87], v[168:171], v[224:227], v[84:87]
	v_mfma_f32_16x16x32_bf16 v[80:83], v[176:179], v[224:227], v[80:83]
	v_mfma_f32_16x16x32_bf16 v[68:71], v[168:171], v[232:235], v[68:71]
	v_mfma_f32_16x16x32_bf16 v[64:67], v[176:179], v[232:235], v[64:67]
	s_barrier
	s_add_i32 s16, s31, s38
	v_lshl_add_u64 v[198:199], v[198:199], 0, s[12:13]
	s_mov_b32 m0, s16
	global_load_lds_dwordx4 v[198:199], off
	v_lshl_add_u64 v[198:199], v[202:203], 0, s[12:13]
	s_add_i32 m0, s16, 0x2000
	s_add_i32 s16, s35, s38
	global_load_lds_dwordx4 v[198:199], off
	v_lshl_add_u64 v[198:199], v[236:237], 0, s[12:13]
	s_mov_b32 m0, s16
	s_nop 0
	global_load_lds_dwordx4 v[198:199], off
	v_lshl_add_u64 v[198:199], v[238:239], 0, s[12:13]
	s_add_i32 m0, s16, 0x2000
	s_nop 0
	global_load_lds_dwordx4 v[198:199], off
	v_lshl_add_u64 v[198:199], v[240:241], 0, s[12:13]
	s_mov_b32 m0, s47
	s_nop 0
	global_load_lds_dwordx4 v[198:199], off
	v_lshl_add_u64 v[198:199], v[242:243], 0, s[12:13]
	s_mov_b32 m0, s48
	s_nop 0
	global_load_lds_dwordx4 v[198:199], off
	ds_read_b128 v[194:197], v166 offset:49152
	ds_read_b128 v[206:209], v166 offset:50176
	ds_read_b128 v[210:213], v166 offset:51200
	ds_read_b128 v[214:217], v166 offset:52224
	ds_read_b128 v[220:223], v166 offset:53248
	ds_read_b128 v[224:227], v166 offset:54272
	ds_read_b128 v[228:231], v166 offset:55296
	ds_read_b128 v[232:235], v166 offset:56320
	s_waitcnt vmcnt(8)
	s_waitcnt lgkmcnt(0)
	s_barrier
	s_waitcnt lgkmcnt(0)
	v_mfma_f32_16x16x32_bf16 v[60:63], v[144:147], v[194:197], v[60:63]
	s_add_u32 s0, s0, 0x100
	v_mfma_f32_16x16x32_bf16 v[56:59], v[152:155], v[194:197], v[56:59]
	s_addc_u32 s1, s1, 0
	v_mfma_f32_16x16x32_bf16 v[44:47], v[144:147], v[210:213], v[44:47]
	s_add_u32 s10, s10, 0x100
	v_mfma_f32_16x16x32_bf16 v[40:43], v[152:155], v[210:213], v[40:43]
	s_addc_u32 s11, s11, 0
	v_mfma_f32_16x16x32_bf16 v[28:31], v[144:147], v[220:223], v[28:31]
	s_mov_b32 s16, s30
	v_mfma_f32_16x16x32_bf16 v[24:27], v[152:155], v[220:223], v[24:27]
	s_cmp_ge_i32 s30, s49
	v_mfma_f32_16x16x32_bf16 v[12:15], v[144:147], v[228:231], v[12:15]
	s_cselect_b32 s99, 1, 0
	v_mfma_f32_16x16x32_bf16 v[8:11], v[152:155], v[228:231], v[8:11]
	s_add_i32 s30, s16, 2
	v_mfma_f32_16x16x32_bf16 v[60:63], v[148:151], v[206:209], v[60:63]
	s_add_u32 s31, s0, 0x80
	v_mfma_f32_16x16x32_bf16 v[56:59], v[156:159], v[206:209], v[56:59]
	s_addc_u32 s17, s1, 0
	v_mfma_f32_16x16x32_bf16 v[44:47], v[148:151], v[214:217], v[44:47]
	s_add_i32 s35, 0, 0x10000
	v_mfma_f32_16x16x32_bf16 v[40:43], v[156:159], v[214:217], v[40:43]
	s_cmp_eq_u32 s57, s16
	v_mfma_f32_16x16x32_bf16 v[28:31], v[148:151], v[224:227], v[28:31]
	s_cselect_b32 s17, s27, s17
	v_mfma_f32_16x16x32_bf16 v[24:27], v[156:159], v[224:227], v[24:27]
	s_cselect_b32 s16, s26, s31
	v_mfma_f32_16x16x32_bf16 v[12:15], v[148:151], v[232:235], v[12:15]
	s_cselect_b32 s43, s29, s11
	v_mfma_f32_16x16x32_bf16 v[8:11], v[156:159], v[232:235], v[8:11]
	s_cselect_b32 s42, s28, s10
	v_mfma_f32_16x16x32_bf16 v[52:55], v[160:163], v[194:197], v[52:55]
	s_add_i32 s31, 0, 0x14000
	v_mfma_f32_16x16x32_bf16 v[48:51], v[172:175], v[194:197], v[48:51]
	v_mfma_f32_16x16x32_bf16 v[36:39], v[160:163], v[210:213], v[36:39]
	v_mfma_f32_16x16x32_bf16 v[32:35], v[172:175], v[210:213], v[32:35]
	v_mfma_f32_16x16x32_bf16 v[20:23], v[160:163], v[220:223], v[20:23]
	v_mfma_f32_16x16x32_bf16 v[16:19], v[172:175], v[220:223], v[16:19]
	v_mfma_f32_16x16x32_bf16 v[4:7], v[160:163], v[228:231], v[4:7]
	v_mfma_f32_16x16x32_bf16 v[0:3], v[172:175], v[228:231], v[0:3]
	v_mfma_f32_16x16x32_bf16 v[52:55], v[168:171], v[206:209], v[52:55]
	v_mfma_f32_16x16x32_bf16 v[48:51], v[176:179], v[206:209], v[48:51]
	v_mfma_f32_16x16x32_bf16 v[36:39], v[168:171], v[214:217], v[36:39]
	v_mfma_f32_16x16x32_bf16 v[32:35], v[176:179], v[214:217], v[32:35]
	v_mfma_f32_16x16x32_bf16 v[20:23], v[168:171], v[224:227], v[20:23]
	v_mfma_f32_16x16x32_bf16 v[16:19], v[176:179], v[224:227], v[16:19]
	v_mfma_f32_16x16x32_bf16 v[4:7], v[168:171], v[232:235], v[4:7]
	v_mfma_f32_16x16x32_bf16 v[0:3], v[176:179], v[232:235], v[0:3]
	s_barrier
	s_cmp_lg_u32 s99, 0
	s_cbranch_scc0 .LBB0_844

.Llbb_9:
	s_add_i32 s30, s16, 2
	s_add_u32 s31, s28, 0x80
	s_addc_u32 s17, s29, 0
	s_add_i32 s62, 0, 0x10000
	s_cmp_eq_u32 s56, s16
	s_cselect_b32 s17, s25, s17
	s_cselect_b32 s16, s24, s31
	s_cselect_b32 s45, s27, s11
	s_cselect_b32 s44, s26, s10
	s_add_i32 s31, 0, 0x14000
	v_lshl_add_u64 v[178:179], s[28:29], 0, v[162:163]
	s_add_i32 m0, s37, 0xc000
	global_load_lds_dwordx4 v[178:179], off
	v_lshl_add_u64 v[178:179], s[28:29], 0, v[164:165]
	s_add_i32 m0, s37, 0xe000
	s_nop 0
	global_load_lds_dwordx4 v[178:179], off
	v_add_u32_e32 v140, s62, v199
	v_add_u32_e32 v166, s31, v199
	ds_read_b128 v[128:131], v140
	ds_read_b128 v[132:135], v140 offset:1024
	ds_read_b128 v[136:139], v140 offset:2048
	ds_read_b128 v[140:143], v140 offset:3072
	ds_read_b128 v[144:147], v166
	ds_read_b128 v[148:151], v166 offset:1024
	ds_read_b128 v[152:155], v166 offset:2048
	ds_read_b128 v[166:169], v166 offset:3072
	ds_read_b128 v[170:173], v206
	ds_read_b128 v[174:177], v206 offset:1024
	ds_read_b128 v[194:197], v206 offset:2048
	ds_read_b128 v[208:211], v206 offset:3072
	ds_read_b128 v[212:215], v206 offset:4096
	ds_read_b128 v[220:223], v206 offset:5120
	ds_read_b128 v[224:227], v206 offset:6144
	ds_read_b128 v[228:231], v206 offset:7168
	s_waitcnt vmcnt(8)
	s_waitcnt lgkmcnt(0)
	s_barrier
	s_waitcnt lgkmcnt(0)
	v_mfma_f32_16x16x32_bf16 v[120:123], v[128:131], v[170:173], 0
	v_mfma_f32_16x16x32_bf16 v[124:127], v[136:139], v[170:173], 0
	v_mfma_f32_16x16x32_bf16 v[108:111], v[128:131], v[194:197], 0
	v_mfma_f32_16x16x32_bf16 v[104:107], v[136:139], v[194:197], 0
	v_mfma_f32_16x16x32_bf16 v[92:95], v[128:131], v[212:215], 0
	v_mfma_f32_16x16x32_bf16 v[88:91], v[136:139], v[212:215], 0
	v_mfma_f32_16x16x32_bf16 v[76:79], v[128:131], v[224:227], 0
	v_mfma_f32_16x16x32_bf16 v[72:75], v[136:139], v[224:227], 0
	v_mfma_f32_16x16x32_bf16 v[120:123], v[132:135], v[174:177], v[120:123]
	v_mfma_f32_16x16x32_bf16 v[124:127], v[140:143], v[174:177], v[124:127]
	v_mfma_f32_16x16x32_bf16 v[108:111], v[132:135], v[208:211], v[108:111]
	v_mfma_f32_16x16x32_bf16 v[104:107], v[140:143], v[208:211], v[104:107]
	v_mfma_f32_16x16x32_bf16 v[92:95], v[132:135], v[220:223], v[92:95]
	v_mfma_f32_16x16x32_bf16 v[88:91], v[140:143], v[220:223], v[88:91]
	v_mfma_f32_16x16x32_bf16 v[76:79], v[132:135], v[228:231], v[76:79]
	v_mfma_f32_16x16x32_bf16 v[72:75], v[140:143], v[228:231], v[72:75]
	v_mfma_f32_16x16x32_bf16 v[116:119], v[144:147], v[170:173], 0
	v_mfma_f32_16x16x32_bf16 v[112:115], v[152:155], v[170:173], 0
	v_mfma_f32_16x16x32_bf16 v[100:103], v[144:147], v[194:197], 0
	v_mfma_f32_16x16x32_bf16 v[96:99], v[152:155], v[194:197], 0
	v_mfma_f32_16x16x32_bf16 v[84:87], v[144:147], v[212:215], 0
	v_mfma_f32_16x16x32_bf16 v[80:83], v[152:155], v[212:215], 0
	v_mfma_f32_16x16x32_bf16 v[68:71], v[144:147], v[224:227], 0
	v_mfma_f32_16x16x32_bf16 v[64:67], v[152:155], v[224:227], 0
	v_mfma_f32_16x16x32_bf16 v[116:119], v[148:151], v[174:177], v[116:119]
	v_mfma_f32_16x16x32_bf16 v[112:115], v[166:169], v[174:177], v[112:115]
	v_mfma_f32_16x16x32_bf16 v[100:103], v[148:151], v[208:211], v[100:103]
	v_mfma_f32_16x16x32_bf16 v[96:99], v[166:169], v[208:211], v[96:99]
	v_mfma_f32_16x16x32_bf16 v[84:87], v[148:151], v[220:223], v[84:87]
	v_mfma_f32_16x16x32_bf16 v[80:83], v[166:169], v[220:223], v[80:83]
	v_mfma_f32_16x16x32_bf16 v[68:71], v[148:151], v[228:231], v[68:71]
	v_mfma_f32_16x16x32_bf16 v[64:67], v[166:169], v[228:231], v[64:67]
	s_barrier
	s_add_i32 s62, s62, s36
	v_lshl_add_u64 v[178:179], s[44:45], 0, v[180:181]
	s_mov_b32 m0, s62
	global_load_lds_dwordx4 v[178:179], off
	s_add_i32 m0, s62, 0x2000
	v_lshl_add_u64 v[202:203], s[44:45], 0, v[156:157]
	s_add_u32 s44, s44, s6
	s_addc_u32 s45, s45, s7
	s_add_i32 s31, s31, s36
	global_load_lds_dwordx4 v[202:203], off
	v_lshl_add_u64 v[216:217], s[44:45], 0, v[180:181]
	s_mov_b32 m0, s31
	v_lshl_add_u64 v[232:233], s[44:45], 0, v[156:157]
	global_load_lds_dwordx4 v[216:217], off
	s_add_i32 m0, s31, 0x2000
	v_lshl_add_u64 v[234:235], s[16:17], 0, v[160:161]
	global_load_lds_dwordx4 v[232:233], off
	s_mov_b32 m0, s37
	v_lshl_add_u64 v[236:237], s[16:17], 0, v[158:159]
	global_load_lds_dwordx4 v[234:235], off
	s_mov_b32 m0, s38
	s_nop 0
	global_load_lds_dwordx4 v[236:237], off
	ds_read_b128 v[170:173], v206 offset:16384
	ds_read_b128 v[174:177], v206 offset:17408
	ds_read_b128 v[194:197], v206 offset:18432
	ds_read_b128 v[208:211], v206 offset:19456
	ds_read_b128 v[212:215], v206 offset:20480
	ds_read_b128 v[220:223], v206 offset:21504
	ds_read_b128 v[224:227], v206 offset:22528
	ds_read_b128 v[228:231], v206 offset:23552
	s_waitcnt vmcnt(8)
	s_waitcnt lgkmcnt(0)
	s_barrier
	s_waitcnt lgkmcnt(0)
	v_mfma_f32_16x16x32_bf16 v[60:63], v[128:131], v[170:173], 0
	v_mfma_f32_16x16x32_bf16 v[56:59], v[136:139], v[170:173], 0
	v_mfma_f32_16x16x32_bf16 v[44:47], v[128:131], v[194:197], 0
	v_mfma_f32_16x16x32_bf16 v[40:43], v[136:139], v[194:197], 0
	v_mfma_f32_16x16x32_bf16 v[28:31], v[128:131], v[212:215], 0
	v_mfma_f32_16x16x32_bf16 v[24:27], v[136:139], v[212:215], 0
	v_mfma_f32_16x16x32_bf16 v[12:15], v[128:131], v[224:227], 0
	v_mfma_f32_16x16x32_bf16 v[8:11], v[136:139], v[224:227], 0
	v_mfma_f32_16x16x32_bf16 v[60:63], v[132:135], v[174:177], v[60:63]
	v_mfma_f32_16x16x32_bf16 v[56:59], v[140:143], v[174:177], v[56:59]
	v_mfma_f32_16x16x32_bf16 v[44:47], v[132:135], v[208:211], v[44:47]
	v_mfma_f32_16x16x32_bf16 v[40:43], v[140:143], v[208:211], v[40:43]
	v_mfma_f32_16x16x32_bf16 v[28:31], v[132:135], v[220:223], v[28:31]
	v_mfma_f32_16x16x32_bf16 v[24:27], v[140:143], v[220:223], v[24:27]
	v_mfma_f32_16x16x32_bf16 v[12:15], v[132:135], v[228:231], v[12:15]
	v_mfma_f32_16x16x32_bf16 v[8:11], v[140:143], v[228:231], v[8:11]
	v_mfma_f32_16x16x32_bf16 v[52:55], v[144:147], v[170:173], 0
	v_mfma_f32_16x16x32_bf16 v[48:51], v[152:155], v[170:173], 0
	v_mfma_f32_16x16x32_bf16 v[36:39], v[144:147], v[194:197], 0
	v_mfma_f32_16x16x32_bf16 v[32:35], v[152:155], v[194:197], 0
	v_mfma_f32_16x16x32_bf16 v[20:23], v[144:147], v[212:215], 0
	v_mfma_f32_16x16x32_bf16 v[16:19], v[152:155], v[212:215], 0
	v_mfma_f32_16x16x32_bf16 v[4:7], v[144:147], v[224:227], 0
	v_mfma_f32_16x16x32_bf16 v[0:3], v[152:155], v[224:227], 0
	v_mfma_f32_16x16x32_bf16 v[52:55], v[148:151], v[174:177], v[52:55]
	v_mfma_f32_16x16x32_bf16 v[48:51], v[166:169], v[174:177], v[48:51]
	v_mfma_f32_16x16x32_bf16 v[36:39], v[148:151], v[208:211], v[36:39]
	v_mfma_f32_16x16x32_bf16 v[32:35], v[166:169], v[208:211], v[32:35]
	v_mfma_f32_16x16x32_bf16 v[20:23], v[148:151], v[220:223], v[20:23]
	v_mfma_f32_16x16x32_bf16 v[16:19], v[166:169], v[220:223], v[16:19]
	v_mfma_f32_16x16x32_bf16 v[4:7], v[148:151], v[228:231], v[4:7]
	v_mfma_f32_16x16x32_bf16 v[0:3], v[166:169], v[228:231], v[0:3]
	s_barrier
	s_add_i32 s31, 0, 0x18000
	s_add_i32 s44, 0, 0x1c000
	s_add_u32 s16, s16, s6
	s_addc_u32 s17, s17, s7
	s_mov_b32 m0, s39
	v_lshl_add_u64 v[238:239], s[16:17], 0, v[160:161]
	global_load_lds_dwordx4 v[238:239], off
	v_lshl_add_u64 v[238:239], s[16:17], 0, v[158:159]
	s_mov_b32 m0, s46
	s_nop 0
	global_load_lds_dwordx4 v[238:239], off
	v_add_u32_e32 v140, s31, v199
	v_add_u32_e32 v166, s44, v199
	ds_read_b128 v[128:131], v140
	ds_read_b128 v[132:135], v140 offset:1024
	ds_read_b128 v[136:139], v140 offset:2048
	ds_read_b128 v[140:143], v140 offset:3072
	ds_read_b128 v[144:147], v166
	ds_read_b128 v[148:151], v166 offset:1024
	ds_read_b128 v[152:155], v166 offset:2048
	ds_read_b128 v[166:169], v166 offset:3072
	ds_read_b128 v[170:173], v206 offset:32768
	ds_read_b128 v[174:177], v206 offset:33792
	ds_read_b128 v[194:197], v206 offset:34816
	ds_read_b128 v[208:211], v206 offset:35840
	ds_read_b128 v[212:215], v206 offset:36864
	ds_read_b128 v[220:223], v206 offset:37888
	ds_read_b128 v[224:227], v206 offset:38912
	ds_read_b128 v[228:231], v206 offset:39936
	s_waitcnt vmcnt(8)
	s_waitcnt lgkmcnt(0)
	s_barrier
	s_waitcnt lgkmcnt(0)
	v_mfma_f32_16x16x32_bf16 v[120:123], v[128:131], v[170:173], v[120:123]
	v_mfma_f32_16x16x32_bf16 v[124:127], v[136:139], v[170:173], v[124:127]
	v_mfma_f32_16x16x32_bf16 v[108:111], v[128:131], v[194:197], v[108:111]
	v_mfma_f32_16x16x32_bf16 v[104:107], v[136:139], v[194:197], v[104:107]
	v_mfma_f32_16x16x32_bf16 v[92:95], v[128:131], v[212:215], v[92:95]
	v_mfma_f32_16x16x32_bf16 v[88:91], v[136:139], v[212:215], v[88:91]
	v_mfma_f32_16x16x32_bf16 v[76:79], v[128:131], v[224:227], v[76:79]
	v_mfma_f32_16x16x32_bf16 v[72:75], v[136:139], v[224:227], v[72:75]
	v_mfma_f32_16x16x32_bf16 v[120:123], v[132:135], v[174:177], v[120:123]
	v_mfma_f32_16x16x32_bf16 v[124:127], v[140:143], v[174:177], v[124:127]
	v_mfma_f32_16x16x32_bf16 v[108:111], v[132:135], v[208:211], v[108:111]
	v_mfma_f32_16x16x32_bf16 v[104:107], v[140:143], v[208:211], v[104:107]
	v_mfma_f32_16x16x32_bf16 v[92:95], v[132:135], v[220:223], v[92:95]
	v_mfma_f32_16x16x32_bf16 v[88:91], v[140:143], v[220:223], v[88:91]
	v_mfma_f32_16x16x32_bf16 v[76:79], v[132:135], v[228:231], v[76:79]
	v_mfma_f32_16x16x32_bf16 v[72:75], v[140:143], v[228:231], v[72:75]
	v_mfma_f32_16x16x32_bf16 v[116:119], v[144:147], v[170:173], v[116:119]
	v_mfma_f32_16x16x32_bf16 v[112:115], v[152:155], v[170:173], v[112:115]
	v_mfma_f32_16x16x32_bf16 v[100:103], v[144:147], v[194:197], v[100:103]
	v_mfma_f32_16x16x32_bf16 v[96:99], v[152:155], v[194:197], v[96:99]
	v_mfma_f32_16x16x32_bf16 v[84:87], v[144:147], v[212:215], v[84:87]
	v_mfma_f32_16x16x32_bf16 v[80:83], v[152:155], v[212:215], v[80:83]
	v_mfma_f32_16x16x32_bf16 v[68:71], v[144:147], v[224:227], v[68:71]
	v_mfma_f32_16x16x32_bf16 v[64:67], v[152:155], v[224:227], v[64:67]
	v_mfma_f32_16x16x32_bf16 v[116:119], v[148:151], v[174:177], v[116:119]
	v_mfma_f32_16x16x32_bf16 v[112:115], v[166:169], v[174:177], v[112:115]
	v_mfma_f32_16x16x32_bf16 v[100:103], v[148:151], v[208:211], v[100:103]
	v_mfma_f32_16x16x32_bf16 v[96:99], v[166:169], v[208:211], v[96:99]
	v_mfma_f32_16x16x32_bf16 v[84:87], v[148:151], v[220:223], v[84:87]
	v_mfma_f32_16x16x32_bf16 v[80:83], v[166:169], v[220:223], v[80:83]
	v_mfma_f32_16x16x32_bf16 v[68:71], v[148:151], v[228:231], v[68:71]
	v_mfma_f32_16x16x32_bf16 v[64:67], v[166:169], v[228:231], v[64:67]
	s_barrier
	s_add_i32 s16, s31, s36
	v_lshl_add_u64 v[178:179], v[178:179], 0, s[12:13]
	s_mov_b32 m0, s16
	global_load_lds_dwordx4 v[178:179], off
	v_lshl_add_u64 v[178:179], v[202:203], 0, s[12:13]
	s_add_i32 m0, s16, 0x2000
	s_add_i32 s16, s44, s36
	global_load_lds_dwordx4 v[178:179], off
	v_lshl_add_u64 v[178:179], v[216:217], 0, s[12:13]
	s_mov_b32 m0, s16
	s_nop 0
	global_load_lds_dwordx4 v[178:179], off
	v_lshl_add_u64 v[178:179], v[232:233], 0, s[12:13]
	s_add_i32 m0, s16, 0x2000
	s_nop 0
	global_load_lds_dwordx4 v[178:179], off
	v_lshl_add_u64 v[178:179], v[234:235], 0, s[12:13]
	s_mov_b32 m0, s49
	s_nop 0
	global_load_lds_dwordx4 v[178:179], off
	v_lshl_add_u64 v[178:179], v[236:237], 0, s[12:13]
	s_mov_b32 m0, s52
	s_nop 0
	global_load_lds_dwordx4 v[178:179], off
	ds_read_b128 v[170:173], v206 offset:49152
	ds_read_b128 v[174:177], v206 offset:50176
	ds_read_b128 v[194:197], v206 offset:51200
	ds_read_b128 v[208:211], v206 offset:52224
	ds_read_b128 v[212:215], v206 offset:53248
	ds_read_b128 v[220:223], v206 offset:54272
	ds_read_b128 v[224:227], v206 offset:55296
	ds_read_b128 v[228:231], v206 offset:56320
	s_waitcnt vmcnt(8)
	s_waitcnt lgkmcnt(0)
	s_barrier
	s_waitcnt lgkmcnt(0)
	v_mfma_f32_16x16x32_bf16 v[60:63], v[128:131], v[170:173], v[60:63]
	s_add_u32 s28, s28, 0x100
	v_mfma_f32_16x16x32_bf16 v[56:59], v[136:139], v[170:173], v[56:59]
	s_addc_u32 s29, s29, 0
	v_mfma_f32_16x16x32_bf16 v[44:47], v[128:131], v[194:197], v[44:47]
	s_add_u32 s10, s10, 0x100
	v_mfma_f32_16x16x32_bf16 v[40:43], v[136:139], v[194:197], v[40:43]
	s_addc_u32 s11, s11, 0
	v_mfma_f32_16x16x32_bf16 v[28:31], v[128:131], v[212:215], v[28:31]
	s_mov_b32 s16, s30
	v_mfma_f32_16x16x32_bf16 v[24:27], v[136:139], v[212:215], v[24:27]
	s_cmp_ge_i32 s30, s48
	v_mfma_f32_16x16x32_bf16 v[12:15], v[128:131], v[224:227], v[12:15]
	s_cselect_b32 s99, 1, 0
	v_mfma_f32_16x16x32_bf16 v[8:11], v[136:139], v[224:227], v[8:11]
	s_add_i32 s30, s16, 2
	v_mfma_f32_16x16x32_bf16 v[60:63], v[132:135], v[174:177], v[60:63]
	s_add_u32 s31, s28, 0x80
	v_mfma_f32_16x16x32_bf16 v[56:59], v[140:143], v[174:177], v[56:59]
	s_addc_u32 s17, s29, 0
	v_mfma_f32_16x16x32_bf16 v[44:47], v[132:135], v[208:211], v[44:47]
	s_add_i32 s62, 0, 0x10000
	v_mfma_f32_16x16x32_bf16 v[40:43], v[140:143], v[208:211], v[40:43]
	s_cmp_eq_u32 s56, s16
	v_mfma_f32_16x16x32_bf16 v[28:31], v[132:135], v[220:223], v[28:31]
	s_cselect_b32 s17, s25, s17
	v_mfma_f32_16x16x32_bf16 v[24:27], v[140:143], v[220:223], v[24:27]
	s_cselect_b32 s16, s24, s31
	v_mfma_f32_16x16x32_bf16 v[12:15], v[132:135], v[228:231], v[12:15]
	s_cselect_b32 s45, s27, s11
	v_mfma_f32_16x16x32_bf16 v[8:11], v[140:143], v[228:231], v[8:11]
	s_cselect_b32 s44, s26, s10
	v_mfma_f32_16x16x32_bf16 v[52:55], v[144:147], v[170:173], v[52:55]
	s_add_i32 s31, 0, 0x14000
	v_mfma_f32_16x16x32_bf16 v[48:51], v[152:155], v[170:173], v[48:51]
	v_mfma_f32_16x16x32_bf16 v[36:39], v[144:147], v[194:197], v[36:39]
	v_mfma_f32_16x16x32_bf16 v[32:35], v[152:155], v[194:197], v[32:35]
	v_mfma_f32_16x16x32_bf16 v[20:23], v[144:147], v[212:215], v[20:23]
	v_mfma_f32_16x16x32_bf16 v[16:19], v[152:155], v[212:215], v[16:19]
	v_mfma_f32_16x16x32_bf16 v[4:7], v[144:147], v[224:227], v[4:7]
	v_mfma_f32_16x16x32_bf16 v[0:3], v[152:155], v[224:227], v[0:3]
	v_mfma_f32_16x16x32_bf16 v[52:55], v[148:151], v[174:177], v[52:55]
	v_mfma_f32_16x16x32_bf16 v[48:51], v[166:169], v[174:177], v[48:51]
	v_mfma_f32_16x16x32_bf16 v[36:39], v[148:151], v[208:211], v[36:39]
	v_mfma_f32_16x16x32_bf16 v[32:35], v[166:169], v[208:211], v[32:35]
	v_mfma_f32_16x16x32_bf16 v[20:23], v[148:151], v[220:223], v[20:23]
	v_mfma_f32_16x16x32_bf16 v[16:19], v[166:169], v[220:223], v[16:19]
	v_mfma_f32_16x16x32_bf16 v[4:7], v[148:151], v[228:231], v[4:7]
	v_mfma_f32_16x16x32_bf16 v[0:3], v[166:169], v[228:231], v[0:3]
	s_barrier
	s_cmp_lg_u32 s99, 0
	s_cbranch_scc1 .Lpeelx_13
.LBB0_1053:
	v_lshl_add_u64 v[178:179], s[28:29], 0, v[162:163]
	s_add_i32 m0, s37, 0xc000
	global_load_lds_dwordx4 v[178:179], off
	v_lshl_add_u64 v[178:179], s[28:29], 0, v[164:165]
	s_add_i32 m0, s37, 0xe000
	s_nop 0
	global_load_lds_dwordx4 v[178:179], off
	v_add_u32_e32 v140, s62, v199
	v_add_u32_e32 v166, s31, v199
	ds_read_b128 v[128:131], v140
	ds_read_b128 v[132:135], v140 offset:1024
	ds_read_b128 v[136:139], v140 offset:2048
	ds_read_b128 v[140:143], v140 offset:3072
	ds_read_b128 v[144:147], v166
	ds_read_b128 v[148:151], v166 offset:1024
	ds_read_b128 v[152:155], v166 offset:2048
	ds_read_b128 v[166:169], v166 offset:3072
	ds_read_b128 v[170:173], v206
	ds_read_b128 v[174:177], v206 offset:1024
	ds_read_b128 v[194:197], v206 offset:2048
	ds_read_b128 v[208:211], v206 offset:3072
	ds_read_b128 v[212:215], v206 offset:4096
	ds_read_b128 v[220:223], v206 offset:5120
	ds_read_b128 v[224:227], v206 offset:6144
	ds_read_b128 v[228:231], v206 offset:7168
	s_waitcnt vmcnt(8)
	s_waitcnt lgkmcnt(0)
	s_barrier
	s_waitcnt lgkmcnt(0)
	v_mfma_f32_16x16x32_bf16 v[120:123], v[128:131], v[170:173], v[120:123]
	v_mfma_f32_16x16x32_bf16 v[124:127], v[136:139], v[170:173], v[124:127]
	v_mfma_f32_16x16x32_bf16 v[108:111], v[128:131], v[194:197], v[108:111]
	v_mfma_f32_16x16x32_bf16 v[104:107], v[136:139], v[194:197], v[104:107]
	v_mfma_f32_16x16x32_bf16 v[92:95], v[128:131], v[212:215], v[92:95]
	v_mfma_f32_16x16x32_bf16 v[88:91], v[136:139], v[212:215], v[88:91]
	v_mfma_f32_16x16x32_bf16 v[76:79], v[128:131], v[224:227], v[76:79]
	v_mfma_f32_16x16x32_bf16 v[72:75], v[136:139], v[224:227], v[72:75]
	v_mfma_f32_16x16x32_bf16 v[120:123], v[132:135], v[174:177], v[120:123]
	v_mfma_f32_16x16x32_bf16 v[124:127], v[140:143], v[174:177], v[124:127]
	v_mfma_f32_16x16x32_bf16 v[108:111], v[132:135], v[208:211], v[108:111]
	v_mfma_f32_16x16x32_bf16 v[104:107], v[140:143], v[208:211], v[104:107]
	v_mfma_f32_16x16x32_bf16 v[92:95], v[132:135], v[220:223], v[92:95]
	v_mfma_f32_16x16x32_bf16 v[88:91], v[140:143], v[220:223], v[88:91]
	v_mfma_f32_16x16x32_bf16 v[76:79], v[132:135], v[228:231], v[76:79]
	v_mfma_f32_16x16x32_bf16 v[72:75], v[140:143], v[228:231], v[72:75]
	v_mfma_f32_16x16x32_bf16 v[116:119], v[144:147], v[170:173], v[116:119]
	v_mfma_f32_16x16x32_bf16 v[112:115], v[152:155], v[170:173], v[112:115]
	v_mfma_f32_16x16x32_bf16 v[100:103], v[144:147], v[194:197], v[100:103]
	v_mfma_f32_16x16x32_bf16 v[96:99], v[152:155], v[194:197], v[96:99]
	v_mfma_f32_16x16x32_bf16 v[84:87], v[144:147], v[212:215], v[84:87]
	v_mfma_f32_16x16x32_bf16 v[80:83], v[152:155], v[212:215], v[80:83]
	v_mfma_f32_16x16x32_bf16 v[68:71], v[144:147], v[224:227], v[68:71]
	v_mfma_f32_16x16x32_bf16 v[64:67], v[152:155], v[224:227], v[64:67]
	v_mfma_f32_16x16x32_bf16 v[116:119], v[148:151], v[174:177], v[116:119]
	v_mfma_f32_16x16x32_bf16 v[112:115], v[166:169], v[174:177], v[112:115]
	v_mfma_f32_16x16x32_bf16 v[100:103], v[148:151], v[208:211], v[100:103]
	v_mfma_f32_16x16x32_bf16 v[96:99], v[166:169], v[208:211], v[96:99]
	v_mfma_f32_16x16x32_bf16 v[84:87], v[148:151], v[220:223], v[84:87]
	v_mfma_f32_16x16x32_bf16 v[80:83], v[166:169], v[220:223], v[80:83]
	v_mfma_f32_16x16x32_bf16 v[68:71], v[148:151], v[228:231], v[68:71]
	v_mfma_f32_16x16x32_bf16 v[64:67], v[166:169], v[228:231], v[64:67]
	s_barrier
	s_add_i32 s62, s62, s36
	v_lshl_add_u64 v[178:179], s[44:45], 0, v[180:181]
	s_mov_b32 m0, s62
	global_load_lds_dwordx4 v[178:179], off
	s_add_i32 m0, s62, 0x2000
	v_lshl_add_u64 v[202:203], s[44:45], 0, v[156:157]
	s_add_u32 s44, s44, s6
	s_addc_u32 s45, s45, s7
	s_add_i32 s31, s31, s36
	global_load_lds_dwordx4 v[202:203], off
	v_lshl_add_u64 v[216:217], s[44:45], 0, v[180:181]
	s_mov_b32 m0, s31
	v_lshl_add_u64 v[232:233], s[44:45], 0, v[156:157]
	global_load_lds_dwordx4 v[216:217], off
	s_add_i32 m0, s31, 0x2000
	v_lshl_add_u64 v[234:235], s[16:17], 0, v[160:161]
	global_load_lds_dwordx4 v[232:233], off
	s_mov_b32 m0, s37
	v_lshl_add_u64 v[236:237], s[16:17], 0, v[158:159]
	global_load_lds_dwordx4 v[234:235], off
	s_mov_b32 m0, s38
	s_nop 0
	global_load_lds_dwordx4 v[236:237], off
	ds_read_b128 v[170:173], v206 offset:16384
	ds_read_b128 v[174:177], v206 offset:17408
	ds_read_b128 v[194:197], v206 offset:18432
	ds_read_b128 v[208:211], v206 offset:19456
	ds_read_b128 v[212:215], v206 offset:20480
	ds_read_b128 v[220:223], v206 offset:21504
	ds_read_b128 v[224:227], v206 offset:22528
	ds_read_b128 v[228:231], v206 offset:23552
	s_waitcnt vmcnt(8)
	s_waitcnt lgkmcnt(0)
	s_barrier
	s_waitcnt lgkmcnt(0)
	v_mfma_f32_16x16x32_bf16 v[60:63], v[128:131], v[170:173], v[60:63]
	v_mfma_f32_16x16x32_bf16 v[56:59], v[136:139], v[170:173], v[56:59]
	v_mfma_f32_16x16x32_bf16 v[44:47], v[128:131], v[194:197], v[44:47]
	v_mfma_f32_16x16x32_bf16 v[40:43], v[136:139], v[194:197], v[40:43]
	v_mfma_f32_16x16x32_bf16 v[28:31], v[128:131], v[212:215], v[28:31]
	v_mfma_f32_16x16x32_bf16 v[24:27], v[136:139], v[212:215], v[24:27]
	v_mfma_f32_16x16x32_bf16 v[12:15], v[128:131], v[224:227], v[12:15]
	v_mfma_f32_16x16x32_bf16 v[8:11], v[136:139], v[224:227], v[8:11]
	v_mfma_f32_16x16x32_bf16 v[60:63], v[132:135], v[174:177], v[60:63]
	v_mfma_f32_16x16x32_bf16 v[56:59], v[140:143], v[174:177], v[56:59]
	v_mfma_f32_16x16x32_bf16 v[44:47], v[132:135], v[208:211], v[44:47]
	v_mfma_f32_16x16x32_bf16 v[40:43], v[140:143], v[208:211], v[40:43]
	v_mfma_f32_16x16x32_bf16 v[28:31], v[132:135], v[220:223], v[28:31]
	v_mfma_f32_16x16x32_bf16 v[24:27], v[140:143], v[220:223], v[24:27]
	v_mfma_f32_16x16x32_bf16 v[12:15], v[132:135], v[228:231], v[12:15]
	v_mfma_f32_16x16x32_bf16 v[8:11], v[140:143], v[228:231], v[8:11]
	v_mfma_f32_16x16x32_bf16 v[52:55], v[144:147], v[170:173], v[52:55]
	v_mfma_f32_16x16x32_bf16 v[48:51], v[152:155], v[170:173], v[48:51]
	v_mfma_f32_16x16x32_bf16 v[36:39], v[144:147], v[194:197], v[36:39]
	v_mfma_f32_16x16x32_bf16 v[32:35], v[152:155], v[194:197], v[32:35]
	v_mfma_f32_16x16x32_bf16 v[20:23], v[144:147], v[212:215], v[20:23]
	v_mfma_f32_16x16x32_bf16 v[16:19], v[152:155], v[212:215], v[16:19]
	v_mfma_f32_16x16x32_bf16 v[4:7], v[144:147], v[224:227], v[4:7]
	v_mfma_f32_16x16x32_bf16 v[0:3], v[152:155], v[224:227], v[0:3]
	v_mfma_f32_16x16x32_bf16 v[52:55], v[148:151], v[174:177], v[52:55]
	v_mfma_f32_16x16x32_bf16 v[48:51], v[166:169], v[174:177], v[48:51]
	v_mfma_f32_16x16x32_bf16 v[36:39], v[148:151], v[208:211], v[36:39]
	v_mfma_f32_16x16x32_bf16 v[32:35], v[166:169], v[208:211], v[32:35]
	v_mfma_f32_16x16x32_bf16 v[20:23], v[148:151], v[220:223], v[20:23]
	v_mfma_f32_16x16x32_bf16 v[16:19], v[166:169], v[220:223], v[16:19]
	v_mfma_f32_16x16x32_bf16 v[4:7], v[148:151], v[228:231], v[4:7]
	v_mfma_f32_16x16x32_bf16 v[0:3], v[166:169], v[228:231], v[0:3]
	s_barrier
	s_add_i32 s31, 0, 0x18000
	s_add_i32 s44, 0, 0x1c000
	s_add_u32 s16, s16, s6
	s_addc_u32 s17, s17, s7
	s_mov_b32 m0, s39
	v_lshl_add_u64 v[238:239], s[16:17], 0, v[160:161]
	global_load_lds_dwordx4 v[238:239], off
	v_lshl_add_u64 v[238:239], s[16:17], 0, v[158:159]
	s_mov_b32 m0, s46
	s_nop 0
	global_load_lds_dwordx4 v[238:239], off
	v_add_u32_e32 v140, s31, v199
	v_add_u32_e32 v166, s44, v199
	ds_read_b128 v[128:131], v140
	ds_read_b128 v[132:135], v140 offset:1024
	ds_read_b128 v[136:139], v140 offset:2048
	ds_read_b128 v[140:143], v140 offset:3072
	ds_read_b128 v[144:147], v166
	ds_read_b128 v[148:151], v166 offset:1024
	ds_read_b128 v[152:155], v166 offset:2048
	ds_read_b128 v[166:169], v166 offset:3072
	ds_read_b128 v[170:173], v206 offset:32768
	ds_read_b128 v[174:177], v206 offset:33792
	ds_read_b128 v[194:197], v206 offset:34816
	ds_read_b128 v[208:211], v206 offset:35840
	ds_read_b128 v[212:215], v206 offset:36864
	ds_read_b128 v[220:223], v206 offset:37888
	ds_read_b128 v[224:227], v206 offset:38912
	ds_read_b128 v[228:231], v206 offset:39936
	s_waitcnt vmcnt(8)
	s_waitcnt lgkmcnt(0)
	s_barrier
	s_waitcnt lgkmcnt(0)
	v_mfma_f32_16x16x32_bf16 v[120:123], v[128:131], v[170:173], v[120:123]
	v_mfma_f32_16x16x32_bf16 v[124:127], v[136:139], v[170:173], v[124:127]
	v_mfma_f32_16x16x32_bf16 v[108:111], v[128:131], v[194:197], v[108:111]
	v_mfma_f32_16x16x32_bf16 v[104:107], v[136:139], v[194:197], v[104:107]
	v_mfma_f32_16x16x32_bf16 v[92:95], v[128:131], v[212:215], v[92:95]
	v_mfma_f32_16x16x32_bf16 v[88:91], v[136:139], v[212:215], v[88:91]
	v_mfma_f32_16x16x32_bf16 v[76:79], v[128:131], v[224:227], v[76:79]
	v_mfma_f32_16x16x32_bf16 v[72:75], v[136:139], v[224:227], v[72:75]
	v_mfma_f32_16x16x32_bf16 v[120:123], v[132:135], v[174:177], v[120:123]
	v_mfma_f32_16x16x32_bf16 v[124:127], v[140:143], v[174:177], v[124:127]
	v_mfma_f32_16x16x32_bf16 v[108:111], v[132:135], v[208:211], v[108:111]
	v_mfma_f32_16x16x32_bf16 v[104:107], v[140:143], v[208:211], v[104:107]
	v_mfma_f32_16x16x32_bf16 v[92:95], v[132:135], v[220:223], v[92:95]
	v_mfma_f32_16x16x32_bf16 v[88:91], v[140:143], v[220:223], v[88:91]
	v_mfma_f32_16x16x32_bf16 v[76:79], v[132:135], v[228:231], v[76:79]
	v_mfma_f32_16x16x32_bf16 v[72:75], v[140:143], v[228:231], v[72:75]
	v_mfma_f32_16x16x32_bf16 v[116:119], v[144:147], v[170:173], v[116:119]
	v_mfma_f32_16x16x32_bf16 v[112:115], v[152:155], v[170:173], v[112:115]
	v_mfma_f32_16x16x32_bf16 v[100:103], v[144:147], v[194:197], v[100:103]
	v_mfma_f32_16x16x32_bf16 v[96:99], v[152:155], v[194:197], v[96:99]
	v_mfma_f32_16x16x32_bf16 v[84:87], v[144:147], v[212:215], v[84:87]
	v_mfma_f32_16x16x32_bf16 v[80:83], v[152:155], v[212:215], v[80:83]
	v_mfma_f32_16x16x32_bf16 v[68:71], v[144:147], v[224:227], v[68:71]
	v_mfma_f32_16x16x32_bf16 v[64:67], v[152:155], v[224:227], v[64:67]
	v_mfma_f32_16x16x32_bf16 v[116:119], v[148:151], v[174:177], v[116:119]
	v_mfma_f32_16x16x32_bf16 v[112:115], v[166:169], v[174:177], v[112:115]
	v_mfma_f32_16x16x32_bf16 v[100:103], v[148:151], v[208:211], v[100:103]
	v_mfma_f32_16x16x32_bf16 v[96:99], v[166:169], v[208:211], v[96:99]
	v_mfma_f32_16x16x32_bf16 v[84:87], v[148:151], v[220:223], v[84:87]
	v_mfma_f32_16x16x32_bf16 v[80:83], v[166:169], v[220:223], v[80:83]
	v_mfma_f32_16x16x32_bf16 v[68:71], v[148:151], v[228:231], v[68:71]
	v_mfma_f32_16x16x32_bf16 v[64:67], v[166:169], v[228:231], v[64:67]
	s_barrier
	s_add_i32 s16, s31, s36
	v_lshl_add_u64 v[178:179], v[178:179], 0, s[12:13]
	s_mov_b32 m0, s16
	global_load_lds_dwordx4 v[178:179], off
	v_lshl_add_u64 v[178:179], v[202:203], 0, s[12:13]
	s_add_i32 m0, s16, 0x2000
	s_add_i32 s16, s44, s36
	global_load_lds_dwordx4 v[178:179], off
	v_lshl_add_u64 v[178:179], v[216:217], 0, s[12:13]
	s_mov_b32 m0, s16
	s_nop 0
	global_load_lds_dwordx4 v[178:179], off
	v_lshl_add_u64 v[178:179], v[232:233], 0, s[12:13]
	s_add_i32 m0, s16, 0x2000
	s_nop 0
	global_load_lds_dwordx4 v[178:179], off
	v_lshl_add_u64 v[178:179], v[234:235], 0, s[12:13]
	s_mov_b32 m0, s49
	s_nop 0
	global_load_lds_dwordx4 v[178:179], off
	v_lshl_add_u64 v[178:179], v[236:237], 0, s[12:13]
	s_mov_b32 m0, s52
	s_nop 0
	global_load_lds_dwordx4 v[178:179], off
	ds_read_b128 v[170:173], v206 offset:49152
	ds_read_b128 v[174:177], v206 offset:50176
	ds_read_b128 v[194:197], v206 offset:51200
	ds_read_b128 v[208:211], v206 offset:52224
	ds_read_b128 v[212:215], v206 offset:53248
	ds_read_b128 v[220:223], v206 offset:54272
	ds_read_b128 v[224:227], v206 offset:55296
	ds_read_b128 v[228:231], v206 offset:56320
	s_waitcnt vmcnt(8)
	s_waitcnt lgkmcnt(0)
	s_barrier
	s_waitcnt lgkmcnt(0)
	v_mfma_f32_16x16x32_bf16 v[60:63], v[128:131], v[170:173], v[60:63]
	s_add_u32 s28, s28, 0x100
	v_mfma_f32_16x16x32_bf16 v[56:59], v[136:139], v[170:173], v[56:59]
	s_addc_u32 s29, s29, 0
	v_mfma_f32_16x16x32_bf16 v[44:47], v[128:131], v[194:197], v[44:47]
	s_add_u32 s10, s10, 0x100
	v_mfma_f32_16x16x32_bf16 v[40:43], v[136:139], v[194:197], v[40:43]
	s_addc_u32 s11, s11, 0
	v_mfma_f32_16x16x32_bf16 v[28:31], v[128:131], v[212:215], v[28:31]
	s_mov_b32 s16, s30
	v_mfma_f32_16x16x32_bf16 v[24:27], v[136:139], v[212:215], v[24:27]
	s_cmp_ge_i32 s30, s48
	v_mfma_f32_16x16x32_bf16 v[12:15], v[128:131], v[224:227], v[12:15]
	s_cselect_b32 s99, 1, 0
	v_mfma_f32_16x16x32_bf16 v[8:11], v[136:139], v[224:227], v[8:11]
	s_add_i32 s30, s16, 2
	v_mfma_f32_16x16x32_bf16 v[60:63], v[132:135], v[174:177], v[60:63]
	s_add_u32 s31, s28, 0x80
	v_mfma_f32_16x16x32_bf16 v[56:59], v[140:143], v[174:177], v[56:59]
	s_addc_u32 s17, s29, 0
	v_mfma_f32_16x16x32_bf16 v[44:47], v[132:135], v[208:211], v[44:47]
	s_add_i32 s62, 0, 0x10000
	v_mfma_f32_16x16x32_bf16 v[40:43], v[140:143], v[208:211], v[40:43]
	s_cmp_eq_u32 s56, s16
	v_mfma_f32_16x16x32_bf16 v[28:31], v[132:135], v[220:223], v[28:31]
	s_cselect_b32 s17, s25, s17
	v_mfma_f32_16x16x32_bf16 v[24:27], v[140:143], v[220:223], v[24:27]
	s_cselect_b32 s16, s24, s31
	v_mfma_f32_16x16x32_bf16 v[12:15], v[132:135], v[228:231], v[12:15]
	s_cselect_b32 s45, s27, s11
	v_mfma_f32_16x16x32_bf16 v[8:11], v[140:143], v[228:231], v[8:11]
	s_cselect_b32 s44, s26, s10
	v_mfma_f32_16x16x32_bf16 v[52:55], v[144:147], v[170:173], v[52:55]
	s_add_i32 s31, 0, 0x14000
	v_mfma_f32_16x16x32_bf16 v[48:51], v[152:155], v[170:173], v[48:51]
	v_mfma_f32_16x16x32_bf16 v[36:39], v[144:147], v[194:197], v[36:39]
	v_mfma_f32_16x16x32_bf16 v[32:35], v[152:155], v[194:197], v[32:35]
	v_mfma_f32_16x16x32_bf16 v[20:23], v[144:147], v[212:215], v[20:23]
	v_mfma_f32_16x16x32_bf16 v[16:19], v[152:155], v[212:215], v[16:19]
	v_mfma_f32_16x16x32_bf16 v[4:7], v[144:147], v[224:227], v[4:7]
	v_mfma_f32_16x16x32_bf16 v[0:3], v[152:155], v[224:227], v[0:3]
	v_mfma_f32_16x16x32_bf16 v[52:55], v[148:151], v[174:177], v[52:55]
	v_mfma_f32_16x16x32_bf16 v[48:51], v[166:169], v[174:177], v[48:51]
	v_mfma_f32_16x16x32_bf16 v[36:39], v[148:151], v[208:211], v[36:39]
	v_mfma_f32_16x16x32_bf16 v[32:35], v[166:169], v[208:211], v[32:35]
	v_mfma_f32_16x16x32_bf16 v[20:23], v[148:151], v[220:223], v[20:23]
	v_mfma_f32_16x16x32_bf16 v[16:19], v[166:169], v[220:223], v[16:19]
	v_mfma_f32_16x16x32_bf16 v[4:7], v[148:151], v[228:231], v[4:7]
	v_mfma_f32_16x16x32_bf16 v[0:3], v[166:169], v[228:231], v[0:3]
	s_barrier
	s_cmp_lg_u32 s99, 0
	s_cbranch_scc0 .LBB0_1053

.Llbb_10:
	s_add_i32 s30, s16, 2
	s_add_u32 s31, s28, 0x80
	s_addc_u32 s17, s29, 0
	s_add_i32 s63, 0, 0x10000
	s_cmp_eq_u32 s56, s16
	s_cselect_b32 s17, s25, s17
	s_cselect_b32 s16, s24, s31
	s_cselect_b32 s45, s27, s11
	s_cselect_b32 s44, s26, s10
	s_add_i32 s31, 0, 0x14000
	v_lshl_add_u64 v[198:199], s[28:29], 0, v[138:139]
	s_add_i32 m0, s37, 0xc000
	global_load_lds_dwordx4 v[198:199], off
	v_lshl_add_u64 v[198:199], s[28:29], 0, v[140:141]
	s_add_i32 m0, s37, 0xe000
	s_nop 0
	global_load_lds_dwordx4 v[198:199], off
	v_add_u32_e32 v156, s63, v151
	v_add_u32_e32 v172, s31, v151
	ds_read_b128 v[128:131], v156
	ds_read_b128 v[142:145], v156 offset:1024
	ds_read_b128 v[146:149], v156 offset:2048
	ds_read_b128 v[156:159], v156 offset:3072
	ds_read_b128 v[160:163], v172
	ds_read_b128 v[164:167], v172 offset:1024
	ds_read_b128 v[168:171], v172 offset:2048
	ds_read_b128 v[172:175], v172 offset:3072
	ds_read_b128 v[176:179], v155
	ds_read_b128 v[194:197], v155 offset:1024
	ds_read_b128 v[206:209], v155 offset:2048
	ds_read_b128 v[210:213], v155 offset:3072
	ds_read_b128 v[214:217], v155 offset:4096
	ds_read_b128 v[220:223], v155 offset:5120
	ds_read_b128 v[224:227], v155 offset:6144
	ds_read_b128 v[228:231], v155 offset:7168
	s_waitcnt vmcnt(8)
	s_waitcnt lgkmcnt(0)
	s_barrier
	s_waitcnt lgkmcnt(0)
	v_mfma_f32_16x16x32_bf16 v[120:123], v[128:131], v[176:179], 0
	v_mfma_f32_16x16x32_bf16 v[116:119], v[146:149], v[176:179], 0
	v_mfma_f32_16x16x32_bf16 v[108:111], v[128:131], v[206:209], 0
	v_mfma_f32_16x16x32_bf16 v[100:103], v[146:149], v[206:209], 0
	v_mfma_f32_16x16x32_bf16 v[92:95], v[128:131], v[214:217], 0
	v_mfma_f32_16x16x32_bf16 v[84:87], v[146:149], v[214:217], 0
	v_mfma_f32_16x16x32_bf16 v[76:79], v[128:131], v[224:227], 0
	v_mfma_f32_16x16x32_bf16 v[68:71], v[146:149], v[224:227], 0
	v_mfma_f32_16x16x32_bf16 v[120:123], v[142:145], v[194:197], v[120:123]
	v_mfma_f32_16x16x32_bf16 v[116:119], v[156:159], v[194:197], v[116:119]
	v_mfma_f32_16x16x32_bf16 v[108:111], v[142:145], v[210:213], v[108:111]
	v_mfma_f32_16x16x32_bf16 v[100:103], v[156:159], v[210:213], v[100:103]
	v_mfma_f32_16x16x32_bf16 v[92:95], v[142:145], v[220:223], v[92:95]
	v_mfma_f32_16x16x32_bf16 v[84:87], v[156:159], v[220:223], v[84:87]
	v_mfma_f32_16x16x32_bf16 v[76:79], v[142:145], v[228:231], v[76:79]
	v_mfma_f32_16x16x32_bf16 v[68:71], v[156:159], v[228:231], v[68:71]
	v_mfma_f32_16x16x32_bf16 v[124:127], v[160:163], v[176:179], 0
	v_mfma_f32_16x16x32_bf16 v[112:115], v[168:171], v[176:179], 0
	v_mfma_f32_16x16x32_bf16 v[104:107], v[160:163], v[206:209], 0
	v_mfma_f32_16x16x32_bf16 v[96:99], v[168:171], v[206:209], 0
	v_mfma_f32_16x16x32_bf16 v[88:91], v[160:163], v[214:217], 0
	v_mfma_f32_16x16x32_bf16 v[80:83], v[168:171], v[214:217], 0
	v_mfma_f32_16x16x32_bf16 v[72:75], v[160:163], v[224:227], 0
	v_mfma_f32_16x16x32_bf16 v[64:67], v[168:171], v[224:227], 0
	v_mfma_f32_16x16x32_bf16 v[124:127], v[164:167], v[194:197], v[124:127]
	v_mfma_f32_16x16x32_bf16 v[112:115], v[172:175], v[194:197], v[112:115]
	v_mfma_f32_16x16x32_bf16 v[104:107], v[164:167], v[210:213], v[104:107]
	v_mfma_f32_16x16x32_bf16 v[96:99], v[172:175], v[210:213], v[96:99]
	v_mfma_f32_16x16x32_bf16 v[88:91], v[164:167], v[220:223], v[88:91]
	v_mfma_f32_16x16x32_bf16 v[80:83], v[172:175], v[220:223], v[80:83]
	v_mfma_f32_16x16x32_bf16 v[72:75], v[164:167], v[228:231], v[72:75]
	v_mfma_f32_16x16x32_bf16 v[64:67], v[172:175], v[228:231], v[64:67]
	s_barrier
	s_add_i32 s63, s63, s36
	v_lshl_add_u64 v[198:199], s[44:45], 0, v[180:181]
	s_mov_b32 m0, s63
	global_load_lds_dwordx4 v[198:199], off
	s_add_i32 m0, s63, 0x2000
	v_lshl_add_u64 v[202:203], s[44:45], 0, v[132:133]
	s_add_u32 s44, s44, s6
	s_addc_u32 s45, s45, s7
	s_add_i32 s31, s31, s36
	global_load_lds_dwordx4 v[202:203], off
	v_lshl_add_u64 v[232:233], s[44:45], 0, v[180:181]
	s_mov_b32 m0, s31
	v_lshl_add_u64 v[234:235], s[44:45], 0, v[132:133]
	global_load_lds_dwordx4 v[232:233], off
	s_add_i32 m0, s31, 0x2000
	v_lshl_add_u64 v[236:237], s[16:17], 0, v[136:137]
	global_load_lds_dwordx4 v[234:235], off
	s_mov_b32 m0, s37
	v_lshl_add_u64 v[238:239], s[16:17], 0, v[134:135]
	global_load_lds_dwordx4 v[236:237], off
	s_mov_b32 m0, s38
	s_nop 0
	global_load_lds_dwordx4 v[238:239], off
	ds_read_b128 v[176:179], v155 offset:16384
	ds_read_b128 v[194:197], v155 offset:17408
	ds_read_b128 v[206:209], v155 offset:18432
	ds_read_b128 v[210:213], v155 offset:19456
	ds_read_b128 v[214:217], v155 offset:20480
	ds_read_b128 v[220:223], v155 offset:21504
	ds_read_b128 v[224:227], v155 offset:22528
	ds_read_b128 v[228:231], v155 offset:23552
	s_waitcnt vmcnt(8)
	s_waitcnt lgkmcnt(0)
	s_barrier
	s_waitcnt lgkmcnt(0)
	v_mfma_f32_16x16x32_bf16 v[60:63], v[128:131], v[176:179], 0
	v_mfma_f32_16x16x32_bf16 v[52:55], v[146:149], v[176:179], 0
	v_mfma_f32_16x16x32_bf16 v[44:47], v[128:131], v[206:209], 0
	v_mfma_f32_16x16x32_bf16 v[36:39], v[146:149], v[206:209], 0
	v_mfma_f32_16x16x32_bf16 v[28:31], v[128:131], v[214:217], 0
	v_mfma_f32_16x16x32_bf16 v[20:23], v[146:149], v[214:217], 0
	v_mfma_f32_16x16x32_bf16 v[12:15], v[128:131], v[224:227], 0
	v_mfma_f32_16x16x32_bf16 v[4:7], v[146:149], v[224:227], 0
	v_mfma_f32_16x16x32_bf16 v[60:63], v[142:145], v[194:197], v[60:63]
	v_mfma_f32_16x16x32_bf16 v[52:55], v[156:159], v[194:197], v[52:55]
	v_mfma_f32_16x16x32_bf16 v[44:47], v[142:145], v[210:213], v[44:47]
	v_mfma_f32_16x16x32_bf16 v[36:39], v[156:159], v[210:213], v[36:39]
	v_mfma_f32_16x16x32_bf16 v[28:31], v[142:145], v[220:223], v[28:31]
	v_mfma_f32_16x16x32_bf16 v[20:23], v[156:159], v[220:223], v[20:23]
	v_mfma_f32_16x16x32_bf16 v[12:15], v[142:145], v[228:231], v[12:15]
	v_mfma_f32_16x16x32_bf16 v[4:7], v[156:159], v[228:231], v[4:7]
	v_mfma_f32_16x16x32_bf16 v[56:59], v[160:163], v[176:179], 0
	v_mfma_f32_16x16x32_bf16 v[48:51], v[168:171], v[176:179], 0
	v_mfma_f32_16x16x32_bf16 v[40:43], v[160:163], v[206:209], 0
	v_mfma_f32_16x16x32_bf16 v[32:35], v[168:171], v[206:209], 0
	v_mfma_f32_16x16x32_bf16 v[24:27], v[160:163], v[214:217], 0
	v_mfma_f32_16x16x32_bf16 v[16:19], v[168:171], v[214:217], 0
	v_mfma_f32_16x16x32_bf16 v[8:11], v[160:163], v[224:227], 0
	v_mfma_f32_16x16x32_bf16 v[0:3], v[168:171], v[224:227], 0
	v_mfma_f32_16x16x32_bf16 v[56:59], v[164:167], v[194:197], v[56:59]
	v_mfma_f32_16x16x32_bf16 v[48:51], v[172:175], v[194:197], v[48:51]
	v_mfma_f32_16x16x32_bf16 v[40:43], v[164:167], v[210:213], v[40:43]
	v_mfma_f32_16x16x32_bf16 v[32:35], v[172:175], v[210:213], v[32:35]
	v_mfma_f32_16x16x32_bf16 v[24:27], v[164:167], v[220:223], v[24:27]
	v_mfma_f32_16x16x32_bf16 v[16:19], v[172:175], v[220:223], v[16:19]
	v_mfma_f32_16x16x32_bf16 v[8:11], v[164:167], v[228:231], v[8:11]
	v_mfma_f32_16x16x32_bf16 v[0:3], v[172:175], v[228:231], v[0:3]
	s_barrier
	s_add_i32 s31, 0, 0x18000
	s_add_i32 s44, 0, 0x1c000
	s_add_u32 s16, s16, s6
	s_addc_u32 s17, s17, s7
	s_mov_b32 m0, s39
	v_lshl_add_u64 v[240:241], s[16:17], 0, v[136:137]
	global_load_lds_dwordx4 v[240:241], off
	v_lshl_add_u64 v[240:241], s[16:17], 0, v[134:135]
	s_mov_b32 m0, s46
	s_nop 0
	global_load_lds_dwordx4 v[240:241], off
	v_add_u32_e32 v156, s31, v151
	v_add_u32_e32 v172, s44, v151
	ds_read_b128 v[128:131], v156
	ds_read_b128 v[142:145], v156 offset:1024
	ds_read_b128 v[146:149], v156 offset:2048
	ds_read_b128 v[156:159], v156 offset:3072
	ds_read_b128 v[160:163], v172
	ds_read_b128 v[164:167], v172 offset:1024
	ds_read_b128 v[168:171], v172 offset:2048
	ds_read_b128 v[172:175], v172 offset:3072
	ds_read_b128 v[176:179], v155 offset:32768
	ds_read_b128 v[194:197], v155 offset:33792
	ds_read_b128 v[206:209], v155 offset:34816
	ds_read_b128 v[210:213], v155 offset:35840
	ds_read_b128 v[214:217], v155 offset:36864
	ds_read_b128 v[220:223], v155 offset:37888
	ds_read_b128 v[224:227], v155 offset:38912
	ds_read_b128 v[228:231], v155 offset:39936
	s_waitcnt vmcnt(8)
	s_waitcnt lgkmcnt(0)
	s_barrier
	s_waitcnt lgkmcnt(0)
	v_mfma_f32_16x16x32_bf16 v[120:123], v[128:131], v[176:179], v[120:123]
	v_mfma_f32_16x16x32_bf16 v[116:119], v[146:149], v[176:179], v[116:119]
	v_mfma_f32_16x16x32_bf16 v[108:111], v[128:131], v[206:209], v[108:111]
	v_mfma_f32_16x16x32_bf16 v[100:103], v[146:149], v[206:209], v[100:103]
	v_mfma_f32_16x16x32_bf16 v[92:95], v[128:131], v[214:217], v[92:95]
	v_mfma_f32_16x16x32_bf16 v[84:87], v[146:149], v[214:217], v[84:87]
	v_mfma_f32_16x16x32_bf16 v[76:79], v[128:131], v[224:227], v[76:79]
	v_mfma_f32_16x16x32_bf16 v[68:71], v[146:149], v[224:227], v[68:71]
	v_mfma_f32_16x16x32_bf16 v[120:123], v[142:145], v[194:197], v[120:123]
	v_mfma_f32_16x16x32_bf16 v[116:119], v[156:159], v[194:197], v[116:119]
	v_mfma_f32_16x16x32_bf16 v[108:111], v[142:145], v[210:213], v[108:111]
	v_mfma_f32_16x16x32_bf16 v[100:103], v[156:159], v[210:213], v[100:103]
	v_mfma_f32_16x16x32_bf16 v[92:95], v[142:145], v[220:223], v[92:95]
	v_mfma_f32_16x16x32_bf16 v[84:87], v[156:159], v[220:223], v[84:87]
	v_mfma_f32_16x16x32_bf16 v[76:79], v[142:145], v[228:231], v[76:79]
	v_mfma_f32_16x16x32_bf16 v[68:71], v[156:159], v[228:231], v[68:71]
	v_mfma_f32_16x16x32_bf16 v[124:127], v[160:163], v[176:179], v[124:127]
	v_mfma_f32_16x16x32_bf16 v[112:115], v[168:171], v[176:179], v[112:115]
	v_mfma_f32_16x16x32_bf16 v[104:107], v[160:163], v[206:209], v[104:107]
	v_mfma_f32_16x16x32_bf16 v[96:99], v[168:171], v[206:209], v[96:99]
	v_mfma_f32_16x16x32_bf16 v[88:91], v[160:163], v[214:217], v[88:91]
	v_mfma_f32_16x16x32_bf16 v[80:83], v[168:171], v[214:217], v[80:83]
	v_mfma_f32_16x16x32_bf16 v[72:75], v[160:163], v[224:227], v[72:75]
	v_mfma_f32_16x16x32_bf16 v[64:67], v[168:171], v[224:227], v[64:67]
	v_mfma_f32_16x16x32_bf16 v[124:127], v[164:167], v[194:197], v[124:127]
	v_mfma_f32_16x16x32_bf16 v[112:115], v[172:175], v[194:197], v[112:115]
	v_mfma_f32_16x16x32_bf16 v[104:107], v[164:167], v[210:213], v[104:107]
	v_mfma_f32_16x16x32_bf16 v[96:99], v[172:175], v[210:213], v[96:99]
	v_mfma_f32_16x16x32_bf16 v[88:91], v[164:167], v[220:223], v[88:91]
	v_mfma_f32_16x16x32_bf16 v[80:83], v[172:175], v[220:223], v[80:83]
	v_mfma_f32_16x16x32_bf16 v[72:75], v[164:167], v[228:231], v[72:75]
	v_mfma_f32_16x16x32_bf16 v[64:67], v[172:175], v[228:231], v[64:67]
	s_barrier
	s_add_i32 s16, s31, s36
	v_lshl_add_u64 v[198:199], v[198:199], 0, s[12:13]
	s_mov_b32 m0, s16
	global_load_lds_dwordx4 v[198:199], off
	v_lshl_add_u64 v[198:199], v[202:203], 0, s[12:13]
	s_add_i32 m0, s16, 0x2000
	s_add_i32 s16, s44, s36
	global_load_lds_dwordx4 v[198:199], off
	v_lshl_add_u64 v[198:199], v[232:233], 0, s[12:13]
	s_mov_b32 m0, s16
	s_nop 0
	global_load_lds_dwordx4 v[198:199], off
	v_lshl_add_u64 v[198:199], v[234:235], 0, s[12:13]
	s_add_i32 m0, s16, 0x2000
	s_nop 0
	global_load_lds_dwordx4 v[198:199], off
	v_lshl_add_u64 v[198:199], v[236:237], 0, s[12:13]
	s_mov_b32 m0, s49
	s_nop 0
	global_load_lds_dwordx4 v[198:199], off
	v_lshl_add_u64 v[198:199], v[238:239], 0, s[12:13]
	s_mov_b32 m0, s52
	s_nop 0
	global_load_lds_dwordx4 v[198:199], off
	ds_read_b128 v[176:179], v155 offset:49152
	ds_read_b128 v[194:197], v155 offset:50176
	ds_read_b128 v[206:209], v155 offset:51200
	ds_read_b128 v[210:213], v155 offset:52224
	ds_read_b128 v[214:217], v155 offset:53248
	ds_read_b128 v[220:223], v155 offset:54272
	ds_read_b128 v[224:227], v155 offset:55296
	ds_read_b128 v[228:231], v155 offset:56320
	s_waitcnt vmcnt(8)
	s_waitcnt lgkmcnt(0)
	s_barrier
	s_waitcnt lgkmcnt(0)
	v_mfma_f32_16x16x32_bf16 v[60:63], v[128:131], v[176:179], v[60:63]
	s_add_u32 s28, s28, 0x100
	v_mfma_f32_16x16x32_bf16 v[52:55], v[146:149], v[176:179], v[52:55]
	s_addc_u32 s29, s29, 0
	v_mfma_f32_16x16x32_bf16 v[44:47], v[128:131], v[206:209], v[44:47]
	s_add_u32 s10, s10, 0x100
	v_mfma_f32_16x16x32_bf16 v[36:39], v[146:149], v[206:209], v[36:39]
	s_addc_u32 s11, s11, 0
	v_mfma_f32_16x16x32_bf16 v[28:31], v[128:131], v[214:217], v[28:31]
	s_mov_b32 s16, s30
	v_mfma_f32_16x16x32_bf16 v[20:23], v[146:149], v[214:217], v[20:23]
	s_cmp_ge_i32 s30, s47
	v_mfma_f32_16x16x32_bf16 v[12:15], v[128:131], v[224:227], v[12:15]
	s_cselect_b32 s99, 1, 0
	v_mfma_f32_16x16x32_bf16 v[4:7], v[146:149], v[224:227], v[4:7]
	s_add_i32 s30, s16, 2
	v_mfma_f32_16x16x32_bf16 v[60:63], v[142:145], v[194:197], v[60:63]
	s_add_u32 s31, s28, 0x80
	v_mfma_f32_16x16x32_bf16 v[52:55], v[156:159], v[194:197], v[52:55]
	s_addc_u32 s17, s29, 0
	v_mfma_f32_16x16x32_bf16 v[44:47], v[142:145], v[210:213], v[44:47]
	s_add_i32 s63, 0, 0x10000
	v_mfma_f32_16x16x32_bf16 v[36:39], v[156:159], v[210:213], v[36:39]
	s_cmp_eq_u32 s56, s16
	v_mfma_f32_16x16x32_bf16 v[28:31], v[142:145], v[220:223], v[28:31]
	s_cselect_b32 s17, s25, s17
	v_mfma_f32_16x16x32_bf16 v[20:23], v[156:159], v[220:223], v[20:23]
	s_cselect_b32 s16, s24, s31
	v_mfma_f32_16x16x32_bf16 v[12:15], v[142:145], v[228:231], v[12:15]
	s_cselect_b32 s45, s27, s11
	v_mfma_f32_16x16x32_bf16 v[4:7], v[156:159], v[228:231], v[4:7]
	s_cselect_b32 s44, s26, s10
	v_mfma_f32_16x16x32_bf16 v[56:59], v[160:163], v[176:179], v[56:59]
	s_add_i32 s31, 0, 0x14000
	v_mfma_f32_16x16x32_bf16 v[48:51], v[168:171], v[176:179], v[48:51]
	v_mfma_f32_16x16x32_bf16 v[40:43], v[160:163], v[206:209], v[40:43]
	v_mfma_f32_16x16x32_bf16 v[32:35], v[168:171], v[206:209], v[32:35]
	v_mfma_f32_16x16x32_bf16 v[24:27], v[160:163], v[214:217], v[24:27]
	v_mfma_f32_16x16x32_bf16 v[16:19], v[168:171], v[214:217], v[16:19]
	v_mfma_f32_16x16x32_bf16 v[8:11], v[160:163], v[224:227], v[8:11]
	v_mfma_f32_16x16x32_bf16 v[0:3], v[168:171], v[224:227], v[0:3]
	v_mfma_f32_16x16x32_bf16 v[56:59], v[164:167], v[194:197], v[56:59]
	v_mfma_f32_16x16x32_bf16 v[48:51], v[172:175], v[194:197], v[48:51]
	v_mfma_f32_16x16x32_bf16 v[40:43], v[164:167], v[210:213], v[40:43]
	v_mfma_f32_16x16x32_bf16 v[32:35], v[172:175], v[210:213], v[32:35]
	v_mfma_f32_16x16x32_bf16 v[24:27], v[164:167], v[220:223], v[24:27]
	v_mfma_f32_16x16x32_bf16 v[16:19], v[172:175], v[220:223], v[16:19]
	v_mfma_f32_16x16x32_bf16 v[8:11], v[164:167], v[228:231], v[8:11]
	v_mfma_f32_16x16x32_bf16 v[0:3], v[172:175], v[228:231], v[0:3]
	s_barrier
	s_cmp_lg_u32 s99, 0
	s_cbranch_scc1 .Lpeelx_14
.LBB0_1144:
	v_lshl_add_u64 v[198:199], s[28:29], 0, v[138:139]
	s_add_i32 m0, s37, 0xc000
	global_load_lds_dwordx4 v[198:199], off
	v_lshl_add_u64 v[198:199], s[28:29], 0, v[140:141]
	s_add_i32 m0, s37, 0xe000
	s_nop 0
	global_load_lds_dwordx4 v[198:199], off
	v_add_u32_e32 v156, s63, v151
	v_add_u32_e32 v172, s31, v151
	ds_read_b128 v[128:131], v156
	ds_read_b128 v[142:145], v156 offset:1024
	ds_read_b128 v[146:149], v156 offset:2048
	ds_read_b128 v[156:159], v156 offset:3072
	ds_read_b128 v[160:163], v172
	ds_read_b128 v[164:167], v172 offset:1024
	ds_read_b128 v[168:171], v172 offset:2048
	ds_read_b128 v[172:175], v172 offset:3072
	ds_read_b128 v[176:179], v155
	ds_read_b128 v[194:197], v155 offset:1024
	ds_read_b128 v[206:209], v155 offset:2048
	ds_read_b128 v[210:213], v155 offset:3072
	ds_read_b128 v[214:217], v155 offset:4096
	ds_read_b128 v[220:223], v155 offset:5120
	ds_read_b128 v[224:227], v155 offset:6144
	ds_read_b128 v[228:231], v155 offset:7168
	s_waitcnt vmcnt(8)
	s_waitcnt lgkmcnt(0)
	s_barrier
	s_waitcnt lgkmcnt(0)
	v_mfma_f32_16x16x32_bf16 v[120:123], v[128:131], v[176:179], v[120:123]
	v_mfma_f32_16x16x32_bf16 v[116:119], v[146:149], v[176:179], v[116:119]
	v_mfma_f32_16x16x32_bf16 v[108:111], v[128:131], v[206:209], v[108:111]
	v_mfma_f32_16x16x32_bf16 v[100:103], v[146:149], v[206:209], v[100:103]
	v_mfma_f32_16x16x32_bf16 v[92:95], v[128:131], v[214:217], v[92:95]
	v_mfma_f32_16x16x32_bf16 v[84:87], v[146:149], v[214:217], v[84:87]
	v_mfma_f32_16x16x32_bf16 v[76:79], v[128:131], v[224:227], v[76:79]
	v_mfma_f32_16x16x32_bf16 v[68:71], v[146:149], v[224:227], v[68:71]
	v_mfma_f32_16x16x32_bf16 v[120:123], v[142:145], v[194:197], v[120:123]
	v_mfma_f32_16x16x32_bf16 v[116:119], v[156:159], v[194:197], v[116:119]
	v_mfma_f32_16x16x32_bf16 v[108:111], v[142:145], v[210:213], v[108:111]
	v_mfma_f32_16x16x32_bf16 v[100:103], v[156:159], v[210:213], v[100:103]
	v_mfma_f32_16x16x32_bf16 v[92:95], v[142:145], v[220:223], v[92:95]
	v_mfma_f32_16x16x32_bf16 v[84:87], v[156:159], v[220:223], v[84:87]
	v_mfma_f32_16x16x32_bf16 v[76:79], v[142:145], v[228:231], v[76:79]
	v_mfma_f32_16x16x32_bf16 v[68:71], v[156:159], v[228:231], v[68:71]
	v_mfma_f32_16x16x32_bf16 v[124:127], v[160:163], v[176:179], v[124:127]
	v_mfma_f32_16x16x32_bf16 v[112:115], v[168:171], v[176:179], v[112:115]
	v_mfma_f32_16x16x32_bf16 v[104:107], v[160:163], v[206:209], v[104:107]
	v_mfma_f32_16x16x32_bf16 v[96:99], v[168:171], v[206:209], v[96:99]
	v_mfma_f32_16x16x32_bf16 v[88:91], v[160:163], v[214:217], v[88:91]
	v_mfma_f32_16x16x32_bf16 v[80:83], v[168:171], v[214:217], v[80:83]
	v_mfma_f32_16x16x32_bf16 v[72:75], v[160:163], v[224:227], v[72:75]
	v_mfma_f32_16x16x32_bf16 v[64:67], v[168:171], v[224:227], v[64:67]
	v_mfma_f32_16x16x32_bf16 v[124:127], v[164:167], v[194:197], v[124:127]
	v_mfma_f32_16x16x32_bf16 v[112:115], v[172:175], v[194:197], v[112:115]
	v_mfma_f32_16x16x32_bf16 v[104:107], v[164:167], v[210:213], v[104:107]
	v_mfma_f32_16x16x32_bf16 v[96:99], v[172:175], v[210:213], v[96:99]
	v_mfma_f32_16x16x32_bf16 v[88:91], v[164:167], v[220:223], v[88:91]
	v_mfma_f32_16x16x32_bf16 v[80:83], v[172:175], v[220:223], v[80:83]
	v_mfma_f32_16x16x32_bf16 v[72:75], v[164:167], v[228:231], v[72:75]
	v_mfma_f32_16x16x32_bf16 v[64:67], v[172:175], v[228:231], v[64:67]
	s_barrier
	s_add_i32 s63, s63, s36
	v_lshl_add_u64 v[198:199], s[44:45], 0, v[180:181]
	s_mov_b32 m0, s63
	global_load_lds_dwordx4 v[198:199], off
	s_add_i32 m0, s63, 0x2000
	v_lshl_add_u64 v[202:203], s[44:45], 0, v[132:133]
	s_add_u32 s44, s44, s6
	s_addc_u32 s45, s45, s7
	s_add_i32 s31, s31, s36
	global_load_lds_dwordx4 v[202:203], off
	v_lshl_add_u64 v[232:233], s[44:45], 0, v[180:181]
	s_mov_b32 m0, s31
	v_lshl_add_u64 v[234:235], s[44:45], 0, v[132:133]
	global_load_lds_dwordx4 v[232:233], off
	s_add_i32 m0, s31, 0x2000
	v_lshl_add_u64 v[236:237], s[16:17], 0, v[136:137]
	global_load_lds_dwordx4 v[234:235], off
	s_mov_b32 m0, s37
	v_lshl_add_u64 v[238:239], s[16:17], 0, v[134:135]
	global_load_lds_dwordx4 v[236:237], off
	s_mov_b32 m0, s38
	s_nop 0
	global_load_lds_dwordx4 v[238:239], off
	ds_read_b128 v[176:179], v155 offset:16384
	ds_read_b128 v[194:197], v155 offset:17408
	ds_read_b128 v[206:209], v155 offset:18432
	ds_read_b128 v[210:213], v155 offset:19456
	ds_read_b128 v[214:217], v155 offset:20480
	ds_read_b128 v[220:223], v155 offset:21504
	ds_read_b128 v[224:227], v155 offset:22528
	ds_read_b128 v[228:231], v155 offset:23552
	s_waitcnt vmcnt(8)
	s_waitcnt lgkmcnt(0)
	s_barrier
	s_waitcnt lgkmcnt(0)
	v_mfma_f32_16x16x32_bf16 v[60:63], v[128:131], v[176:179], v[60:63]
	v_mfma_f32_16x16x32_bf16 v[52:55], v[146:149], v[176:179], v[52:55]
	v_mfma_f32_16x16x32_bf16 v[44:47], v[128:131], v[206:209], v[44:47]
	v_mfma_f32_16x16x32_bf16 v[36:39], v[146:149], v[206:209], v[36:39]
	v_mfma_f32_16x16x32_bf16 v[28:31], v[128:131], v[214:217], v[28:31]
	v_mfma_f32_16x16x32_bf16 v[20:23], v[146:149], v[214:217], v[20:23]
	v_mfma_f32_16x16x32_bf16 v[12:15], v[128:131], v[224:227], v[12:15]
	v_mfma_f32_16x16x32_bf16 v[4:7], v[146:149], v[224:227], v[4:7]
	v_mfma_f32_16x16x32_bf16 v[60:63], v[142:145], v[194:197], v[60:63]
	v_mfma_f32_16x16x32_bf16 v[52:55], v[156:159], v[194:197], v[52:55]
	v_mfma_f32_16x16x32_bf16 v[44:47], v[142:145], v[210:213], v[44:47]
	v_mfma_f32_16x16x32_bf16 v[36:39], v[156:159], v[210:213], v[36:39]
	v_mfma_f32_16x16x32_bf16 v[28:31], v[142:145], v[220:223], v[28:31]
	v_mfma_f32_16x16x32_bf16 v[20:23], v[156:159], v[220:223], v[20:23]
	v_mfma_f32_16x16x32_bf16 v[12:15], v[142:145], v[228:231], v[12:15]
	v_mfma_f32_16x16x32_bf16 v[4:7], v[156:159], v[228:231], v[4:7]
	v_mfma_f32_16x16x32_bf16 v[56:59], v[160:163], v[176:179], v[56:59]
	v_mfma_f32_16x16x32_bf16 v[48:51], v[168:171], v[176:179], v[48:51]
	v_mfma_f32_16x16x32_bf16 v[40:43], v[160:163], v[206:209], v[40:43]
	v_mfma_f32_16x16x32_bf16 v[32:35], v[168:171], v[206:209], v[32:35]
	v_mfma_f32_16x16x32_bf16 v[24:27], v[160:163], v[214:217], v[24:27]
	v_mfma_f32_16x16x32_bf16 v[16:19], v[168:171], v[214:217], v[16:19]
	v_mfma_f32_16x16x32_bf16 v[8:11], v[160:163], v[224:227], v[8:11]
	v_mfma_f32_16x16x32_bf16 v[0:3], v[168:171], v[224:227], v[0:3]
	v_mfma_f32_16x16x32_bf16 v[56:59], v[164:167], v[194:197], v[56:59]
	v_mfma_f32_16x16x32_bf16 v[48:51], v[172:175], v[194:197], v[48:51]
	v_mfma_f32_16x16x32_bf16 v[40:43], v[164:167], v[210:213], v[40:43]
	v_mfma_f32_16x16x32_bf16 v[32:35], v[172:175], v[210:213], v[32:35]
	v_mfma_f32_16x16x32_bf16 v[24:27], v[164:167], v[220:223], v[24:27]
	v_mfma_f32_16x16x32_bf16 v[16:19], v[172:175], v[220:223], v[16:19]
	v_mfma_f32_16x16x32_bf16 v[8:11], v[164:167], v[228:231], v[8:11]
	v_mfma_f32_16x16x32_bf16 v[0:3], v[172:175], v[228:231], v[0:3]
	s_barrier
	s_add_i32 s31, 0, 0x18000
	s_add_i32 s44, 0, 0x1c000
	s_add_u32 s16, s16, s6
	s_addc_u32 s17, s17, s7
	s_mov_b32 m0, s39
	v_lshl_add_u64 v[240:241], s[16:17], 0, v[136:137]
	global_load_lds_dwordx4 v[240:241], off
	v_lshl_add_u64 v[240:241], s[16:17], 0, v[134:135]
	s_mov_b32 m0, s46
	s_nop 0
	global_load_lds_dwordx4 v[240:241], off
	v_add_u32_e32 v156, s31, v151
	v_add_u32_e32 v172, s44, v151
	ds_read_b128 v[128:131], v156
	ds_read_b128 v[142:145], v156 offset:1024
	ds_read_b128 v[146:149], v156 offset:2048
	ds_read_b128 v[156:159], v156 offset:3072
	ds_read_b128 v[160:163], v172
	ds_read_b128 v[164:167], v172 offset:1024
	ds_read_b128 v[168:171], v172 offset:2048
	ds_read_b128 v[172:175], v172 offset:3072
	ds_read_b128 v[176:179], v155 offset:32768
	ds_read_b128 v[194:197], v155 offset:33792
	ds_read_b128 v[206:209], v155 offset:34816
	ds_read_b128 v[210:213], v155 offset:35840
	ds_read_b128 v[214:217], v155 offset:36864
	ds_read_b128 v[220:223], v155 offset:37888
	ds_read_b128 v[224:227], v155 offset:38912
	ds_read_b128 v[228:231], v155 offset:39936
	s_waitcnt vmcnt(8)
	s_waitcnt lgkmcnt(0)
	s_barrier
	s_waitcnt lgkmcnt(0)
	v_mfma_f32_16x16x32_bf16 v[120:123], v[128:131], v[176:179], v[120:123]
	v_mfma_f32_16x16x32_bf16 v[116:119], v[146:149], v[176:179], v[116:119]
	v_mfma_f32_16x16x32_bf16 v[108:111], v[128:131], v[206:209], v[108:111]
	v_mfma_f32_16x16x32_bf16 v[100:103], v[146:149], v[206:209], v[100:103]
	v_mfma_f32_16x16x32_bf16 v[92:95], v[128:131], v[214:217], v[92:95]
	v_mfma_f32_16x16x32_bf16 v[84:87], v[146:149], v[214:217], v[84:87]
	v_mfma_f32_16x16x32_bf16 v[76:79], v[128:131], v[224:227], v[76:79]
	v_mfma_f32_16x16x32_bf16 v[68:71], v[146:149], v[224:227], v[68:71]
	v_mfma_f32_16x16x32_bf16 v[120:123], v[142:145], v[194:197], v[120:123]
	v_mfma_f32_16x16x32_bf16 v[116:119], v[156:159], v[194:197], v[116:119]
	v_mfma_f32_16x16x32_bf16 v[108:111], v[142:145], v[210:213], v[108:111]
	v_mfma_f32_16x16x32_bf16 v[100:103], v[156:159], v[210:213], v[100:103]
	v_mfma_f32_16x16x32_bf16 v[92:95], v[142:145], v[220:223], v[92:95]
	v_mfma_f32_16x16x32_bf16 v[84:87], v[156:159], v[220:223], v[84:87]
	v_mfma_f32_16x16x32_bf16 v[76:79], v[142:145], v[228:231], v[76:79]
	v_mfma_f32_16x16x32_bf16 v[68:71], v[156:159], v[228:231], v[68:71]
	v_mfma_f32_16x16x32_bf16 v[124:127], v[160:163], v[176:179], v[124:127]
	v_mfma_f32_16x16x32_bf16 v[112:115], v[168:171], v[176:179], v[112:115]
	v_mfma_f32_16x16x32_bf16 v[104:107], v[160:163], v[206:209], v[104:107]
	v_mfma_f32_16x16x32_bf16 v[96:99], v[168:171], v[206:209], v[96:99]
	v_mfma_f32_16x16x32_bf16 v[88:91], v[160:163], v[214:217], v[88:91]
	v_mfma_f32_16x16x32_bf16 v[80:83], v[168:171], v[214:217], v[80:83]
	v_mfma_f32_16x16x32_bf16 v[72:75], v[160:163], v[224:227], v[72:75]
	v_mfma_f32_16x16x32_bf16 v[64:67], v[168:171], v[224:227], v[64:67]
	v_mfma_f32_16x16x32_bf16 v[124:127], v[164:167], v[194:197], v[124:127]
	v_mfma_f32_16x16x32_bf16 v[112:115], v[172:175], v[194:197], v[112:115]
	v_mfma_f32_16x16x32_bf16 v[104:107], v[164:167], v[210:213], v[104:107]
	v_mfma_f32_16x16x32_bf16 v[96:99], v[172:175], v[210:213], v[96:99]
	v_mfma_f32_16x16x32_bf16 v[88:91], v[164:167], v[220:223], v[88:91]
	v_mfma_f32_16x16x32_bf16 v[80:83], v[172:175], v[220:223], v[80:83]
	v_mfma_f32_16x16x32_bf16 v[72:75], v[164:167], v[228:231], v[72:75]
	v_mfma_f32_16x16x32_bf16 v[64:67], v[172:175], v[228:231], v[64:67]
	s_barrier
	s_add_i32 s16, s31, s36
	v_lshl_add_u64 v[198:199], v[198:199], 0, s[12:13]
	s_mov_b32 m0, s16
	global_load_lds_dwordx4 v[198:199], off
	v_lshl_add_u64 v[198:199], v[202:203], 0, s[12:13]
	s_add_i32 m0, s16, 0x2000
	s_add_i32 s16, s44, s36
	global_load_lds_dwordx4 v[198:199], off
	v_lshl_add_u64 v[198:199], v[232:233], 0, s[12:13]
	s_mov_b32 m0, s16
	s_nop 0
	global_load_lds_dwordx4 v[198:199], off
	v_lshl_add_u64 v[198:199], v[234:235], 0, s[12:13]
	s_add_i32 m0, s16, 0x2000
	s_nop 0
	global_load_lds_dwordx4 v[198:199], off
	v_lshl_add_u64 v[198:199], v[236:237], 0, s[12:13]
	s_mov_b32 m0, s49
	s_nop 0
	global_load_lds_dwordx4 v[198:199], off
	v_lshl_add_u64 v[198:199], v[238:239], 0, s[12:13]
	s_mov_b32 m0, s52
	s_nop 0
	global_load_lds_dwordx4 v[198:199], off
	ds_read_b128 v[176:179], v155 offset:49152
	ds_read_b128 v[194:197], v155 offset:50176
	ds_read_b128 v[206:209], v155 offset:51200
	ds_read_b128 v[210:213], v155 offset:52224
	ds_read_b128 v[214:217], v155 offset:53248
	ds_read_b128 v[220:223], v155 offset:54272
	ds_read_b128 v[224:227], v155 offset:55296
	ds_read_b128 v[228:231], v155 offset:56320
	s_waitcnt vmcnt(8)
	s_waitcnt lgkmcnt(0)
	s_barrier
	s_waitcnt lgkmcnt(0)
	v_mfma_f32_16x16x32_bf16 v[60:63], v[128:131], v[176:179], v[60:63]
	s_add_u32 s28, s28, 0x100
	v_mfma_f32_16x16x32_bf16 v[52:55], v[146:149], v[176:179], v[52:55]
	s_addc_u32 s29, s29, 0
	v_mfma_f32_16x16x32_bf16 v[44:47], v[128:131], v[206:209], v[44:47]
	s_add_u32 s10, s10, 0x100
	v_mfma_f32_16x16x32_bf16 v[36:39], v[146:149], v[206:209], v[36:39]
	s_addc_u32 s11, s11, 0
	v_mfma_f32_16x16x32_bf16 v[28:31], v[128:131], v[214:217], v[28:31]
	s_mov_b32 s16, s30
	v_mfma_f32_16x16x32_bf16 v[20:23], v[146:149], v[214:217], v[20:23]
	s_cmp_ge_i32 s30, s47
	v_mfma_f32_16x16x32_bf16 v[12:15], v[128:131], v[224:227], v[12:15]
	s_cselect_b32 s99, 1, 0
	v_mfma_f32_16x16x32_bf16 v[4:7], v[146:149], v[224:227], v[4:7]
	s_add_i32 s30, s16, 2
	v_mfma_f32_16x16x32_bf16 v[60:63], v[142:145], v[194:197], v[60:63]
	s_add_u32 s31, s28, 0x80
	v_mfma_f32_16x16x32_bf16 v[52:55], v[156:159], v[194:197], v[52:55]
	s_addc_u32 s17, s29, 0
	v_mfma_f32_16x16x32_bf16 v[44:47], v[142:145], v[210:213], v[44:47]
	s_add_i32 s63, 0, 0x10000
	v_mfma_f32_16x16x32_bf16 v[36:39], v[156:159], v[210:213], v[36:39]
	s_cmp_eq_u32 s56, s16
	v_mfma_f32_16x16x32_bf16 v[28:31], v[142:145], v[220:223], v[28:31]
	s_cselect_b32 s17, s25, s17
	v_mfma_f32_16x16x32_bf16 v[20:23], v[156:159], v[220:223], v[20:23]
	s_cselect_b32 s16, s24, s31
	v_mfma_f32_16x16x32_bf16 v[12:15], v[142:145], v[228:231], v[12:15]
	s_cselect_b32 s45, s27, s11
	v_mfma_f32_16x16x32_bf16 v[4:7], v[156:159], v[228:231], v[4:7]
	s_cselect_b32 s44, s26, s10
	v_mfma_f32_16x16x32_bf16 v[56:59], v[160:163], v[176:179], v[56:59]
	s_add_i32 s31, 0, 0x14000
	v_mfma_f32_16x16x32_bf16 v[48:51], v[168:171], v[176:179], v[48:51]
	v_mfma_f32_16x16x32_bf16 v[40:43], v[160:163], v[206:209], v[40:43]
	v_mfma_f32_16x16x32_bf16 v[32:35], v[168:171], v[206:209], v[32:35]
	v_mfma_f32_16x16x32_bf16 v[24:27], v[160:163], v[214:217], v[24:27]
	v_mfma_f32_16x16x32_bf16 v[16:19], v[168:171], v[214:217], v[16:19]
	v_mfma_f32_16x16x32_bf16 v[8:11], v[160:163], v[224:227], v[8:11]
	v_mfma_f32_16x16x32_bf16 v[0:3], v[168:171], v[224:227], v[0:3]
	v_mfma_f32_16x16x32_bf16 v[56:59], v[164:167], v[194:197], v[56:59]
	v_mfma_f32_16x16x32_bf16 v[48:51], v[172:175], v[194:197], v[48:51]
	v_mfma_f32_16x16x32_bf16 v[40:43], v[164:167], v[210:213], v[40:43]
	v_mfma_f32_16x16x32_bf16 v[32:35], v[172:175], v[210:213], v[32:35]
	v_mfma_f32_16x16x32_bf16 v[24:27], v[164:167], v[220:223], v[24:27]
	v_mfma_f32_16x16x32_bf16 v[16:19], v[172:175], v[220:223], v[16:19]
	v_mfma_f32_16x16x32_bf16 v[8:11], v[164:167], v[228:231], v[8:11]
	v_mfma_f32_16x16x32_bf16 v[0:3], v[172:175], v[228:231], v[0:3]
	s_barrier
	s_cmp_lg_u32 s99, 0
	s_cbranch_scc0 .LBB0_1144

.Llbb_11:
	s_add_i32 s44, s28, 2
	s_add_u32 s45, s26, 0x80
	s_addc_u32 s29, s27, 0
	s_add_i32 s62, 0, 0x10000
	s_cmp_eq_u32 s49, s28
	s_cselect_b32 s29, s23, s29
	s_cselect_b32 s28, s22, s45
	s_cselect_b32 s61, s25, s11
	s_cselect_b32 s60, s24, s10
	s_add_i32 s45, 0, 0x14000
	v_lshl_add_u64 v[178:179], s[26:27], 0, v[162:163]
	s_add_i32 m0, s35, 0xc000
	global_load_lds_dwordx4 v[178:179], off
	v_lshl_add_u64 v[178:179], s[26:27], 0, v[164:165]
	s_add_i32 m0, s35, 0xe000
	s_nop 0
	global_load_lds_dwordx4 v[178:179], off
	v_add_u32_e32 v140, s62, v199
	v_add_u32_e32 v166, s45, v199
	ds_read_b128 v[128:131], v140
	ds_read_b128 v[132:135], v140 offset:1024
	ds_read_b128 v[136:139], v140 offset:2048
	ds_read_b128 v[140:143], v140 offset:3072
	ds_read_b128 v[144:147], v166
	ds_read_b128 v[148:151], v166 offset:1024
	ds_read_b128 v[152:155], v166 offset:2048
	ds_read_b128 v[166:169], v166 offset:3072
	ds_read_b128 v[170:173], v206
	ds_read_b128 v[174:177], v206 offset:1024
	ds_read_b128 v[194:197], v206 offset:2048
	ds_read_b128 v[208:211], v206 offset:3072
	ds_read_b128 v[212:215], v206 offset:4096
	ds_read_b128 v[220:223], v206 offset:5120
	ds_read_b128 v[224:227], v206 offset:6144
	ds_read_b128 v[228:231], v206 offset:7168
	s_waitcnt vmcnt(8)
	s_waitcnt lgkmcnt(0)
	s_barrier
	s_waitcnt lgkmcnt(0)
	v_mfma_f32_16x16x32_bf16 v[120:123], v[128:131], v[170:173], 0
	v_mfma_f32_16x16x32_bf16 v[124:127], v[136:139], v[170:173], 0
	v_mfma_f32_16x16x32_bf16 v[108:111], v[128:131], v[194:197], 0
	v_mfma_f32_16x16x32_bf16 v[104:107], v[136:139], v[194:197], 0
	v_mfma_f32_16x16x32_bf16 v[92:95], v[128:131], v[212:215], 0
	v_mfma_f32_16x16x32_bf16 v[88:91], v[136:139], v[212:215], 0
	v_mfma_f32_16x16x32_bf16 v[76:79], v[128:131], v[224:227], 0
	v_mfma_f32_16x16x32_bf16 v[72:75], v[136:139], v[224:227], 0
	v_mfma_f32_16x16x32_bf16 v[120:123], v[132:135], v[174:177], v[120:123]
	v_mfma_f32_16x16x32_bf16 v[124:127], v[140:143], v[174:177], v[124:127]
	v_mfma_f32_16x16x32_bf16 v[108:111], v[132:135], v[208:211], v[108:111]
	v_mfma_f32_16x16x32_bf16 v[104:107], v[140:143], v[208:211], v[104:107]
	v_mfma_f32_16x16x32_bf16 v[92:95], v[132:135], v[220:223], v[92:95]
	v_mfma_f32_16x16x32_bf16 v[88:91], v[140:143], v[220:223], v[88:91]
	v_mfma_f32_16x16x32_bf16 v[76:79], v[132:135], v[228:231], v[76:79]
	v_mfma_f32_16x16x32_bf16 v[72:75], v[140:143], v[228:231], v[72:75]
	v_mfma_f32_16x16x32_bf16 v[116:119], v[144:147], v[170:173], 0
	v_mfma_f32_16x16x32_bf16 v[112:115], v[152:155], v[170:173], 0
	v_mfma_f32_16x16x32_bf16 v[100:103], v[144:147], v[194:197], 0
	v_mfma_f32_16x16x32_bf16 v[96:99], v[152:155], v[194:197], 0
	v_mfma_f32_16x16x32_bf16 v[84:87], v[144:147], v[212:215], 0
	v_mfma_f32_16x16x32_bf16 v[80:83], v[152:155], v[212:215], 0
	v_mfma_f32_16x16x32_bf16 v[68:71], v[144:147], v[224:227], 0
	v_mfma_f32_16x16x32_bf16 v[64:67], v[152:155], v[224:227], 0
	v_mfma_f32_16x16x32_bf16 v[116:119], v[148:151], v[174:177], v[116:119]
	v_mfma_f32_16x16x32_bf16 v[112:115], v[166:169], v[174:177], v[112:115]
	v_mfma_f32_16x16x32_bf16 v[100:103], v[148:151], v[208:211], v[100:103]
	v_mfma_f32_16x16x32_bf16 v[96:99], v[166:169], v[208:211], v[96:99]
	v_mfma_f32_16x16x32_bf16 v[84:87], v[148:151], v[220:223], v[84:87]
	v_mfma_f32_16x16x32_bf16 v[80:83], v[166:169], v[220:223], v[80:83]
	v_mfma_f32_16x16x32_bf16 v[68:71], v[148:151], v[228:231], v[68:71]
	v_mfma_f32_16x16x32_bf16 v[64:67], v[166:169], v[228:231], v[64:67]
	s_barrier
	s_add_i32 s62, s62, s34
	v_lshl_add_u64 v[178:179], s[60:61], 0, v[180:181]
	s_mov_b32 m0, s62
	global_load_lds_dwordx4 v[178:179], off
	s_add_i32 m0, s62, 0x2000
	v_lshl_add_u64 v[202:203], s[60:61], 0, v[156:157]
	s_add_u32 s60, s60, s6
	s_addc_u32 s61, s61, s7
	s_add_i32 s45, s45, s34
	global_load_lds_dwordx4 v[202:203], off
	v_lshl_add_u64 v[216:217], s[60:61], 0, v[180:181]
	s_mov_b32 m0, s45
	v_lshl_add_u64 v[232:233], s[60:61], 0, v[156:157]
	global_load_lds_dwordx4 v[216:217], off
	s_add_i32 m0, s45, 0x2000
	v_lshl_add_u64 v[234:235], s[28:29], 0, v[160:161]
	global_load_lds_dwordx4 v[232:233], off
	s_mov_b32 m0, s35
	v_lshl_add_u64 v[236:237], s[28:29], 0, v[158:159]
	global_load_lds_dwordx4 v[234:235], off
	s_mov_b32 m0, s36
	s_nop 0
	global_load_lds_dwordx4 v[236:237], off
	ds_read_b128 v[170:173], v206 offset:16384
	ds_read_b128 v[174:177], v206 offset:17408
	ds_read_b128 v[194:197], v206 offset:18432
	ds_read_b128 v[208:211], v206 offset:19456
	ds_read_b128 v[212:215], v206 offset:20480
	ds_read_b128 v[220:223], v206 offset:21504
	ds_read_b128 v[224:227], v206 offset:22528
	ds_read_b128 v[228:231], v206 offset:23552
	s_waitcnt vmcnt(8)
	s_waitcnt lgkmcnt(0)
	s_barrier
	s_waitcnt lgkmcnt(0)
	v_mfma_f32_16x16x32_bf16 v[60:63], v[128:131], v[170:173], 0
	v_mfma_f32_16x16x32_bf16 v[56:59], v[136:139], v[170:173], 0
	v_mfma_f32_16x16x32_bf16 v[44:47], v[128:131], v[194:197], 0
	v_mfma_f32_16x16x32_bf16 v[40:43], v[136:139], v[194:197], 0
	v_mfma_f32_16x16x32_bf16 v[28:31], v[128:131], v[212:215], 0
	v_mfma_f32_16x16x32_bf16 v[24:27], v[136:139], v[212:215], 0
	v_mfma_f32_16x16x32_bf16 v[12:15], v[128:131], v[224:227], 0
	v_mfma_f32_16x16x32_bf16 v[8:11], v[136:139], v[224:227], 0
	v_mfma_f32_16x16x32_bf16 v[60:63], v[132:135], v[174:177], v[60:63]
	v_mfma_f32_16x16x32_bf16 v[56:59], v[140:143], v[174:177], v[56:59]
	v_mfma_f32_16x16x32_bf16 v[44:47], v[132:135], v[208:211], v[44:47]
	v_mfma_f32_16x16x32_bf16 v[40:43], v[140:143], v[208:211], v[40:43]
	v_mfma_f32_16x16x32_bf16 v[28:31], v[132:135], v[220:223], v[28:31]
	v_mfma_f32_16x16x32_bf16 v[24:27], v[140:143], v[220:223], v[24:27]
	v_mfma_f32_16x16x32_bf16 v[12:15], v[132:135], v[228:231], v[12:15]
	v_mfma_f32_16x16x32_bf16 v[8:11], v[140:143], v[228:231], v[8:11]
	v_mfma_f32_16x16x32_bf16 v[52:55], v[144:147], v[170:173], 0
	v_mfma_f32_16x16x32_bf16 v[48:51], v[152:155], v[170:173], 0
	v_mfma_f32_16x16x32_bf16 v[36:39], v[144:147], v[194:197], 0
	v_mfma_f32_16x16x32_bf16 v[32:35], v[152:155], v[194:197], 0
	v_mfma_f32_16x16x32_bf16 v[20:23], v[144:147], v[212:215], 0
	v_mfma_f32_16x16x32_bf16 v[16:19], v[152:155], v[212:215], 0
	v_mfma_f32_16x16x32_bf16 v[4:7], v[144:147], v[224:227], 0
	v_mfma_f32_16x16x32_bf16 v[0:3], v[152:155], v[224:227], 0
	v_mfma_f32_16x16x32_bf16 v[52:55], v[148:151], v[174:177], v[52:55]
	v_mfma_f32_16x16x32_bf16 v[48:51], v[166:169], v[174:177], v[48:51]
	v_mfma_f32_16x16x32_bf16 v[36:39], v[148:151], v[208:211], v[36:39]
	v_mfma_f32_16x16x32_bf16 v[32:35], v[166:169], v[208:211], v[32:35]
	v_mfma_f32_16x16x32_bf16 v[20:23], v[148:151], v[220:223], v[20:23]
	v_mfma_f32_16x16x32_bf16 v[16:19], v[166:169], v[220:223], v[16:19]
	v_mfma_f32_16x16x32_bf16 v[4:7], v[148:151], v[228:231], v[4:7]
	v_mfma_f32_16x16x32_bf16 v[0:3], v[166:169], v[228:231], v[0:3]
	s_barrier
	s_add_i32 s45, 0, 0x18000
	s_add_i32 s60, 0, 0x1c000
	s_add_u32 s28, s28, s6
	s_addc_u32 s29, s29, s7
	s_mov_b32 m0, s37
	v_lshl_add_u64 v[238:239], s[28:29], 0, v[160:161]
	global_load_lds_dwordx4 v[238:239], off
	v_lshl_add_u64 v[238:239], s[28:29], 0, v[158:159]
	s_mov_b32 m0, s38
	s_nop 0
	global_load_lds_dwordx4 v[238:239], off
	v_add_u32_e32 v140, s45, v199
	v_add_u32_e32 v166, s60, v199
	ds_read_b128 v[128:131], v140
	ds_read_b128 v[132:135], v140 offset:1024
	ds_read_b128 v[136:139], v140 offset:2048
	ds_read_b128 v[140:143], v140 offset:3072
	ds_read_b128 v[144:147], v166
	ds_read_b128 v[148:151], v166 offset:1024
	ds_read_b128 v[152:155], v166 offset:2048
	ds_read_b128 v[166:169], v166 offset:3072
	ds_read_b128 v[170:173], v206 offset:32768
	ds_read_b128 v[174:177], v206 offset:33792
	ds_read_b128 v[194:197], v206 offset:34816
	ds_read_b128 v[208:211], v206 offset:35840
	ds_read_b128 v[212:215], v206 offset:36864
	ds_read_b128 v[220:223], v206 offset:37888
	ds_read_b128 v[224:227], v206 offset:38912
	ds_read_b128 v[228:231], v206 offset:39936
	s_waitcnt vmcnt(8)
	s_waitcnt lgkmcnt(0)
	s_barrier
	s_waitcnt lgkmcnt(0)
	v_mfma_f32_16x16x32_bf16 v[120:123], v[128:131], v[170:173], v[120:123]
	v_mfma_f32_16x16x32_bf16 v[124:127], v[136:139], v[170:173], v[124:127]
	v_mfma_f32_16x16x32_bf16 v[108:111], v[128:131], v[194:197], v[108:111]
	v_mfma_f32_16x16x32_bf16 v[104:107], v[136:139], v[194:197], v[104:107]
	v_mfma_f32_16x16x32_bf16 v[92:95], v[128:131], v[212:215], v[92:95]
	v_mfma_f32_16x16x32_bf16 v[88:91], v[136:139], v[212:215], v[88:91]
	v_mfma_f32_16x16x32_bf16 v[76:79], v[128:131], v[224:227], v[76:79]
	v_mfma_f32_16x16x32_bf16 v[72:75], v[136:139], v[224:227], v[72:75]
	v_mfma_f32_16x16x32_bf16 v[120:123], v[132:135], v[174:177], v[120:123]
	v_mfma_f32_16x16x32_bf16 v[124:127], v[140:143], v[174:177], v[124:127]
	v_mfma_f32_16x16x32_bf16 v[108:111], v[132:135], v[208:211], v[108:111]
	v_mfma_f32_16x16x32_bf16 v[104:107], v[140:143], v[208:211], v[104:107]
	v_mfma_f32_16x16x32_bf16 v[92:95], v[132:135], v[220:223], v[92:95]
	v_mfma_f32_16x16x32_bf16 v[88:91], v[140:143], v[220:223], v[88:91]
	v_mfma_f32_16x16x32_bf16 v[76:79], v[132:135], v[228:231], v[76:79]
	v_mfma_f32_16x16x32_bf16 v[72:75], v[140:143], v[228:231], v[72:75]
	v_mfma_f32_16x16x32_bf16 v[116:119], v[144:147], v[170:173], v[116:119]
	v_mfma_f32_16x16x32_bf16 v[112:115], v[152:155], v[170:173], v[112:115]
	v_mfma_f32_16x16x32_bf16 v[100:103], v[144:147], v[194:197], v[100:103]
	v_mfma_f32_16x16x32_bf16 v[96:99], v[152:155], v[194:197], v[96:99]
	v_mfma_f32_16x16x32_bf16 v[84:87], v[144:147], v[212:215], v[84:87]
	v_mfma_f32_16x16x32_bf16 v[80:83], v[152:155], v[212:215], v[80:83]
	v_mfma_f32_16x16x32_bf16 v[68:71], v[144:147], v[224:227], v[68:71]
	v_mfma_f32_16x16x32_bf16 v[64:67], v[152:155], v[224:227], v[64:67]
	v_mfma_f32_16x16x32_bf16 v[116:119], v[148:151], v[174:177], v[116:119]
	v_mfma_f32_16x16x32_bf16 v[112:115], v[166:169], v[174:177], v[112:115]
	v_mfma_f32_16x16x32_bf16 v[100:103], v[148:151], v[208:211], v[100:103]
	v_mfma_f32_16x16x32_bf16 v[96:99], v[166:169], v[208:211], v[96:99]
	v_mfma_f32_16x16x32_bf16 v[84:87], v[148:151], v[220:223], v[84:87]
	v_mfma_f32_16x16x32_bf16 v[80:83], v[166:169], v[220:223], v[80:83]
	v_mfma_f32_16x16x32_bf16 v[68:71], v[148:151], v[228:231], v[68:71]
	v_mfma_f32_16x16x32_bf16 v[64:67], v[166:169], v[228:231], v[64:67]
	s_barrier
	s_add_i32 s28, s45, s34
	v_lshl_add_u64 v[178:179], v[178:179], 0, s[12:13]
	s_mov_b32 m0, s28
	global_load_lds_dwordx4 v[178:179], off
	v_lshl_add_u64 v[178:179], v[202:203], 0, s[12:13]
	s_add_i32 m0, s28, 0x2000
	s_add_i32 s28, s60, s34
	global_load_lds_dwordx4 v[178:179], off
	v_lshl_add_u64 v[178:179], v[216:217], 0, s[12:13]
	s_mov_b32 m0, s28
	s_nop 0
	global_load_lds_dwordx4 v[178:179], off
	v_lshl_add_u64 v[178:179], v[232:233], 0, s[12:13]
	s_add_i32 m0, s28, 0x2000
	s_nop 0
	global_load_lds_dwordx4 v[178:179], off
	v_lshl_add_u64 v[178:179], v[234:235], 0, s[12:13]
	s_mov_b32 m0, s47
	s_nop 0
	global_load_lds_dwordx4 v[178:179], off
	v_lshl_add_u64 v[178:179], v[236:237], 0, s[12:13]
	s_mov_b32 m0, s48
	s_nop 0
	global_load_lds_dwordx4 v[178:179], off
	ds_read_b128 v[170:173], v206 offset:49152
	ds_read_b128 v[174:177], v206 offset:50176
	ds_read_b128 v[194:197], v206 offset:51200
	ds_read_b128 v[208:211], v206 offset:52224
	ds_read_b128 v[212:215], v206 offset:53248
	ds_read_b128 v[220:223], v206 offset:54272
	ds_read_b128 v[224:227], v206 offset:55296
	ds_read_b128 v[228:231], v206 offset:56320
	s_waitcnt vmcnt(8)
	s_waitcnt lgkmcnt(0)
	s_barrier
	s_waitcnt lgkmcnt(0)
	v_mfma_f32_16x16x32_bf16 v[60:63], v[128:131], v[170:173], v[60:63]
	s_add_u32 s26, s26, 0x100
	v_mfma_f32_16x16x32_bf16 v[56:59], v[136:139], v[170:173], v[56:59]
	s_addc_u32 s27, s27, 0
	v_mfma_f32_16x16x32_bf16 v[44:47], v[128:131], v[194:197], v[44:47]
	s_add_u32 s10, s10, 0x100
	v_mfma_f32_16x16x32_bf16 v[40:43], v[136:139], v[194:197], v[40:43]
	s_addc_u32 s11, s11, 0
	v_mfma_f32_16x16x32_bf16 v[28:31], v[128:131], v[212:215], v[28:31]
	s_mov_b32 s28, s44
	v_mfma_f32_16x16x32_bf16 v[24:27], v[136:139], v[212:215], v[24:27]
	s_cmp_ge_i32 s44, s46
	v_mfma_f32_16x16x32_bf16 v[12:15], v[128:131], v[224:227], v[12:15]
	s_cselect_b32 s99, 1, 0
	v_mfma_f32_16x16x32_bf16 v[8:11], v[136:139], v[224:227], v[8:11]
	s_add_i32 s44, s28, 2
	v_mfma_f32_16x16x32_bf16 v[60:63], v[132:135], v[174:177], v[60:63]
	s_add_u32 s45, s26, 0x80
	v_mfma_f32_16x16x32_bf16 v[56:59], v[140:143], v[174:177], v[56:59]
	s_addc_u32 s29, s27, 0
	v_mfma_f32_16x16x32_bf16 v[44:47], v[132:135], v[208:211], v[44:47]
	s_add_i32 s62, 0, 0x10000
	v_mfma_f32_16x16x32_bf16 v[40:43], v[140:143], v[208:211], v[40:43]
	s_cmp_eq_u32 s49, s28
	v_mfma_f32_16x16x32_bf16 v[28:31], v[132:135], v[220:223], v[28:31]
	s_cselect_b32 s29, s23, s29
	v_mfma_f32_16x16x32_bf16 v[24:27], v[140:143], v[220:223], v[24:27]
	s_cselect_b32 s28, s22, s45
	v_mfma_f32_16x16x32_bf16 v[12:15], v[132:135], v[228:231], v[12:15]
	s_cselect_b32 s61, s25, s11
	v_mfma_f32_16x16x32_bf16 v[8:11], v[140:143], v[228:231], v[8:11]
	s_cselect_b32 s60, s24, s10
	v_mfma_f32_16x16x32_bf16 v[52:55], v[144:147], v[170:173], v[52:55]
	s_add_i32 s45, 0, 0x14000
	v_mfma_f32_16x16x32_bf16 v[48:51], v[152:155], v[170:173], v[48:51]
	v_mfma_f32_16x16x32_bf16 v[36:39], v[144:147], v[194:197], v[36:39]
	v_mfma_f32_16x16x32_bf16 v[32:35], v[152:155], v[194:197], v[32:35]
	v_mfma_f32_16x16x32_bf16 v[20:23], v[144:147], v[212:215], v[20:23]
	v_mfma_f32_16x16x32_bf16 v[16:19], v[152:155], v[212:215], v[16:19]
	v_mfma_f32_16x16x32_bf16 v[4:7], v[144:147], v[224:227], v[4:7]
	v_mfma_f32_16x16x32_bf16 v[0:3], v[152:155], v[224:227], v[0:3]
	v_mfma_f32_16x16x32_bf16 v[52:55], v[148:151], v[174:177], v[52:55]
	v_mfma_f32_16x16x32_bf16 v[48:51], v[166:169], v[174:177], v[48:51]
	v_mfma_f32_16x16x32_bf16 v[36:39], v[148:151], v[208:211], v[36:39]
	v_mfma_f32_16x16x32_bf16 v[32:35], v[166:169], v[208:211], v[32:35]
	v_mfma_f32_16x16x32_bf16 v[20:23], v[148:151], v[220:223], v[20:23]
	v_mfma_f32_16x16x32_bf16 v[16:19], v[166:169], v[220:223], v[16:19]
	v_mfma_f32_16x16x32_bf16 v[4:7], v[148:151], v[228:231], v[4:7]
	v_mfma_f32_16x16x32_bf16 v[0:3], v[166:169], v[228:231], v[0:3]
	s_barrier
	s_cmp_lg_u32 s99, 0
	s_cbranch_scc1 .Lpeelx_15
.LBB0_1224:
	v_lshl_add_u64 v[178:179], s[26:27], 0, v[162:163]
	s_add_i32 m0, s35, 0xc000
	global_load_lds_dwordx4 v[178:179], off
	v_lshl_add_u64 v[178:179], s[26:27], 0, v[164:165]
	s_add_i32 m0, s35, 0xe000
	s_nop 0
	global_load_lds_dwordx4 v[178:179], off
	v_add_u32_e32 v140, s62, v199
	v_add_u32_e32 v166, s45, v199
	ds_read_b128 v[128:131], v140
	ds_read_b128 v[132:135], v140 offset:1024
	ds_read_b128 v[136:139], v140 offset:2048
	ds_read_b128 v[140:143], v140 offset:3072
	ds_read_b128 v[144:147], v166
	ds_read_b128 v[148:151], v166 offset:1024
	ds_read_b128 v[152:155], v166 offset:2048
	ds_read_b128 v[166:169], v166 offset:3072
	ds_read_b128 v[170:173], v206
	ds_read_b128 v[174:177], v206 offset:1024
	ds_read_b128 v[194:197], v206 offset:2048
	ds_read_b128 v[208:211], v206 offset:3072
	ds_read_b128 v[212:215], v206 offset:4096
	ds_read_b128 v[220:223], v206 offset:5120
	ds_read_b128 v[224:227], v206 offset:6144
	ds_read_b128 v[228:231], v206 offset:7168
	s_waitcnt vmcnt(8)
	s_waitcnt lgkmcnt(0)
	s_barrier
	s_waitcnt lgkmcnt(0)
	v_mfma_f32_16x16x32_bf16 v[120:123], v[128:131], v[170:173], v[120:123]
	v_mfma_f32_16x16x32_bf16 v[124:127], v[136:139], v[170:173], v[124:127]
	v_mfma_f32_16x16x32_bf16 v[108:111], v[128:131], v[194:197], v[108:111]
	v_mfma_f32_16x16x32_bf16 v[104:107], v[136:139], v[194:197], v[104:107]
	v_mfma_f32_16x16x32_bf16 v[92:95], v[128:131], v[212:215], v[92:95]
	v_mfma_f32_16x16x32_bf16 v[88:91], v[136:139], v[212:215], v[88:91]
	v_mfma_f32_16x16x32_bf16 v[76:79], v[128:131], v[224:227], v[76:79]
	v_mfma_f32_16x16x32_bf16 v[72:75], v[136:139], v[224:227], v[72:75]
	v_mfma_f32_16x16x32_bf16 v[120:123], v[132:135], v[174:177], v[120:123]
	v_mfma_f32_16x16x32_bf16 v[124:127], v[140:143], v[174:177], v[124:127]
	v_mfma_f32_16x16x32_bf16 v[108:111], v[132:135], v[208:211], v[108:111]
	v_mfma_f32_16x16x32_bf16 v[104:107], v[140:143], v[208:211], v[104:107]
	v_mfma_f32_16x16x32_bf16 v[92:95], v[132:135], v[220:223], v[92:95]
	v_mfma_f32_16x16x32_bf16 v[88:91], v[140:143], v[220:223], v[88:91]
	v_mfma_f32_16x16x32_bf16 v[76:79], v[132:135], v[228:231], v[76:79]
	v_mfma_f32_16x16x32_bf16 v[72:75], v[140:143], v[228:231], v[72:75]
	v_mfma_f32_16x16x32_bf16 v[116:119], v[144:147], v[170:173], v[116:119]
	v_mfma_f32_16x16x32_bf16 v[112:115], v[152:155], v[170:173], v[112:115]
	v_mfma_f32_16x16x32_bf16 v[100:103], v[144:147], v[194:197], v[100:103]
	v_mfma_f32_16x16x32_bf16 v[96:99], v[152:155], v[194:197], v[96:99]
	v_mfma_f32_16x16x32_bf16 v[84:87], v[144:147], v[212:215], v[84:87]
	v_mfma_f32_16x16x32_bf16 v[80:83], v[152:155], v[212:215], v[80:83]
	v_mfma_f32_16x16x32_bf16 v[68:71], v[144:147], v[224:227], v[68:71]
	v_mfma_f32_16x16x32_bf16 v[64:67], v[152:155], v[224:227], v[64:67]
	v_mfma_f32_16x16x32_bf16 v[116:119], v[148:151], v[174:177], v[116:119]
	v_mfma_f32_16x16x32_bf16 v[112:115], v[166:169], v[174:177], v[112:115]
	v_mfma_f32_16x16x32_bf16 v[100:103], v[148:151], v[208:211], v[100:103]
	v_mfma_f32_16x16x32_bf16 v[96:99], v[166:169], v[208:211], v[96:99]
	v_mfma_f32_16x16x32_bf16 v[84:87], v[148:151], v[220:223], v[84:87]
	v_mfma_f32_16x16x32_bf16 v[80:83], v[166:169], v[220:223], v[80:83]
	v_mfma_f32_16x16x32_bf16 v[68:71], v[148:151], v[228:231], v[68:71]
	v_mfma_f32_16x16x32_bf16 v[64:67], v[166:169], v[228:231], v[64:67]
	s_barrier
	s_add_i32 s62, s62, s34
	v_lshl_add_u64 v[178:179], s[60:61], 0, v[180:181]
	s_mov_b32 m0, s62
	global_load_lds_dwordx4 v[178:179], off
	s_add_i32 m0, s62, 0x2000
	v_lshl_add_u64 v[202:203], s[60:61], 0, v[156:157]
	s_add_u32 s60, s60, s6
	s_addc_u32 s61, s61, s7
	s_add_i32 s45, s45, s34
	global_load_lds_dwordx4 v[202:203], off
	v_lshl_add_u64 v[216:217], s[60:61], 0, v[180:181]
	s_mov_b32 m0, s45
	v_lshl_add_u64 v[232:233], s[60:61], 0, v[156:157]
	global_load_lds_dwordx4 v[216:217], off
	s_add_i32 m0, s45, 0x2000
	v_lshl_add_u64 v[234:235], s[28:29], 0, v[160:161]
	global_load_lds_dwordx4 v[232:233], off
	s_mov_b32 m0, s35
	v_lshl_add_u64 v[236:237], s[28:29], 0, v[158:159]
	global_load_lds_dwordx4 v[234:235], off
	s_mov_b32 m0, s36
	s_nop 0
	global_load_lds_dwordx4 v[236:237], off
	ds_read_b128 v[170:173], v206 offset:16384
	ds_read_b128 v[174:177], v206 offset:17408
	ds_read_b128 v[194:197], v206 offset:18432
	ds_read_b128 v[208:211], v206 offset:19456
	ds_read_b128 v[212:215], v206 offset:20480
	ds_read_b128 v[220:223], v206 offset:21504
	ds_read_b128 v[224:227], v206 offset:22528
	ds_read_b128 v[228:231], v206 offset:23552
	s_waitcnt vmcnt(8)
	s_waitcnt lgkmcnt(0)
	s_barrier
	s_waitcnt lgkmcnt(0)
	v_mfma_f32_16x16x32_bf16 v[60:63], v[128:131], v[170:173], v[60:63]
	v_mfma_f32_16x16x32_bf16 v[56:59], v[136:139], v[170:173], v[56:59]
	v_mfma_f32_16x16x32_bf16 v[44:47], v[128:131], v[194:197], v[44:47]
	v_mfma_f32_16x16x32_bf16 v[40:43], v[136:139], v[194:197], v[40:43]
	v_mfma_f32_16x16x32_bf16 v[28:31], v[128:131], v[212:215], v[28:31]
	v_mfma_f32_16x16x32_bf16 v[24:27], v[136:139], v[212:215], v[24:27]
	v_mfma_f32_16x16x32_bf16 v[12:15], v[128:131], v[224:227], v[12:15]
	v_mfma_f32_16x16x32_bf16 v[8:11], v[136:139], v[224:227], v[8:11]
	v_mfma_f32_16x16x32_bf16 v[60:63], v[132:135], v[174:177], v[60:63]
	v_mfma_f32_16x16x32_bf16 v[56:59], v[140:143], v[174:177], v[56:59]
	v_mfma_f32_16x16x32_bf16 v[44:47], v[132:135], v[208:211], v[44:47]
	v_mfma_f32_16x16x32_bf16 v[40:43], v[140:143], v[208:211], v[40:43]
	v_mfma_f32_16x16x32_bf16 v[28:31], v[132:135], v[220:223], v[28:31]
	v_mfma_f32_16x16x32_bf16 v[24:27], v[140:143], v[220:223], v[24:27]
	v_mfma_f32_16x16x32_bf16 v[12:15], v[132:135], v[228:231], v[12:15]
	v_mfma_f32_16x16x32_bf16 v[8:11], v[140:143], v[228:231], v[8:11]
	v_mfma_f32_16x16x32_bf16 v[52:55], v[144:147], v[170:173], v[52:55]
	v_mfma_f32_16x16x32_bf16 v[48:51], v[152:155], v[170:173], v[48:51]
	v_mfma_f32_16x16x32_bf16 v[36:39], v[144:147], v[194:197], v[36:39]
	v_mfma_f32_16x16x32_bf16 v[32:35], v[152:155], v[194:197], v[32:35]
	v_mfma_f32_16x16x32_bf16 v[20:23], v[144:147], v[212:215], v[20:23]
	v_mfma_f32_16x16x32_bf16 v[16:19], v[152:155], v[212:215], v[16:19]
	v_mfma_f32_16x16x32_bf16 v[4:7], v[144:147], v[224:227], v[4:7]
	v_mfma_f32_16x16x32_bf16 v[0:3], v[152:155], v[224:227], v[0:3]
	v_mfma_f32_16x16x32_bf16 v[52:55], v[148:151], v[174:177], v[52:55]
	v_mfma_f32_16x16x32_bf16 v[48:51], v[166:169], v[174:177], v[48:51]
	v_mfma_f32_16x16x32_bf16 v[36:39], v[148:151], v[208:211], v[36:39]
	v_mfma_f32_16x16x32_bf16 v[32:35], v[166:169], v[208:211], v[32:35]
	v_mfma_f32_16x16x32_bf16 v[20:23], v[148:151], v[220:223], v[20:23]
	v_mfma_f32_16x16x32_bf16 v[16:19], v[166:169], v[220:223], v[16:19]
	v_mfma_f32_16x16x32_bf16 v[4:7], v[148:151], v[228:231], v[4:7]
	v_mfma_f32_16x16x32_bf16 v[0:3], v[166:169], v[228:231], v[0:3]
	s_barrier
	s_add_i32 s45, 0, 0x18000
	s_add_i32 s60, 0, 0x1c000
	s_add_u32 s28, s28, s6
	s_addc_u32 s29, s29, s7
	s_mov_b32 m0, s37
	v_lshl_add_u64 v[238:239], s[28:29], 0, v[160:161]
	global_load_lds_dwordx4 v[238:239], off
	v_lshl_add_u64 v[238:239], s[28:29], 0, v[158:159]
	s_mov_b32 m0, s38
	s_nop 0
	global_load_lds_dwordx4 v[238:239], off
	v_add_u32_e32 v140, s45, v199
	v_add_u32_e32 v166, s60, v199
	ds_read_b128 v[128:131], v140
	ds_read_b128 v[132:135], v140 offset:1024
	ds_read_b128 v[136:139], v140 offset:2048
	ds_read_b128 v[140:143], v140 offset:3072
	ds_read_b128 v[144:147], v166
	ds_read_b128 v[148:151], v166 offset:1024
	ds_read_b128 v[152:155], v166 offset:2048
	ds_read_b128 v[166:169], v166 offset:3072
	ds_read_b128 v[170:173], v206 offset:32768
	ds_read_b128 v[174:177], v206 offset:33792
	ds_read_b128 v[194:197], v206 offset:34816
	ds_read_b128 v[208:211], v206 offset:35840
	ds_read_b128 v[212:215], v206 offset:36864
	ds_read_b128 v[220:223], v206 offset:37888
	ds_read_b128 v[224:227], v206 offset:38912
	ds_read_b128 v[228:231], v206 offset:39936
	s_waitcnt vmcnt(8)
	s_waitcnt lgkmcnt(0)
	s_barrier
	s_waitcnt lgkmcnt(0)
	v_mfma_f32_16x16x32_bf16 v[120:123], v[128:131], v[170:173], v[120:123]
	v_mfma_f32_16x16x32_bf16 v[124:127], v[136:139], v[170:173], v[124:127]
	v_mfma_f32_16x16x32_bf16 v[108:111], v[128:131], v[194:197], v[108:111]
	v_mfma_f32_16x16x32_bf16 v[104:107], v[136:139], v[194:197], v[104:107]
	v_mfma_f32_16x16x32_bf16 v[92:95], v[128:131], v[212:215], v[92:95]
	v_mfma_f32_16x16x32_bf16 v[88:91], v[136:139], v[212:215], v[88:91]
	v_mfma_f32_16x16x32_bf16 v[76:79], v[128:131], v[224:227], v[76:79]
	v_mfma_f32_16x16x32_bf16 v[72:75], v[136:139], v[224:227], v[72:75]
	v_mfma_f32_16x16x32_bf16 v[120:123], v[132:135], v[174:177], v[120:123]
	v_mfma_f32_16x16x32_bf16 v[124:127], v[140:143], v[174:177], v[124:127]
	v_mfma_f32_16x16x32_bf16 v[108:111], v[132:135], v[208:211], v[108:111]
	v_mfma_f32_16x16x32_bf16 v[104:107], v[140:143], v[208:211], v[104:107]
	v_mfma_f32_16x16x32_bf16 v[92:95], v[132:135], v[220:223], v[92:95]
	v_mfma_f32_16x16x32_bf16 v[88:91], v[140:143], v[220:223], v[88:91]
	v_mfma_f32_16x16x32_bf16 v[76:79], v[132:135], v[228:231], v[76:79]
	v_mfma_f32_16x16x32_bf16 v[72:75], v[140:143], v[228:231], v[72:75]
	v_mfma_f32_16x16x32_bf16 v[116:119], v[144:147], v[170:173], v[116:119]
	v_mfma_f32_16x16x32_bf16 v[112:115], v[152:155], v[170:173], v[112:115]
	v_mfma_f32_16x16x32_bf16 v[100:103], v[144:147], v[194:197], v[100:103]
	v_mfma_f32_16x16x32_bf16 v[96:99], v[152:155], v[194:197], v[96:99]
	v_mfma_f32_16x16x32_bf16 v[84:87], v[144:147], v[212:215], v[84:87]
	v_mfma_f32_16x16x32_bf16 v[80:83], v[152:155], v[212:215], v[80:83]
	v_mfma_f32_16x16x32_bf16 v[68:71], v[144:147], v[224:227], v[68:71]
	v_mfma_f32_16x16x32_bf16 v[64:67], v[152:155], v[224:227], v[64:67]
	v_mfma_f32_16x16x32_bf16 v[116:119], v[148:151], v[174:177], v[116:119]
	v_mfma_f32_16x16x32_bf16 v[112:115], v[166:169], v[174:177], v[112:115]
	v_mfma_f32_16x16x32_bf16 v[100:103], v[148:151], v[208:211], v[100:103]
	v_mfma_f32_16x16x32_bf16 v[96:99], v[166:169], v[208:211], v[96:99]
	v_mfma_f32_16x16x32_bf16 v[84:87], v[148:151], v[220:223], v[84:87]
	v_mfma_f32_16x16x32_bf16 v[80:83], v[166:169], v[220:223], v[80:83]
	v_mfma_f32_16x16x32_bf16 v[68:71], v[148:151], v[228:231], v[68:71]
	v_mfma_f32_16x16x32_bf16 v[64:67], v[166:169], v[228:231], v[64:67]
	s_barrier
	s_add_i32 s28, s45, s34
	v_lshl_add_u64 v[178:179], v[178:179], 0, s[12:13]
	s_mov_b32 m0, s28
	global_load_lds_dwordx4 v[178:179], off
	v_lshl_add_u64 v[178:179], v[202:203], 0, s[12:13]
	s_add_i32 m0, s28, 0x2000
	s_add_i32 s28, s60, s34
	global_load_lds_dwordx4 v[178:179], off
	v_lshl_add_u64 v[178:179], v[216:217], 0, s[12:13]
	s_mov_b32 m0, s28
	s_nop 0
	global_load_lds_dwordx4 v[178:179], off
	v_lshl_add_u64 v[178:179], v[232:233], 0, s[12:13]
	s_add_i32 m0, s28, 0x2000
	s_nop 0
	global_load_lds_dwordx4 v[178:179], off
	v_lshl_add_u64 v[178:179], v[234:235], 0, s[12:13]
	s_mov_b32 m0, s47
	s_nop 0
	global_load_lds_dwordx4 v[178:179], off
	v_lshl_add_u64 v[178:179], v[236:237], 0, s[12:13]
	s_mov_b32 m0, s48
	s_nop 0
	global_load_lds_dwordx4 v[178:179], off
	ds_read_b128 v[170:173], v206 offset:49152
	ds_read_b128 v[174:177], v206 offset:50176
	ds_read_b128 v[194:197], v206 offset:51200
	ds_read_b128 v[208:211], v206 offset:52224
	ds_read_b128 v[212:215], v206 offset:53248
	ds_read_b128 v[220:223], v206 offset:54272
	ds_read_b128 v[224:227], v206 offset:55296
	ds_read_b128 v[228:231], v206 offset:56320
	s_waitcnt vmcnt(8)
	s_waitcnt lgkmcnt(0)
	s_barrier
	s_waitcnt lgkmcnt(0)
	v_mfma_f32_16x16x32_bf16 v[60:63], v[128:131], v[170:173], v[60:63]
	s_add_u32 s26, s26, 0x100
	v_mfma_f32_16x16x32_bf16 v[56:59], v[136:139], v[170:173], v[56:59]
	s_addc_u32 s27, s27, 0
	v_mfma_f32_16x16x32_bf16 v[44:47], v[128:131], v[194:197], v[44:47]
	s_add_u32 s10, s10, 0x100
	v_mfma_f32_16x16x32_bf16 v[40:43], v[136:139], v[194:197], v[40:43]
	s_addc_u32 s11, s11, 0
	v_mfma_f32_16x16x32_bf16 v[28:31], v[128:131], v[212:215], v[28:31]
	s_mov_b32 s28, s44
	v_mfma_f32_16x16x32_bf16 v[24:27], v[136:139], v[212:215], v[24:27]
	s_cmp_ge_i32 s44, s46
	v_mfma_f32_16x16x32_bf16 v[12:15], v[128:131], v[224:227], v[12:15]
	s_cselect_b32 s99, 1, 0
	v_mfma_f32_16x16x32_bf16 v[8:11], v[136:139], v[224:227], v[8:11]
	s_add_i32 s44, s28, 2
	v_mfma_f32_16x16x32_bf16 v[60:63], v[132:135], v[174:177], v[60:63]
	s_add_u32 s45, s26, 0x80
	v_mfma_f32_16x16x32_bf16 v[56:59], v[140:143], v[174:177], v[56:59]
	s_addc_u32 s29, s27, 0
	v_mfma_f32_16x16x32_bf16 v[44:47], v[132:135], v[208:211], v[44:47]
	s_add_i32 s62, 0, 0x10000
	v_mfma_f32_16x16x32_bf16 v[40:43], v[140:143], v[208:211], v[40:43]
	s_cmp_eq_u32 s49, s28
	v_mfma_f32_16x16x32_bf16 v[28:31], v[132:135], v[220:223], v[28:31]
	s_cselect_b32 s29, s23, s29
	v_mfma_f32_16x16x32_bf16 v[24:27], v[140:143], v[220:223], v[24:27]
	s_cselect_b32 s28, s22, s45
	v_mfma_f32_16x16x32_bf16 v[12:15], v[132:135], v[228:231], v[12:15]
	s_cselect_b32 s61, s25, s11
	v_mfma_f32_16x16x32_bf16 v[8:11], v[140:143], v[228:231], v[8:11]
	s_cselect_b32 s60, s24, s10
	v_mfma_f32_16x16x32_bf16 v[52:55], v[144:147], v[170:173], v[52:55]
	s_add_i32 s45, 0, 0x14000
	v_mfma_f32_16x16x32_bf16 v[48:51], v[152:155], v[170:173], v[48:51]
	v_mfma_f32_16x16x32_bf16 v[36:39], v[144:147], v[194:197], v[36:39]
	v_mfma_f32_16x16x32_bf16 v[32:35], v[152:155], v[194:197], v[32:35]
	v_mfma_f32_16x16x32_bf16 v[20:23], v[144:147], v[212:215], v[20:23]
	v_mfma_f32_16x16x32_bf16 v[16:19], v[152:155], v[212:215], v[16:19]
	v_mfma_f32_16x16x32_bf16 v[4:7], v[144:147], v[224:227], v[4:7]
	v_mfma_f32_16x16x32_bf16 v[0:3], v[152:155], v[224:227], v[0:3]
	v_mfma_f32_16x16x32_bf16 v[52:55], v[148:151], v[174:177], v[52:55]
	v_mfma_f32_16x16x32_bf16 v[48:51], v[166:169], v[174:177], v[48:51]
	v_mfma_f32_16x16x32_bf16 v[36:39], v[148:151], v[208:211], v[36:39]
	v_mfma_f32_16x16x32_bf16 v[32:35], v[166:169], v[208:211], v[32:35]
	v_mfma_f32_16x16x32_bf16 v[20:23], v[148:151], v[220:223], v[20:23]
	v_mfma_f32_16x16x32_bf16 v[16:19], v[166:169], v[220:223], v[16:19]
	v_mfma_f32_16x16x32_bf16 v[4:7], v[148:151], v[228:231], v[4:7]
	v_mfma_f32_16x16x32_bf16 v[0:3], v[166:169], v[228:231], v[0:3]
	s_barrier
	s_cmp_lg_u32 s99, 0
	s_cbranch_scc0 .LBB0_1224
